# v21_saddr
# speedup vs baseline: 1.0089x; 1.0034x over previous
; #define PG8_STAGE(bufoff, gbase, voff) do { _Pragma("unroll") for (int _i = 0; _i < 2; ++_i) \
;         __builtin_amdgcn_global_load_lds((const unsigned*)((const char*)(gbase) + (voff)[_i]), (PG8_LAS unsigned*)(lds + (bufoff) + ldsw + _i * 8192), 16, 0, 0); } while (0)
; #define PG8_LDA(dst, b, h) do { _Pragma("unroll") for (int m = 0; m < 4; ++m) _Pragma("unroll") for (int k = 0; k < 2; ++k) dst[m][k] = *(const PG8_LAS bf16x8*)(lds + PG8_SA(b, h) + aoff + m * 2048 + k * 1024); } while (0)
; #define PG8_LDB(dst, b, h) do { _Pragma("unroll") for (int n = 0; n < 2; ++n) _Pragma("unroll") for (int k = 0; k < 2; ++k) dst[n][k] = *(const PG8_LAS bf16x8*)(lds + PG8_SB(b, h) + boff + n * 2048 + k * 1024); } while (0)
; #define PG8_MMA(ai, bj, At, Bt) do { __builtin_amdgcn_s_setprio(1); _Pragma("unroll") for (int m = 0; m < 4; ++m) _Pragma("unroll") for (int n = 0; n < 2; ++n) _Pragma("unroll") for (int k = 0; k < 2; ++k) \
;         acc[ai][bj][m][n] = __builtin_amdgcn_mfma_f32_16x16x32_bf16(Bt[n][k], At[m][k], acc[ai][bj][m][n], 0, 0, 0); __builtin_amdgcn_s_setprio(0); } while (0)
; #define PG8_WAIT_V(n) asm volatile("s_waitcnt vmcnt(" #n ")" ::: "memory")
; #define PG8_WAIT_L(n) asm volatile("s_waitcnt lgkmcnt(" #n ")" ::: "memory")
; #define PG8_BAR __builtin_amdgcn_s_barrier()
; #define PG8_SCHED __builtin_amdgcn_sched_barrier(0)
; template <class Epi, class Sched, bool ALIGN_EPI = false, bool SP2 = false>
; __device__ __forceinline__ void gemm_phase(PG8_LAS unsigned char* lds, const Gemm g, const Sched& S, const Epi& E) {
;     ...
;             PG8_LDB(B0, 0, 0); PG8_LDB(B1, 0, 1); PG8_SCHED; PG8_LDA(At, 0, 0); PG8_STAGE(PG8_SA(1, 1), a1 + hstep, voffA);
;             PG8_WAIT_V(8); PG8_WAIT_L(0); PG8_BAR; PG8_MMA(0, 0, At, B0); PG8_MMA(0, 1, At, B1); PG8_BAR; PG8_SCHED;
;             PG8_LDA(At, 0, 1); PG8_STAGE(PG8_SB(0, 0), b2, voffB); PG8_STAGE(PG8_SB(0, 1), b2 + hstep, voffB); PG8_STAGE(PG8_SA(0, 0), a2, voffA);
;             PG8_WAIT_V(8); PG8_WAIT_L(0); PG8_BAR; PG8_MMA(1, 0, At, B0); PG8_MMA(1, 1, At, B1); PG8_BAR; PG8_SCHED;
.LBB0_169:
	ds_read_b128 v[152:155], v149
	ds_read_b128 v[156:159], v149 offset:1024
	ds_read_b128 v[160:163], v149 offset:2048
	ds_read_b128 v[164:167], v149 offset:3072
	ds_read_b128 v[168:171], v150
	ds_read_b128 v[172:175], v150 offset:1024
	ds_read_b128 v[176:179], v150 offset:2048
	ds_read_b128 v[180:183], v150 offset:3072
	s_add_u32 s40, s38, 0xfff80080
	s_addc_u32 s41, s39, -1
	s_cmp_eq_u32 s61, 28
	s_cselect_b32 s43, s29, s41
	s_cselect_b32 s42, s57, s40
	s_cselect_b32 s41, s27, s60
	s_cselect_b32 s40, s58, s59
	s_add_i32 m0, s37, 0xc000
	ds_read_b128 v[184:187], v151
	ds_read_b128 v[188:191], v151 offset:1024
	ds_read_b128 v[192:195], v151 offset:2048
	ds_read_b128 v[196:199], v151 offset:3072
	ds_read_b128 v[200:203], v151 offset:4096
	ds_read_b128 v[204:207], v151 offset:5120
	ds_read_b128 v[208:211], v151 offset:6144
	ds_read_b128 v[214:217], v151 offset:7168
	global_load_lds_dwordx4 v136, s[38:39]
	s_add_i32 m0, s37, 0xe000
	s_nop 0
	global_load_lds_dwordx4 v138, s[38:39]
	s_waitcnt vmcnt(8)
	s_waitcnt lgkmcnt(0)
	s_barrier
	s_setprio 1
	s_waitcnt lgkmcnt(0)
	v_mfma_f32_16x16x32_bf16 v[124:127], v[152:155], v[184:187], v[124:127]
	v_mfma_f32_16x16x32_bf16 v[120:123], v[160:163], v[184:187], v[120:123]
	v_mfma_f32_16x16x32_bf16 v[108:111], v[152:155], v[192:195], v[108:111]
	v_mfma_f32_16x16x32_bf16 v[104:107], v[160:163], v[192:195], v[104:107]
	v_mfma_f32_16x16x32_bf16 v[92:95], v[152:155], v[200:203], v[92:95]
	v_mfma_f32_16x16x32_bf16 v[88:91], v[160:163], v[200:203], v[88:91]
	v_mfma_f32_16x16x32_bf16 v[76:79], v[152:155], v[208:211], v[76:79]
	v_mfma_f32_16x16x32_bf16 v[72:75], v[160:163], v[208:211], v[72:75]
	v_mfma_f32_16x16x32_bf16 v[124:127], v[156:159], v[188:191], v[124:127]
	v_mfma_f32_16x16x32_bf16 v[120:123], v[164:167], v[188:191], v[120:123]
	v_mfma_f32_16x16x32_bf16 v[108:111], v[156:159], v[196:199], v[108:111]
	v_mfma_f32_16x16x32_bf16 v[104:107], v[164:167], v[196:199], v[104:107]
	v_mfma_f32_16x16x32_bf16 v[92:95], v[156:159], v[204:207], v[92:95]
	v_mfma_f32_16x16x32_bf16 v[88:91], v[164:167], v[204:207], v[88:91]
	v_mfma_f32_16x16x32_bf16 v[76:79], v[156:159], v[214:217], v[76:79]
	v_mfma_f32_16x16x32_bf16 v[72:75], v[164:167], v[214:217], v[72:75]
	s_setprio 0
	s_setprio 1
	v_mfma_f32_16x16x32_bf16 v[116:119], v[168:171], v[184:187], v[116:119]
	v_mfma_f32_16x16x32_bf16 v[112:115], v[176:179], v[184:187], v[112:115]
	v_mfma_f32_16x16x32_bf16 v[100:103], v[168:171], v[192:195], v[100:103]
	v_mfma_f32_16x16x32_bf16 v[96:99], v[176:179], v[192:195], v[96:99]
	v_mfma_f32_16x16x32_bf16 v[84:87], v[168:171], v[200:203], v[84:87]
	v_mfma_f32_16x16x32_bf16 v[80:83], v[176:179], v[200:203], v[80:83]
	v_mfma_f32_16x16x32_bf16 v[68:71], v[168:171], v[208:211], v[68:71]
	v_mfma_f32_16x16x32_bf16 v[64:67], v[176:179], v[208:211], v[64:67]
	v_mfma_f32_16x16x32_bf16 v[116:119], v[172:175], v[188:191], v[116:119]
	v_mfma_f32_16x16x32_bf16 v[112:115], v[180:183], v[188:191], v[112:115]
	v_mfma_f32_16x16x32_bf16 v[100:103], v[172:175], v[196:199], v[100:103]
	v_mfma_f32_16x16x32_bf16 v[96:99], v[180:183], v[196:199], v[96:99]
	v_mfma_f32_16x16x32_bf16 v[84:87], v[172:175], v[204:207], v[84:87]
	v_mfma_f32_16x16x32_bf16 v[80:83], v[180:183], v[204:207], v[80:83]
	v_mfma_f32_16x16x32_bf16 v[68:71], v[172:175], v[214:217], v[68:71]
	v_mfma_f32_16x16x32_bf16 v[64:67], v[180:183], v[214:217], v[64:67]
	s_setprio 0
	s_barrier
	s_add_i32 s62, s53, s24
	s_mov_b32 m0, s62
	ds_read_b128 v[184:187], v151 offset:16384
	ds_read_b128 v[188:191], v151 offset:17408
	ds_read_b128 v[192:195], v151 offset:18432
	ds_read_b128 v[196:199], v151 offset:19456
	ds_read_b128 v[200:203], v151 offset:20480
	ds_read_b128 v[204:207], v151 offset:21504
	ds_read_b128 v[208:211], v151 offset:22528
	ds_read_b128 v[214:217], v151 offset:23552
	global_load_lds_dwordx4 v132, s[40:41]
	s_add_i32 m0, s62, 0x2000
	s_add_u32 s62, s40, 0x80000
	s_addc_u32 s63, s41, 0
	s_add_i32 s64, s54, s24
	global_load_lds_dwordx4 v128, s[40:41]
	s_mov_b32 m0, s64
	s_nop 0
	global_load_lds_dwordx4 v132, s[62:63]
	s_add_i32 m0, s64, 0x2000
	s_nop 0
	global_load_lds_dwordx4 v128, s[62:63]
	s_mov_b32 m0, s37
	s_nop 0
	global_load_lds_dwordx4 v134, s[42:43]
	s_mov_b32 m0, s45
	s_nop 0
	global_load_lds_dwordx4 v130, s[42:43]
	s_waitcnt vmcnt(8)
	s_waitcnt lgkmcnt(0)
	s_barrier
	s_setprio 1
	s_waitcnt lgkmcnt(0)
	v_mfma_f32_16x16x32_bf16 v[60:63], v[152:155], v[184:187], v[60:63]
	v_mfma_f32_16x16x32_bf16 v[56:59], v[160:163], v[184:187], v[56:59]
	v_mfma_f32_16x16x32_bf16 v[44:47], v[152:155], v[192:195], v[44:47]
	v_mfma_f32_16x16x32_bf16 v[40:43], v[160:163], v[192:195], v[40:43]
	v_mfma_f32_16x16x32_bf16 v[28:31], v[152:155], v[200:203], v[28:31]
	v_mfma_f32_16x16x32_bf16 v[24:27], v[160:163], v[200:203], v[24:27]
	v_mfma_f32_16x16x32_bf16 v[12:15], v[152:155], v[208:211], v[12:15]
	v_mfma_f32_16x16x32_bf16 v[8:11], v[160:163], v[208:211], v[8:11]
	v_mfma_f32_16x16x32_bf16 v[60:63], v[156:159], v[188:191], v[60:63]
	v_mfma_f32_16x16x32_bf16 v[56:59], v[164:167], v[188:191], v[56:59]
	v_mfma_f32_16x16x32_bf16 v[44:47], v[156:159], v[196:199], v[44:47]
	v_mfma_f32_16x16x32_bf16 v[40:43], v[164:167], v[196:199], v[40:43]
	v_mfma_f32_16x16x32_bf16 v[28:31], v[156:159], v[204:207], v[28:31]
	v_mfma_f32_16x16x32_bf16 v[24:27], v[164:167], v[204:207], v[24:27]
	v_mfma_f32_16x16x32_bf16 v[12:15], v[156:159], v[214:217], v[12:15]
	v_mfma_f32_16x16x32_bf16 v[8:11], v[164:167], v[214:217], v[8:11]
	s_setprio 0
	s_setprio 1
	v_mfma_f32_16x16x32_bf16 v[52:55], v[168:171], v[184:187], v[52:55]
	v_mfma_f32_16x16x32_bf16 v[48:51], v[176:179], v[184:187], v[48:51]
	v_mfma_f32_16x16x32_bf16 v[36:39], v[168:171], v[192:195], v[36:39]
	v_mfma_f32_16x16x32_bf16 v[32:35], v[176:179], v[192:195], v[32:35]
	v_mfma_f32_16x16x32_bf16 v[20:23], v[168:171], v[200:203], v[20:23]
	v_mfma_f32_16x16x32_bf16 v[16:19], v[176:179], v[200:203], v[16:19]
	v_mfma_f32_16x16x32_bf16 v[4:7], v[168:171], v[208:211], v[4:7]
	v_mfma_f32_16x16x32_bf16 v[0:3], v[176:179], v[208:211], v[0:3]
	v_mfma_f32_16x16x32_bf16 v[52:55], v[172:175], v[188:191], v[52:55]
	v_mfma_f32_16x16x32_bf16 v[48:51], v[180:183], v[188:191], v[48:51]
	v_mfma_f32_16x16x32_bf16 v[36:39], v[172:175], v[196:199], v[36:39]
	v_mfma_f32_16x16x32_bf16 v[32:35], v[180:183], v[196:199], v[32:35]
	v_mfma_f32_16x16x32_bf16 v[20:23], v[172:175], v[204:207], v[20:23]
	v_mfma_f32_16x16x32_bf16 v[16:19], v[180:183], v[204:207], v[16:19]
	v_mfma_f32_16x16x32_bf16 v[4:7], v[172:175], v[214:217], v[4:7]
	v_mfma_f32_16x16x32_bf16 v[0:3], v[180:183], v[214:217], v[0:3]
	s_setprio 0
	s_barrier
; #define PG8_STAGE(bufoff, gbase, voff) do { _Pragma("unroll") for (int _i = 0; _i < 2; ++_i) \
;         __builtin_amdgcn_global_load_lds((const unsigned*)((const char*)(gbase) + (voff)[_i]), (PG8_LAS unsigned*)(lds + (bufoff) + ldsw + _i * 8192), 16, 0, 0); } while (0)
; #define PG8_LDA(dst, b, h) do { _Pragma("unroll") for (int m = 0; m < 4; ++m) _Pragma("unroll") for (int k = 0; k < 2; ++k) dst[m][k] = *(const PG8_LAS bf16x8*)(lds + PG8_SA(b, h) + aoff + m * 2048 + k * 1024); } while (0)
; #define PG8_LDB(dst, b, h) do { _Pragma("unroll") for (int n = 0; n < 2; ++n) _Pragma("unroll") for (int k = 0; k < 2; ++k) dst[n][k] = *(const PG8_LAS bf16x8*)(lds + PG8_SB(b, h) + boff + n * 2048 + k * 1024); } while (0)
; #define PG8_MMA(ai, bj, At, Bt) do { __builtin_amdgcn_s_setprio(1); _Pragma("unroll") for (int m = 0; m < 4; ++m) _Pragma("unroll") for (int n = 0; n < 2; ++n) _Pragma("unroll") for (int k = 0; k < 2; ++k) \
;         acc[ai][bj][m][n] = __builtin_amdgcn_mfma_f32_16x16x32_bf16(Bt[n][k], At[m][k], acc[ai][bj][m][n], 0, 0, 0); __builtin_amdgcn_s_setprio(0); } while (0)
; #define PG8_WAIT_V(n) asm volatile("s_waitcnt vmcnt(" #n ")" ::: "memory")
; #define PG8_WAIT_L(n) asm volatile("s_waitcnt lgkmcnt(" #n ")" ::: "memory")
; #define PG8_BAR __builtin_amdgcn_s_barrier()
; #define PG8_SCHED __builtin_amdgcn_sched_barrier(0)
; template <class Epi, class Sched, bool ALIGN_EPI = false, bool SP2 = false>
; __device__ __forceinline__ void gemm_phase(PG8_LAS unsigned char* lds, const Gemm g, const Sched& S, const Epi& E) {
;     ...
;             PG8_LDB(B0, 1, 0); PG8_LDB(B1, 1, 1); PG8_SCHED; PG8_LDA(At, 1, 0); PG8_STAGE(PG8_SA(0, 1), a2 + hstep, voffA);
;             PG8_WAIT_V(8); PG8_WAIT_L(0); PG8_BAR; PG8_MMA(0, 0, At, B0); PG8_MMA(0, 1, At, B1); PG8_BAR; PG8_SCHED;
;             PG8_LDA(At, 1, 1); PG8_STAGE(PG8_SB(1, 0), b3, voffB); PG8_STAGE(PG8_SB(1, 1), b3 + hstep, voffB); PG8_STAGE(PG8_SA(1, 0), a3, voffA);
;             PG8_WAIT_V(8); PG8_WAIT_L(0); PG8_BAR; PG8_MMA(1, 0, At, B0); PG8_MMA(1, 1, At, B1); PG8_BAR; PG8_SCHED;
	s_add_i32 s62, 0, 0x18000
	s_add_i32 s63, 0, 0x1c000
	v_add_u32_e32 v164, s62, v147
	v_add_u32_e32 v180, s63, v147
	ds_read_b128 v[152:155], v164
	ds_read_b128 v[156:159], v164 offset:1024
	ds_read_b128 v[160:163], v164 offset:2048
	ds_read_b128 v[164:167], v164 offset:3072
	ds_read_b128 v[168:171], v180
	ds_read_b128 v[172:175], v180 offset:1024
	ds_read_b128 v[176:179], v180 offset:2048
	ds_read_b128 v[180:183], v180 offset:3072
	s_add_u32 s84, s42, 0x80
	s_addc_u32 s85, s43, 0
	s_add_u32 s42, s42, 0x80000
	s_addc_u32 s43, s43, 0
	s_mov_b32 m0, s46
	ds_read_b128 v[184:187], v151 offset:32768
	ds_read_b128 v[188:191], v151 offset:33792
	ds_read_b128 v[192:195], v151 offset:34816
	ds_read_b128 v[196:199], v151 offset:35840
	ds_read_b128 v[200:203], v151 offset:36864
	ds_read_b128 v[204:207], v151 offset:37888
	ds_read_b128 v[208:211], v151 offset:38912
	ds_read_b128 v[214:217], v151 offset:39936
	global_load_lds_dwordx4 v134, s[42:43]
	s_mov_b32 m0, s47
	s_nop 0
	global_load_lds_dwordx4 v130, s[42:43]
	s_waitcnt vmcnt(8)
	s_waitcnt lgkmcnt(0)
	s_barrier
	s_setprio 1
	s_waitcnt lgkmcnt(0)
	v_mfma_f32_16x16x32_bf16 v[124:127], v[152:155], v[184:187], v[124:127]
	v_mfma_f32_16x16x32_bf16 v[120:123], v[160:163], v[184:187], v[120:123]
	v_mfma_f32_16x16x32_bf16 v[108:111], v[152:155], v[192:195], v[108:111]
	v_mfma_f32_16x16x32_bf16 v[104:107], v[160:163], v[192:195], v[104:107]
	v_mfma_f32_16x16x32_bf16 v[92:95], v[152:155], v[200:203], v[92:95]
	v_mfma_f32_16x16x32_bf16 v[88:91], v[160:163], v[200:203], v[88:91]
	v_mfma_f32_16x16x32_bf16 v[76:79], v[152:155], v[208:211], v[76:79]
	v_mfma_f32_16x16x32_bf16 v[72:75], v[160:163], v[208:211], v[72:75]
	v_mfma_f32_16x16x32_bf16 v[124:127], v[156:159], v[188:191], v[124:127]
	v_mfma_f32_16x16x32_bf16 v[120:123], v[164:167], v[188:191], v[120:123]
	v_mfma_f32_16x16x32_bf16 v[108:111], v[156:159], v[196:199], v[108:111]
	v_mfma_f32_16x16x32_bf16 v[104:107], v[164:167], v[196:199], v[104:107]
	v_mfma_f32_16x16x32_bf16 v[92:95], v[156:159], v[204:207], v[92:95]
	v_mfma_f32_16x16x32_bf16 v[88:91], v[164:167], v[204:207], v[88:91]
	v_mfma_f32_16x16x32_bf16 v[76:79], v[156:159], v[214:217], v[76:79]
	v_mfma_f32_16x16x32_bf16 v[72:75], v[164:167], v[214:217], v[72:75]
	s_setprio 0
	s_setprio 1
	v_mfma_f32_16x16x32_bf16 v[116:119], v[168:171], v[184:187], v[116:119]
	v_mfma_f32_16x16x32_bf16 v[112:115], v[176:179], v[184:187], v[112:115]
	v_mfma_f32_16x16x32_bf16 v[100:103], v[168:171], v[192:195], v[100:103]
	v_mfma_f32_16x16x32_bf16 v[96:99], v[176:179], v[192:195], v[96:99]
	v_mfma_f32_16x16x32_bf16 v[84:87], v[168:171], v[200:203], v[84:87]
	v_mfma_f32_16x16x32_bf16 v[80:83], v[176:179], v[200:203], v[80:83]
	v_mfma_f32_16x16x32_bf16 v[68:71], v[168:171], v[208:211], v[68:71]
	v_mfma_f32_16x16x32_bf16 v[64:67], v[176:179], v[208:211], v[64:67]
	v_mfma_f32_16x16x32_bf16 v[116:119], v[172:175], v[188:191], v[116:119]
	v_mfma_f32_16x16x32_bf16 v[112:115], v[180:183], v[188:191], v[112:115]
	v_mfma_f32_16x16x32_bf16 v[100:103], v[172:175], v[196:199], v[100:103]
	v_mfma_f32_16x16x32_bf16 v[96:99], v[180:183], v[196:199], v[96:99]
	v_mfma_f32_16x16x32_bf16 v[84:87], v[172:175], v[204:207], v[84:87]
	v_mfma_f32_16x16x32_bf16 v[80:83], v[180:183], v[204:207], v[80:83]
	v_mfma_f32_16x16x32_bf16 v[68:71], v[172:175], v[214:217], v[68:71]
	v_mfma_f32_16x16x32_bf16 v[64:67], v[180:183], v[214:217], v[64:67]
	s_setprio 0
	s_barrier
	s_add_i32 s42, s62, s24
	s_add_u32 s86, s40, 0x80
	s_addc_u32 s87, s41, 0
	s_mov_b32 m0, s42
	ds_read_b128 v[184:187], v151 offset:49152
	ds_read_b128 v[188:191], v151 offset:50176
	ds_read_b128 v[192:195], v151 offset:51200
	ds_read_b128 v[196:199], v151 offset:52224
	ds_read_b128 v[200:203], v151 offset:53248
	ds_read_b128 v[204:207], v151 offset:54272
	ds_read_b128 v[208:211], v151 offset:55296
	ds_read_b128 v[214:217], v151 offset:56320
	global_load_lds_dwordx4 v132, s[86:87]
	s_add_i32 m0, s42, 0x2000
	s_add_u32 s40, s40, 0x80080
	s_addc_u32 s41, s41, 0
	s_add_i32 s42, s63, s24
	global_load_lds_dwordx4 v128, s[86:87]
	s_mov_b32 m0, s42
	s_nop 0
	global_load_lds_dwordx4 v132, s[40:41]
	s_add_i32 m0, s42, 0x2000
	s_nop 0
	global_load_lds_dwordx4 v128, s[40:41]
	s_mov_b32 m0, s49
	s_nop 0
	global_load_lds_dwordx4 v134, s[84:85]
	s_mov_b32 m0, s50
	s_nop 0
	global_load_lds_dwordx4 v130, s[84:85]
	s_waitcnt vmcnt(8)
	s_waitcnt lgkmcnt(0)
	s_barrier
	s_setprio 1
	s_waitcnt lgkmcnt(0)
	v_mfma_f32_16x16x32_bf16 v[60:63], v[152:155], v[184:187], v[60:63]
	v_mfma_f32_16x16x32_bf16 v[56:59], v[160:163], v[184:187], v[56:59]
	v_mfma_f32_16x16x32_bf16 v[44:47], v[152:155], v[192:195], v[44:47]
	v_mfma_f32_16x16x32_bf16 v[40:43], v[160:163], v[192:195], v[40:43]
	v_mfma_f32_16x16x32_bf16 v[28:31], v[152:155], v[200:203], v[28:31]
	v_mfma_f32_16x16x32_bf16 v[24:27], v[160:163], v[200:203], v[24:27]
	v_mfma_f32_16x16x32_bf16 v[12:15], v[152:155], v[208:211], v[12:15]
	v_mfma_f32_16x16x32_bf16 v[8:11], v[160:163], v[208:211], v[8:11]
	v_mfma_f32_16x16x32_bf16 v[60:63], v[156:159], v[188:191], v[60:63]
	v_mfma_f32_16x16x32_bf16 v[56:59], v[164:167], v[188:191], v[56:59]
	v_mfma_f32_16x16x32_bf16 v[44:47], v[156:159], v[196:199], v[44:47]
	v_mfma_f32_16x16x32_bf16 v[40:43], v[164:167], v[196:199], v[40:43]
	v_mfma_f32_16x16x32_bf16 v[28:31], v[156:159], v[204:207], v[28:31]
	v_mfma_f32_16x16x32_bf16 v[24:27], v[164:167], v[204:207], v[24:27]
	v_mfma_f32_16x16x32_bf16 v[12:15], v[156:159], v[214:217], v[12:15]
	v_mfma_f32_16x16x32_bf16 v[8:11], v[164:167], v[214:217], v[8:11]
	s_setprio 0
	s_setprio 1
	v_mfma_f32_16x16x32_bf16 v[52:55], v[168:171], v[184:187], v[52:55]
	v_mfma_f32_16x16x32_bf16 v[48:51], v[176:179], v[184:187], v[48:51]
	v_mfma_f32_16x16x32_bf16 v[36:39], v[168:171], v[192:195], v[36:39]
	v_mfma_f32_16x16x32_bf16 v[32:35], v[176:179], v[192:195], v[32:35]
	v_mfma_f32_16x16x32_bf16 v[20:23], v[168:171], v[200:203], v[20:23]
	v_mfma_f32_16x16x32_bf16 v[16:19], v[176:179], v[200:203], v[16:19]
	v_mfma_f32_16x16x32_bf16 v[4:7], v[168:171], v[208:211], v[4:7]
	v_mfma_f32_16x16x32_bf16 v[0:3], v[176:179], v[208:211], v[0:3]
	v_mfma_f32_16x16x32_bf16 v[52:55], v[172:175], v[188:191], v[52:55]
	v_mfma_f32_16x16x32_bf16 v[48:51], v[180:183], v[188:191], v[48:51]
	v_mfma_f32_16x16x32_bf16 v[36:39], v[172:175], v[196:199], v[36:39]
	v_mfma_f32_16x16x32_bf16 v[32:35], v[180:183], v[196:199], v[32:35]
	v_mfma_f32_16x16x32_bf16 v[20:23], v[172:175], v[204:207], v[20:23]
	v_mfma_f32_16x16x32_bf16 v[16:19], v[180:183], v[204:207], v[16:19]
	v_mfma_f32_16x16x32_bf16 v[4:7], v[172:175], v[214:217], v[4:7]
	v_mfma_f32_16x16x32_bf16 v[0:3], v[180:183], v[214:217], v[0:3]
	s_setprio 0
	s_barrier
; __device__ __forceinline__ float fsilu(float v) { return v * fsigmoid(v); }
; __device__ __forceinline__ u32x4 pack8(const f32x4 a, const f32x4 b) { u32x4 w; w.x = cvt_pk_bf16(a[0], a[1]); w.y = cvt_pk_bf16(a[2], a[3]); w.z = cvt_pk_bf16(b[0], b[1]); w.w = cvt_pk_bf16(b[2], b[3]); return w; }
;     __device__ __forceinline__ void operator()(const f32x4 (&acc)[2][2][4][2], const Unit& u, int wr, int wc, int fr, int fq) const {
;         const int row0 = u.pm * BM + wr * 64 + fr, col0 = u.pn * 128 + wc * 32 + 8 * fq;
; #pragma unroll
;         for (int ai = 0; ai < 2; ++ai)
; #pragma unroll
;             for (int m = 0; m < 4; ++m) {
;                 bf16_t* rowp = O + (size_t)(row0 + ai * HALF + m * 16) * ldc + col0;
;                 f32x4 h0, h1;
; #pragma unroll
;                 for (int j = 0; j < 4; ++j) { h0[j] = fsilu(acc[ai][0][m][0][j]) * acc[ai][1][m][0][j]; h1[j] = fsilu(acc[ai][0][m][1][j]) * acc[ai][1][m][1][j]; }
;                 *(u32x4*)rowp = pack8(h0, h1);
; template <class Epi, class Sched, bool ALIGN_EPI = false, bool SP2 = false>
; __device__ __forceinline__ void gemm_phase(PG8_LAS unsigned char* lds, const Gemm g, const Sched& S, const Epi& E) {
;     ...
;         for (int t = 0; t < nt; t += 2) {
	s_add_i32 s61, s61, 2
	s_add_u32 s38, s38, 0x100
	s_addc_u32 s39, s39, 0
	s_add_u32 s59, s59, 0x100
	s_addc_u32 s60, s60, 0
	s_cmp_gt_u32 s61, 29
	s_cbranch_scc0 .LBB0_169
	v_mul_f32_e32 v153, 0xbfb8aa3b, v124
	v_mul_f32_e32 v158, 0xbfb8aa3b, v120
	v_exp_f32_e32 v153, v153
	v_exp_f32_e32 v159, v158
	v_mul_f32_e32 v158, 0xbfb8aa3b, v125
	v_exp_f32_e32 v160, v158
	v_add_f32_e32 v153, 1.0, v153
	v_rcp_f32_e32 v158, v153
	v_add_f32_e32 v153, 1.0, v159
	v_add_f32_e32 v159, 1.0, v160
	v_rcp_f32_e32 v159, v159
	v_mul_f32_e32 v160, 0xbfb8aa3b, v121
	v_exp_f32_e32 v161, v160
	v_rcp_f32_e32 v160, v153
	v_pk_mul_f32 v[124:125], v[124:125], v[158:159]
	v_mul_f32_e32 v153, 0xbfb8aa3b, v127
	v_pk_mul_f32 v[116:117], v[124:125], v[116:117]
	v_add_f32_e32 v124, 1.0, v161
	v_mul_f32_e32 v125, 0xbfb8aa3b, v122
	v_rcp_f32_e32 v161, v124
	v_mul_f32_e32 v124, 0xbfb8aa3b, v126
	v_exp_f32_e32 v125, v125
	v_exp_f32_e32 v124, v124
	v_exp_f32_e32 v153, v153
	v_mul_f32_e32 v158, 0xbfb8aa3b, v123
	v_exp_f32_e32 v159, v158
	v_add_f32_e32 v125, 1.0, v125
	v_add_f32_e32 v124, 1.0, v124
	v_rcp_f32_e32 v158, v125
	v_add_f32_e32 v125, 1.0, v153
	v_rcp_f32_e32 v124, v124
	v_rcp_f32_e32 v125, v125
	v_add_f32_e32 v153, 1.0, v159
	v_rcp_f32_e32 v159, v153
	v_pk_mul_f32 v[120:121], v[120:121], v[160:161]
	v_lshl_or_b32 v154, s56, 7, v148
	v_pk_mul_f32 v[120:121], v[120:121], v[112:113]
	v_pk_mul_f32 v[112:113], v[126:127], v[124:125]
	v_lshl_add_u32 v152, s36, 8, v146
	v_ashrrev_i32_e32 v155, 31, v154
	v_mov_b64_e32 v[144:145], s[10:11]
	v_pk_mul_f32 v[118:119], v[112:113], v[118:119]
	v_pk_mul_f32 v[112:113], v[122:123], v[158:159]
	v_mad_i64_i32 v[156:157], s[38:39], v152, s55, v[144:145]
	v_pk_mul_f32 v[122:123], v[112:113], v[114:115]
	v_lshlrev_b64 v[112:113], 1, v[154:155]
	v_lshl_add_u64 v[124:125], v[156:157], 0, v[112:113]
	v_cvt_pk_bf16_f32 v114, v116, v117
	v_cvt_pk_bf16_f32 v115, v118, v119
	v_cvt_pk_bf16_f32 v116, v120, v121
	v_cvt_pk_bf16_f32 v117, v122, v123
	global_store_dwordx4 v[124:125], v[114:117], off
	v_mul_f32_e32 v118, 0xbfb8aa3b, v109
	v_exp_f32_e32 v118, v118
	v_mul_f32_e32 v116, 0xbfb8aa3b, v108
	v_mul_f32_e32 v117, 0xbfb8aa3b, v104
	v_exp_f32_e32 v116, v116
	v_exp_f32_e32 v117, v117
	v_or_b32_e32 v114, 16, v152
	v_mad_i64_i32 v[114:115], s[38:39], v114, s55, v[144:145]
	v_add_f32_e32 v116, 1.0, v116
	v_add_f32_e32 v119, 1.0, v117
	v_add_f32_e32 v117, 1.0, v118
	v_rcp_f32_e32 v116, v116
	v_rcp_f32_e32 v117, v117
	v_mul_f32_e32 v118, 0xbfb8aa3b, v105
	v_exp_f32_e32 v120, v118
	v_rcp_f32_e32 v118, v119
	v_pk_mul_f32 v[108:109], v[108:109], v[116:117]
	v_mul_f32_e32 v116, 0xbfb8aa3b, v111
	v_pk_mul_f32 v[100:101], v[108:109], v[100:101]
	v_add_f32_e32 v108, 1.0, v120
	v_rcp_f32_e32 v119, v108
	v_mul_f32_e32 v109, 0xbfb8aa3b, v106
	v_mul_f32_e32 v108, 0xbfb8aa3b, v110
	v_exp_f32_e32 v109, v109
	v_exp_f32_e32 v108, v108
	v_exp_f32_e32 v117, v116
	v_mul_f32_e32 v116, 0xbfb8aa3b, v107
	v_pk_mul_f32 v[104:105], v[104:105], v[118:119]
	v_exp_f32_e32 v118, v116
	v_add_f32_e32 v109, 1.0, v109
	v_add_f32_e32 v108, 1.0, v108
	v_rcp_f32_e32 v116, v109
	v_add_f32_e32 v109, 1.0, v117
	v_rcp_f32_e32 v108, v108
	v_rcp_f32_e32 v109, v109
	v_add_f32_e32 v117, 1.0, v118
	v_rcp_f32_e32 v117, v117
	v_pk_mul_f32 v[104:105], v[104:105], v[96:97]
	v_pk_mul_f32 v[96:97], v[110:111], v[108:109]
	v_lshl_add_u64 v[108:109], v[114:115], 0, v[112:113]
	v_pk_mul_f32 v[102:103], v[96:97], v[102:103]
	v_pk_mul_f32 v[96:97], v[106:107], v[116:117]
	s_and_b64 vcc, exec, s[8:9]
	v_pk_mul_f32 v[106:107], v[96:97], v[98:99]
	v_cvt_pk_bf16_f32 v96, v100, v101
	v_cvt_pk_bf16_f32 v97, v102, v103
	v_cvt_pk_bf16_f32 v98, v104, v105
	v_cvt_pk_bf16_f32 v99, v106, v107
	global_store_dwordx4 v[108:109], v[96:99], off
	v_mul_f32_e32 v100, 0xbfb8aa3b, v93
	v_exp_f32_e32 v100, v100
	v_mul_f32_e32 v98, 0xbfb8aa3b, v92
	v_mul_f32_e32 v99, 0xbfb8aa3b, v88
	v_exp_f32_e32 v98, v98
	v_exp_f32_e32 v99, v99
	v_or_b32_e32 v96, 32, v152
	v_mad_i64_i32 v[96:97], s[38:39], v96, s55, v[144:145]
	v_add_f32_e32 v98, 1.0, v98
	v_add_f32_e32 v101, 1.0, v99
	v_add_f32_e32 v99, 1.0, v100
	v_rcp_f32_e32 v98, v98
	v_rcp_f32_e32 v99, v99
	v_mul_f32_e32 v100, 0xbfb8aa3b, v89
	v_exp_f32_e32 v102, v100
	v_rcp_f32_e32 v100, v101
	v_pk_mul_f32 v[92:93], v[92:93], v[98:99]
	v_mul_f32_e32 v98, 0xbfb8aa3b, v95
	v_pk_mul_f32 v[84:85], v[92:93], v[84:85]
	v_add_f32_e32 v92, 1.0, v102
	v_rcp_f32_e32 v101, v92
	v_mul_f32_e32 v93, 0xbfb8aa3b, v90
	v_mul_f32_e32 v92, 0xbfb8aa3b, v94
	v_exp_f32_e32 v93, v93
	v_exp_f32_e32 v92, v92
	v_exp_f32_e32 v99, v98
	v_mul_f32_e32 v98, 0xbfb8aa3b, v91
	v_pk_mul_f32 v[88:89], v[88:89], v[100:101]
	v_exp_f32_e32 v100, v98
	v_add_f32_e32 v93, 1.0, v93
	v_add_f32_e32 v92, 1.0, v92
	v_rcp_f32_e32 v98, v93
	v_add_f32_e32 v93, 1.0, v99
	v_rcp_f32_e32 v92, v92
	v_rcp_f32_e32 v93, v93
	v_add_f32_e32 v99, 1.0, v100
	v_rcp_f32_e32 v99, v99
	v_pk_mul_f32 v[88:89], v[88:89], v[80:81]
	v_pk_mul_f32 v[80:81], v[94:95], v[92:93]
	v_lshl_add_u64 v[92:93], v[96:97], 0, v[112:113]
	v_pk_mul_f32 v[86:87], v[80:81], v[86:87]
	v_pk_mul_f32 v[80:81], v[90:91], v[98:99]
	s_mov_b32 s56, s26
	v_pk_mul_f32 v[90:91], v[80:81], v[82:83]
	v_cvt_pk_bf16_f32 v80, v84, v85
	v_cvt_pk_bf16_f32 v81, v86, v87
	v_cvt_pk_bf16_f32 v82, v88, v89
	v_cvt_pk_bf16_f32 v83, v90, v91
	global_store_dwordx4 v[92:93], v[80:83], off
	v_mul_f32_e32 v84, 0xbfb8aa3b, v77
	v_exp_f32_e32 v84, v84
	v_mul_f32_e32 v82, 0xbfb8aa3b, v76
	v_mul_f32_e32 v83, 0xbfb8aa3b, v72
	v_exp_f32_e32 v82, v82
	v_exp_f32_e32 v83, v83
	v_or_b32_e32 v80, 48, v152
	v_mad_i64_i32 v[80:81], s[38:39], v80, s55, v[144:145]
	v_add_f32_e32 v82, 1.0, v82
	v_add_f32_e32 v85, 1.0, v83
; __device__ __forceinline__ float fsilu(float v) { return v * fsigmoid(v); }
; __device__ __forceinline__ u32x4 pack8(const f32x4 a, const f32x4 b) { u32x4 w; w.x = cvt_pk_bf16(a[0], a[1]); w.y = cvt_pk_bf16(a[2], a[3]); w.z = cvt_pk_bf16(b[0], b[1]); w.w = cvt_pk_bf16(b[2], b[3]); return w; }
;     __device__ __forceinline__ void operator()(const f32x4 (&acc)[2][2][4][2], const Unit& u, int wr, int wc, int fr, int fq) const {
;         const int row0 = u.pm * BM + wr * 64 + fr, col0 = u.pn * 128 + wc * 32 + 8 * fq;
; #pragma unroll
;         for (int ai = 0; ai < 2; ++ai)
; #pragma unroll
;             for (int m = 0; m < 4; ++m) {
;                 bf16_t* rowp = O + (size_t)(row0 + ai * HALF + m * 16) * ldc + col0;
;                 f32x4 h0, h1;
; #pragma unroll
;                 for (int j = 0; j < 4; ++j) { h0[j] = fsilu(acc[ai][0][m][0][j]) * acc[ai][1][m][0][j]; h1[j] = fsilu(acc[ai][0][m][1][j]) * acc[ai][1][m][1][j]; }
;                 *(u32x4*)rowp = pack8(h0, h1);
	v_add_f32_e32 v83, 1.0, v84
	v_rcp_f32_e32 v82, v82
	v_rcp_f32_e32 v83, v83
	v_mul_f32_e32 v84, 0xbfb8aa3b, v73
	v_exp_f32_e32 v86, v84
	v_rcp_f32_e32 v84, v85
	v_pk_mul_f32 v[76:77], v[76:77], v[82:83]
	v_mul_f32_e32 v82, 0xbfb8aa3b, v79
	v_pk_mul_f32 v[68:69], v[76:77], v[68:69]
	v_add_f32_e32 v76, 1.0, v86
	v_rcp_f32_e32 v85, v76
	v_mul_f32_e32 v77, 0xbfb8aa3b, v74
	v_mul_f32_e32 v76, 0xbfb8aa3b, v78
	v_exp_f32_e32 v77, v77
	v_exp_f32_e32 v76, v76
	v_exp_f32_e32 v83, v82
	v_mul_f32_e32 v82, 0xbfb8aa3b, v75
	v_pk_mul_f32 v[72:73], v[72:73], v[84:85]
	v_exp_f32_e32 v84, v82
	v_add_f32_e32 v77, 1.0, v77
	v_add_f32_e32 v76, 1.0, v76
	v_rcp_f32_e32 v82, v77
	v_add_f32_e32 v77, 1.0, v83
	v_rcp_f32_e32 v76, v76
	v_rcp_f32_e32 v77, v77
	v_add_f32_e32 v83, 1.0, v84
	v_rcp_f32_e32 v83, v83
	v_pk_mul_f32 v[72:73], v[72:73], v[64:65]
	v_pk_mul_f32 v[64:65], v[78:79], v[76:77]
	v_lshl_add_u64 v[76:77], v[80:81], 0, v[112:113]
	v_pk_mul_f32 v[70:71], v[64:65], v[70:71]
	v_pk_mul_f32 v[64:65], v[74:75], v[82:83]
	s_mov_b32 s36, s28
	v_pk_mul_f32 v[74:75], v[64:65], v[66:67]
	v_cvt_pk_bf16_f32 v64, v68, v69
	v_cvt_pk_bf16_f32 v65, v70, v71
	v_cvt_pk_bf16_f32 v66, v72, v73
	v_cvt_pk_bf16_f32 v67, v74, v75
	global_store_dwordx4 v[76:77], v[64:67], off
	v_mul_f32_e32 v68, 0xbfb8aa3b, v61
	v_exp_f32_e32 v68, v68
	v_mul_f32_e32 v66, 0xbfb8aa3b, v60
	v_mul_f32_e32 v67, 0xbfb8aa3b, v56
	v_exp_f32_e32 v66, v66
	v_exp_f32_e32 v67, v67
	v_add_u32_e32 v64, 0x80, v152
	v_mad_i64_i32 v[64:65], s[38:39], v64, s55, v[144:145]
	v_add_f32_e32 v66, 1.0, v66
	v_add_f32_e32 v69, 1.0, v67
	v_add_f32_e32 v67, 1.0, v68
	v_rcp_f32_e32 v66, v66
	v_rcp_f32_e32 v67, v67
	v_mul_f32_e32 v68, 0xbfb8aa3b, v57
	v_exp_f32_e32 v70, v68
	v_rcp_f32_e32 v68, v69
	v_pk_mul_f32 v[60:61], v[60:61], v[66:67]
	v_mul_f32_e32 v66, 0xbfb8aa3b, v63
	v_pk_mul_f32 v[52:53], v[60:61], v[52:53]
	v_add_f32_e32 v60, 1.0, v70
	v_rcp_f32_e32 v69, v60
	v_mul_f32_e32 v61, 0xbfb8aa3b, v58
	v_mul_f32_e32 v60, 0xbfb8aa3b, v62
	v_exp_f32_e32 v61, v61
	v_exp_f32_e32 v60, v60
	v_exp_f32_e32 v67, v66
	v_mul_f32_e32 v66, 0xbfb8aa3b, v59
	v_pk_mul_f32 v[56:57], v[56:57], v[68:69]
	v_exp_f32_e32 v68, v66
	v_add_f32_e32 v61, 1.0, v61
	v_add_f32_e32 v60, 1.0, v60
	v_rcp_f32_e32 v66, v61
	v_add_f32_e32 v61, 1.0, v67
	v_rcp_f32_e32 v60, v60
	v_rcp_f32_e32 v61, v61
	v_add_f32_e32 v67, 1.0, v68
	v_rcp_f32_e32 v67, v67
	v_pk_mul_f32 v[56:57], v[56:57], v[48:49]
	v_pk_mul_f32 v[48:49], v[62:63], v[60:61]
	v_lshl_add_u64 v[60:61], v[64:65], 0, v[112:113]
	v_pk_mul_f32 v[54:55], v[48:49], v[54:55]
	v_pk_mul_f32 v[48:49], v[58:59], v[66:67]
	s_mov_b64 s[40:41], s[34:35]
	v_pk_mul_f32 v[58:59], v[48:49], v[50:51]
	v_cvt_pk_bf16_f32 v48, v52, v53
	v_cvt_pk_bf16_f32 v49, v54, v55
	v_cvt_pk_bf16_f32 v50, v56, v57
	v_cvt_pk_bf16_f32 v51, v58, v59
	global_store_dwordx4 v[60:61], v[48:51], off
	v_mul_f32_e32 v52, 0xbfb8aa3b, v45
	v_exp_f32_e32 v52, v52
	v_mul_f32_e32 v50, 0xbfb8aa3b, v44
	v_mul_f32_e32 v51, 0xbfb8aa3b, v40
	v_exp_f32_e32 v50, v50
	v_exp_f32_e32 v51, v51
	v_add_u32_e32 v48, 0x90, v152
	v_mad_i64_i32 v[48:49], s[38:39], v48, s55, v[144:145]
	v_add_f32_e32 v50, 1.0, v50
	v_add_f32_e32 v53, 1.0, v51
	v_add_f32_e32 v51, 1.0, v52
	v_rcp_f32_e32 v50, v50
	v_rcp_f32_e32 v51, v51
	v_mul_f32_e32 v52, 0xbfb8aa3b, v41
	v_exp_f32_e32 v54, v52
	v_rcp_f32_e32 v52, v53
	v_pk_mul_f32 v[44:45], v[44:45], v[50:51]
	v_mul_f32_e32 v50, 0xbfb8aa3b, v47
	v_pk_mul_f32 v[36:37], v[44:45], v[36:37]
	v_add_f32_e32 v44, 1.0, v54
	v_rcp_f32_e32 v53, v44
	v_mul_f32_e32 v45, 0xbfb8aa3b, v42
	v_mul_f32_e32 v44, 0xbfb8aa3b, v46
	v_exp_f32_e32 v45, v45
	v_exp_f32_e32 v44, v44
	v_exp_f32_e32 v51, v50
	v_mul_f32_e32 v50, 0xbfb8aa3b, v43
	v_pk_mul_f32 v[40:41], v[40:41], v[52:53]
	v_exp_f32_e32 v52, v50
	v_add_f32_e32 v45, 1.0, v45
	v_add_f32_e32 v44, 1.0, v44
; __device__ __forceinline__ float fsilu(float v) { return v * fsigmoid(v); }
; __device__ __forceinline__ u32x4 pack8(const f32x4 a, const f32x4 b) { u32x4 w; w.x = cvt_pk_bf16(a[0], a[1]); w.y = cvt_pk_bf16(a[2], a[3]); w.z = cvt_pk_bf16(b[0], b[1]); w.w = cvt_pk_bf16(b[2], b[3]); return w; }
;     __device__ __forceinline__ void operator()(const f32x4 (&acc)[2][2][4][2], const Unit& u, int wr, int wc, int fr, int fq) const {
;         const int row0 = u.pm * BM + wr * 64 + fr, col0 = u.pn * 128 + wc * 32 + 8 * fq;
; #pragma unroll
;         for (int ai = 0; ai < 2; ++ai)
; #pragma unroll
;             for (int m = 0; m < 4; ++m) {
;                 bf16_t* rowp = O + (size_t)(row0 + ai * HALF + m * 16) * ldc + col0;
;                 f32x4 h0, h1;
; #pragma unroll
;                 for (int j = 0; j < 4; ++j) { h0[j] = fsilu(acc[ai][0][m][0][j]) * acc[ai][1][m][0][j]; h1[j] = fsilu(acc[ai][0][m][1][j]) * acc[ai][1][m][1][j]; }
;                 *(u32x4*)rowp = pack8(h0, h1);
; template <class Epi, class Sched, bool ALIGN_EPI = false, bool SP2 = false>
; __device__ __forceinline__ void gemm_phase(PG8_LAS unsigned char* lds, const Gemm g, const Sched& S, const Epi& E) {
;     ...
;         if (!has_next) break;
; #pragma unroll
;         for (int a = 0; a < 2; ++a)
; #pragma unroll
;             for (int b = 0; b < 2; ++b)
; #pragma unroll
;                 for (int m = 0; m < 4; ++m)
; #pragma unroll
;                     for (int n = 0; n < 2; ++n) acc[a][b][m][n] = (f32x4){0.f, 0.f, 0.f, 0.f};
;         cur = nxt; cA = nA; cB = nB; ++ui;
	v_rcp_f32_e32 v50, v45
	v_add_f32_e32 v45, 1.0, v51
	v_rcp_f32_e32 v44, v44
	v_rcp_f32_e32 v45, v45
	v_add_f32_e32 v51, 1.0, v52
	v_rcp_f32_e32 v51, v51
	v_pk_mul_f32 v[40:41], v[40:41], v[32:33]
	v_pk_mul_f32 v[32:33], v[46:47], v[44:45]
	v_lshl_add_u64 v[44:45], v[48:49], 0, v[112:113]
	v_pk_mul_f32 v[38:39], v[32:33], v[38:39]
	v_pk_mul_f32 v[32:33], v[42:43], v[50:51]
	s_nop 0
	v_pk_mul_f32 v[42:43], v[32:33], v[34:35]
	v_cvt_pk_bf16_f32 v32, v36, v37
	v_cvt_pk_bf16_f32 v33, v38, v39
	v_cvt_pk_bf16_f32 v34, v40, v41
	v_cvt_pk_bf16_f32 v35, v42, v43
	global_store_dwordx4 v[44:45], v[32:35], off
	v_mul_f32_e32 v36, 0xbfb8aa3b, v29
	v_exp_f32_e32 v36, v36
	v_mul_f32_e32 v34, 0xbfb8aa3b, v28
	v_mul_f32_e32 v35, 0xbfb8aa3b, v24
	v_exp_f32_e32 v34, v34
	v_exp_f32_e32 v35, v35
	v_add_u32_e32 v32, 0xa0, v152
	v_mad_i64_i32 v[32:33], s[38:39], v32, s55, v[144:145]
	v_add_f32_e32 v34, 1.0, v34
	v_add_f32_e32 v37, 1.0, v35
	v_add_f32_e32 v35, 1.0, v36
	v_rcp_f32_e32 v34, v34
	v_rcp_f32_e32 v35, v35
	v_mul_f32_e32 v36, 0xbfb8aa3b, v25
	v_exp_f32_e32 v38, v36
	v_rcp_f32_e32 v36, v37
	v_pk_mul_f32 v[28:29], v[28:29], v[34:35]
	v_mul_f32_e32 v34, 0xbfb8aa3b, v31
	v_pk_mul_f32 v[20:21], v[28:29], v[20:21]
	v_add_f32_e32 v28, 1.0, v38
	v_rcp_f32_e32 v37, v28
	v_mul_f32_e32 v29, 0xbfb8aa3b, v26
	v_mul_f32_e32 v28, 0xbfb8aa3b, v30
	v_exp_f32_e32 v29, v29
	v_exp_f32_e32 v28, v28
	v_exp_f32_e32 v35, v34
	v_mul_f32_e32 v34, 0xbfb8aa3b, v27
	v_pk_mul_f32 v[24:25], v[24:25], v[36:37]
	v_exp_f32_e32 v36, v34
	v_add_f32_e32 v29, 1.0, v29
	v_add_f32_e32 v28, 1.0, v28
	v_rcp_f32_e32 v34, v29
	v_add_f32_e32 v29, 1.0, v35
	v_rcp_f32_e32 v28, v28
	v_rcp_f32_e32 v29, v29
	v_add_f32_e32 v35, 1.0, v36
	v_rcp_f32_e32 v35, v35
	v_pk_mul_f32 v[24:25], v[24:25], v[16:17]
	v_pk_mul_f32 v[16:17], v[30:31], v[28:29]
	v_lshl_add_u64 v[28:29], v[32:33], 0, v[112:113]
	v_pk_mul_f32 v[22:23], v[16:17], v[22:23]
	v_pk_mul_f32 v[16:17], v[26:27], v[34:35]
	s_nop 0
	v_pk_mul_f32 v[26:27], v[16:17], v[18:19]
	v_cvt_pk_bf16_f32 v16, v20, v21
	v_cvt_pk_bf16_f32 v17, v22, v23
	v_cvt_pk_bf16_f32 v18, v24, v25
	v_cvt_pk_bf16_f32 v19, v26, v27
	global_store_dwordx4 v[28:29], v[16:19], off
	v_mul_f32_e32 v20, 0xbfb8aa3b, v13
	v_exp_f32_e32 v20, v20
	v_mul_f32_e32 v18, 0xbfb8aa3b, v12
	v_mul_f32_e32 v19, 0xbfb8aa3b, v8
	v_exp_f32_e32 v18, v18
	v_exp_f32_e32 v19, v19
	v_add_u32_e32 v16, 0xb0, v152
	v_mad_i64_i32 v[16:17], s[38:39], v16, s55, v[144:145]
	v_add_f32_e32 v18, 1.0, v18
	v_add_f32_e32 v21, 1.0, v19
	v_add_f32_e32 v19, 1.0, v20
	v_rcp_f32_e32 v18, v18
	v_rcp_f32_e32 v19, v19
	v_mul_f32_e32 v20, 0xbfb8aa3b, v9
	v_exp_f32_e32 v22, v20
	v_rcp_f32_e32 v20, v21
	v_pk_mul_f32 v[12:13], v[12:13], v[18:19]
	v_mul_f32_e32 v18, 0xbfb8aa3b, v15
	v_pk_mul_f32 v[4:5], v[12:13], v[4:5]
	v_add_f32_e32 v12, 1.0, v22
	v_rcp_f32_e32 v21, v12
	v_mul_f32_e32 v13, 0xbfb8aa3b, v10
	v_mul_f32_e32 v12, 0xbfb8aa3b, v14
	v_exp_f32_e32 v13, v13
	v_exp_f32_e32 v12, v12
	v_exp_f32_e32 v19, v18
	v_mul_f32_e32 v18, 0xbfb8aa3b, v11
	v_pk_mul_f32 v[8:9], v[8:9], v[20:21]
	v_exp_f32_e32 v20, v18
	v_add_f32_e32 v13, 1.0, v13
	v_add_f32_e32 v12, 1.0, v12
	v_rcp_f32_e32 v18, v13
	v_add_f32_e32 v13, 1.0, v19
	v_rcp_f32_e32 v12, v12
	v_rcp_f32_e32 v13, v13
	v_add_f32_e32 v19, 1.0, v20
	v_rcp_f32_e32 v19, v19
	v_pk_mul_f32 v[8:9], v[8:9], v[0:1]
	v_pk_mul_f32 v[0:1], v[14:15], v[12:13]
	v_lshl_add_u64 v[12:13], v[16:17], 0, v[112:113]
	v_pk_mul_f32 v[6:7], v[0:1], v[6:7]
	v_pk_mul_f32 v[0:1], v[10:11], v[18:19]
	s_mov_b64 s[38:39], s[30:31]
	v_pk_mul_f32 v[10:11], v[0:1], v[2:3]
	v_cvt_pk_bf16_f32 v0, v4, v5
	v_cvt_pk_bf16_f32 v1, v6, v7
	v_cvt_pk_bf16_f32 v2, v8, v9
	v_cvt_pk_bf16_f32 v3, v10, v11
	global_store_dwordx4 v[12:13], v[0:3], off
	s_cbranch_vccz .LBB0_166
	s_waitcnt vmcnt(0)
	s_cmpk_gt_u32 s3, 0xff
	s_cbranch_scc1 .LBB0_173
	s_barrier

; #define PG8_STAGE(bufoff, gbase, voff) do { _Pragma("unroll") for (int _i = 0; _i < 2; ++_i) \
;         __builtin_amdgcn_global_load_lds((const unsigned*)((const char*)(gbase) + (voff)[_i]), (PG8_LAS unsigned*)(lds + (bufoff) + ldsw + _i * 8192), 16, 0, 0); } while (0)
; #define PG8_LDA(dst, b, h) do { _Pragma("unroll") for (int m = 0; m < 4; ++m) _Pragma("unroll") for (int k = 0; k < 2; ++k) dst[m][k] = *(const PG8_LAS bf16x8*)(lds + PG8_SA(b, h) + aoff + m * 2048 + k * 1024); } while (0)
; #define PG8_LDB(dst, b, h) do { _Pragma("unroll") for (int n = 0; n < 2; ++n) _Pragma("unroll") for (int k = 0; k < 2; ++k) dst[n][k] = *(const PG8_LAS bf16x8*)(lds + PG8_SB(b, h) + boff + n * 2048 + k * 1024); } while (0)
; #define PG8_MMA(ai, bj, At, Bt) do { __builtin_amdgcn_s_setprio(1); _Pragma("unroll") for (int m = 0; m < 4; ++m) _Pragma("unroll") for (int n = 0; n < 2; ++n) _Pragma("unroll") for (int k = 0; k < 2; ++k) \
;         acc[ai][bj][m][n] = __builtin_amdgcn_mfma_f32_16x16x32_bf16(Bt[n][k], At[m][k], acc[ai][bj][m][n], 0, 0, 0); __builtin_amdgcn_s_setprio(0); } while (0)
; #define PG8_WAIT_V(n) asm volatile("s_waitcnt vmcnt(" #n ")" ::: "memory")
; #define PG8_WAIT_L(n) asm volatile("s_waitcnt lgkmcnt(" #n ")" ::: "memory")
; #define PG8_BAR __builtin_amdgcn_s_barrier()
; #define PG8_SCHED __builtin_amdgcn_sched_barrier(0)
; template <class Epi, class Sched, bool ALIGN_EPI = false, bool SP2 = false>
; __device__ __forceinline__ void gemm_phase(PG8_LAS unsigned char* lds, const Gemm g, const Sched& S, const Epi& E) {
;     ...
;             PG8_LDB(B0, 0, 0); PG8_LDB(B1, 0, 1); PG8_SCHED; PG8_LDA(At, 0, 0); PG8_STAGE(PG8_SA(1, 1), a1 + hstep, voffA);
;             PG8_WAIT_V(8); PG8_WAIT_L(0); PG8_BAR; PG8_MMA(0, 0, At, B0); PG8_MMA(0, 1, At, B1); PG8_BAR; PG8_SCHED;
;             PG8_LDA(At, 0, 1); PG8_STAGE(PG8_SB(0, 0), b2, voffB); PG8_STAGE(PG8_SB(0, 1), b2 + hstep, voffB); PG8_STAGE(PG8_SA(0, 0), a2, voffA);
;             PG8_WAIT_V(8); PG8_WAIT_L(0); PG8_BAR; PG8_MMA(1, 0, At, B0); PG8_MMA(1, 1, At, B1); PG8_BAR; PG8_SCHED;
.LBB0_245:
	ds_read_b128 v[140:143], v169
	ds_read_b128 v[144:147], v169 offset:1024
	ds_read_b128 v[148:151], v169 offset:2048
	ds_read_b128 v[152:155], v169 offset:3072
	ds_read_b128 v[156:159], v170
	ds_read_b128 v[160:163], v170 offset:1024
	ds_read_b128 v[172:175], v170 offset:2048
	ds_read_b128 v[176:179], v170 offset:3072
	s_add_u32 s46, s44, 0x100
	s_addc_u32 s47, s45, 0
	s_cmpk_eq_i32 s69, 0x54
	s_cselect_b32 s51, s11, s47
	s_cselect_b32 s50, s10, s46
	s_cselect_b32 s49, s13, s68
	s_cselect_b32 s48, s12, s67
	s_add_i32 m0, s26, 0xc000
	ds_read_b128 v[180:183], v171
	ds_read_b128 v[184:187], v171 offset:1024
	ds_read_b128 v[188:191], v171 offset:2048
	ds_read_b128 v[192:195], v171 offset:3072
	ds_read_b128 v[196:199], v171 offset:4096
	ds_read_b128 v[200:203], v171 offset:5120
	ds_read_b128 v[204:207], v171 offset:6144
	ds_read_b128 v[208:211], v171 offset:7168
	global_load_lds_dwordx4 v136, s[44:45]
	s_add_i32 m0, s26, 0xe000
	s_nop 0
	global_load_lds_dwordx4 v138, s[44:45]
	s_waitcnt vmcnt(8)
	s_waitcnt lgkmcnt(0)
	s_barrier
	s_setprio 1
	s_waitcnt lgkmcnt(0)
	v_mfma_f32_16x16x32_bf16 v[124:127], v[140:143], v[180:183], v[124:127]
	v_mfma_f32_16x16x32_bf16 v[120:123], v[148:151], v[180:183], v[120:123]
	v_mfma_f32_16x16x32_bf16 v[116:119], v[140:143], v[188:191], v[116:119]
	v_mfma_f32_16x16x32_bf16 v[112:115], v[148:151], v[188:191], v[112:115]
	v_mfma_f32_16x16x32_bf16 v[108:111], v[140:143], v[196:199], v[108:111]
	v_mfma_f32_16x16x32_bf16 v[96:99], v[148:151], v[196:199], v[96:99]
	v_mfma_f32_16x16x32_bf16 v[84:87], v[140:143], v[204:207], v[84:87]
	v_mfma_f32_16x16x32_bf16 v[76:79], v[148:151], v[204:207], v[76:79]
	v_mfma_f32_16x16x32_bf16 v[124:127], v[144:147], v[184:187], v[124:127]
	v_mfma_f32_16x16x32_bf16 v[120:123], v[152:155], v[184:187], v[120:123]
	v_mfma_f32_16x16x32_bf16 v[116:119], v[144:147], v[192:195], v[116:119]
	v_mfma_f32_16x16x32_bf16 v[112:115], v[152:155], v[192:195], v[112:115]
	v_mfma_f32_16x16x32_bf16 v[108:111], v[144:147], v[200:203], v[108:111]
	v_mfma_f32_16x16x32_bf16 v[96:99], v[152:155], v[200:203], v[96:99]
	v_mfma_f32_16x16x32_bf16 v[84:87], v[144:147], v[208:211], v[84:87]
	v_mfma_f32_16x16x32_bf16 v[76:79], v[152:155], v[208:211], v[76:79]
	s_setprio 0
	s_setprio 1
	v_mfma_f32_16x16x32_bf16 v[104:107], v[156:159], v[180:183], v[104:107]
	v_mfma_f32_16x16x32_bf16 v[100:103], v[172:175], v[180:183], v[100:103]
	v_mfma_f32_16x16x32_bf16 v[92:95], v[156:159], v[188:191], v[92:95]
	v_mfma_f32_16x16x32_bf16 v[88:91], v[172:175], v[188:191], v[88:91]
	v_mfma_f32_16x16x32_bf16 v[80:83], v[156:159], v[196:199], v[80:83]
	v_mfma_f32_16x16x32_bf16 v[72:75], v[172:175], v[196:199], v[72:75]
	v_mfma_f32_16x16x32_bf16 v[68:71], v[156:159], v[204:207], v[68:71]
	v_mfma_f32_16x16x32_bf16 v[64:67], v[172:175], v[204:207], v[64:67]
	v_mfma_f32_16x16x32_bf16 v[104:107], v[160:163], v[184:187], v[104:107]
	v_mfma_f32_16x16x32_bf16 v[100:103], v[176:179], v[184:187], v[100:103]
	v_mfma_f32_16x16x32_bf16 v[92:95], v[160:163], v[192:195], v[92:95]
	v_mfma_f32_16x16x32_bf16 v[88:91], v[176:179], v[192:195], v[88:91]
	v_mfma_f32_16x16x32_bf16 v[80:83], v[160:163], v[200:203], v[80:83]
	v_mfma_f32_16x16x32_bf16 v[72:75], v[176:179], v[200:203], v[72:75]
	v_mfma_f32_16x16x32_bf16 v[68:71], v[160:163], v[208:211], v[68:71]
	v_mfma_f32_16x16x32_bf16 v[64:67], v[176:179], v[208:211], v[64:67]
	s_setprio 0
	s_barrier
	s_add_i32 s44, s61, s25
	s_mov_b32 m0, s44
	ds_read_b128 v[180:183], v171 offset:16384
	ds_read_b128 v[184:187], v171 offset:17408
	ds_read_b128 v[188:191], v171 offset:18432
	ds_read_b128 v[192:195], v171 offset:19456
	ds_read_b128 v[196:199], v171 offset:20480
	ds_read_b128 v[200:203], v171 offset:21504
	ds_read_b128 v[204:207], v171 offset:22528
	ds_read_b128 v[208:211], v171 offset:23552
	global_load_lds_dwordx4 v130, s[48:49]
	s_add_i32 m0, s44, 0x2000
	s_add_u32 s44, s48, 0x160000
	s_addc_u32 s45, s49, 0
	s_add_i32 s70, s62, s25
	global_load_lds_dwordx4 v134, s[48:49]
	s_mov_b32 m0, s70
	s_nop 0
	global_load_lds_dwordx4 v130, s[44:45]
	s_add_i32 m0, s70, 0x2000
	s_nop 0
	global_load_lds_dwordx4 v134, s[44:45]
	s_mov_b32 m0, s26
	s_nop 0
	global_load_lds_dwordx4 v128, s[50:51]
	s_mov_b32 m0, s27
	s_nop 0
	global_load_lds_dwordx4 v132, s[50:51]
	s_waitcnt vmcnt(8)
	s_waitcnt lgkmcnt(0)
	s_barrier
	s_setprio 1
	s_waitcnt lgkmcnt(0)
	v_mfma_f32_16x16x32_bf16 v[60:63], v[140:143], v[180:183], v[60:63]
	v_mfma_f32_16x16x32_bf16 v[56:59], v[148:151], v[180:183], v[56:59]
	v_mfma_f32_16x16x32_bf16 v[52:55], v[140:143], v[188:191], v[52:55]
	v_mfma_f32_16x16x32_bf16 v[48:51], v[148:151], v[188:191], v[48:51]
	v_mfma_f32_16x16x32_bf16 v[44:47], v[140:143], v[196:199], v[44:47]
	v_mfma_f32_16x16x32_bf16 v[32:35], v[148:151], v[196:199], v[32:35]
	v_mfma_f32_16x16x32_bf16 v[20:23], v[140:143], v[204:207], v[20:23]
	v_mfma_f32_16x16x32_bf16 v[12:15], v[148:151], v[204:207], v[12:15]
	v_mfma_f32_16x16x32_bf16 v[60:63], v[144:147], v[184:187], v[60:63]
	v_mfma_f32_16x16x32_bf16 v[56:59], v[152:155], v[184:187], v[56:59]
	v_mfma_f32_16x16x32_bf16 v[52:55], v[144:147], v[192:195], v[52:55]
	v_mfma_f32_16x16x32_bf16 v[48:51], v[152:155], v[192:195], v[48:51]
	v_mfma_f32_16x16x32_bf16 v[44:47], v[144:147], v[200:203], v[44:47]
	v_mfma_f32_16x16x32_bf16 v[32:35], v[152:155], v[200:203], v[32:35]
	v_mfma_f32_16x16x32_bf16 v[20:23], v[144:147], v[208:211], v[20:23]
	v_mfma_f32_16x16x32_bf16 v[12:15], v[152:155], v[208:211], v[12:15]
	s_setprio 0
	s_setprio 1
	v_mfma_f32_16x16x32_bf16 v[40:43], v[156:159], v[180:183], v[40:43]
	v_mfma_f32_16x16x32_bf16 v[36:39], v[172:175], v[180:183], v[36:39]
	v_mfma_f32_16x16x32_bf16 v[28:31], v[156:159], v[188:191], v[28:31]
	v_mfma_f32_16x16x32_bf16 v[24:27], v[172:175], v[188:191], v[24:27]
	v_mfma_f32_16x16x32_bf16 v[16:19], v[156:159], v[196:199], v[16:19]
	v_mfma_f32_16x16x32_bf16 v[8:11], v[172:175], v[196:199], v[8:11]
	v_mfma_f32_16x16x32_bf16 v[4:7], v[156:159], v[204:207], v[4:7]
	v_mfma_f32_16x16x32_bf16 v[0:3], v[172:175], v[204:207], v[0:3]
	v_mfma_f32_16x16x32_bf16 v[40:43], v[160:163], v[184:187], v[40:43]
	v_mfma_f32_16x16x32_bf16 v[36:39], v[176:179], v[184:187], v[36:39]
	v_mfma_f32_16x16x32_bf16 v[28:31], v[160:163], v[192:195], v[28:31]
	v_mfma_f32_16x16x32_bf16 v[24:27], v[176:179], v[192:195], v[24:27]
	v_mfma_f32_16x16x32_bf16 v[16:19], v[160:163], v[200:203], v[16:19]
	v_mfma_f32_16x16x32_bf16 v[8:11], v[176:179], v[200:203], v[8:11]
	v_mfma_f32_16x16x32_bf16 v[4:7], v[160:163], v[208:211], v[4:7]
	v_mfma_f32_16x16x32_bf16 v[0:3], v[176:179], v[208:211], v[0:3]
	s_setprio 0
	s_barrier
; #define PG8_STAGE(bufoff, gbase, voff) do { _Pragma("unroll") for (int _i = 0; _i < 2; ++_i) \
;         __builtin_amdgcn_global_load_lds((const unsigned*)((const char*)(gbase) + (voff)[_i]), (PG8_LAS unsigned*)(lds + (bufoff) + ldsw + _i * 8192), 16, 0, 0); } while (0)
; #define PG8_LDA(dst, b, h) do { _Pragma("unroll") for (int m = 0; m < 4; ++m) _Pragma("unroll") for (int k = 0; k < 2; ++k) dst[m][k] = *(const PG8_LAS bf16x8*)(lds + PG8_SA(b, h) + aoff + m * 2048 + k * 1024); } while (0)
; #define PG8_LDB(dst, b, h) do { _Pragma("unroll") for (int n = 0; n < 2; ++n) _Pragma("unroll") for (int k = 0; k < 2; ++k) dst[n][k] = *(const PG8_LAS bf16x8*)(lds + PG8_SB(b, h) + boff + n * 2048 + k * 1024); } while (0)
; #define PG8_MMA(ai, bj, At, Bt) do { __builtin_amdgcn_s_setprio(1); _Pragma("unroll") for (int m = 0; m < 4; ++m) _Pragma("unroll") for (int n = 0; n < 2; ++n) _Pragma("unroll") for (int k = 0; k < 2; ++k) \
;         acc[ai][bj][m][n] = __builtin_amdgcn_mfma_f32_16x16x32_bf16(Bt[n][k], At[m][k], acc[ai][bj][m][n], 0, 0, 0); __builtin_amdgcn_s_setprio(0); } while (0)
; #define PG8_WAIT_V(n) asm volatile("s_waitcnt vmcnt(" #n ")" ::: "memory")
; #define PG8_WAIT_L(n) asm volatile("s_waitcnt lgkmcnt(" #n ")" ::: "memory")
; #define PG8_BAR __builtin_amdgcn_s_barrier()
; #define PG8_SCHED __builtin_amdgcn_sched_barrier(0)
; template <class Epi, class Sched, bool ALIGN_EPI = false, bool SP2 = false>
; __device__ __forceinline__ void gemm_phase(PG8_LAS unsigned char* lds, const Gemm g, const Sched& S, const Epi& E) {
;     ...
;             PG8_LDB(B0, 1, 0); PG8_LDB(B1, 1, 1); PG8_SCHED; PG8_LDA(At, 1, 0); PG8_STAGE(PG8_SA(0, 1), a2 + hstep, voffA);
;             PG8_WAIT_V(8); PG8_WAIT_L(0); PG8_BAR; PG8_MMA(0, 0, At, B0); PG8_MMA(0, 1, At, B1); PG8_BAR; PG8_SCHED;
;             PG8_LDA(At, 1, 1); PG8_STAGE(PG8_SB(1, 0), b3, voffB); PG8_STAGE(PG8_SB(1, 1), b3 + hstep, voffB); PG8_STAGE(PG8_SA(1, 0), a3, voffA);
;             PG8_WAIT_V(8); PG8_WAIT_L(0); PG8_BAR; PG8_MMA(1, 0, At, B0); PG8_MMA(1, 1, At, B1); PG8_BAR; PG8_SCHED;
	s_add_i32 s70, 0, 0x18000
	s_add_i32 s71, 0, 0x1c000
	v_add_u32_e32 v152, s70, v167
	v_add_u32_e32 v176, s71, v167
	ds_read_b128 v[140:143], v152
	ds_read_b128 v[144:147], v152 offset:1024
	ds_read_b128 v[148:151], v152 offset:2048
	ds_read_b128 v[152:155], v152 offset:3072
	ds_read_b128 v[156:159], v176
	ds_read_b128 v[160:163], v176 offset:1024
	ds_read_b128 v[172:175], v176 offset:2048
	ds_read_b128 v[176:179], v176 offset:3072
	s_add_u32 s44, s50, 0x160000
	s_addc_u32 s45, s51, 0
	s_mov_b32 m0, s52
	ds_read_b128 v[180:183], v171 offset:32768
	ds_read_b128 v[184:187], v171 offset:33792
	ds_read_b128 v[188:191], v171 offset:34816
	ds_read_b128 v[192:195], v171 offset:35840
	ds_read_b128 v[196:199], v171 offset:36864
	ds_read_b128 v[200:203], v171 offset:37888
	ds_read_b128 v[204:207], v171 offset:38912
	ds_read_b128 v[208:211], v171 offset:39936
	global_load_lds_dwordx4 v128, s[44:45]
	s_mov_b32 m0, s53
	s_nop 0
	global_load_lds_dwordx4 v132, s[44:45]
	s_waitcnt vmcnt(8)
	s_waitcnt lgkmcnt(0)
	s_barrier
	s_setprio 1
	s_waitcnt lgkmcnt(0)
	v_mfma_f32_16x16x32_bf16 v[124:127], v[140:143], v[180:183], v[124:127]
	v_mfma_f32_16x16x32_bf16 v[120:123], v[148:151], v[180:183], v[120:123]
	v_mfma_f32_16x16x32_bf16 v[116:119], v[140:143], v[188:191], v[116:119]
	v_mfma_f32_16x16x32_bf16 v[112:115], v[148:151], v[188:191], v[112:115]
	v_mfma_f32_16x16x32_bf16 v[108:111], v[140:143], v[196:199], v[108:111]
	v_mfma_f32_16x16x32_bf16 v[96:99], v[148:151], v[196:199], v[96:99]
	v_mfma_f32_16x16x32_bf16 v[84:87], v[140:143], v[204:207], v[84:87]
	v_mfma_f32_16x16x32_bf16 v[76:79], v[148:151], v[204:207], v[76:79]
	v_mfma_f32_16x16x32_bf16 v[124:127], v[144:147], v[184:187], v[124:127]
	v_mfma_f32_16x16x32_bf16 v[120:123], v[152:155], v[184:187], v[120:123]
	v_mfma_f32_16x16x32_bf16 v[116:119], v[144:147], v[192:195], v[116:119]
	v_mfma_f32_16x16x32_bf16 v[112:115], v[152:155], v[192:195], v[112:115]
	v_mfma_f32_16x16x32_bf16 v[108:111], v[144:147], v[200:203], v[108:111]
	v_mfma_f32_16x16x32_bf16 v[96:99], v[152:155], v[200:203], v[96:99]
	v_mfma_f32_16x16x32_bf16 v[84:87], v[144:147], v[208:211], v[84:87]
	v_mfma_f32_16x16x32_bf16 v[76:79], v[152:155], v[208:211], v[76:79]
	s_setprio 0
	s_setprio 1
	v_mfma_f32_16x16x32_bf16 v[104:107], v[156:159], v[180:183], v[104:107]
	v_mfma_f32_16x16x32_bf16 v[100:103], v[172:175], v[180:183], v[100:103]
	v_mfma_f32_16x16x32_bf16 v[92:95], v[156:159], v[188:191], v[92:95]
	v_mfma_f32_16x16x32_bf16 v[88:91], v[172:175], v[188:191], v[88:91]
	v_mfma_f32_16x16x32_bf16 v[80:83], v[156:159], v[196:199], v[80:83]
	v_mfma_f32_16x16x32_bf16 v[72:75], v[172:175], v[196:199], v[72:75]
	v_mfma_f32_16x16x32_bf16 v[68:71], v[156:159], v[204:207], v[68:71]
	v_mfma_f32_16x16x32_bf16 v[64:67], v[172:175], v[204:207], v[64:67]
	v_mfma_f32_16x16x32_bf16 v[104:107], v[160:163], v[184:187], v[104:107]
	v_mfma_f32_16x16x32_bf16 v[100:103], v[176:179], v[184:187], v[100:103]
	v_mfma_f32_16x16x32_bf16 v[92:95], v[160:163], v[192:195], v[92:95]
	v_mfma_f32_16x16x32_bf16 v[88:91], v[176:179], v[192:195], v[88:91]
	v_mfma_f32_16x16x32_bf16 v[80:83], v[160:163], v[200:203], v[80:83]
	v_mfma_f32_16x16x32_bf16 v[72:75], v[176:179], v[200:203], v[72:75]
	v_mfma_f32_16x16x32_bf16 v[68:71], v[160:163], v[208:211], v[68:71]
	v_mfma_f32_16x16x32_bf16 v[64:67], v[176:179], v[208:211], v[64:67]
	s_setprio 0
	s_barrier
	s_add_i32 s44, s70, s25
	s_add_u32 s86, s48, 0x80
	s_addc_u32 s87, s49, 0
	s_mov_b32 m0, s44
	ds_read_b128 v[180:183], v171 offset:49152
	ds_read_b128 v[184:187], v171 offset:50176
	ds_read_b128 v[188:191], v171 offset:51200
	ds_read_b128 v[192:195], v171 offset:52224
	ds_read_b128 v[196:199], v171 offset:53248
	ds_read_b128 v[200:203], v171 offset:54272
	ds_read_b128 v[204:207], v171 offset:55296
	ds_read_b128 v[208:211], v171 offset:56320
	global_load_lds_dwordx4 v130, s[86:87]
	s_add_i32 m0, s44, 0x2000
	s_add_u32 s44, s48, 0x160080
	s_addc_u32 s45, s49, 0
	s_add_i32 s48, s71, s25
	global_load_lds_dwordx4 v134, s[86:87]
	s_mov_b32 m0, s48
	s_nop 0
	global_load_lds_dwordx4 v130, s[44:45]
	s_add_i32 m0, s48, 0x2000
	s_nop 0
	global_load_lds_dwordx4 v134, s[44:45]
	s_add_u32 s84, s50, 0x80
	s_addc_u32 s85, s51, 0
	s_mov_b32 m0, s57
	s_nop 0
	global_load_lds_dwordx4 v128, s[84:85]
	s_mov_b32 m0, s58
	s_nop 0
	global_load_lds_dwordx4 v132, s[84:85]
	s_waitcnt vmcnt(8)
	s_waitcnt lgkmcnt(0)
	s_barrier
	s_setprio 1
	s_waitcnt lgkmcnt(0)
	v_mfma_f32_16x16x32_bf16 v[60:63], v[140:143], v[180:183], v[60:63]
	v_mfma_f32_16x16x32_bf16 v[56:59], v[148:151], v[180:183], v[56:59]
	v_mfma_f32_16x16x32_bf16 v[52:55], v[140:143], v[188:191], v[52:55]
	v_mfma_f32_16x16x32_bf16 v[48:51], v[148:151], v[188:191], v[48:51]
	v_mfma_f32_16x16x32_bf16 v[44:47], v[140:143], v[196:199], v[44:47]
	v_mfma_f32_16x16x32_bf16 v[32:35], v[148:151], v[196:199], v[32:35]
	v_mfma_f32_16x16x32_bf16 v[20:23], v[140:143], v[204:207], v[20:23]
	v_mfma_f32_16x16x32_bf16 v[12:15], v[148:151], v[204:207], v[12:15]
	v_mfma_f32_16x16x32_bf16 v[60:63], v[144:147], v[184:187], v[60:63]
	v_mfma_f32_16x16x32_bf16 v[56:59], v[152:155], v[184:187], v[56:59]
	v_mfma_f32_16x16x32_bf16 v[52:55], v[144:147], v[192:195], v[52:55]
	v_mfma_f32_16x16x32_bf16 v[48:51], v[152:155], v[192:195], v[48:51]
	v_mfma_f32_16x16x32_bf16 v[44:47], v[144:147], v[200:203], v[44:47]
	v_mfma_f32_16x16x32_bf16 v[32:35], v[152:155], v[200:203], v[32:35]
	v_mfma_f32_16x16x32_bf16 v[20:23], v[144:147], v[208:211], v[20:23]
	v_mfma_f32_16x16x32_bf16 v[12:15], v[152:155], v[208:211], v[12:15]
	s_setprio 0
	s_setprio 1
	v_mfma_f32_16x16x32_bf16 v[40:43], v[156:159], v[180:183], v[40:43]
	v_mfma_f32_16x16x32_bf16 v[36:39], v[172:175], v[180:183], v[36:39]
	v_mfma_f32_16x16x32_bf16 v[28:31], v[156:159], v[188:191], v[28:31]
	v_mfma_f32_16x16x32_bf16 v[24:27], v[172:175], v[188:191], v[24:27]
	v_mfma_f32_16x16x32_bf16 v[16:19], v[156:159], v[196:199], v[16:19]
	v_mfma_f32_16x16x32_bf16 v[8:11], v[172:175], v[196:199], v[8:11]
	v_mfma_f32_16x16x32_bf16 v[4:7], v[156:159], v[204:207], v[4:7]
	v_mfma_f32_16x16x32_bf16 v[0:3], v[172:175], v[204:207], v[0:3]
	v_mfma_f32_16x16x32_bf16 v[40:43], v[160:163], v[184:187], v[40:43]
	v_mfma_f32_16x16x32_bf16 v[36:39], v[176:179], v[184:187], v[36:39]
	v_mfma_f32_16x16x32_bf16 v[28:31], v[160:163], v[192:195], v[28:31]
	v_mfma_f32_16x16x32_bf16 v[24:27], v[176:179], v[192:195], v[24:27]
	v_mfma_f32_16x16x32_bf16 v[16:19], v[160:163], v[200:203], v[16:19]
	v_mfma_f32_16x16x32_bf16 v[8:11], v[176:179], v[200:203], v[8:11]
	v_mfma_f32_16x16x32_bf16 v[4:7], v[160:163], v[208:211], v[4:7]
	v_mfma_f32_16x16x32_bf16 v[0:3], v[176:179], v[208:211], v[0:3]
	s_setprio 0
	s_barrier
;     __device__ __forceinline__ void operator()(const f32x4 (&acc)[2][2][4][2], const Unit& u, int wr, int wc, int fr, int fq) const {
;         const int row0 = u.pm * BM + wr * 64 + fr, col0 = u.pn * BM + wc * 32 + 8 * fq;
;         const float* gp = gate + (u.pm >> 5) * 18432 + col0;
;         f32x4 gv[2][2];
; #pragma unroll
;         for (int bj = 0; bj < 2; ++bj)
; #pragma unroll
;             for (int n = 0; n < 2; ++n) gv[bj][n] = *(const f32x4*)(gp + bj * HALF + 4 * n) * scale;
; #pragma unroll
;         for (int ai = 0; ai < 2; ++ai) { f32x4 r[4][2][2];
; #pragma unroll
;             for (int m = 0; m < 4; ++m) { const size_t off = (size_t)(row0 + ai * HALF + m * 16) * 2048 + col0;
; #pragma unroll
;                 for (int bj = 0; bj < 2; ++bj)
; #pragma unroll
;                     for (int n = 0; n < 2; ++n) r[m][bj][n] = *(const f32x4*)(res + off + bj * HALF + 4 * n); }
; #pragma unroll
;             for (int m = 0; m < 4; ++m) { const size_t off = (size_t)(row0 + ai * HALF + m * 16) * 2048 + col0;
; #pragma unroll
;                 for (int bj = 0; bj < 2; ++bj)
; #pragma unroll
;                     for (int n = 0; n < 2; ++n) *(f32x4*)(out + off + bj * HALF + 4 * n) = r[m][bj][n] + gv[bj][n] * acc[ai][bj][m][n]; } }
	s_add_i32 s69, s69, 2
	s_add_u32 s67, s67, 0x100
	s_addc_u32 s68, s68, 0
	s_cmpk_gt_u32 s69, 0x55
	s_mov_b64 s[44:45], s[46:47]
	s_cbranch_scc0 .LBB0_245
	s_lshr_b32 s44, s65, 5
	s_mulk_i32 s44, 0x4800
	s_ashr_i32 s45, s44, 31
	v_lshl_or_b32 v140, s66, 8, v168
	s_lshl_b64 s[44:45], s[44:45], 2
	s_add_u32 s44, s55, s44
	v_ashrrev_i32_e32 v141, 31, v140
	s_addc_u32 s45, s56, s45
	v_lshlrev_b64 v[144:145], 2, v[140:141]
	v_lshl_add_u64 v[140:141], s[44:45], 0, v[144:145]
	global_load_dwordx4 v[146:149], v[140:141], off offset:16
	global_load_dwordx4 v[150:153], v[140:141], off
	global_load_dwordx4 v[172:175], v[140:141], off offset:528
	global_load_dwordx4 v[176:179], v[140:141], off offset:512
	v_lshl_add_u32 v140, s65, 8, v166
	v_ashrrev_i32_e32 v141, 31, v140
	v_lshl_add_u64 v[162:163], s[28:29], 0, v[144:145]
	v_lshlrev_b64 v[164:165], 13, v[140:141]
	v_lshl_add_u64 v[142:143], v[162:163], 0, v[164:165]
	global_load_dwordx4 v[180:183], v[142:143], off
	global_load_dwordx4 v[184:187], v[142:143], off offset:16
	global_load_dwordx4 v[188:191], v[142:143], off offset:528
	global_load_dwordx4 v[192:195], v[142:143], off offset:512
	v_or_b32_e32 v142, 16, v140
	v_ashrrev_i32_e32 v143, 31, v142
	v_lshlrev_b64 v[154:155], 13, v[142:143]
	v_lshl_add_u64 v[142:143], v[162:163], 0, v[154:155]
	global_load_dwordx4 v[196:199], v[142:143], off
	global_load_dwordx4 v[200:203], v[142:143], off offset:16
	global_load_dwordx4 v[204:207], v[142:143], off offset:528
	global_load_dwordx4 v[208:211], v[142:143], off offset:512
	v_or_b32_e32 v142, 32, v140
	v_ashrrev_i32_e32 v143, 31, v142
	v_lshlrev_b64 v[156:157], 13, v[142:143]
	v_or_b32_e32 v140, 48, v140
	v_lshl_add_u64 v[142:143], v[162:163], 0, v[156:157]
	v_ashrrev_i32_e32 v141, 31, v140
	global_load_dwordx4 v[214:217], v[142:143], off
	global_load_dwordx4 v[222:225], v[142:143], off offset:16
	global_load_dwordx4 v[232:235], v[142:143], off offset:512
	global_load_dwordx4 v[236:239], v[142:143], off offset:528
	v_lshlrev_b64 v[212:213], 13, v[140:141]
	v_lshl_add_u64 v[140:141], v[162:163], 0, v[212:213]
	global_load_dwordx4 v[240:243], v[140:141], off
	global_load_dwordx4 v[244:247], v[140:141], off offset:16
	global_load_dwordx4 v[248:251], v[140:141], off offset:512
	s_nop 0
	global_load_dwordx4 v[140:143], v[140:141], off offset:528
	v_lshl_add_u64 v[158:159], s[30:31], 0, v[164:165]
	v_lshl_add_u64 v[230:231], v[158:159], 0, v[144:145]
	v_lshl_add_u64 v[154:155], s[30:31], 0, v[154:155]
	v_lshl_add_u64 v[156:157], s[30:31], 0, v[156:157]
	v_lshl_add_u64 v[218:219], v[154:155], 0, v[144:145]
	v_lshl_add_u64 v[252:253], v[156:157], 0, v[144:145]
	s_and_b64 vcc, exec, s[8:9]
	s_mov_b32 s66, s63
	s_mov_b32 s65, s64
	s_mov_b64 s[46:47], s[12:13]
	s_mov_b64 s[44:45], s[10:11]
	s_waitcnt vmcnt(0)
	v_pk_mul_f32 v[154:155], v[148:149], 0.5 op_sel_hi:[1,0]
	v_pk_mul_f32 v[158:159], v[152:153], 0.5 op_sel_hi:[1,0]
	v_pk_mul_f32 v[160:161], v[150:151], 0.5 op_sel_hi:[1,0]
	v_pk_mul_f32 v[150:151], v[178:179], 0.5 op_sel_hi:[1,0]
	v_pk_mul_f32 v[152:153], v[176:177], 0.5 op_sel_hi:[1,0]
	v_pk_mul_f32 v[156:157], v[146:147], 0.5 op_sel_hi:[1,0]
	v_pk_mul_f32 v[146:147], v[174:175], 0.5 op_sel_hi:[1,0]
	v_pk_mul_f32 v[148:149], v[172:173], 0.5 op_sel_hi:[1,0]
	v_pk_fma_f32 v[126:127], v[126:127], v[158:159], v[182:183]
	v_pk_fma_f32 v[124:125], v[124:125], v[160:161], v[180:181]
	v_pk_fma_f32 v[122:123], v[122:123], v[154:155], v[186:187]
	v_pk_fma_f32 v[120:121], v[120:121], v[156:157], v[184:185]
	v_pk_fma_f32 v[106:107], v[106:107], v[150:151], v[194:195]
	v_pk_fma_f32 v[104:105], v[104:105], v[152:153], v[192:193]
	v_pk_fma_f32 v[102:103], v[102:103], v[146:147], v[190:191]
	v_pk_fma_f32 v[100:101], v[100:101], v[148:149], v[188:189]
	v_pk_fma_f32 v[118:119], v[118:119], v[158:159], v[198:199]
	v_pk_fma_f32 v[116:117], v[116:117], v[160:161], v[196:197]
	v_pk_fma_f32 v[114:115], v[114:115], v[154:155], v[202:203]
	v_pk_fma_f32 v[112:113], v[112:113], v[156:157], v[200:201]
	v_pk_fma_f32 v[82:83], v[82:83], v[150:151], v[234:235]
	v_pk_fma_f32 v[80:81], v[80:81], v[152:153], v[232:233]
	v_pk_fma_f32 v[94:95], v[94:95], v[150:151], v[210:211]
	v_pk_fma_f32 v[92:93], v[92:93], v[152:153], v[208:209]
	v_pk_fma_f32 v[90:91], v[90:91], v[146:147], v[206:207]
	v_pk_fma_f32 v[88:89], v[88:89], v[148:149], v[204:205]
	v_pk_fma_f32 v[110:111], v[110:111], v[158:159], v[216:217]
	v_pk_fma_f32 v[108:109], v[108:109], v[160:161], v[214:215]
	v_pk_fma_f32 v[98:99], v[98:99], v[154:155], v[224:225]
	v_pk_fma_f32 v[96:97], v[96:97], v[156:157], v[222:223]
	global_store_dwordx4 v[230:231], v[124:127], off
	global_store_dwordx4 v[230:231], v[120:123], off offset:16
	global_store_dwordx4 v[230:231], v[104:107], off offset:512
	global_store_dwordx4 v[230:231], v[100:103], off offset:528
	global_store_dwordx4 v[218:219], v[116:119], off
	global_store_dwordx4 v[218:219], v[112:115], off offset:16
	global_store_dwordx4 v[218:219], v[92:95], off offset:512
	global_store_dwordx4 v[218:219], v[88:91], off offset:528
	global_store_dwordx4 v[252:253], v[108:111], off
	global_store_dwordx4 v[252:253], v[96:99], off offset:16
	global_store_dwordx4 v[252:253], v[80:83], off offset:512
	v_pk_fma_f32 v[74:75], v[74:75], v[146:147], v[238:239]
	v_pk_fma_f32 v[72:73], v[72:73], v[148:149], v[236:237]
	v_lshl_add_u64 v[80:81], s[30:31], 0, v[212:213]
	global_store_dwordx4 v[252:253], v[72:75], off offset:528
;     __device__ __forceinline__ void operator()(const f32x4 (&acc)[2][2][4][2], const Unit& u, int wr, int wc, int fr, int fq) const {
;         const int row0 = u.pm * BM + wr * 64 + fr, col0 = u.pn * BM + wc * 32 + 8 * fq;
;         const float* gp = gate + (u.pm >> 5) * 18432 + col0;
;         f32x4 gv[2][2];
; #pragma unroll
;         for (int bj = 0; bj < 2; ++bj)
; #pragma unroll
;             for (int n = 0; n < 2; ++n) gv[bj][n] = *(const f32x4*)(gp + bj * HALF + 4 * n) * scale;
; #pragma unroll
;         for (int ai = 0; ai < 2; ++ai) { f32x4 r[4][2][2];
; #pragma unroll
;             for (int m = 0; m < 4; ++m) { const size_t off = (size_t)(row0 + ai * HALF + m * 16) * 2048 + col0;
; #pragma unroll
;                 for (int bj = 0; bj < 2; ++bj)
; #pragma unroll
;                     for (int n = 0; n < 2; ++n) r[m][bj][n] = *(const f32x4*)(res + off + bj * HALF + 4 * n); }
; #pragma unroll
;             for (int m = 0; m < 4; ++m) { const size_t off = (size_t)(row0 + ai * HALF + m * 16) * 2048 + col0;
; #pragma unroll
;                 for (int bj = 0; bj < 2; ++bj)
; #pragma unroll
;                     for (int n = 0; n < 2; ++n) *(f32x4*)(out + off + bj * HALF + 4 * n) = r[m][bj][n] + gv[bj][n] * acc[ai][bj][m][n]; } }
; template <class Epi, class Sched, bool ALIGN_EPI = false, bool SP2 = false>
; __device__ __forceinline__ void gemm_phase(PG8_LAS unsigned char* lds, const Gemm g, const Sched& S, const Epi& E) {
;     ...
;         if (!has_next) break;
; #pragma unroll
;         for (int a = 0; a < 2; ++a)
; #pragma unroll
;             for (int b = 0; b < 2; ++b)
; #pragma unroll
;                 for (int m = 0; m < 4; ++m)
; #pragma unroll
;                     for (int n = 0; n < 2; ++n) acc[a][b][m][n] = (f32x4){0.f, 0.f, 0.f, 0.f};
;         cur = nxt; cA = nA; cB = nB; ++ui;
	v_lshl_add_u64 v[80:81], v[80:81], 0, v[144:145]
	v_pk_fma_f32 v[70:71], v[70:71], v[150:151], v[250:251]
	v_pk_fma_f32 v[74:75], v[86:87], v[158:159], v[242:243]
	v_pk_fma_f32 v[72:73], v[84:85], v[160:161], v[240:241]
	global_store_dwordx4 v[80:81], v[72:75], off
	v_pk_fma_f32 v[68:69], v[68:69], v[152:153], v[248:249]
	v_pk_fma_f32 v[66:67], v[66:67], v[146:147], v[142:143]
	v_pk_fma_f32 v[74:75], v[78:79], v[154:155], v[246:247]
	v_pk_fma_f32 v[72:73], v[76:77], v[156:157], v[244:245]
	v_pk_fma_f32 v[64:65], v[64:65], v[148:149], v[140:141]
	v_lshl_add_u64 v[140:141], v[164:165], 0, s[38:39]
	v_lshl_add_u64 v[142:143], v[164:165], 0, s[40:41]
	v_lshl_add_u64 v[172:173], v[164:165], 0, s[42:43]
	global_store_dwordx4 v[80:81], v[72:75], off offset:16
	global_store_dwordx4 v[80:81], v[68:71], off offset:512
	global_store_dwordx4 v[80:81], v[64:67], off offset:528
	v_lshl_add_u64 v[76:77], v[162:163], 0, v[140:141]
	v_lshl_add_u64 v[92:93], v[162:163], 0, v[142:143]
	v_lshl_add_u64 v[108:109], v[162:163], 0, v[172:173]
	global_load_dwordx4 v[64:67], v[76:77], off
	global_load_dwordx4 v[68:71], v[76:77], off offset:16
	global_load_dwordx4 v[72:75], v[76:77], off offset:512
	s_nop 0
	global_load_dwordx4 v[76:79], v[76:77], off offset:528
	s_nop 0
	global_load_dwordx4 v[80:83], v[92:93], off
	global_load_dwordx4 v[84:87], v[92:93], off offset:16
	global_load_dwordx4 v[88:91], v[92:93], off offset:512
	s_nop 0
	global_load_dwordx4 v[92:95], v[92:93], off offset:528
	s_nop 0
	global_load_dwordx4 v[96:99], v[108:109], off
	global_load_dwordx4 v[100:103], v[108:109], off offset:16
	global_load_dwordx4 v[104:107], v[108:109], off offset:512
	s_nop 0
	global_load_dwordx4 v[108:111], v[108:109], off offset:528
	v_lshl_add_u64 v[164:165], v[164:165], 0, s[34:35]
	v_lshl_add_u64 v[124:125], v[162:163], 0, v[164:165]
	global_load_dwordx4 v[112:115], v[124:125], off
	global_load_dwordx4 v[116:119], v[124:125], off offset:16
	global_load_dwordx4 v[120:123], v[124:125], off offset:512
	s_nop 0
	global_load_dwordx4 v[124:127], v[124:125], off offset:528
	v_lshl_add_u64 v[140:141], s[30:31], 0, v[140:141]
	v_lshl_add_u64 v[162:163], s[30:31], 0, v[172:173]
	v_lshl_add_u64 v[142:143], s[30:31], 0, v[142:143]
	v_lshl_add_u64 v[140:141], v[140:141], 0, v[144:145]
	v_lshl_add_u64 v[162:163], v[162:163], 0, v[144:145]
	v_lshl_add_u64 v[142:143], v[142:143], 0, v[144:145]
	v_mov_b32_e32 v251, v220
	s_waitcnt vmcnt(15)
	v_pk_fma_f32 v[62:63], v[62:63], v[158:159], v[66:67]
	v_pk_fma_f32 v[60:61], v[60:61], v[160:161], v[64:65]
	s_waitcnt vmcnt(14)
	v_pk_fma_f32 v[58:59], v[58:59], v[154:155], v[70:71]
	v_pk_fma_f32 v[56:57], v[56:57], v[156:157], v[68:69]
	s_waitcnt vmcnt(5)
	v_pk_fma_f32 v[18:19], v[18:19], v[150:151], v[106:107]
	v_pk_fma_f32 v[16:17], v[16:17], v[152:153], v[104:105]
	v_pk_fma_f32 v[42:43], v[42:43], v[150:151], v[74:75]
	v_pk_fma_f32 v[40:41], v[40:41], v[152:153], v[72:73]
	v_pk_fma_f32 v[38:39], v[38:39], v[146:147], v[78:79]
	v_pk_fma_f32 v[36:37], v[36:37], v[148:149], v[76:77]
	v_pk_fma_f32 v[54:55], v[54:55], v[158:159], v[82:83]
	v_pk_fma_f32 v[52:53], v[52:53], v[160:161], v[80:81]
	v_pk_fma_f32 v[50:51], v[50:51], v[154:155], v[86:87]
	v_pk_fma_f32 v[48:49], v[48:49], v[156:157], v[84:85]
	v_pk_fma_f32 v[30:31], v[30:31], v[150:151], v[90:91]
	v_pk_fma_f32 v[28:29], v[28:29], v[152:153], v[88:89]
	v_pk_fma_f32 v[26:27], v[26:27], v[146:147], v[94:95]
	v_pk_fma_f32 v[24:25], v[24:25], v[148:149], v[92:93]
	v_pk_fma_f32 v[46:47], v[46:47], v[158:159], v[98:99]
	v_pk_fma_f32 v[44:45], v[44:45], v[160:161], v[96:97]
	v_pk_fma_f32 v[34:35], v[34:35], v[154:155], v[102:103]
	v_pk_fma_f32 v[32:33], v[32:33], v[156:157], v[100:101]
	global_store_dwordx4 v[140:141], v[60:63], off
	global_store_dwordx4 v[140:141], v[56:59], off offset:16
	global_store_dwordx4 v[140:141], v[40:43], off offset:512
	global_store_dwordx4 v[140:141], v[36:39], off offset:528
	global_store_dwordx4 v[142:143], v[52:55], off
	global_store_dwordx4 v[142:143], v[48:51], off offset:16
	global_store_dwordx4 v[142:143], v[28:31], off offset:512
	global_store_dwordx4 v[142:143], v[24:27], off offset:528
	global_store_dwordx4 v[162:163], v[44:47], off
	global_store_dwordx4 v[162:163], v[32:35], off offset:16
	global_store_dwordx4 v[162:163], v[16:19], off offset:512
	s_waitcnt vmcnt(15)
	v_pk_fma_f32 v[10:11], v[10:11], v[146:147], v[110:111]
	v_pk_fma_f32 v[8:9], v[8:9], v[148:149], v[108:109]
	v_lshl_add_u64 v[16:17], s[30:31], 0, v[164:165]
	global_store_dwordx4 v[162:163], v[8:11], off offset:528
	v_lshl_add_u64 v[16:17], v[16:17], 0, v[144:145]
	s_waitcnt vmcnt(13)
	v_pk_fma_f32 v[6:7], v[6:7], v[150:151], v[122:123]
	v_pk_fma_f32 v[10:11], v[22:23], v[158:159], v[114:115]
	v_pk_fma_f32 v[8:9], v[20:21], v[160:161], v[112:113]
	global_store_dwordx4 v[16:17], v[8:11], off
	v_pk_fma_f32 v[4:5], v[4:5], v[152:153], v[120:121]
	s_waitcnt vmcnt(13)
	v_pk_fma_f32 v[2:3], v[2:3], v[146:147], v[126:127]
	v_pk_fma_f32 v[10:11], v[14:15], v[154:155], v[118:119]
	v_pk_fma_f32 v[8:9], v[12:13], v[156:157], v[116:117]
	v_pk_fma_f32 v[0:1], v[0:1], v[148:149], v[124:125]
	global_store_dwordx4 v[16:17], v[8:11], off offset:16
	global_store_dwordx4 v[16:17], v[4:7], off offset:512
	global_store_dwordx4 v[16:17], v[0:3], off offset:528
	s_cbranch_vccz .LBB0_234
	s_waitcnt vmcnt(0)
	s_cmpk_gt_u32 s3, 0xff
	s_cbranch_scc1 .LBB0_249
	s_barrier

; #define PG8_STAGE(bufoff, gbase, voff) do { _Pragma("unroll") for (int _i = 0; _i < 2; ++_i) \
;         __builtin_amdgcn_global_load_lds((const unsigned*)((const char*)(gbase) + (voff)[_i]), (PG8_LAS unsigned*)(lds + (bufoff) + ldsw + _i * 8192), 16, 0, 0); } while (0)
; #define PG8_LDA(dst, b, h) do { _Pragma("unroll") for (int m = 0; m < 4; ++m) _Pragma("unroll") for (int k = 0; k < 2; ++k) dst[m][k] = *(const PG8_LAS bf16x8*)(lds + PG8_SA(b, h) + aoff + m * 2048 + k * 1024); } while (0)
; #define PG8_LDB(dst, b, h) do { _Pragma("unroll") for (int n = 0; n < 2; ++n) _Pragma("unroll") for (int k = 0; k < 2; ++k) dst[n][k] = *(const PG8_LAS bf16x8*)(lds + PG8_SB(b, h) + boff + n * 2048 + k * 1024); } while (0)
; #define PG8_MMA(ai, bj, At, Bt) do { __builtin_amdgcn_s_setprio(1); _Pragma("unroll") for (int m = 0; m < 4; ++m) _Pragma("unroll") for (int n = 0; n < 2; ++n) _Pragma("unroll") for (int k = 0; k < 2; ++k) \
;         acc[ai][bj][m][n] = __builtin_amdgcn_mfma_f32_16x16x32_bf16(Bt[n][k], At[m][k], acc[ai][bj][m][n], 0, 0, 0); __builtin_amdgcn_s_setprio(0); } while (0)
; #define PG8_WAIT_V(n) asm volatile("s_waitcnt vmcnt(" #n ")" ::: "memory")
; #define PG8_WAIT_L(n) asm volatile("s_waitcnt lgkmcnt(" #n ")" ::: "memory")
; #define PG8_BAR __builtin_amdgcn_s_barrier()
; #define PG8_SCHED __builtin_amdgcn_sched_barrier(0)
; template <class Epi, class Sched, bool ALIGN_EPI = false, bool SP2 = false>
; __device__ __forceinline__ void gemm_phase(PG8_LAS unsigned char* lds, const Gemm g, const Sched& S, const Epi& E) {
;     ...
;             PG8_LDB(B0, 0, 0); PG8_LDB(B1, 0, 1); PG8_SCHED; PG8_LDA(At, 0, 0); PG8_STAGE(PG8_SA(1, 1), a1 + hstep, voffA);
;             PG8_WAIT_V(8); PG8_WAIT_L(0); PG8_BAR; PG8_MMA(0, 0, At, B0); PG8_MMA(0, 1, At, B1); PG8_BAR; PG8_SCHED;
;             PG8_LDA(At, 0, 1); PG8_STAGE(PG8_SB(0, 0), b2, voffB); PG8_STAGE(PG8_SB(0, 1), b2 + hstep, voffB); PG8_STAGE(PG8_SA(0, 0), a2, voffA);
;             PG8_WAIT_V(8); PG8_WAIT_L(0); PG8_BAR; PG8_MMA(1, 0, At, B0); PG8_MMA(1, 1, At, B1); PG8_BAR; PG8_SCHED;
.LBB0_364:
	ds_read_b128 v[128:131], v214
	ds_read_b128 v[132:135], v214 offset:1024
	ds_read_b128 v[136:139], v214 offset:2048
	ds_read_b128 v[140:143], v214 offset:3072
	ds_read_b128 v[144:147], v215
	ds_read_b128 v[148:151], v215 offset:1024
	ds_read_b128 v[152:155], v215 offset:2048
	ds_read_b128 v[156:159], v215 offset:3072
	s_add_u32 s58, s84, 0xfff80080
	s_addc_u32 s59, s85, -1
	s_cmp_eq_u32 s39, 28
	s_cselect_b32 s89, s77, s59
	s_cselect_b32 s88, s83, s58
	s_cselect_b32 s87, s75, s38
	s_cselect_b32 s86, vcc_lo, vcc_hi
	s_add_i32 m0, s7, 0xc000
	ds_read_b128 v[160:163], v216
	ds_read_b128 v[182:185], v216 offset:1024
	ds_read_b128 v[186:189], v216 offset:2048
	ds_read_b128 v[190:193], v216 offset:3072
	ds_read_b128 v[222:225], v216 offset:4096
	ds_read_b128 v[232:235], v216 offset:5120
	ds_read_b128 v[236:239], v216 offset:6144
	ds_read_b128 v[240:243], v216 offset:7168
	global_load_lds_dwordx4 v174, s[84:85]
	s_add_i32 m0, s7, 0xe000
	s_nop 0
	global_load_lds_dwordx4 v176, s[84:85]
	s_waitcnt vmcnt(8)
	s_waitcnt lgkmcnt(0)
	s_barrier
	s_setprio 1
	s_waitcnt lgkmcnt(0)
	v_mfma_f32_16x16x32_bf16 v[124:127], v[128:131], v[160:163], v[124:127]
	v_mfma_f32_16x16x32_bf16 v[120:123], v[136:139], v[160:163], v[120:123]
	v_mfma_f32_16x16x32_bf16 v[116:119], v[128:131], v[186:189], v[116:119]
	v_mfma_f32_16x16x32_bf16 v[112:115], v[136:139], v[186:189], v[112:115]
	v_mfma_f32_16x16x32_bf16 v[100:103], v[128:131], v[222:225], v[100:103]
	v_mfma_f32_16x16x32_bf16 v[96:99], v[136:139], v[222:225], v[96:99]
	v_mfma_f32_16x16x32_bf16 v[84:87], v[128:131], v[236:239], v[84:87]
	v_mfma_f32_16x16x32_bf16 v[80:83], v[136:139], v[236:239], v[80:83]
	v_mfma_f32_16x16x32_bf16 v[124:127], v[132:135], v[182:185], v[124:127]
	v_mfma_f32_16x16x32_bf16 v[120:123], v[140:143], v[182:185], v[120:123]
	v_mfma_f32_16x16x32_bf16 v[116:119], v[132:135], v[190:193], v[116:119]
	v_mfma_f32_16x16x32_bf16 v[112:115], v[140:143], v[190:193], v[112:115]
	v_mfma_f32_16x16x32_bf16 v[100:103], v[132:135], v[232:235], v[100:103]
	v_mfma_f32_16x16x32_bf16 v[96:99], v[140:143], v[232:235], v[96:99]
	v_mfma_f32_16x16x32_bf16 v[84:87], v[132:135], v[240:243], v[84:87]
	v_mfma_f32_16x16x32_bf16 v[80:83], v[140:143], v[240:243], v[80:83]
	s_setprio 0
	s_setprio 1
	v_mfma_f32_16x16x32_bf16 v[108:111], v[144:147], v[160:163], v[108:111]
	v_mfma_f32_16x16x32_bf16 v[104:107], v[152:155], v[160:163], v[104:107]
	v_mfma_f32_16x16x32_bf16 v[92:95], v[144:147], v[186:189], v[92:95]
	v_mfma_f32_16x16x32_bf16 v[88:91], v[152:155], v[186:189], v[88:91]
	v_mfma_f32_16x16x32_bf16 v[76:79], v[144:147], v[222:225], v[76:79]
	v_mfma_f32_16x16x32_bf16 v[72:75], v[152:155], v[222:225], v[72:75]
	v_mfma_f32_16x16x32_bf16 v[68:71], v[144:147], v[236:239], v[68:71]
	v_mfma_f32_16x16x32_bf16 v[64:67], v[152:155], v[236:239], v[64:67]
	v_mfma_f32_16x16x32_bf16 v[108:111], v[148:151], v[182:185], v[108:111]
	v_mfma_f32_16x16x32_bf16 v[104:107], v[156:159], v[182:185], v[104:107]
	v_mfma_f32_16x16x32_bf16 v[92:95], v[148:151], v[190:193], v[92:95]
	v_mfma_f32_16x16x32_bf16 v[88:91], v[156:159], v[190:193], v[88:91]
	v_mfma_f32_16x16x32_bf16 v[76:79], v[148:151], v[232:235], v[76:79]
	v_mfma_f32_16x16x32_bf16 v[72:75], v[156:159], v[232:235], v[72:75]
	v_mfma_f32_16x16x32_bf16 v[68:71], v[148:151], v[240:243], v[68:71]
	v_mfma_f32_16x16x32_bf16 v[64:67], v[156:159], v[240:243], v[64:67]
	s_setprio 0
	s_barrier
	s_add_i32 s58, s34, s24
	v_lshl_add_u64 v[194:195], s[86:87], 0, v[168:169]
	s_mov_b32 m0, s58
	ds_read_b128 v[160:163], v216 offset:16384
	ds_read_b128 v[182:185], v216 offset:17408
	ds_read_b128 v[186:189], v216 offset:18432
	ds_read_b128 v[190:193], v216 offset:19456
	ds_read_b128 v[222:225], v216 offset:20480
	ds_read_b128 v[232:235], v216 offset:21504
	ds_read_b128 v[236:239], v216 offset:22528
	ds_read_b128 v[240:243], v216 offset:23552
	global_load_lds_dwordx4 v168, s[86:87]
	s_add_i32 m0, s58, 0x2000
	s_add_u32 s58, s86, 0x80000
	v_lshl_add_u64 v[230:231], s[86:87], 0, v[164:165]
	s_addc_u32 s59, s87, 0
	s_add_i32 s48, s35, s24
	global_load_lds_dwordx4 v164, s[86:87]
	s_mov_b32 m0, s48
	v_lshl_add_u64 v[246:247], s[88:89], 0, v[166:167]
	global_load_lds_dwordx4 v168, s[58:59]
	s_add_i32 m0, s48, 0x2000
	s_nop 0
	global_load_lds_dwordx4 v164, s[58:59]
	v_lshl_add_u64 v[244:245], s[88:89], 0, v[170:171]
	s_mov_b32 m0, s7
	s_nop 0
	global_load_lds_dwordx4 v170, s[88:89]
	s_mov_b32 m0, s8
	s_nop 0
	global_load_lds_dwordx4 v166, s[88:89]
	s_waitcnt vmcnt(8)
	s_waitcnt lgkmcnt(0)
	s_barrier
; #define PG8_STAGE(bufoff, gbase, voff) do { _Pragma("unroll") for (int _i = 0; _i < 2; ++_i) \
;         __builtin_amdgcn_global_load_lds((const unsigned*)((const char*)(gbase) + (voff)[_i]), (PG8_LAS unsigned*)(lds + (bufoff) + ldsw + _i * 8192), 16, 0, 0); } while (0)
; #define PG8_LDA(dst, b, h) do { _Pragma("unroll") for (int m = 0; m < 4; ++m) _Pragma("unroll") for (int k = 0; k < 2; ++k) dst[m][k] = *(const PG8_LAS bf16x8*)(lds + PG8_SA(b, h) + aoff + m * 2048 + k * 1024); } while (0)
; #define PG8_LDB(dst, b, h) do { _Pragma("unroll") for (int n = 0; n < 2; ++n) _Pragma("unroll") for (int k = 0; k < 2; ++k) dst[n][k] = *(const PG8_LAS bf16x8*)(lds + PG8_SB(b, h) + boff + n * 2048 + k * 1024); } while (0)
; #define PG8_MMA(ai, bj, At, Bt) do { __builtin_amdgcn_s_setprio(1); _Pragma("unroll") for (int m = 0; m < 4; ++m) _Pragma("unroll") for (int n = 0; n < 2; ++n) _Pragma("unroll") for (int k = 0; k < 2; ++k) \
;         acc[ai][bj][m][n] = __builtin_amdgcn_mfma_f32_16x16x32_bf16(Bt[n][k], At[m][k], acc[ai][bj][m][n], 0, 0, 0); __builtin_amdgcn_s_setprio(0); } while (0)
; #define PG8_WAIT_V(n) asm volatile("s_waitcnt vmcnt(" #n ")" ::: "memory")
; #define PG8_WAIT_L(n) asm volatile("s_waitcnt lgkmcnt(" #n ")" ::: "memory")
; #define PG8_BAR __builtin_amdgcn_s_barrier()
; #define PG8_SCHED __builtin_amdgcn_sched_barrier(0)
; template <class Epi, class Sched, bool ALIGN_EPI = false, bool SP2 = false>
; __device__ __forceinline__ void gemm_phase(PG8_LAS unsigned char* lds, const Gemm g, const Sched& S, const Epi& E) {
;     ...
;             PG8_WAIT_V(8); PG8_WAIT_L(0); PG8_BAR; PG8_MMA(1, 0, At, B0); PG8_MMA(1, 1, At, B1); PG8_BAR; PG8_SCHED;
;             PG8_LDB(B0, 1, 0); PG8_LDB(B1, 1, 1); PG8_SCHED; PG8_LDA(At, 1, 0); PG8_STAGE(PG8_SA(0, 1), a2 + hstep, voffA);
;             PG8_WAIT_V(8); PG8_WAIT_L(0); PG8_BAR; PG8_MMA(0, 0, At, B0); PG8_MMA(0, 1, At, B1); PG8_BAR; PG8_SCHED;
;             PG8_LDA(At, 1, 1); PG8_STAGE(PG8_SB(1, 0), b3, voffB); PG8_STAGE(PG8_SB(1, 1), b3 + hstep, voffB); PG8_STAGE(PG8_SA(1, 0), a3, voffA);
	s_setprio 1
	s_waitcnt lgkmcnt(0)
	v_mfma_f32_16x16x32_bf16 v[60:63], v[128:131], v[160:163], v[60:63]
	v_mfma_f32_16x16x32_bf16 v[56:59], v[136:139], v[160:163], v[56:59]
	v_mfma_f32_16x16x32_bf16 v[52:55], v[128:131], v[186:189], v[52:55]
	v_mfma_f32_16x16x32_bf16 v[48:51], v[136:139], v[186:189], v[48:51]
	v_mfma_f32_16x16x32_bf16 v[36:39], v[128:131], v[222:225], v[36:39]
	v_mfma_f32_16x16x32_bf16 v[32:35], v[136:139], v[222:225], v[32:35]
	v_mfma_f32_16x16x32_bf16 v[20:23], v[128:131], v[236:239], v[20:23]
	v_mfma_f32_16x16x32_bf16 v[16:19], v[136:139], v[236:239], v[16:19]
	v_mfma_f32_16x16x32_bf16 v[60:63], v[132:135], v[182:185], v[60:63]
	v_mfma_f32_16x16x32_bf16 v[56:59], v[140:143], v[182:185], v[56:59]
	v_mfma_f32_16x16x32_bf16 v[52:55], v[132:135], v[190:193], v[52:55]
	v_mfma_f32_16x16x32_bf16 v[48:51], v[140:143], v[190:193], v[48:51]
	v_mfma_f32_16x16x32_bf16 v[36:39], v[132:135], v[232:235], v[36:39]
	v_mfma_f32_16x16x32_bf16 v[32:35], v[140:143], v[232:235], v[32:35]
	v_mfma_f32_16x16x32_bf16 v[20:23], v[132:135], v[240:243], v[20:23]
	v_mfma_f32_16x16x32_bf16 v[16:19], v[140:143], v[240:243], v[16:19]
	s_setprio 0
	s_setprio 1
	v_mfma_f32_16x16x32_bf16 v[44:47], v[144:147], v[160:163], v[44:47]
	v_mfma_f32_16x16x32_bf16 v[40:43], v[152:155], v[160:163], v[40:43]
	v_mfma_f32_16x16x32_bf16 v[28:31], v[144:147], v[186:189], v[28:31]
	v_mfma_f32_16x16x32_bf16 v[24:27], v[152:155], v[186:189], v[24:27]
	v_mfma_f32_16x16x32_bf16 v[12:15], v[144:147], v[222:225], v[12:15]
	v_mfma_f32_16x16x32_bf16 v[8:11], v[152:155], v[222:225], v[8:11]
	v_mfma_f32_16x16x32_bf16 v[4:7], v[144:147], v[236:239], v[4:7]
	v_mfma_f32_16x16x32_bf16 v[0:3], v[152:155], v[236:239], v[0:3]
	v_mfma_f32_16x16x32_bf16 v[44:47], v[148:151], v[182:185], v[44:47]
	v_mfma_f32_16x16x32_bf16 v[40:43], v[156:159], v[182:185], v[40:43]
	v_mfma_f32_16x16x32_bf16 v[28:31], v[148:151], v[190:193], v[28:31]
	v_mfma_f32_16x16x32_bf16 v[24:27], v[156:159], v[190:193], v[24:27]
	v_mfma_f32_16x16x32_bf16 v[12:15], v[148:151], v[232:235], v[12:15]
	v_mfma_f32_16x16x32_bf16 v[8:11], v[156:159], v[232:235], v[8:11]
	v_mfma_f32_16x16x32_bf16 v[4:7], v[148:151], v[240:243], v[4:7]
	v_mfma_f32_16x16x32_bf16 v[0:3], v[156:159], v[240:243], v[0:3]
	s_setprio 0
	s_barrier
	s_add_i32 s48, 0, 0x18000
	s_add_i32 s60, 0, 0x1c000
	v_add_u32_e32 v140, s48, v197
	v_add_u32_e32 v156, s60, v197
	ds_read_b128 v[128:131], v140
	ds_read_b128 v[132:135], v140 offset:1024
	ds_read_b128 v[136:139], v140 offset:2048
	ds_read_b128 v[140:143], v140 offset:3072
	ds_read_b128 v[144:147], v156
	ds_read_b128 v[148:151], v156 offset:1024
	ds_read_b128 v[152:155], v156 offset:2048
	ds_read_b128 v[156:159], v156 offset:3072
	s_add_u32 s58, s88, 0x80000
	s_addc_u32 s59, s89, 0
	s_mov_b32 m0, s9
	ds_read_b128 v[160:163], v216 offset:32768
	ds_read_b128 v[182:185], v216 offset:33792
	ds_read_b128 v[186:189], v216 offset:34816
	ds_read_b128 v[190:193], v216 offset:35840
	ds_read_b128 v[222:225], v216 offset:36864
	ds_read_b128 v[232:235], v216 offset:37888
	ds_read_b128 v[236:239], v216 offset:38912
	ds_read_b128 v[240:243], v216 offset:39936
	global_load_lds_dwordx4 v170, s[58:59]
	s_mov_b32 m0, s26
	s_nop 0
	global_load_lds_dwordx4 v166, s[58:59]
	s_waitcnt vmcnt(8)
	s_waitcnt lgkmcnt(0)
	s_barrier
	s_setprio 1
	s_waitcnt lgkmcnt(0)
	v_mfma_f32_16x16x32_bf16 v[124:127], v[128:131], v[160:163], v[124:127]
	v_mfma_f32_16x16x32_bf16 v[120:123], v[136:139], v[160:163], v[120:123]
	v_mfma_f32_16x16x32_bf16 v[116:119], v[128:131], v[186:189], v[116:119]
	v_mfma_f32_16x16x32_bf16 v[112:115], v[136:139], v[186:189], v[112:115]
	v_mfma_f32_16x16x32_bf16 v[100:103], v[128:131], v[222:225], v[100:103]
	v_mfma_f32_16x16x32_bf16 v[96:99], v[136:139], v[222:225], v[96:99]
	v_mfma_f32_16x16x32_bf16 v[84:87], v[128:131], v[236:239], v[84:87]
	v_mfma_f32_16x16x32_bf16 v[80:83], v[136:139], v[236:239], v[80:83]
	v_mfma_f32_16x16x32_bf16 v[124:127], v[132:135], v[182:185], v[124:127]
	v_mfma_f32_16x16x32_bf16 v[120:123], v[140:143], v[182:185], v[120:123]
	v_mfma_f32_16x16x32_bf16 v[116:119], v[132:135], v[190:193], v[116:119]
	v_mfma_f32_16x16x32_bf16 v[112:115], v[140:143], v[190:193], v[112:115]
	v_mfma_f32_16x16x32_bf16 v[100:103], v[132:135], v[232:235], v[100:103]
	v_mfma_f32_16x16x32_bf16 v[96:99], v[140:143], v[232:235], v[96:99]
	v_mfma_f32_16x16x32_bf16 v[84:87], v[132:135], v[240:243], v[84:87]
	v_mfma_f32_16x16x32_bf16 v[80:83], v[140:143], v[240:243], v[80:83]
	s_setprio 0
	s_setprio 1
	v_mfma_f32_16x16x32_bf16 v[108:111], v[144:147], v[160:163], v[108:111]
	v_mfma_f32_16x16x32_bf16 v[104:107], v[152:155], v[160:163], v[104:107]
	v_mfma_f32_16x16x32_bf16 v[92:95], v[144:147], v[186:189], v[92:95]
	v_mfma_f32_16x16x32_bf16 v[88:91], v[152:155], v[186:189], v[88:91]
	v_mfma_f32_16x16x32_bf16 v[76:79], v[144:147], v[222:225], v[76:79]
	v_mfma_f32_16x16x32_bf16 v[72:75], v[152:155], v[222:225], v[72:75]
	v_mfma_f32_16x16x32_bf16 v[68:71], v[144:147], v[236:239], v[68:71]
	v_mfma_f32_16x16x32_bf16 v[64:67], v[152:155], v[236:239], v[64:67]
	v_mfma_f32_16x16x32_bf16 v[108:111], v[148:151], v[182:185], v[108:111]
	v_mfma_f32_16x16x32_bf16 v[104:107], v[156:159], v[182:185], v[104:107]
	v_mfma_f32_16x16x32_bf16 v[92:95], v[148:151], v[190:193], v[92:95]
	v_mfma_f32_16x16x32_bf16 v[88:91], v[156:159], v[190:193], v[88:91]
	v_mfma_f32_16x16x32_bf16 v[76:79], v[148:151], v[232:235], v[76:79]
	v_mfma_f32_16x16x32_bf16 v[72:75], v[156:159], v[232:235], v[72:75]
	v_mfma_f32_16x16x32_bf16 v[68:71], v[148:151], v[240:243], v[68:71]
	v_mfma_f32_16x16x32_bf16 v[64:67], v[156:159], v[240:243], v[64:67]
	s_setprio 0
	s_barrier
; __device__ __forceinline__ float fsigmoid(float v) { return __builtin_amdgcn_rcpf(1.0f + __builtin_amdgcn_exp2f(-LOG2E * v)); }
; __device__ __forceinline__ float fsilu(float v) { return v * fsigmoid(v); }
; __device__ __forceinline__ u32x4 pack8(const f32x4 a, const f32x4 b) { u32x4 w; w.x = cvt_pk_bf16(a[0], a[1]); w.y = cvt_pk_bf16(a[2], a[3]); w.z = cvt_pk_bf16(b[0], b[1]); w.w = cvt_pk_bf16(b[2], b[3]); return w; }
; #define PG8_STAGE(bufoff, gbase, voff) do { _Pragma("unroll") for (int _i = 0; _i < 2; ++_i) \
;         __builtin_amdgcn_global_load_lds((const unsigned*)((const char*)(gbase) + (voff)[_i]), (PG8_LAS unsigned*)(lds + (bufoff) + ldsw + _i * 8192), 16, 0, 0); } while (0)
; #define PG8_LDA(dst, b, h) do { _Pragma("unroll") for (int m = 0; m < 4; ++m) _Pragma("unroll") for (int k = 0; k < 2; ++k) dst[m][k] = *(const PG8_LAS bf16x8*)(lds + PG8_SA(b, h) + aoff + m * 2048 + k * 1024); } while (0)
; #define PG8_WAIT_V(n) asm volatile("s_waitcnt vmcnt(" #n ")" ::: "memory")
; #define PG8_WAIT_L(n) asm volatile("s_waitcnt lgkmcnt(" #n ")" ::: "memory")
;     template <int ACT> __device__ __forceinline__ void ew(const f32x4 (&acc)[2][2][4][2], bf16_t* D, int ld, int row0, int col0) const {
; #pragma unroll
;         for (int ai = 0; ai < 2; ++ai)
; #pragma unroll
;             for (int m = 0; m < 4; ++m) { bf16_t* rowp = D + (size_t)(row0 + ai * HALF + m * 16) * ld + col0;
; #pragma unroll
;                 for (int bj = 0; bj < 2; ++bj) { f32x4 v0 = acc[ai][bj][m][0], v1 = acc[ai][bj][m][1];
;                     if (ACT == 1) {
; #pragma unroll
;                         for (int j = 0; j < 4; ++j) { v0[j] = fsilu(v0[j]); v1[j] = fsilu(v1[j]); } }
;                     if (ACT == 2) {
; #pragma unroll
;                         for (int j = 0; j < 4; ++j) { v0[j] = fsigmoid(v0[j]); v1[j] = fsigmoid(v1[j]); } }
;                     *(u32x4*)(rowp + bj * HALF) = pack8(v0, v1); } }
; template <class Epi, class Sched, bool ALIGN_EPI = false, bool SP2 = false>
; __device__ __forceinline__ void gemm_phase(PG8_LAS unsigned char* lds, const Gemm g, const Sched& S, const Epi& E) {
;     ...
;             PG8_LDA(At, 1, 1); PG8_STAGE(PG8_SB(1, 0), b3, voffB); PG8_STAGE(PG8_SB(1, 1), b3 + hstep, voffB); PG8_STAGE(PG8_SA(1, 0), a3, voffA);
;             PG8_WAIT_V(8); PG8_WAIT_L(0); PG8_BAR; PG8_MMA(1, 0, At, B0); PG8_MMA(1, 1, At, B1); PG8_BAR; PG8_SCHED;
	s_add_i32 s48, s48, s24
	v_lshl_add_u64 v[194:195], v[194:195], 0, s[54:55]
	s_mov_b32 m0, s48
	ds_read_b128 v[160:163], v216 offset:49152
	ds_read_b128 v[182:185], v216 offset:50176
	ds_read_b128 v[186:189], v216 offset:51200
	ds_read_b128 v[190:193], v216 offset:52224
	ds_read_b128 v[222:225], v216 offset:53248
	ds_read_b128 v[232:235], v216 offset:54272
	ds_read_b128 v[236:239], v216 offset:55296
	ds_read_b128 v[240:243], v216 offset:56320
	global_load_lds_dwordx4 v[194:195], off
	s_add_i32 m0, s48, 0x2000
	s_add_u32 s58, s86, 0x80080
	v_lshl_add_u64 v[194:195], v[230:231], 0, s[54:55]
	s_addc_u32 s59, s87, 0
	s_add_i32 s48, s60, s24
	global_load_lds_dwordx4 v[194:195], off
	s_mov_b32 m0, s48
	s_nop 0
	global_load_lds_dwordx4 v168, s[58:59]
	s_add_i32 m0, s48, 0x2000
	s_nop 0
	global_load_lds_dwordx4 v164, s[58:59]
	v_lshl_add_u64 v[194:195], v[244:245], 0, s[54:55]
	s_mov_b32 m0, s36
	s_nop 0
	global_load_lds_dwordx4 v[194:195], off
	v_lshl_add_u64 v[194:195], v[246:247], 0, s[54:55]
	s_mov_b32 m0, s37
	s_nop 0
	global_load_lds_dwordx4 v[194:195], off
	s_waitcnt vmcnt(8)
	s_waitcnt lgkmcnt(0)
	s_barrier
	s_setprio 1
	s_waitcnt lgkmcnt(0)
	v_mfma_f32_16x16x32_bf16 v[60:63], v[128:131], v[160:163], v[60:63]
	v_mfma_f32_16x16x32_bf16 v[56:59], v[136:139], v[160:163], v[56:59]
	v_mfma_f32_16x16x32_bf16 v[52:55], v[128:131], v[186:189], v[52:55]
	v_mfma_f32_16x16x32_bf16 v[48:51], v[136:139], v[186:189], v[48:51]
	v_mfma_f32_16x16x32_bf16 v[36:39], v[128:131], v[222:225], v[36:39]
	v_mfma_f32_16x16x32_bf16 v[32:35], v[136:139], v[222:225], v[32:35]
	v_mfma_f32_16x16x32_bf16 v[20:23], v[128:131], v[236:239], v[20:23]
	v_mfma_f32_16x16x32_bf16 v[16:19], v[136:139], v[236:239], v[16:19]
	v_mfma_f32_16x16x32_bf16 v[60:63], v[132:135], v[182:185], v[60:63]
	v_mfma_f32_16x16x32_bf16 v[56:59], v[140:143], v[182:185], v[56:59]
	v_mfma_f32_16x16x32_bf16 v[52:55], v[132:135], v[190:193], v[52:55]
	v_mfma_f32_16x16x32_bf16 v[48:51], v[140:143], v[190:193], v[48:51]
	v_mfma_f32_16x16x32_bf16 v[36:39], v[132:135], v[232:235], v[36:39]
	v_mfma_f32_16x16x32_bf16 v[32:35], v[140:143], v[232:235], v[32:35]
	v_mfma_f32_16x16x32_bf16 v[20:23], v[132:135], v[240:243], v[20:23]
	v_mfma_f32_16x16x32_bf16 v[16:19], v[140:143], v[240:243], v[16:19]
	s_setprio 0
	s_setprio 1
	v_mfma_f32_16x16x32_bf16 v[44:47], v[144:147], v[160:163], v[44:47]
	v_mfma_f32_16x16x32_bf16 v[40:43], v[152:155], v[160:163], v[40:43]
	v_mfma_f32_16x16x32_bf16 v[28:31], v[144:147], v[186:189], v[28:31]
	v_mfma_f32_16x16x32_bf16 v[24:27], v[152:155], v[186:189], v[24:27]
	v_mfma_f32_16x16x32_bf16 v[12:15], v[144:147], v[222:225], v[12:15]
	v_mfma_f32_16x16x32_bf16 v[8:11], v[152:155], v[222:225], v[8:11]
	v_mfma_f32_16x16x32_bf16 v[4:7], v[144:147], v[236:239], v[4:7]
	v_mfma_f32_16x16x32_bf16 v[0:3], v[152:155], v[236:239], v[0:3]
	v_mfma_f32_16x16x32_bf16 v[44:47], v[148:151], v[182:185], v[44:47]
	v_mfma_f32_16x16x32_bf16 v[40:43], v[156:159], v[182:185], v[40:43]
	v_mfma_f32_16x16x32_bf16 v[28:31], v[148:151], v[190:193], v[28:31]
	v_mfma_f32_16x16x32_bf16 v[24:27], v[156:159], v[190:193], v[24:27]
	v_mfma_f32_16x16x32_bf16 v[12:15], v[148:151], v[232:235], v[12:15]
	v_mfma_f32_16x16x32_bf16 v[8:11], v[156:159], v[232:235], v[8:11]
	v_mfma_f32_16x16x32_bf16 v[4:7], v[148:151], v[240:243], v[4:7]
	v_mfma_f32_16x16x32_bf16 v[0:3], v[156:159], v[240:243], v[0:3]
	s_setprio 0
	s_barrier
	s_add_i32 s39, s39, 2
	s_add_u32 s84, s84, 0x100
	s_addc_u32 s85, s85, 0
	s_add_u32 vcc_hi, vcc_hi, 0x100
	s_addc_u32 s38, s38, 0
	s_cmp_gt_u32 s39, 29
	s_cbranch_scc0 .LBB0_364
	v_lshl_add_u32 v182, s82, 8, v196
	s_cmp_gt_i32 s23, 3
	s_mov_b64 s[82:83], -1
	s_cbranch_scc0 .LBB0_391
	s_cmp_gt_u32 s23, 7
	s_cbranch_scc0 .LBB0_388
	s_cmp_gt_u32 s23, 11
	s_cbranch_scc0 .LBB0_385
	s_cmp_gt_u32 s23, 15
	s_cbranch_scc0 .LBB0_382
	s_cmp_gt_u32 s23, 23
	s_cbranch_scc0 .LBB0_379
	s_lshl_b32 s75, s23, 8
	s_cmp_gt_u32 s23, 27
	s_cbranch_scc0 .LBB0_376
	v_mul_f32_e32 v129, 0xbfb8aa3b, v120
	v_exp_f32_e32 v129, v129
	v_mul_f32_e32 v130, 0xbfb8aa3b, v125
	v_mul_f32_e32 v131, 0xbfb8aa3b, v121
	v_exp_f32_e32 v130, v130
	v_exp_f32_e32 v131, v131
	v_add_f32_e32 v129, 1.0, v129
	v_mul_f32_e32 v128, 0xbfb8aa3b, v124
	v_rcp_f32_e32 v132, v129
	v_add_f32_e32 v129, 1.0, v130
	v_add_f32_e32 v130, 1.0, v131
	v_mul_f32_e32 v131, 0xbfb8aa3b, v126
	v_mul_f32_e32 v134, 0xbfb8aa3b, v127
	v_exp_f32_e32 v128, v128
	v_exp_f32_e32 v131, v131
	v_exp_f32_e32 v134, v134
	v_rcp_f32_e32 v129, v129
	v_add_f32_e32 v128, 1.0, v128
	v_add_f32_e32 v131, 1.0, v131
	v_add_f32_e32 v134, 1.0, v134
	v_rcp_f32_e32 v128, v128
	v_mul_f32_e32 v133, 0xbfb8aa3b, v122
	v_rcp_f32_e32 v131, v131
	v_mul_f32_e32 v135, 0xbfb8aa3b, v123
	v_rcp_f32_e32 v134, v134
	v_exp_f32_e32 v133, v133
	v_rcp_f32_e32 v130, v130
	v_exp_f32_e32 v135, v135
	v_cvt_pk_bf16_f32 v128, v128, v129
	v_cvt_pk_bf16_f32 v129, v131, v134
	v_mul_f32_e32 v131, 0xbfb8aa3b, v108
	v_add_f32_e32 v133, 1.0, v133
	v_add_f32_e32 v135, 1.0, v135
	v_cvt_pk_bf16_f32 v130, v132, v130
	v_exp_f32_e32 v132, v131
	v_mul_f32_e32 v131, 0xbfb8aa3b, v104
	v_rcp_f32_e32 v133, v133
	v_rcp_f32_e32 v135, v135
	v_exp_f32_e32 v134, v131
	v_mul_f32_e32 v137, 0xbfb8aa3b, v106
	v_mul_f32_e32 v138, 0xbfb8aa3b, v111
	v_cvt_pk_bf16_f32 v131, v133, v135
	v_add_f32_e32 v133, 1.0, v134
	v_mul_f32_e32 v134, 0xbfb8aa3b, v109
	v_mul_f32_e32 v135, 0xbfb8aa3b, v105
	v_exp_f32_e32 v134, v134
	v_exp_f32_e32 v135, v135
	v_rcp_f32_e32 v136, v133
	v_mul_f32_e32 v139, 0xbfb8aa3b, v107
	v_add_f32_e32 v133, 1.0, v134
	v_add_f32_e32 v134, 1.0, v135
	v_mul_f32_e32 v135, 0xbfb8aa3b, v110
	v_exp_f32_e32 v135, v135
	v_exp_f32_e32 v137, v137
; __device__ __forceinline__ float fsigmoid(float v) { return __builtin_amdgcn_rcpf(1.0f + __builtin_amdgcn_exp2f(-LOG2E * v)); }
; __device__ __forceinline__ float fsilu(float v) { return v * fsigmoid(v); }
; __device__ __forceinline__ u32x4 pack8(const f32x4 a, const f32x4 b) { u32x4 w; w.x = cvt_pk_bf16(a[0], a[1]); w.y = cvt_pk_bf16(a[2], a[3]); w.z = cvt_pk_bf16(b[0], b[1]); w.w = cvt_pk_bf16(b[2], b[3]); return w; }
;     template <int ACT> __device__ __forceinline__ void ew(const f32x4 (&acc)[2][2][4][2], bf16_t* D, int ld, int row0, int col0) const {
; #pragma unroll
;         for (int ai = 0; ai < 2; ++ai)
; #pragma unroll
;             for (int m = 0; m < 4; ++m) { bf16_t* rowp = D + (size_t)(row0 + ai * HALF + m * 16) * ld + col0;
; #pragma unroll
;                 for (int bj = 0; bj < 2; ++bj) { f32x4 v0 = acc[ai][bj][m][0], v1 = acc[ai][bj][m][1];
;                     if (ACT == 1) {
; #pragma unroll
;                         for (int j = 0; j < 4; ++j) { v0[j] = fsilu(v0[j]); v1[j] = fsilu(v1[j]); } }
;                     if (ACT == 2) {
; #pragma unroll
;                         for (int j = 0; j < 4; ++j) { v0[j] = fsigmoid(v0[j]); v1[j] = fsigmoid(v1[j]); } }
;                     *(u32x4*)(rowp + bj * HALF) = pack8(v0, v1); } }
;     }
	v_exp_f32_e32 v138, v138
	v_exp_f32_e32 v139, v139
	v_add_f32_e32 v132, 1.0, v132
	v_add_f32_e32 v135, 1.0, v135
	v_add_f32_e32 v137, 1.0, v137
	v_add_f32_e32 v138, 1.0, v138
	v_add_f32_e32 v139, 1.0, v139
	v_rcp_f32_e32 v132, v132
	v_rcp_f32_e32 v133, v133
	v_rcp_f32_e32 v135, v135
	v_rcp_f32_e32 v137, v137
	v_rcp_f32_e32 v138, v138
	v_rcp_f32_e32 v139, v139
	v_rcp_f32_e32 v134, v134
	v_cvt_pk_bf16_f32 v132, v132, v133
	v_cvt_pk_bf16_f32 v133, v135, v138
	v_cvt_pk_bf16_f32 v135, v137, v139
	v_mul_f32_e32 v138, 0xbfb8aa3b, v116
	v_mul_f32_e32 v139, 0xbfb8aa3b, v112
	v_exp_f32_e32 v138, v138
	v_exp_f32_e32 v139, v139
	v_cvt_pk_bf16_f32 v134, v136, v134
	v_or_b32_e32 v136, 16, v182
	v_ashrrev_i32_e32 v137, 31, v136
	v_lshlrev_b64 v[186:187], 12, v[136:137]
	v_add_f32_e32 v136, 1.0, v138
	v_add_f32_e32 v137, 1.0, v139
	v_mul_f32_e32 v138, 0xbfb8aa3b, v117
	v_mul_f32_e32 v139, 0xbfb8aa3b, v113
	v_exp_f32_e32 v138, v138
	v_exp_f32_e32 v139, v139
	v_rcp_f32_e32 v140, v137
	v_mul_f32_e32 v142, 0xbfb8aa3b, v119
	v_add_f32_e32 v137, 1.0, v138
	v_add_f32_e32 v138, 1.0, v139
	v_mul_f32_e32 v139, 0xbfb8aa3b, v118
	v_exp_f32_e32 v139, v139
	v_exp_f32_e32 v142, v142
	v_rcp_f32_e32 v136, v136
	v_rcp_f32_e32 v137, v137
	v_add_f32_e32 v139, 1.0, v139
	v_add_f32_e32 v142, 1.0, v142
	v_mul_f32_e32 v141, 0xbfb8aa3b, v114
	v_rcp_f32_e32 v139, v139
	v_mul_f32_e32 v143, 0xbfb8aa3b, v115
	v_rcp_f32_e32 v142, v142
	v_exp_f32_e32 v141, v141
	v_rcp_f32_e32 v138, v138
	v_exp_f32_e32 v143, v143
	v_cvt_pk_bf16_f32 v136, v136, v137
	v_cvt_pk_bf16_f32 v137, v139, v142
	v_mul_f32_e32 v139, 0xbfb8aa3b, v92
	v_add_f32_e32 v141, 1.0, v141
	v_add_f32_e32 v143, 1.0, v143
	v_cvt_pk_bf16_f32 v138, v140, v138
	v_exp_f32_e32 v140, v139
	v_mul_f32_e32 v139, 0xbfb8aa3b, v88
	v_rcp_f32_e32 v141, v141
	v_rcp_f32_e32 v143, v143
	v_exp_f32_e32 v142, v139
	v_mul_f32_e32 v145, 0xbfb8aa3b, v90
	v_mul_f32_e32 v146, 0xbfb8aa3b, v95
	v_cvt_pk_bf16_f32 v139, v141, v143
	v_add_f32_e32 v141, 1.0, v142
	v_mul_f32_e32 v142, 0xbfb8aa3b, v93
	v_mul_f32_e32 v143, 0xbfb8aa3b, v89
	v_exp_f32_e32 v142, v142
	v_exp_f32_e32 v143, v143
	v_rcp_f32_e32 v144, v141
	v_mul_f32_e32 v147, 0xbfb8aa3b, v91
	v_add_f32_e32 v141, 1.0, v142
	v_add_f32_e32 v142, 1.0, v143
	v_mul_f32_e32 v143, 0xbfb8aa3b, v94
	v_exp_f32_e32 v143, v143
	v_exp_f32_e32 v145, v145
	v_exp_f32_e32 v146, v146
	v_exp_f32_e32 v147, v147
	v_add_f32_e32 v140, 1.0, v140
	v_add_f32_e32 v143, 1.0, v143
	v_add_f32_e32 v145, 1.0, v145
	v_add_f32_e32 v146, 1.0, v146
	v_add_f32_e32 v147, 1.0, v147
	v_rcp_f32_e32 v140, v140
	v_rcp_f32_e32 v141, v141
	v_rcp_f32_e32 v143, v143
	v_rcp_f32_e32 v145, v145
	v_rcp_f32_e32 v146, v146
	v_rcp_f32_e32 v147, v147
	v_rcp_f32_e32 v142, v142
	v_cvt_pk_bf16_f32 v140, v140, v141
	v_cvt_pk_bf16_f32 v141, v143, v146
	v_cvt_pk_bf16_f32 v143, v145, v147
	v_mul_f32_e32 v146, 0xbfb8aa3b, v100
	v_mul_f32_e32 v147, 0xbfb8aa3b, v96
	v_exp_f32_e32 v146, v146
	v_exp_f32_e32 v147, v147
	v_cvt_pk_bf16_f32 v142, v144, v142
	v_or_b32_e32 v144, 32, v182
	v_ashrrev_i32_e32 v145, 31, v144
	v_lshlrev_b64 v[188:189], 12, v[144:145]
	v_add_f32_e32 v144, 1.0, v146
	v_add_f32_e32 v145, 1.0, v147
	v_mul_f32_e32 v146, 0xbfb8aa3b, v101
	v_mul_f32_e32 v147, 0xbfb8aa3b, v97
	v_exp_f32_e32 v146, v146
	v_exp_f32_e32 v147, v147
	v_rcp_f32_e32 v148, v145
	v_mul_f32_e32 v150, 0xbfb8aa3b, v103
	v_add_f32_e32 v145, 1.0, v146
	v_add_f32_e32 v146, 1.0, v147
	v_mul_f32_e32 v147, 0xbfb8aa3b, v102
	v_exp_f32_e32 v147, v147
	v_exp_f32_e32 v150, v150
	v_rcp_f32_e32 v144, v144
	v_rcp_f32_e32 v145, v145
	v_add_f32_e32 v147, 1.0, v147
	v_add_f32_e32 v150, 1.0, v150
	v_mul_f32_e32 v149, 0xbfb8aa3b, v98
	v_rcp_f32_e32 v147, v147
	v_mul_f32_e32 v151, 0xbfb8aa3b, v99
	v_rcp_f32_e32 v150, v150
	v_exp_f32_e32 v149, v149
	v_rcp_f32_e32 v146, v146
	v_exp_f32_e32 v151, v151
	v_cvt_pk_bf16_f32 v144, v144, v145
	v_cvt_pk_bf16_f32 v145, v147, v150
	v_mul_f32_e32 v147, 0xbfb8aa3b, v76
	v_add_f32_e32 v149, 1.0, v149
	v_add_f32_e32 v151, 1.0, v151
	v_cvt_pk_bf16_f32 v146, v148, v146
	v_exp_f32_e32 v148, v147
	v_mul_f32_e32 v147, 0xbfb8aa3b, v72
	v_rcp_f32_e32 v149, v149
	v_rcp_f32_e32 v151, v151
	v_exp_f32_e32 v150, v147
	v_mul_f32_e32 v153, 0xbfb8aa3b, v74
	v_mul_f32_e32 v154, 0xbfb8aa3b, v79
	v_cvt_pk_bf16_f32 v147, v149, v151
	v_add_f32_e32 v149, 1.0, v150
	v_mul_f32_e32 v150, 0xbfb8aa3b, v77
	v_mul_f32_e32 v151, 0xbfb8aa3b, v73
	v_exp_f32_e32 v150, v150
	v_exp_f32_e32 v151, v151
	v_rcp_f32_e32 v152, v149
	v_mul_f32_e32 v155, 0xbfb8aa3b, v75
	v_add_f32_e32 v149, 1.0, v150
	v_add_f32_e32 v150, 1.0, v151
	v_mul_f32_e32 v151, 0xbfb8aa3b, v78
	v_exp_f32_e32 v151, v151
	v_exp_f32_e32 v153, v153
	v_exp_f32_e32 v154, v154
	v_exp_f32_e32 v155, v155
	v_add_f32_e32 v148, 1.0, v148
	v_add_f32_e32 v151, 1.0, v151
	v_add_f32_e32 v153, 1.0, v153
	v_add_f32_e32 v154, 1.0, v154
	v_add_f32_e32 v155, 1.0, v155
	v_rcp_f32_e32 v148, v148
	v_rcp_f32_e32 v149, v149
	v_rcp_f32_e32 v151, v151
	v_rcp_f32_e32 v153, v153
	v_rcp_f32_e32 v154, v154
	v_rcp_f32_e32 v155, v155
	v_rcp_f32_e32 v150, v150
	v_cvt_pk_bf16_f32 v148, v148, v149
	v_cvt_pk_bf16_f32 v149, v151, v154
	v_cvt_pk_bf16_f32 v151, v153, v155
	v_mul_f32_e32 v154, 0xbfb8aa3b, v84
	v_mul_f32_e32 v155, 0xbfb8aa3b, v80
	v_exp_f32_e32 v154, v154
	v_exp_f32_e32 v155, v155
	v_cvt_pk_bf16_f32 v150, v152, v150
	v_or_b32_e32 v152, 48, v182
	v_ashrrev_i32_e32 v153, 31, v152
	v_lshlrev_b64 v[190:191], 12, v[152:153]
	v_add_f32_e32 v152, 1.0, v154
	v_add_f32_e32 v153, 1.0, v155
	v_mul_f32_e32 v154, 0xbfb8aa3b, v85
	v_mul_f32_e32 v155, 0xbfb8aa3b, v81
	v_exp_f32_e32 v154, v154
	v_exp_f32_e32 v155, v155
	v_rcp_f32_e32 v156, v153
	v_mul_f32_e32 v158, 0xbfb8aa3b, v87
; __device__ __forceinline__ float fsigmoid(float v) { return __builtin_amdgcn_rcpf(1.0f + __builtin_amdgcn_exp2f(-LOG2E * v)); }
; __device__ __forceinline__ float fsilu(float v) { return v * fsigmoid(v); }
; __device__ __forceinline__ u32x4 pack8(const f32x4 a, const f32x4 b) { u32x4 w; w.x = cvt_pk_bf16(a[0], a[1]); w.y = cvt_pk_bf16(a[2], a[3]); w.z = cvt_pk_bf16(b[0], b[1]); w.w = cvt_pk_bf16(b[2], b[3]); return w; }
;     template <int ACT> __device__ __forceinline__ void ew(const f32x4 (&acc)[2][2][4][2], bf16_t* D, int ld, int row0, int col0) const {
; #pragma unroll
;         for (int ai = 0; ai < 2; ++ai)
; #pragma unroll
;             for (int m = 0; m < 4; ++m) { bf16_t* rowp = D + (size_t)(row0 + ai * HALF + m * 16) * ld + col0;
; #pragma unroll
;                 for (int bj = 0; bj < 2; ++bj) { f32x4 v0 = acc[ai][bj][m][0], v1 = acc[ai][bj][m][1];
;                     if (ACT == 1) {
; #pragma unroll
;                         for (int j = 0; j < 4; ++j) { v0[j] = fsilu(v0[j]); v1[j] = fsilu(v1[j]); } }
;                     if (ACT == 2) {
; #pragma unroll
;                         for (int j = 0; j < 4; ++j) { v0[j] = fsigmoid(v0[j]); v1[j] = fsigmoid(v1[j]); } }
;                     *(u32x4*)(rowp + bj * HALF) = pack8(v0, v1); } }
;     }
;     __device__ __forceinline__ void operator()(const f32x4 (&acc)[2][2][4][2], const Unit& u, int wr, int wc, int fr, int fq) const {
;     ...
;         else if (pn < 36) ew<2>(acc, SGA, 2048, row0, (pn - 28) * 256 + cl);
;         else ew<2>(acc, SGB, 2048, row0, (pn - 36) * 256 + cl);
	v_add_f32_e32 v153, 1.0, v154
	v_add_f32_e32 v154, 1.0, v155
	v_mul_f32_e32 v155, 0xbfb8aa3b, v86
	v_exp_f32_e32 v155, v155
	v_exp_f32_e32 v158, v158
	v_rcp_f32_e32 v152, v152
	v_rcp_f32_e32 v153, v153
	v_add_f32_e32 v155, 1.0, v155
	v_add_f32_e32 v158, 1.0, v158
	v_mul_f32_e32 v157, 0xbfb8aa3b, v82
	v_rcp_f32_e32 v155, v155
	v_mul_f32_e32 v159, 0xbfb8aa3b, v83
	v_rcp_f32_e32 v158, v158
	v_exp_f32_e32 v157, v157
	v_rcp_f32_e32 v154, v154
	v_exp_f32_e32 v159, v159
	v_cvt_pk_bf16_f32 v152, v152, v153
	v_cvt_pk_bf16_f32 v153, v155, v158
	v_mul_f32_e32 v155, 0xbfb8aa3b, v68
	v_add_f32_e32 v157, 1.0, v157
	v_add_f32_e32 v159, 1.0, v159
	v_cvt_pk_bf16_f32 v154, v156, v154
	v_exp_f32_e32 v156, v155
	v_mul_f32_e32 v155, 0xbfb8aa3b, v64
	v_rcp_f32_e32 v157, v157
	v_rcp_f32_e32 v159, v159
	v_exp_f32_e32 v158, v155
	v_mul_f32_e32 v161, 0xbfb8aa3b, v66
	v_mul_f32_e32 v162, 0xbfb8aa3b, v71
	v_cvt_pk_bf16_f32 v155, v157, v159
	v_add_f32_e32 v157, 1.0, v158
	v_mul_f32_e32 v158, 0xbfb8aa3b, v69
	v_mul_f32_e32 v159, 0xbfb8aa3b, v65
	v_exp_f32_e32 v158, v158
	v_exp_f32_e32 v159, v159
	v_rcp_f32_e32 v160, v157
	v_mul_f32_e32 v163, 0xbfb8aa3b, v67
	v_add_f32_e32 v157, 1.0, v158
	v_add_f32_e32 v158, 1.0, v159
	v_mul_f32_e32 v159, 0xbfb8aa3b, v70
	v_exp_f32_e32 v159, v159
	v_exp_f32_e32 v161, v161
	v_exp_f32_e32 v162, v162
	v_exp_f32_e32 v163, v163
	v_add_f32_e32 v156, 1.0, v156
	v_add_f32_e32 v159, 1.0, v159
	v_add_f32_e32 v161, 1.0, v161
	v_add_f32_e32 v162, 1.0, v162
	v_add_f32_e32 v163, 1.0, v163
	v_rcp_f32_e32 v156, v156
	v_rcp_f32_e32 v157, v157
	v_rcp_f32_e32 v159, v159
	v_rcp_f32_e32 v161, v161
	v_rcp_f32_e32 v162, v162
	v_rcp_f32_e32 v163, v163
	v_cvt_pk_bf16_f32 v156, v156, v157
	v_rcp_f32_e32 v158, v158
	v_cvt_pk_bf16_f32 v157, v159, v162
	v_cvt_pk_bf16_f32 v159, v161, v163
	v_mul_f32_e32 v161, 0xbfb8aa3b, v56
	v_exp_f32_e32 v161, v161
	v_mul_f32_e32 v162, 0xbfb8aa3b, v61
	v_mul_f32_e32 v163, 0xbfb8aa3b, v57
	v_exp_f32_e32 v162, v162
	v_exp_f32_e32 v163, v163
	v_add_f32_e32 v161, 1.0, v161
	v_cvt_pk_bf16_f32 v158, v160, v158
	v_mul_f32_e32 v160, 0xbfb8aa3b, v60
	v_rcp_f32_e32 v172, v161
	v_add_f32_e32 v161, 1.0, v162
	v_add_f32_e32 v162, 1.0, v163
	v_mul_f32_e32 v163, 0xbfb8aa3b, v62
	v_mul_f32_e32 v194, 0xbfb8aa3b, v58
	v_mul_f32_e32 v195, 0xbfb8aa3b, v63
	v_mul_f32_e32 v212, 0xbfb8aa3b, v59
	v_exp_f32_e32 v160, v160
	v_exp_f32_e32 v163, v163
	v_exp_f32_e32 v194, v194
	v_exp_f32_e32 v195, v195
	v_exp_f32_e32 v212, v212
	v_add_f32_e32 v160, 1.0, v160
	v_add_f32_e32 v163, 1.0, v163
	v_add_f32_e32 v194, 1.0, v194
	v_add_f32_e32 v195, 1.0, v195
	v_add_f32_e32 v212, 1.0, v212
	v_rcp_f32_e32 v160, v160
	v_rcp_f32_e32 v161, v161
	v_rcp_f32_e32 v162, v162
	v_rcp_f32_e32 v163, v163
	v_rcp_f32_e32 v194, v194
	v_rcp_f32_e32 v195, v195
	v_rcp_f32_e32 v212, v212
	v_ashrrev_i32_e32 v183, 31, v182
	v_lshlrev_b64 v[184:185], 12, v[182:183]
	s_mov_b64 s[38:39], 0x80000
	s_cmp_gt_u32 s23, 35
	v_lshl_add_u64 v[192:193], v[184:185], 0, s[38:39]
	v_cvt_pk_bf16_f32 v160, v160, v161
	v_cvt_pk_bf16_f32 v161, v163, v195
	v_cvt_pk_bf16_f32 v162, v172, v162
	v_cvt_pk_bf16_f32 v163, v194, v212
	s_cbranch_scc0 .LBB0_373
	v_readlane_b32 s38, v255, 23
	v_add_u32_e32 v172, s75, v199
	v_readlane_b32 s39, v255, 24
	v_mul_f32_e32 v212, 0xbfb8aa3b, v40
	v_mul_f32_e32 v220, 0xbfb8aa3b, v45
	v_lshl_add_u64 v[222:223], v[172:173], 1, s[38:39]
	v_lshl_add_u64 v[194:195], v[222:223], 0, v[184:185]
	v_lshl_add_u64 v[224:225], v[222:223], 0, v[186:187]
	global_store_dwordx4 v[194:195], v[128:131], off
	global_store_dwordx4 v[194:195], v[132:135], off offset:256
	global_store_dwordx4 v[224:225], v[136:139], off
	global_store_dwordx4 v[224:225], v[140:143], off offset:256
	v_lshl_add_u64 v[224:225], v[222:223], 0, v[188:189]
	global_store_dwordx4 v[224:225], v[144:147], off
	global_store_dwordx4 v[224:225], v[148:151], off offset:256
	v_lshl_add_u64 v[224:225], v[222:223], 0, v[190:191]
	v_lshl_add_u64 v[230:231], v[222:223], 0, v[192:193]
	v_mul_f32_e32 v222, 0xbfb8aa3b, v41
	v_exp_f32_e32 v222, v222
	v_mul_f32_e32 v223, 0xbfb8aa3b, v46
	global_store_dwordx4 v[224:225], v[152:155], off
	global_store_dwordx4 v[224:225], v[156:159], off offset:256
	v_exp_f32_e32 v223, v223
	v_mul_f32_e32 v224, 0xbfb8aa3b, v42
	v_exp_f32_e32 v224, v224
	v_add_f32_e32 v222, 1.0, v222
	v_rcp_f32_e32 v225, v222
	v_add_f32_e32 v222, 1.0, v223
	v_rcp_f32_e32 v223, v222
	v_add_f32_e32 v222, 1.0, v224
	v_mul_f32_e32 v224, 0xbfb8aa3b, v47
	v_mul_f32_e32 v172, 0xbfb8aa3b, v44
	v_exp_f32_e32 v224, v224
	v_mul_f32_e32 v232, 0xbfb8aa3b, v43
	v_exp_f32_e32 v172, v172
	v_exp_f32_e32 v212, v212
	v_exp_f32_e32 v220, v220
	v_exp_f32_e32 v232, v232
	v_rcp_f32_e32 v233, v222
	v_add_f32_e32 v222, 1.0, v224
	v_add_f32_e32 v172, 1.0, v172
	v_add_f32_e32 v212, 1.0, v212
	v_add_f32_e32 v220, 1.0, v220
	v_rcp_f32_e32 v224, v222
	v_add_f32_e32 v222, 1.0, v232
	v_rcp_f32_e32 v172, v172
	v_rcp_f32_e32 v212, v212
	v_rcp_f32_e32 v220, v220
	v_rcp_f32_e32 v232, v222
	v_cvt_pk_bf16_f32 v223, v223, v224
	v_cvt_pk_bf16_f32 v224, v212, v225
	v_cvt_pk_bf16_f32 v222, v172, v220
	v_cvt_pk_bf16_f32 v225, v233, v232
	global_store_dwordx4 v[230:231], v[222:225], off offset:256
	v_mul_f32_e32 v212, 0xbfb8aa3b, v48
	v_mul_f32_e32 v232, 0xbfb8aa3b, v51
	v_mul_f32_e32 v222, 0xbfb8aa3b, v49
	v_exp_f32_e32 v222, v222
	v_mul_f32_e32 v223, 0xbfb8aa3b, v54
	v_exp_f32_e32 v223, v223
	v_mul_f32_e32 v224, 0xbfb8aa3b, v50
	v_exp_f32_e32 v224, v224
	v_add_f32_e32 v222, 1.0, v222
	v_rcp_f32_e32 v225, v222
	v_add_f32_e32 v222, 1.0, v223
	v_rcp_f32_e32 v223, v222
	v_add_f32_e32 v222, 1.0, v224
	v_mul_f32_e32 v224, 0xbfb8aa3b, v55
	v_exp_f32_e32 v224, v224
; __device__ __forceinline__ float fsigmoid(float v) { return __builtin_amdgcn_rcpf(1.0f + __builtin_amdgcn_exp2f(-LOG2E * v)); }
; __device__ __forceinline__ float fsilu(float v) { return v * fsigmoid(v); }
; __device__ __forceinline__ u32x4 pack8(const f32x4 a, const f32x4 b) { u32x4 w; w.x = cvt_pk_bf16(a[0], a[1]); w.y = cvt_pk_bf16(a[2], a[3]); w.z = cvt_pk_bf16(b[0], b[1]); w.w = cvt_pk_bf16(b[2], b[3]); return w; }
;     template <int ACT> __device__ __forceinline__ void ew(const f32x4 (&acc)[2][2][4][2], bf16_t* D, int ld, int row0, int col0) const {
; #pragma unroll
;         for (int ai = 0; ai < 2; ++ai)
; #pragma unroll
;             for (int m = 0; m < 4; ++m) { bf16_t* rowp = D + (size_t)(row0 + ai * HALF + m * 16) * ld + col0;
; #pragma unroll
;                 for (int bj = 0; bj < 2; ++bj) { f32x4 v0 = acc[ai][bj][m][0], v1 = acc[ai][bj][m][1];
;                     if (ACT == 1) {
; #pragma unroll
;                         for (int j = 0; j < 4; ++j) { v0[j] = fsilu(v0[j]); v1[j] = fsilu(v1[j]); } }
;                     if (ACT == 2) {
; #pragma unroll
;                         for (int j = 0; j < 4; ++j) { v0[j] = fsigmoid(v0[j]); v1[j] = fsigmoid(v1[j]); } }
;                     *(u32x4*)(rowp + bj * HALF) = pack8(v0, v1); } }
;     }
	v_mul_f32_e32 v172, 0xbfb8aa3b, v52
	v_exp_f32_e32 v212, v212
	v_mul_f32_e32 v220, 0xbfb8aa3b, v53
	v_exp_f32_e32 v232, v232
	v_exp_f32_e32 v172, v172
	v_exp_f32_e32 v220, v220
	v_rcp_f32_e32 v233, v222
	v_add_f32_e32 v222, 1.0, v224
	v_add_f32_e32 v212, 1.0, v212
	v_rcp_f32_e32 v224, v222
	v_add_f32_e32 v222, 1.0, v232
	v_add_f32_e32 v172, 1.0, v172
	v_rcp_f32_e32 v212, v212
	v_add_f32_e32 v220, 1.0, v220
	v_rcp_f32_e32 v232, v222
	v_rcp_f32_e32 v172, v172
	v_rcp_f32_e32 v220, v220
	s_mov_b64 s[38:39], 0x90000
	global_store_dwordx4 v[230:231], v[160:163], off
	v_lshl_add_u64 v[230:231], v[194:195], 0, s[38:39]
	s_mov_b32 s38, 0x90000
	v_cvt_pk_bf16_f32 v223, v223, v224
	v_cvt_pk_bf16_f32 v224, v212, v225
	v_cvt_pk_bf16_f32 v225, v233, v232
	v_add_co_u32_e32 v232, vcc, s38, v194
	v_cvt_pk_bf16_f32 v222, v172, v220
	s_nop 0
	v_addc_co_u32_e32 v233, vcc, 0, v195, vcc
	global_store_dwordx4 v[232:233], v[222:225], off
	v_mul_f32_e32 v172, 0xbfb8aa3b, v28
	v_mul_f32_e32 v212, 0xbfb8aa3b, v24
	v_mul_f32_e32 v222, 0xbfb8aa3b, v25
	v_exp_f32_e32 v222, v222
	v_mul_f32_e32 v223, 0xbfb8aa3b, v30
	v_exp_f32_e32 v223, v223
	v_mul_f32_e32 v224, 0xbfb8aa3b, v26
	v_exp_f32_e32 v224, v224
	v_add_f32_e32 v222, 1.0, v222
	v_rcp_f32_e32 v225, v222
	v_add_f32_e32 v222, 1.0, v223
	v_rcp_f32_e32 v223, v222
	v_add_f32_e32 v222, 1.0, v224
	v_mul_f32_e32 v224, 0xbfb8aa3b, v31
	v_mul_f32_e32 v220, 0xbfb8aa3b, v29
	v_exp_f32_e32 v224, v224
	v_mul_f32_e32 v232, 0xbfb8aa3b, v27
	v_exp_f32_e32 v172, v172
	v_exp_f32_e32 v212, v212
	v_exp_f32_e32 v220, v220
	v_exp_f32_e32 v232, v232
	v_rcp_f32_e32 v233, v222
	v_add_f32_e32 v222, 1.0, v224
	v_add_f32_e32 v172, 1.0, v172
	v_add_f32_e32 v212, 1.0, v212
	v_add_f32_e32 v220, 1.0, v220
	v_rcp_f32_e32 v224, v222
	v_add_f32_e32 v222, 1.0, v232
	v_rcp_f32_e32 v172, v172
	v_rcp_f32_e32 v212, v212
	v_rcp_f32_e32 v220, v220
	v_rcp_f32_e32 v232, v222
	v_cvt_pk_bf16_f32 v223, v223, v224
	v_cvt_pk_bf16_f32 v224, v212, v225
	v_cvt_pk_bf16_f32 v222, v172, v220
	v_cvt_pk_bf16_f32 v225, v233, v232
	global_store_dwordx4 v[230:231], v[222:225], off offset:256
	v_mul_f32_e32 v212, 0xbfb8aa3b, v32
	v_mul_f32_e32 v232, 0xbfb8aa3b, v35
	v_mul_f32_e32 v222, 0xbfb8aa3b, v33
	v_exp_f32_e32 v222, v222
	v_mul_f32_e32 v223, 0xbfb8aa3b, v38
	v_exp_f32_e32 v223, v223
	v_mul_f32_e32 v224, 0xbfb8aa3b, v34
	v_exp_f32_e32 v224, v224
	v_add_f32_e32 v222, 1.0, v222
	v_rcp_f32_e32 v225, v222
	v_add_f32_e32 v222, 1.0, v223
	v_rcp_f32_e32 v223, v222
	v_add_f32_e32 v222, 1.0, v224
	v_mul_f32_e32 v224, 0xbfb8aa3b, v39
	v_exp_f32_e32 v224, v224
	v_mul_f32_e32 v172, 0xbfb8aa3b, v36
	v_exp_f32_e32 v212, v212
	v_mul_f32_e32 v220, 0xbfb8aa3b, v37
	v_exp_f32_e32 v232, v232
	v_exp_f32_e32 v172, v172
	v_exp_f32_e32 v220, v220
	v_rcp_f32_e32 v233, v222
	v_add_f32_e32 v222, 1.0, v224
	v_add_f32_e32 v212, 1.0, v212
	v_rcp_f32_e32 v224, v222
	v_add_f32_e32 v222, 1.0, v232
	v_add_f32_e32 v172, 1.0, v172
	v_rcp_f32_e32 v212, v212
	v_add_f32_e32 v220, 1.0, v220
	v_rcp_f32_e32 v232, v222
	v_rcp_f32_e32 v172, v172
	v_rcp_f32_e32 v220, v220
	v_cvt_pk_bf16_f32 v223, v223, v224
	v_cvt_pk_bf16_f32 v224, v212, v225
	v_cvt_pk_bf16_f32 v225, v233, v232
	v_add_co_u32_e32 v232, vcc, s49, v194
	v_cvt_pk_bf16_f32 v222, v172, v220
	s_nop 0
	v_addc_co_u32_e32 v233, vcc, 0, v195, vcc
	global_store_dwordx4 v[232:233], v[222:225], off
	v_mul_f32_e32 v172, 0xbfb8aa3b, v12
	v_mul_f32_e32 v212, 0xbfb8aa3b, v8
	v_mul_f32_e32 v222, 0xbfb8aa3b, v9
	v_exp_f32_e32 v222, v222
	v_mul_f32_e32 v223, 0xbfb8aa3b, v14
	v_exp_f32_e32 v223, v223
; __device__ __forceinline__ float fsigmoid(float v) { return __builtin_amdgcn_rcpf(1.0f + __builtin_amdgcn_exp2f(-LOG2E * v)); }
; __device__ __forceinline__ float fsilu(float v) { return v * fsigmoid(v); }
; __device__ __forceinline__ u32x4 pack8(const f32x4 a, const f32x4 b) { u32x4 w; w.x = cvt_pk_bf16(a[0], a[1]); w.y = cvt_pk_bf16(a[2], a[3]); w.z = cvt_pk_bf16(b[0], b[1]); w.w = cvt_pk_bf16(b[2], b[3]); return w; }
;     template <int ACT> __device__ __forceinline__ void ew(const f32x4 (&acc)[2][2][4][2], bf16_t* D, int ld, int row0, int col0) const {
; #pragma unroll
;         for (int ai = 0; ai < 2; ++ai)
; #pragma unroll
;             for (int m = 0; m < 4; ++m) { bf16_t* rowp = D + (size_t)(row0 + ai * HALF + m * 16) * ld + col0;
; #pragma unroll
;                 for (int bj = 0; bj < 2; ++bj) { f32x4 v0 = acc[ai][bj][m][0], v1 = acc[ai][bj][m][1];
;                     if (ACT == 1) {
; #pragma unroll
;                         for (int j = 0; j < 4; ++j) { v0[j] = fsilu(v0[j]); v1[j] = fsilu(v1[j]); } }
;                     if (ACT == 2) {
; #pragma unroll
;                         for (int j = 0; j < 4; ++j) { v0[j] = fsigmoid(v0[j]); v1[j] = fsigmoid(v1[j]); } }
;                     *(u32x4*)(rowp + bj * HALF) = pack8(v0, v1); } }
;     }
	v_mul_f32_e32 v224, 0xbfb8aa3b, v10
	v_exp_f32_e32 v224, v224
	v_add_f32_e32 v222, 1.0, v222
	v_rcp_f32_e32 v225, v222
	v_add_f32_e32 v222, 1.0, v223
	v_rcp_f32_e32 v223, v222
	v_add_f32_e32 v222, 1.0, v224
	v_mul_f32_e32 v224, 0xbfb8aa3b, v15
	v_mul_f32_e32 v220, 0xbfb8aa3b, v13
	v_exp_f32_e32 v224, v224
	v_mul_f32_e32 v232, 0xbfb8aa3b, v11
	v_exp_f32_e32 v172, v172
	v_exp_f32_e32 v212, v212
	v_exp_f32_e32 v220, v220
	v_exp_f32_e32 v232, v232
	v_rcp_f32_e32 v233, v222
	v_add_f32_e32 v222, 1.0, v224
	v_add_f32_e32 v172, 1.0, v172
	v_add_f32_e32 v212, 1.0, v212
	v_add_f32_e32 v220, 1.0, v220
	v_rcp_f32_e32 v224, v222
	v_add_f32_e32 v222, 1.0, v232
	v_rcp_f32_e32 v172, v172
	v_rcp_f32_e32 v212, v212
	v_rcp_f32_e32 v220, v220
	v_rcp_f32_e32 v232, v222
	s_mov_b64 s[38:39], 0xa0000
	v_lshl_add_u64 v[230:231], v[194:195], 0, s[38:39]
	v_cvt_pk_bf16_f32 v222, v172, v220
	v_cvt_pk_bf16_f32 v223, v223, v224
	v_cvt_pk_bf16_f32 v224, v212, v225
	v_cvt_pk_bf16_f32 v225, v233, v232
	global_store_dwordx4 v[230:231], v[222:225], off offset:256
	v_mul_f32_e32 v212, 0xbfb8aa3b, v16
	v_exp_f32_e32 v212, v212
	v_mul_f32_e32 v222, 0xbfb8aa3b, v17
	v_exp_f32_e32 v222, v222
	v_mul_f32_e32 v223, 0xbfb8aa3b, v22
	v_exp_f32_e32 v223, v223
	v_mul_f32_e32 v224, 0xbfb8aa3b, v18
	v_exp_f32_e32 v224, v224
	v_add_f32_e32 v222, 1.0, v222
	v_rcp_f32_e32 v225, v222
	v_add_f32_e32 v222, 1.0, v223
	v_rcp_f32_e32 v223, v222
	v_add_f32_e32 v222, 1.0, v224
	v_mul_f32_e32 v224, 0xbfb8aa3b, v23
	v_exp_f32_e32 v224, v224
	v_mul_f32_e32 v172, 0xbfb8aa3b, v20
	v_mul_f32_e32 v220, 0xbfb8aa3b, v21
	v_mul_f32_e32 v232, 0xbfb8aa3b, v19
	v_exp_f32_e32 v172, v172
	v_exp_f32_e32 v220, v220
	v_exp_f32_e32 v232, v232
	v_add_f32_e32 v212, 1.0, v212
	v_rcp_f32_e32 v233, v222
	v_add_f32_e32 v222, 1.0, v224
	v_rcp_f32_e32 v212, v212
	v_rcp_f32_e32 v224, v222
	v_add_f32_e32 v172, 1.0, v172
	v_add_f32_e32 v220, 1.0, v220
	v_add_f32_e32 v222, 1.0, v232
	v_rcp_f32_e32 v172, v172
	v_rcp_f32_e32 v220, v220
	v_rcp_f32_e32 v232, v222
	v_cvt_pk_bf16_f32 v223, v223, v224
	v_cvt_pk_bf16_f32 v224, v212, v225
	v_mul_f32_e32 v212, 0xbfb8aa3b, v0
	v_lshl_add_u64 v[230:231], v[194:195], 0, s[62:63]
	v_add_co_u32_e32 v194, vcc, s50, v194
	v_exp_f32_e32 v212, v212
	v_cvt_pk_bf16_f32 v222, v172, v220
	v_cvt_pk_bf16_f32 v225, v233, v232
	v_addc_co_u32_e32 v195, vcc, 0, v195, vcc
	global_store_dwordx4 v[194:195], v[222:225], off
	v_mul_f32_e32 v172, 0xbfb8aa3b, v4
	v_add_f32_e32 v194, 1.0, v212
	v_mul_f32_e32 v222, 0xbfb8aa3b, v2
	v_exp_f32_e32 v222, v222
	v_mul_f32_e32 v223, 0xbfb8aa3b, v7
	v_mul_f32_e32 v195, 0xbfb8aa3b, v5
	v_mul_f32_e32 v212, 0xbfb8aa3b, v1
	v_mul_f32_e32 v220, 0xbfb8aa3b, v6
	v_exp_f32_e32 v223, v223
	v_mul_f32_e32 v224, 0xbfb8aa3b, v3
	v_exp_f32_e32 v172, v172
	v_exp_f32_e32 v195, v195
	v_exp_f32_e32 v212, v212
	v_exp_f32_e32 v220, v220
	v_exp_f32_e32 v224, v224
	v_add_f32_e32 v222, 1.0, v222
	v_rcp_f32_e32 v225, v222
	v_add_f32_e32 v222, 1.0, v223
	v_add_f32_e32 v172, 1.0, v172
	v_add_f32_e32 v195, 1.0, v195
	v_add_f32_e32 v212, 1.0, v212
	v_add_f32_e32 v220, 1.0, v220
	v_rcp_f32_e32 v223, v222
	v_add_f32_e32 v222, 1.0, v224
	v_rcp_f32_e32 v172, v172
	v_rcp_f32_e32 v194, v194
	v_rcp_f32_e32 v195, v195
	v_rcp_f32_e32 v212, v212
	v_rcp_f32_e32 v220, v220
	v_rcp_f32_e32 v232, v222
	v_cvt_pk_bf16_f32 v222, v172, v195
	v_cvt_pk_bf16_f32 v224, v194, v212
	v_cvt_pk_bf16_f32 v223, v220, v223
	v_cvt_pk_bf16_f32 v225, v225, v232
	global_store_dwordx4 v[230:231], v[222:225], off offset:256
	s_mov_b64 s[82:83], 0

; #define PG8_STAGE(bufoff, gbase, voff) do { _Pragma("unroll") for (int _i = 0; _i < 2; ++_i) \
;         __builtin_amdgcn_global_load_lds((const unsigned*)((const char*)(gbase) + (voff)[_i]), (PG8_LAS unsigned*)(lds + (bufoff) + ldsw + _i * 8192), 16, 0, 0); } while (0)
; #define PG8_LDA(dst, b, h) do { _Pragma("unroll") for (int m = 0; m < 4; ++m) _Pragma("unroll") for (int k = 0; k < 2; ++k) dst[m][k] = *(const PG8_LAS bf16x8*)(lds + PG8_SA(b, h) + aoff + m * 2048 + k * 1024); } while (0)
; #define PG8_LDB(dst, b, h) do { _Pragma("unroll") for (int n = 0; n < 2; ++n) _Pragma("unroll") for (int k = 0; k < 2; ++k) dst[n][k] = *(const PG8_LAS bf16x8*)(lds + PG8_SB(b, h) + boff + n * 2048 + k * 1024); } while (0)
; #define PG8_MMA(ai, bj, At, Bt) do { __builtin_amdgcn_s_setprio(1); _Pragma("unroll") for (int m = 0; m < 4; ++m) _Pragma("unroll") for (int n = 0; n < 2; ++n) _Pragma("unroll") for (int k = 0; k < 2; ++k) \
;         acc[ai][bj][m][n] = __builtin_amdgcn_mfma_f32_16x16x32_bf16(Bt[n][k], At[m][k], acc[ai][bj][m][n], 0, 0, 0); __builtin_amdgcn_s_setprio(0); } while (0)
; #define PG8_WAIT_V(n) asm volatile("s_waitcnt vmcnt(" #n ")" ::: "memory")
; #define PG8_WAIT_L(n) asm volatile("s_waitcnt lgkmcnt(" #n ")" ::: "memory")
; #define PG8_BAR __builtin_amdgcn_s_barrier()
; #define PG8_SCHED __builtin_amdgcn_sched_barrier(0)
; template <class Epi, class Sched, bool ALIGN_EPI = false, bool SP2 = false>
; __device__ __forceinline__ void gemm_phase(PG8_LAS unsigned char* lds, const Gemm g, const Sched& S, const Epi& E) {
;     ...
;             PG8_LDB(B0, 0, 0); PG8_LDB(B1, 0, 1); PG8_SCHED; PG8_LDA(At, 0, 0); PG8_STAGE(PG8_SA(1, 1), a1 + hstep, voffA);
;             PG8_WAIT_V(8); PG8_WAIT_L(0); PG8_BAR; PG8_MMA(0, 0, At, B0); PG8_MMA(0, 1, At, B1); PG8_BAR; PG8_SCHED;
;             PG8_LDA(At, 0, 1); PG8_STAGE(PG8_SB(0, 0), b2, voffB); PG8_STAGE(PG8_SB(0, 1), b2 + hstep, voffB); PG8_STAGE(PG8_SA(0, 0), a2, voffA);
;             PG8_WAIT_V(8); PG8_WAIT_L(0); PG8_BAR; PG8_MMA(1, 0, At, B0); PG8_MMA(1, 1, At, B1); PG8_BAR; PG8_SCHED;
.LBB0_735:
	ds_read_b128 v[144:147], v155
	ds_read_b128 v[148:151], v155 offset:1024
	ds_read_b128 v[158:161], v155 offset:2048
	ds_read_b128 v[162:165], v155 offset:3072
	ds_read_b128 v[166:169], v156
	ds_read_b128 v[170:173], v156 offset:1024
	ds_read_b128 v[174:177], v156 offset:2048
	ds_read_b128 v[178:181], v156 offset:3072
	s_add_u32 s48, s46, 0xfffc0080
	s_addc_u32 s49, s47, -1
	s_cmp_eq_u32 s69, 12
	s_cselect_b32 s51, s39, s49
	s_cselect_b32 s50, s65, s48
	s_cselect_b32 s49, s37, s68
	s_cselect_b32 s48, s66, s67
	s_add_i32 m0, s45, 0xc000
	ds_read_b128 v[182:185], v157
	ds_read_b128 v[186:189], v157 offset:1024
	ds_read_b128 v[190:193], v157 offset:2048
	ds_read_b128 v[194:197], v157 offset:3072
	ds_read_b128 v[198:201], v157 offset:4096
	ds_read_b128 v[202:205], v157 offset:5120
	ds_read_b128 v[206:209], v157 offset:6144
	ds_read_b128 v[214:217], v157 offset:7168
	global_load_lds_dwordx4 v136, s[46:47]
	s_add_i32 m0, s45, 0xe000
	s_nop 0
	global_load_lds_dwordx4 v138, s[46:47]
	s_waitcnt vmcnt(8)
	s_waitcnt lgkmcnt(0)
	s_barrier
	s_setprio 1
	s_waitcnt lgkmcnt(0)
	v_mfma_f32_16x16x32_bf16 v[124:127], v[144:147], v[182:185], v[124:127]
	v_mfma_f32_16x16x32_bf16 v[120:123], v[158:161], v[182:185], v[120:123]
	v_mfma_f32_16x16x32_bf16 v[116:119], v[144:147], v[190:193], v[116:119]
	v_mfma_f32_16x16x32_bf16 v[112:115], v[158:161], v[190:193], v[112:115]
	v_mfma_f32_16x16x32_bf16 v[96:99], v[144:147], v[198:201], v[96:99]
	v_mfma_f32_16x16x32_bf16 v[88:91], v[158:161], v[198:201], v[88:91]
	v_mfma_f32_16x16x32_bf16 v[80:83], v[144:147], v[206:209], v[80:83]
	v_mfma_f32_16x16x32_bf16 v[72:75], v[158:161], v[206:209], v[72:75]
	v_mfma_f32_16x16x32_bf16 v[124:127], v[148:151], v[186:189], v[124:127]
	v_mfma_f32_16x16x32_bf16 v[120:123], v[162:165], v[186:189], v[120:123]
	v_mfma_f32_16x16x32_bf16 v[116:119], v[148:151], v[194:197], v[116:119]
	v_mfma_f32_16x16x32_bf16 v[112:115], v[162:165], v[194:197], v[112:115]
	v_mfma_f32_16x16x32_bf16 v[96:99], v[148:151], v[202:205], v[96:99]
	v_mfma_f32_16x16x32_bf16 v[88:91], v[162:165], v[202:205], v[88:91]
	v_mfma_f32_16x16x32_bf16 v[80:83], v[148:151], v[214:217], v[80:83]
	v_mfma_f32_16x16x32_bf16 v[72:75], v[162:165], v[214:217], v[72:75]
	s_setprio 0
	s_setprio 1
	v_mfma_f32_16x16x32_bf16 v[108:111], v[166:169], v[182:185], v[108:111]
	v_mfma_f32_16x16x32_bf16 v[104:107], v[174:177], v[182:185], v[104:107]
	v_mfma_f32_16x16x32_bf16 v[100:103], v[166:169], v[190:193], v[100:103]
	v_mfma_f32_16x16x32_bf16 v[92:95], v[174:177], v[190:193], v[92:95]
	v_mfma_f32_16x16x32_bf16 v[84:87], v[166:169], v[198:201], v[84:87]
	v_mfma_f32_16x16x32_bf16 v[76:79], v[174:177], v[198:201], v[76:79]
	v_mfma_f32_16x16x32_bf16 v[68:71], v[166:169], v[206:209], v[68:71]
	v_mfma_f32_16x16x32_bf16 v[64:67], v[174:177], v[206:209], v[64:67]
	v_mfma_f32_16x16x32_bf16 v[108:111], v[170:173], v[186:189], v[108:111]
	v_mfma_f32_16x16x32_bf16 v[104:107], v[178:181], v[186:189], v[104:107]
	v_mfma_f32_16x16x32_bf16 v[100:103], v[170:173], v[194:197], v[100:103]
	v_mfma_f32_16x16x32_bf16 v[92:95], v[178:181], v[194:197], v[92:95]
	v_mfma_f32_16x16x32_bf16 v[84:87], v[170:173], v[202:205], v[84:87]
	v_mfma_f32_16x16x32_bf16 v[76:79], v[178:181], v[202:205], v[76:79]
	v_mfma_f32_16x16x32_bf16 v[68:71], v[170:173], v[214:217], v[68:71]
	v_mfma_f32_16x16x32_bf16 v[64:67], v[178:181], v[214:217], v[64:67]
	s_setprio 0
	s_barrier
	s_add_i32 s70, s62, s53
	s_mov_b32 m0, s70
	ds_read_b128 v[182:185], v157 offset:16384
	ds_read_b128 v[186:189], v157 offset:17408
	ds_read_b128 v[190:193], v157 offset:18432
	ds_read_b128 v[194:197], v157 offset:19456
	ds_read_b128 v[198:201], v157 offset:20480
	ds_read_b128 v[202:205], v157 offset:21504
	ds_read_b128 v[206:209], v157 offset:22528
	ds_read_b128 v[214:217], v157 offset:23552
	global_load_lds_dwordx4 v130, s[48:49]
	s_add_i32 m0, s70, 0x2000
	s_add_u32 s70, s48, 0x40000
	s_addc_u32 s71, s49, 0
	s_add_i32 s72, s63, s53
	global_load_lds_dwordx4 v134, s[48:49]
	s_mov_b32 m0, s72
	s_nop 0
	global_load_lds_dwordx4 v130, s[70:71]
	s_add_i32 m0, s72, 0x2000
	s_nop 0
	global_load_lds_dwordx4 v134, s[70:71]
	s_mov_b32 m0, s45
	s_nop 0
	global_load_lds_dwordx4 v128, s[50:51]
	s_mov_b32 m0, s54
	s_nop 0
	global_load_lds_dwordx4 v132, s[50:51]
	s_waitcnt vmcnt(8)
	s_waitcnt lgkmcnt(0)
	s_barrier
	s_setprio 1
	s_waitcnt lgkmcnt(0)
	v_mfma_f32_16x16x32_bf16 v[60:63], v[144:147], v[182:185], v[60:63]
	v_mfma_f32_16x16x32_bf16 v[56:59], v[158:161], v[182:185], v[56:59]
	v_mfma_f32_16x16x32_bf16 v[48:51], v[144:147], v[190:193], v[48:51]
	v_mfma_f32_16x16x32_bf16 v[40:43], v[158:161], v[190:193], v[40:43]
	v_mfma_f32_16x16x32_bf16 v[32:35], v[144:147], v[198:201], v[32:35]
	v_mfma_f32_16x16x32_bf16 v[24:27], v[158:161], v[198:201], v[24:27]
	v_mfma_f32_16x16x32_bf16 v[16:19], v[144:147], v[206:209], v[16:19]
	v_mfma_f32_16x16x32_bf16 v[8:11], v[158:161], v[206:209], v[8:11]
	v_mfma_f32_16x16x32_bf16 v[60:63], v[148:151], v[186:189], v[60:63]
	v_mfma_f32_16x16x32_bf16 v[56:59], v[162:165], v[186:189], v[56:59]
	v_mfma_f32_16x16x32_bf16 v[48:51], v[148:151], v[194:197], v[48:51]
	v_mfma_f32_16x16x32_bf16 v[40:43], v[162:165], v[194:197], v[40:43]
	v_mfma_f32_16x16x32_bf16 v[32:35], v[148:151], v[202:205], v[32:35]
	v_mfma_f32_16x16x32_bf16 v[24:27], v[162:165], v[202:205], v[24:27]
	v_mfma_f32_16x16x32_bf16 v[16:19], v[148:151], v[214:217], v[16:19]
	v_mfma_f32_16x16x32_bf16 v[8:11], v[162:165], v[214:217], v[8:11]
	s_setprio 0
	s_setprio 1
	v_mfma_f32_16x16x32_bf16 v[52:55], v[166:169], v[182:185], v[52:55]
	v_mfma_f32_16x16x32_bf16 v[44:47], v[174:177], v[182:185], v[44:47]
	v_mfma_f32_16x16x32_bf16 v[36:39], v[166:169], v[190:193], v[36:39]
	v_mfma_f32_16x16x32_bf16 v[28:31], v[174:177], v[190:193], v[28:31]
	v_mfma_f32_16x16x32_bf16 v[20:23], v[166:169], v[198:201], v[20:23]
	v_mfma_f32_16x16x32_bf16 v[12:15], v[174:177], v[198:201], v[12:15]
	v_mfma_f32_16x16x32_bf16 v[4:7], v[166:169], v[206:209], v[4:7]
	v_mfma_f32_16x16x32_bf16 v[0:3], v[174:177], v[206:209], v[0:3]
	v_mfma_f32_16x16x32_bf16 v[52:55], v[170:173], v[186:189], v[52:55]
	v_mfma_f32_16x16x32_bf16 v[44:47], v[178:181], v[186:189], v[44:47]
	v_mfma_f32_16x16x32_bf16 v[36:39], v[170:173], v[194:197], v[36:39]
	v_mfma_f32_16x16x32_bf16 v[28:31], v[178:181], v[194:197], v[28:31]
	v_mfma_f32_16x16x32_bf16 v[20:23], v[170:173], v[202:205], v[20:23]
	v_mfma_f32_16x16x32_bf16 v[12:15], v[178:181], v[202:205], v[12:15]
	v_mfma_f32_16x16x32_bf16 v[4:7], v[170:173], v[214:217], v[4:7]
	v_mfma_f32_16x16x32_bf16 v[0:3], v[178:181], v[214:217], v[0:3]
	s_setprio 0
	s_barrier
; #define PG8_STAGE(bufoff, gbase, voff) do { _Pragma("unroll") for (int _i = 0; _i < 2; ++_i) \
;         __builtin_amdgcn_global_load_lds((const unsigned*)((const char*)(gbase) + (voff)[_i]), (PG8_LAS unsigned*)(lds + (bufoff) + ldsw + _i * 8192), 16, 0, 0); } while (0)
; #define PG8_LDA(dst, b, h) do { _Pragma("unroll") for (int m = 0; m < 4; ++m) _Pragma("unroll") for (int k = 0; k < 2; ++k) dst[m][k] = *(const PG8_LAS bf16x8*)(lds + PG8_SA(b, h) + aoff + m * 2048 + k * 1024); } while (0)
; #define PG8_LDB(dst, b, h) do { _Pragma("unroll") for (int n = 0; n < 2; ++n) _Pragma("unroll") for (int k = 0; k < 2; ++k) dst[n][k] = *(const PG8_LAS bf16x8*)(lds + PG8_SB(b, h) + boff + n * 2048 + k * 1024); } while (0)
; #define PG8_MMA(ai, bj, At, Bt) do { __builtin_amdgcn_s_setprio(1); _Pragma("unroll") for (int m = 0; m < 4; ++m) _Pragma("unroll") for (int n = 0; n < 2; ++n) _Pragma("unroll") for (int k = 0; k < 2; ++k) \
;         acc[ai][bj][m][n] = __builtin_amdgcn_mfma_f32_16x16x32_bf16(Bt[n][k], At[m][k], acc[ai][bj][m][n], 0, 0, 0); __builtin_amdgcn_s_setprio(0); } while (0)
; #define PG8_WAIT_V(n) asm volatile("s_waitcnt vmcnt(" #n ")" ::: "memory")
; #define PG8_WAIT_L(n) asm volatile("s_waitcnt lgkmcnt(" #n ")" ::: "memory")
; #define PG8_BAR __builtin_amdgcn_s_barrier()
; #define PG8_SCHED __builtin_amdgcn_sched_barrier(0)
; template <class Epi, class Sched, bool ALIGN_EPI = false, bool SP2 = false>
; __device__ __forceinline__ void gemm_phase(PG8_LAS unsigned char* lds, const Gemm g, const Sched& S, const Epi& E) {
;     ...
;             PG8_LDB(B0, 1, 0); PG8_LDB(B1, 1, 1); PG8_SCHED; PG8_LDA(At, 1, 0); PG8_STAGE(PG8_SA(0, 1), a2 + hstep, voffA);
;             PG8_WAIT_V(8); PG8_WAIT_L(0); PG8_BAR; PG8_MMA(0, 0, At, B0); PG8_MMA(0, 1, At, B1); PG8_BAR; PG8_SCHED;
;             PG8_LDA(At, 1, 1); PG8_STAGE(PG8_SB(1, 0), b3, voffB); PG8_STAGE(PG8_SB(1, 1), b3 + hstep, voffB); PG8_STAGE(PG8_SA(1, 0), a3, voffA);
;             PG8_WAIT_V(8); PG8_WAIT_L(0); PG8_BAR; PG8_MMA(1, 0, At, B0); PG8_MMA(1, 1, At, B1); PG8_BAR; PG8_SCHED;
	s_add_i32 s70, 0, 0x18000
	s_add_i32 s71, 0, 0x1c000
	v_add_u32_e32 v162, s70, v153
	v_add_u32_e32 v178, s71, v153
	ds_read_b128 v[144:147], v162
	ds_read_b128 v[148:151], v162 offset:1024
	ds_read_b128 v[158:161], v162 offset:2048
	ds_read_b128 v[162:165], v162 offset:3072
	ds_read_b128 v[166:169], v178
	ds_read_b128 v[170:173], v178 offset:1024
	ds_read_b128 v[174:177], v178 offset:2048
	ds_read_b128 v[178:181], v178 offset:3072
	s_add_u32 s80, s50, 0x80
	s_addc_u32 s81, s51, 0
	s_add_u32 s50, s50, 0x40000
	s_addc_u32 s51, s51, 0
	s_mov_b32 m0, s55
	ds_read_b128 v[182:185], v157 offset:32768
	ds_read_b128 v[186:189], v157 offset:33792
	ds_read_b128 v[190:193], v157 offset:34816
	ds_read_b128 v[194:197], v157 offset:35840
	ds_read_b128 v[198:201], v157 offset:36864
	ds_read_b128 v[202:205], v157 offset:37888
	ds_read_b128 v[206:209], v157 offset:38912
	ds_read_b128 v[214:217], v157 offset:39936
	global_load_lds_dwordx4 v128, s[50:51]
	s_mov_b32 m0, s56
	s_nop 0
	global_load_lds_dwordx4 v132, s[50:51]
	s_waitcnt vmcnt(8)
	s_waitcnt lgkmcnt(0)
	s_barrier
	s_setprio 1
	s_waitcnt lgkmcnt(0)
	v_mfma_f32_16x16x32_bf16 v[124:127], v[144:147], v[182:185], v[124:127]
	v_mfma_f32_16x16x32_bf16 v[120:123], v[158:161], v[182:185], v[120:123]
	v_mfma_f32_16x16x32_bf16 v[116:119], v[144:147], v[190:193], v[116:119]
	v_mfma_f32_16x16x32_bf16 v[112:115], v[158:161], v[190:193], v[112:115]
	v_mfma_f32_16x16x32_bf16 v[96:99], v[144:147], v[198:201], v[96:99]
	v_mfma_f32_16x16x32_bf16 v[88:91], v[158:161], v[198:201], v[88:91]
	v_mfma_f32_16x16x32_bf16 v[80:83], v[144:147], v[206:209], v[80:83]
	v_mfma_f32_16x16x32_bf16 v[72:75], v[158:161], v[206:209], v[72:75]
	v_mfma_f32_16x16x32_bf16 v[124:127], v[148:151], v[186:189], v[124:127]
	v_mfma_f32_16x16x32_bf16 v[120:123], v[162:165], v[186:189], v[120:123]
	v_mfma_f32_16x16x32_bf16 v[116:119], v[148:151], v[194:197], v[116:119]
	v_mfma_f32_16x16x32_bf16 v[112:115], v[162:165], v[194:197], v[112:115]
	v_mfma_f32_16x16x32_bf16 v[96:99], v[148:151], v[202:205], v[96:99]
	v_mfma_f32_16x16x32_bf16 v[88:91], v[162:165], v[202:205], v[88:91]
	v_mfma_f32_16x16x32_bf16 v[80:83], v[148:151], v[214:217], v[80:83]
	v_mfma_f32_16x16x32_bf16 v[72:75], v[162:165], v[214:217], v[72:75]
	s_setprio 0
	s_setprio 1
	v_mfma_f32_16x16x32_bf16 v[108:111], v[166:169], v[182:185], v[108:111]
	v_mfma_f32_16x16x32_bf16 v[104:107], v[174:177], v[182:185], v[104:107]
	v_mfma_f32_16x16x32_bf16 v[100:103], v[166:169], v[190:193], v[100:103]
	v_mfma_f32_16x16x32_bf16 v[92:95], v[174:177], v[190:193], v[92:95]
	v_mfma_f32_16x16x32_bf16 v[84:87], v[166:169], v[198:201], v[84:87]
	v_mfma_f32_16x16x32_bf16 v[76:79], v[174:177], v[198:201], v[76:79]
	v_mfma_f32_16x16x32_bf16 v[68:71], v[166:169], v[206:209], v[68:71]
	v_mfma_f32_16x16x32_bf16 v[64:67], v[174:177], v[206:209], v[64:67]
	v_mfma_f32_16x16x32_bf16 v[108:111], v[170:173], v[186:189], v[108:111]
	v_mfma_f32_16x16x32_bf16 v[104:107], v[178:181], v[186:189], v[104:107]
	v_mfma_f32_16x16x32_bf16 v[100:103], v[170:173], v[194:197], v[100:103]
	v_mfma_f32_16x16x32_bf16 v[92:95], v[178:181], v[194:197], v[92:95]
	v_mfma_f32_16x16x32_bf16 v[84:87], v[170:173], v[202:205], v[84:87]
	v_mfma_f32_16x16x32_bf16 v[76:79], v[178:181], v[202:205], v[76:79]
	v_mfma_f32_16x16x32_bf16 v[68:71], v[170:173], v[214:217], v[68:71]
	v_mfma_f32_16x16x32_bf16 v[64:67], v[178:181], v[214:217], v[64:67]
	s_setprio 0
	s_barrier
	s_add_i32 s50, s70, s53
	s_add_u32 s82, s48, 0x80
	s_addc_u32 s83, s49, 0
	s_mov_b32 m0, s50
	ds_read_b128 v[182:185], v157 offset:49152
	ds_read_b128 v[186:189], v157 offset:50176
	ds_read_b128 v[190:193], v157 offset:51200
	ds_read_b128 v[194:197], v157 offset:52224
	ds_read_b128 v[198:201], v157 offset:53248
	ds_read_b128 v[202:205], v157 offset:54272
	ds_read_b128 v[206:209], v157 offset:55296
	ds_read_b128 v[214:217], v157 offset:56320
	global_load_lds_dwordx4 v130, s[82:83]
	s_add_i32 m0, s50, 0x2000
	s_add_u32 s48, s48, 0x40080
	s_addc_u32 s49, s49, 0
	s_add_i32 s50, s71, s53
	global_load_lds_dwordx4 v134, s[82:83]
	s_mov_b32 m0, s50
	s_nop 0
	global_load_lds_dwordx4 v130, s[48:49]
	s_add_i32 m0, s50, 0x2000
	s_nop 0
	global_load_lds_dwordx4 v134, s[48:49]
	s_mov_b32 m0, s58
	s_nop 0
	global_load_lds_dwordx4 v128, s[80:81]
	s_mov_b32 m0, s59
	s_nop 0
	global_load_lds_dwordx4 v132, s[80:81]
	s_waitcnt vmcnt(8)
	s_waitcnt lgkmcnt(0)
	s_barrier
	s_setprio 1
	s_waitcnt lgkmcnt(0)
	v_mfma_f32_16x16x32_bf16 v[60:63], v[144:147], v[182:185], v[60:63]
	v_mfma_f32_16x16x32_bf16 v[56:59], v[158:161], v[182:185], v[56:59]
	v_mfma_f32_16x16x32_bf16 v[48:51], v[144:147], v[190:193], v[48:51]
	v_mfma_f32_16x16x32_bf16 v[40:43], v[158:161], v[190:193], v[40:43]
	v_mfma_f32_16x16x32_bf16 v[32:35], v[144:147], v[198:201], v[32:35]
	v_mfma_f32_16x16x32_bf16 v[24:27], v[158:161], v[198:201], v[24:27]
	v_mfma_f32_16x16x32_bf16 v[16:19], v[144:147], v[206:209], v[16:19]
	v_mfma_f32_16x16x32_bf16 v[8:11], v[158:161], v[206:209], v[8:11]
	v_mfma_f32_16x16x32_bf16 v[60:63], v[148:151], v[186:189], v[60:63]
	v_mfma_f32_16x16x32_bf16 v[56:59], v[162:165], v[186:189], v[56:59]
	v_mfma_f32_16x16x32_bf16 v[48:51], v[148:151], v[194:197], v[48:51]
	v_mfma_f32_16x16x32_bf16 v[40:43], v[162:165], v[194:197], v[40:43]
	v_mfma_f32_16x16x32_bf16 v[32:35], v[148:151], v[202:205], v[32:35]
	v_mfma_f32_16x16x32_bf16 v[24:27], v[162:165], v[202:205], v[24:27]
	v_mfma_f32_16x16x32_bf16 v[16:19], v[148:151], v[214:217], v[16:19]
	v_mfma_f32_16x16x32_bf16 v[8:11], v[162:165], v[214:217], v[8:11]
	s_setprio 0
	s_setprio 1
	v_mfma_f32_16x16x32_bf16 v[52:55], v[166:169], v[182:185], v[52:55]
	v_mfma_f32_16x16x32_bf16 v[44:47], v[174:177], v[182:185], v[44:47]
	v_mfma_f32_16x16x32_bf16 v[36:39], v[166:169], v[190:193], v[36:39]
	v_mfma_f32_16x16x32_bf16 v[28:31], v[174:177], v[190:193], v[28:31]
	v_mfma_f32_16x16x32_bf16 v[20:23], v[166:169], v[198:201], v[20:23]
	v_mfma_f32_16x16x32_bf16 v[12:15], v[174:177], v[198:201], v[12:15]
	v_mfma_f32_16x16x32_bf16 v[4:7], v[166:169], v[206:209], v[4:7]
	v_mfma_f32_16x16x32_bf16 v[0:3], v[174:177], v[206:209], v[0:3]
	v_mfma_f32_16x16x32_bf16 v[52:55], v[170:173], v[186:189], v[52:55]
	v_mfma_f32_16x16x32_bf16 v[44:47], v[178:181], v[186:189], v[44:47]
	v_mfma_f32_16x16x32_bf16 v[36:39], v[170:173], v[194:197], v[36:39]
	v_mfma_f32_16x16x32_bf16 v[28:31], v[178:181], v[194:197], v[28:31]
	v_mfma_f32_16x16x32_bf16 v[20:23], v[170:173], v[202:205], v[20:23]
	v_mfma_f32_16x16x32_bf16 v[12:15], v[178:181], v[202:205], v[12:15]
	v_mfma_f32_16x16x32_bf16 v[4:7], v[170:173], v[214:217], v[4:7]
	v_mfma_f32_16x16x32_bf16 v[0:3], v[178:181], v[214:217], v[0:3]
	s_setprio 0
	s_barrier
; __device__ __forceinline__ float bf_lo(unsigned w) { return __uint_as_float(w << 16); }
; __device__ __forceinline__ float bf_hi(unsigned w) { return __uint_as_float(w & 0xffff0000u); }
; __device__ __forceinline__ u32x4 pack8(const f32x4 a, const f32x4 b) { u32x4 w; w.x = cvt_pk_bf16(a[0], a[1]); w.y = cvt_pk_bf16(a[2], a[3]); w.z = cvt_pk_bf16(b[0], b[1]); w.w = cvt_pk_bf16(b[2], b[3]); return w; }
;     __device__ __forceinline__ void operator()(const f32x4 (&acc)[2][2][4][2], const Unit& u, int wr, int wc, int fr, int fq) const {
;         const int row0 = u.pm * BM + wr * 64 + fr, col0 = u.pn * BM + wc * 32 + 8 * fq;
; #pragma unroll
;         for (int ai = 0; ai < 2; ++ai) { u32x4 gw[4][2], pw[4][2];
; #pragma unroll
;             for (int m = 0; m < 4; ++m) { const size_t off = (size_t)(row0 + ai * HALF + m * 16) * 2048 + col0;
; #pragma unroll
;                 for (int bj = 0; bj < 2; ++bj) { gw[m][bj] = *(const u32x4*)(G + off + bj * HALF); if (PASS == 1) pw[m][bj] = *(const u32x4*)(MIX + off + bj * HALF); } }
; #pragma unroll
;             for (int m = 0; m < 4; ++m) { const size_t off = (size_t)(row0 + ai * HALF + m * 16) * 2048 + col0;
; #pragma unroll
;                 for (int bj = 0; bj < 2; ++bj) { const u32x4 g4 = gw[m][bj];
;                     f32x4 v0 = (f32x4){bf_lo(g4.x), bf_hi(g4.x), bf_lo(g4.y), bf_hi(g4.y)} * acc[ai][bj][m][0], v1 = (f32x4){bf_lo(g4.z), bf_hi(g4.z), bf_lo(g4.w), bf_hi(g4.w)} * acc[ai][bj][m][1];
;                     if (PASS == 1) { const u32x4 p4 = pw[m][bj]; v0 += (f32x4){bf_lo(p4.x), bf_hi(p4.x), bf_lo(p4.y), bf_hi(p4.y)}; v1 += (f32x4){bf_lo(p4.z), bf_hi(p4.z), bf_lo(p4.w), bf_hi(p4.w)}; }
;                     *(u32x4*)(MIX + off + bj * HALF) = pack8(v0, v1); } } }
	s_add_i32 s69, s69, 2
	s_add_u32 s46, s46, 0x100
	s_addc_u32 s47, s47, 0
	s_add_u32 s67, s67, 0x100
	s_addc_u32 s68, s68, 0
	s_cmp_gt_u32 s69, 13
	s_cbranch_scc0 .LBB0_735
	v_lshl_add_u32 v150, s44, 8, v152
	v_lshl_or_b32 v144, s64, 8, v154
	v_ashrrev_i32_e32 v145, 31, v144
	v_or_b32_e32 v166, 16, v150
	v_lshlrev_b64 v[144:145], 1, v[144:145]
	v_ashrrev_i32_e32 v151, 31, v150
	v_ashrrev_i32_e32 v167, 31, v166
	v_lshl_add_u64 v[146:147], s[12:13], 0, v[144:145]
	v_lshlrev_b64 v[148:149], 12, v[150:151]
	v_lshlrev_b64 v[178:179], 12, v[166:167]
	v_lshl_add_u64 v[162:163], v[146:147], 0, v[148:149]
	v_lshl_add_u64 v[170:171], v[146:147], 0, v[178:179]
	global_load_dwordx4 v[158:161], v[162:163], off
	s_nop 0
	global_load_dwordx4 v[162:165], v[162:163], off offset:256
	s_nop 0
	global_load_dwordx4 v[166:169], v[170:171], off
	s_nop 0
	global_load_dwordx4 v[170:173], v[170:171], off offset:256
	v_or_b32_e32 v174, 32, v150
	v_ashrrev_i32_e32 v175, 31, v174
	v_lshlrev_b64 v[190:191], 12, v[174:175]
	v_lshl_add_u64 v[180:181], v[146:147], 0, v[190:191]
	global_load_dwordx4 v[174:177], v[180:181], off
	v_or_b32_e32 v150, 48, v150
	v_ashrrev_i32_e32 v151, 31, v150
	v_lshlrev_b64 v[150:151], 12, v[150:151]
	v_lshl_add_u64 v[182:183], s[14:15], 0, v[148:149]
	v_lshl_add_u64 v[186:187], v[146:147], 0, v[150:151]
	v_lshl_add_u64 v[192:193], v[182:183], 0, v[144:145]
	v_lshl_add_u64 v[194:195], s[14:15], 0, v[178:179]
	global_load_dwordx4 v[178:181], v[180:181], off offset:256
	s_nop 0
	global_load_dwordx4 v[182:185], v[186:187], off
	s_nop 0
	global_load_dwordx4 v[186:189], v[186:187], off offset:256
	v_lshl_add_u64 v[194:195], v[194:195], 0, v[144:145]
	s_and_b64 vcc, exec, s[10:11]
	s_mov_b32 s64, s36
	s_mov_b32 s44, s38
	s_mov_b64 s[48:49], s[42:43]
	s_mov_b64 s[46:47], s[40:41]
	s_waitcnt vmcnt(0)
	v_lshlrev_b32_e32 v196, 16, v158
	v_and_b32_e32 v197, 0xffff0000, v158
	v_lshlrev_b32_e32 v158, 16, v159
	v_and_b32_e32 v159, 0xffff0000, v159
	v_lshlrev_b32_e32 v198, 16, v160
	v_and_b32_e32 v199, 0xffff0000, v160
	v_lshlrev_b32_e32 v160, 16, v161
	v_and_b32_e32 v161, 0xffff0000, v161
	v_lshlrev_b32_e32 v200, 16, v162
	v_and_b32_e32 v201, 0xffff0000, v162
	v_lshlrev_b32_e32 v162, 16, v163
	v_and_b32_e32 v163, 0xffff0000, v163
	v_lshlrev_b32_e32 v202, 16, v164
	v_and_b32_e32 v203, 0xffff0000, v164
	v_lshlrev_b32_e32 v164, 16, v165
	v_and_b32_e32 v165, 0xffff0000, v165
	v_lshlrev_b32_e32 v204, 16, v166
	v_and_b32_e32 v205, 0xffff0000, v166
	v_lshlrev_b32_e32 v166, 16, v167
	v_and_b32_e32 v167, 0xffff0000, v167
	v_lshlrev_b32_e32 v206, 16, v168
	v_and_b32_e32 v207, 0xffff0000, v168
	v_lshlrev_b32_e32 v168, 16, v169
	v_and_b32_e32 v169, 0xffff0000, v169
	v_lshlrev_b32_e32 v208, 16, v170
	v_and_b32_e32 v209, 0xffff0000, v170
	v_lshlrev_b32_e32 v170, 16, v171
	v_and_b32_e32 v171, 0xffff0000, v171
	v_pk_mul_f32 v[126:127], v[126:127], v[158:159]
	v_pk_mul_f32 v[124:125], v[124:125], v[196:197]
	v_pk_mul_f32 v[122:123], v[122:123], v[160:161]
	v_pk_mul_f32 v[120:121], v[120:121], v[198:199]
	v_pk_mul_f32 v[110:111], v[110:111], v[162:163]
	v_pk_mul_f32 v[108:109], v[108:109], v[200:201]
	v_pk_mul_f32 v[158:159], v[106:107], v[164:165]
	v_pk_mul_f32 v[106:107], v[104:105], v[202:203]
	v_pk_mul_f32 v[118:119], v[118:119], v[166:167]
	v_pk_mul_f32 v[116:117], v[116:117], v[204:205]
	v_pk_mul_f32 v[114:115], v[114:115], v[168:169]
	v_pk_mul_f32 v[112:113], v[112:113], v[206:207]
	v_pk_mul_f32 v[160:161], v[102:103], v[170:171]
	v_pk_mul_f32 v[162:163], v[100:101], v[208:209]
	v_cvt_pk_bf16_f32 v100, v124, v125
	v_cvt_pk_bf16_f32 v101, v126, v127
	v_cvt_pk_bf16_f32 v102, v120, v121
	v_cvt_pk_bf16_f32 v103, v122, v123
	v_cvt_pk_bf16_f32 v104, v108, v109
	v_cvt_pk_bf16_f32 v105, v110, v111
	v_cvt_pk_bf16_f32 v106, v106, v107
	v_cvt_pk_bf16_f32 v107, v158, v159
	v_cvt_pk_bf16_f32 v108, v116, v117
	v_cvt_pk_bf16_f32 v109, v118, v119
	v_cvt_pk_bf16_f32 v110, v112, v113
	v_cvt_pk_bf16_f32 v111, v114, v115
	global_store_dwordx4 v[192:193], v[100:103], off
	global_store_dwordx4 v[192:193], v[104:107], off offset:256
	global_store_dwordx4 v[194:195], v[108:111], off
	v_lshlrev_b32_e32 v100, 16, v172
	v_and_b32_e32 v101, 0xffff0000, v172
	v_lshlrev_b32_e32 v102, 16, v173
	v_and_b32_e32 v103, 0xffff0000, v173
	v_pk_mul_f32 v[102:103], v[94:95], v[102:103]
	v_pk_mul_f32 v[94:95], v[92:93], v[100:101]
	v_cvt_pk_bf16_f32 v92, v162, v163
	v_cvt_pk_bf16_f32 v93, v160, v161
	v_cvt_pk_bf16_f32 v94, v94, v95
	v_cvt_pk_bf16_f32 v95, v102, v103
	global_store_dwordx4 v[194:195], v[92:95], off offset:256
	v_lshl_add_u64 v[100:101], v[148:149], 0, s[30:31]
	v_lshl_add_u64 v[102:103], v[148:149], 0, s[34:35]
	v_lshlrev_b32_e32 v92, 16, v174
	v_and_b32_e32 v93, 0xffff0000, v174
	v_lshlrev_b32_e32 v94, 16, v175
	v_and_b32_e32 v95, 0xffff0000, v175
	v_pk_mul_f32 v[94:95], v[98:99], v[94:95]
	v_pk_mul_f32 v[92:93], v[96:97], v[92:93]
	v_lshlrev_b32_e32 v96, 16, v176
	v_and_b32_e32 v97, 0xffff0000, v176
	v_lshlrev_b32_e32 v98, 16, v177
	v_and_b32_e32 v99, 0xffff0000, v177
	v_pk_mul_f32 v[98:99], v[90:91], v[98:99]
	v_pk_mul_f32 v[90:91], v[88:89], v[96:97]
	v_cvt_pk_bf16_f32 v88, v92, v93
	v_lshl_add_u64 v[92:93], s[14:15], 0, v[190:191]
	v_cvt_pk_bf16_f32 v89, v94, v95
	v_cvt_pk_bf16_f32 v90, v90, v91
	v_cvt_pk_bf16_f32 v91, v98, v99
	v_lshl_add_u64 v[92:93], v[92:93], 0, v[144:145]
	global_store_dwordx4 v[92:93], v[88:91], off
	v_lshl_add_u64 v[96:97], v[148:149], 0, s[26:27]
	v_lshl_add_u64 v[98:99], v[148:149], 0, s[28:29]
	v_lshlrev_b32_e32 v88, 16, v178
	v_and_b32_e32 v89, 0xffff0000, v178
	v_lshlrev_b32_e32 v90, 16, v179
	v_and_b32_e32 v91, 0xffff0000, v179
	v_pk_mul_f32 v[86:87], v[86:87], v[90:91]
; __device__ __forceinline__ float bf_lo(unsigned w) { return __uint_as_float(w << 16); }
; __device__ __forceinline__ float bf_hi(unsigned w) { return __uint_as_float(w & 0xffff0000u); }
; __device__ __forceinline__ u32x4 pack8(const f32x4 a, const f32x4 b) { u32x4 w; w.x = cvt_pk_bf16(a[0], a[1]); w.y = cvt_pk_bf16(a[2], a[3]); w.z = cvt_pk_bf16(b[0], b[1]); w.w = cvt_pk_bf16(b[2], b[3]); return w; }
;     __device__ __forceinline__ void operator()(const f32x4 (&acc)[2][2][4][2], const Unit& u, int wr, int wc, int fr, int fq) const {
;     ...
;         for (int ai = 0; ai < 2; ++ai) { u32x4 gw[4][2], pw[4][2];
; #pragma unroll
;             for (int m = 0; m < 4; ++m) { const size_t off = (size_t)(row0 + ai * HALF + m * 16) * 2048 + col0;
; #pragma unroll
;                 for (int bj = 0; bj < 2; ++bj) { gw[m][bj] = *(const u32x4*)(G + off + bj * HALF); if (PASS == 1) pw[m][bj] = *(const u32x4*)(MIX + off + bj * HALF); } }
; #pragma unroll
;             for (int m = 0; m < 4; ++m) { const size_t off = (size_t)(row0 + ai * HALF + m * 16) * 2048 + col0;
; #pragma unroll
;                 for (int bj = 0; bj < 2; ++bj) { const u32x4 g4 = gw[m][bj];
;                     f32x4 v0 = (f32x4){bf_lo(g4.x), bf_hi(g4.x), bf_lo(g4.y), bf_hi(g4.y)} * acc[ai][bj][m][0], v1 = (f32x4){bf_lo(g4.z), bf_hi(g4.z), bf_lo(g4.w), bf_hi(g4.w)} * acc[ai][bj][m][1];
;                     if (PASS == 1) { const u32x4 p4 = pw[m][bj]; v0 += (f32x4){bf_lo(p4.x), bf_hi(p4.x), bf_lo(p4.y), bf_hi(p4.y)}; v1 += (f32x4){bf_lo(p4.z), bf_hi(p4.z), bf_lo(p4.w), bf_hi(p4.w)}; }
;                     *(u32x4*)(MIX + off + bj * HALF) = pack8(v0, v1); } } }
	v_pk_mul_f32 v[84:85], v[84:85], v[88:89]
	v_lshlrev_b32_e32 v88, 16, v180
	v_and_b32_e32 v89, 0xffff0000, v180
	v_lshlrev_b32_e32 v90, 16, v181
	v_and_b32_e32 v91, 0xffff0000, v181
	v_pk_mul_f32 v[90:91], v[78:79], v[90:91]
	v_pk_mul_f32 v[78:79], v[76:77], v[88:89]
	v_cvt_pk_bf16_f32 v76, v84, v85
	v_cvt_pk_bf16_f32 v77, v86, v87
	v_cvt_pk_bf16_f32 v78, v78, v79
	v_cvt_pk_bf16_f32 v79, v90, v91
	global_store_dwordx4 v[92:93], v[76:79], off offset:256
	s_nop 1
	v_lshlrev_b32_e32 v76, 16, v182
	v_and_b32_e32 v77, 0xffff0000, v182
	v_lshlrev_b32_e32 v78, 16, v183
	v_and_b32_e32 v79, 0xffff0000, v183
	v_pk_mul_f32 v[78:79], v[82:83], v[78:79]
	v_pk_mul_f32 v[76:77], v[80:81], v[76:77]
	v_lshlrev_b32_e32 v80, 16, v184
	v_and_b32_e32 v81, 0xffff0000, v184
	v_lshlrev_b32_e32 v82, 16, v185
	v_and_b32_e32 v83, 0xffff0000, v185
	v_pk_mul_f32 v[82:83], v[74:75], v[82:83]
	v_pk_mul_f32 v[74:75], v[72:73], v[80:81]
	v_cvt_pk_bf16_f32 v72, v76, v77
	v_lshl_add_u64 v[76:77], s[14:15], 0, v[150:151]
	v_cvt_pk_bf16_f32 v73, v78, v79
	v_cvt_pk_bf16_f32 v74, v74, v75
	v_cvt_pk_bf16_f32 v75, v82, v83
	v_lshl_add_u64 v[76:77], v[76:77], 0, v[144:145]
	global_store_dwordx4 v[76:77], v[72:75], off
	s_nop 1
	v_lshlrev_b32_e32 v72, 16, v186
	v_and_b32_e32 v73, 0xffff0000, v186
	v_lshlrev_b32_e32 v74, 16, v187
	v_and_b32_e32 v75, 0xffff0000, v187
	v_pk_mul_f32 v[70:71], v[70:71], v[74:75]
	v_pk_mul_f32 v[68:69], v[68:69], v[72:73]
	v_lshlrev_b32_e32 v72, 16, v188
	v_and_b32_e32 v73, 0xffff0000, v188
	v_lshlrev_b32_e32 v74, 16, v189
	v_and_b32_e32 v75, 0xffff0000, v189
	v_pk_mul_f32 v[74:75], v[66:67], v[74:75]
	v_pk_mul_f32 v[66:67], v[64:65], v[72:73]
	v_cvt_pk_bf16_f32 v64, v68, v69
	v_cvt_pk_bf16_f32 v65, v70, v71
	v_cvt_pk_bf16_f32 v66, v66, v67
	v_cvt_pk_bf16_f32 v67, v74, v75
	global_store_dwordx4 v[76:77], v[64:67], off offset:256
	s_nop 1
	v_lshl_add_u64 v[64:65], v[146:147], 0, v[96:97]
	global_load_dwordx4 v[68:71], v[64:65], off
	global_load_dwordx4 v[72:75], v[64:65], off offset:256
	v_lshl_add_u64 v[64:65], v[146:147], 0, v[98:99]
	global_load_dwordx4 v[76:79], v[64:65], off
	global_load_dwordx4 v[80:83], v[64:65], off offset:256
	v_lshl_add_u64 v[64:65], v[146:147], 0, v[100:101]
	global_load_dwordx4 v[84:87], v[64:65], off
	global_load_dwordx4 v[88:91], v[64:65], off offset:256
	v_lshl_add_u64 v[64:65], v[146:147], 0, v[102:103]
	global_load_dwordx4 v[92:95], v[64:65], off
	s_nop 0
	global_load_dwordx4 v[64:67], v[64:65], off offset:256
	s_waitcnt vmcnt(7)
	v_lshlrev_b32_e32 v104, 16, v68
	v_and_b32_e32 v105, 0xffff0000, v68
	v_lshlrev_b32_e32 v68, 16, v69
	v_and_b32_e32 v69, 0xffff0000, v69
	v_pk_mul_f32 v[62:63], v[62:63], v[68:69]
	v_pk_mul_f32 v[60:61], v[60:61], v[104:105]
	v_lshlrev_b32_e32 v68, 16, v70
	v_and_b32_e32 v69, 0xffff0000, v70
	v_lshlrev_b32_e32 v70, 16, v71
	v_and_b32_e32 v71, 0xffff0000, v71
	v_pk_mul_f32 v[70:71], v[58:59], v[70:71]
	v_pk_mul_f32 v[58:59], v[56:57], v[68:69]
	v_cvt_pk_bf16_f32 v56, v60, v61
	v_lshl_add_u64 v[60:61], s[14:15], 0, v[96:97]
	v_cvt_pk_bf16_f32 v57, v62, v63
	v_cvt_pk_bf16_f32 v58, v58, v59
	v_cvt_pk_bf16_f32 v59, v70, v71
	v_lshl_add_u64 v[60:61], v[60:61], 0, v[144:145]
	global_store_dwordx4 v[60:61], v[56:59], off
	s_waitcnt vmcnt(7)
	s_nop 0
	v_lshlrev_b32_e32 v56, 16, v72
	v_and_b32_e32 v57, 0xffff0000, v72
	v_lshlrev_b32_e32 v58, 16, v73
	v_and_b32_e32 v59, 0xffff0000, v73
	v_pk_mul_f32 v[54:55], v[54:55], v[58:59]
	v_pk_mul_f32 v[52:53], v[52:53], v[56:57]
	v_lshlrev_b32_e32 v56, 16, v74
	v_and_b32_e32 v57, 0xffff0000, v74
	v_lshlrev_b32_e32 v58, 16, v75
	v_and_b32_e32 v59, 0xffff0000, v75
	v_pk_mul_f32 v[58:59], v[46:47], v[58:59]
	v_pk_mul_f32 v[46:47], v[44:45], v[56:57]
	v_cvt_pk_bf16_f32 v44, v52, v53
	v_cvt_pk_bf16_f32 v45, v54, v55
	v_cvt_pk_bf16_f32 v46, v46, v47
	v_cvt_pk_bf16_f32 v47, v58, v59
	global_store_dwordx4 v[60:61], v[44:47], off offset:256
	s_waitcnt vmcnt(7)
; __device__ __forceinline__ float bf_lo(unsigned w) { return __uint_as_float(w << 16); }
; __device__ __forceinline__ float bf_hi(unsigned w) { return __uint_as_float(w & 0xffff0000u); }
; __device__ __forceinline__ u32x4 pack8(const f32x4 a, const f32x4 b) { u32x4 w; w.x = cvt_pk_bf16(a[0], a[1]); w.y = cvt_pk_bf16(a[2], a[3]); w.z = cvt_pk_bf16(b[0], b[1]); w.w = cvt_pk_bf16(b[2], b[3]); return w; }
; #define PG8_WAIT_V(n) asm volatile("s_waitcnt vmcnt(" #n ")" ::: "memory")
; #define PG8_BAR __builtin_amdgcn_s_barrier()
;     __device__ __forceinline__ void operator()(const f32x4 (&acc)[2][2][4][2], const Unit& u, int wr, int wc, int fr, int fq) const {
;     ...
;         for (int ai = 0; ai < 2; ++ai) { u32x4 gw[4][2], pw[4][2];
; #pragma unroll
;             for (int m = 0; m < 4; ++m) { const size_t off = (size_t)(row0 + ai * HALF + m * 16) * 2048 + col0;
; #pragma unroll
;                 for (int bj = 0; bj < 2; ++bj) { gw[m][bj] = *(const u32x4*)(G + off + bj * HALF); if (PASS == 1) pw[m][bj] = *(const u32x4*)(MIX + off + bj * HALF); } }
; #pragma unroll
;             for (int m = 0; m < 4; ++m) { const size_t off = (size_t)(row0 + ai * HALF + m * 16) * 2048 + col0;
; #pragma unroll
;                 for (int bj = 0; bj < 2; ++bj) { const u32x4 g4 = gw[m][bj];
;                     f32x4 v0 = (f32x4){bf_lo(g4.x), bf_hi(g4.x), bf_lo(g4.y), bf_hi(g4.y)} * acc[ai][bj][m][0], v1 = (f32x4){bf_lo(g4.z), bf_hi(g4.z), bf_lo(g4.w), bf_hi(g4.w)} * acc[ai][bj][m][1];
;                     if (PASS == 1) { const u32x4 p4 = pw[m][bj]; v0 += (f32x4){bf_lo(p4.x), bf_hi(p4.x), bf_lo(p4.y), bf_hi(p4.y)}; v1 += (f32x4){bf_lo(p4.z), bf_hi(p4.z), bf_lo(p4.w), bf_hi(p4.w)}; }
;                     *(u32x4*)(MIX + off + bj * HALF) = pack8(v0, v1); } } }
; template <class Epi, class Sched, bool ALIGN_EPI = false, bool SP2 = false>
; __device__ __forceinline__ void gemm_phase(PG8_LAS unsigned char* lds, const Gemm g, const Sched& S, const Epi& E) {
;     ...
;     PG8_WAIT_V(0);
;     if constexpr (!ALIGN_EPI) { if (wr == 0) PG8_BAR; }
;     PG8_BAR;
	s_nop 0
	v_lshlrev_b32_e32 v44, 16, v76
	v_and_b32_e32 v45, 0xffff0000, v76
	v_lshlrev_b32_e32 v46, 16, v77
	v_and_b32_e32 v47, 0xffff0000, v77
	v_pk_mul_f32 v[46:47], v[50:51], v[46:47]
	v_pk_mul_f32 v[44:45], v[48:49], v[44:45]
	v_lshlrev_b32_e32 v48, 16, v78
	v_and_b32_e32 v49, 0xffff0000, v78
	v_lshlrev_b32_e32 v50, 16, v79
	v_and_b32_e32 v51, 0xffff0000, v79
	v_pk_mul_f32 v[50:51], v[42:43], v[50:51]
	v_pk_mul_f32 v[42:43], v[40:41], v[48:49]
	v_cvt_pk_bf16_f32 v40, v44, v45
	v_lshl_add_u64 v[44:45], s[14:15], 0, v[98:99]
	v_cvt_pk_bf16_f32 v41, v46, v47
	v_cvt_pk_bf16_f32 v42, v42, v43
	v_cvt_pk_bf16_f32 v43, v50, v51
	v_lshl_add_u64 v[44:45], v[44:45], 0, v[144:145]
	global_store_dwordx4 v[44:45], v[40:43], off
	s_waitcnt vmcnt(7)
	s_nop 0
	v_lshlrev_b32_e32 v40, 16, v80
	v_and_b32_e32 v41, 0xffff0000, v80
	v_lshlrev_b32_e32 v42, 16, v81
	v_and_b32_e32 v43, 0xffff0000, v81
	v_pk_mul_f32 v[38:39], v[38:39], v[42:43]
	v_pk_mul_f32 v[36:37], v[36:37], v[40:41]
	v_lshlrev_b32_e32 v40, 16, v82
	v_and_b32_e32 v41, 0xffff0000, v82
	v_lshlrev_b32_e32 v42, 16, v83
	v_and_b32_e32 v43, 0xffff0000, v83
	v_pk_mul_f32 v[42:43], v[30:31], v[42:43]
	v_pk_mul_f32 v[30:31], v[28:29], v[40:41]
	v_cvt_pk_bf16_f32 v28, v36, v37
	v_cvt_pk_bf16_f32 v29, v38, v39
	v_cvt_pk_bf16_f32 v30, v30, v31
	v_cvt_pk_bf16_f32 v31, v42, v43
	global_store_dwordx4 v[44:45], v[28:31], off offset:256
	s_waitcnt vmcnt(7)
	s_nop 0
	v_lshlrev_b32_e32 v28, 16, v84
	v_and_b32_e32 v29, 0xffff0000, v84
	v_lshlrev_b32_e32 v30, 16, v85
	v_and_b32_e32 v31, 0xffff0000, v85
	v_pk_mul_f32 v[30:31], v[34:35], v[30:31]
	v_pk_mul_f32 v[28:29], v[32:33], v[28:29]
	v_lshlrev_b32_e32 v32, 16, v86
	v_and_b32_e32 v33, 0xffff0000, v86
	v_lshlrev_b32_e32 v34, 16, v87
	v_and_b32_e32 v35, 0xffff0000, v87
	v_pk_mul_f32 v[34:35], v[26:27], v[34:35]
	v_pk_mul_f32 v[26:27], v[24:25], v[32:33]
	v_cvt_pk_bf16_f32 v24, v28, v29
	v_lshl_add_u64 v[28:29], s[14:15], 0, v[100:101]
	v_cvt_pk_bf16_f32 v25, v30, v31
	v_cvt_pk_bf16_f32 v26, v26, v27
	v_cvt_pk_bf16_f32 v27, v34, v35
	v_lshl_add_u64 v[28:29], v[28:29], 0, v[144:145]
	global_store_dwordx4 v[28:29], v[24:27], off
	s_waitcnt vmcnt(7)
	s_nop 0
	v_lshlrev_b32_e32 v24, 16, v88
	v_and_b32_e32 v25, 0xffff0000, v88
	v_lshlrev_b32_e32 v26, 16, v89
	v_and_b32_e32 v27, 0xffff0000, v89
	v_pk_mul_f32 v[22:23], v[22:23], v[26:27]
	v_pk_mul_f32 v[20:21], v[20:21], v[24:25]
	v_lshlrev_b32_e32 v24, 16, v90
	v_and_b32_e32 v25, 0xffff0000, v90
	v_lshlrev_b32_e32 v26, 16, v91
	v_and_b32_e32 v27, 0xffff0000, v91
	v_pk_mul_f32 v[26:27], v[14:15], v[26:27]
	v_pk_mul_f32 v[14:15], v[12:13], v[24:25]
	v_cvt_pk_bf16_f32 v12, v20, v21
	v_cvt_pk_bf16_f32 v13, v22, v23
	v_cvt_pk_bf16_f32 v14, v14, v15
	v_cvt_pk_bf16_f32 v15, v26, v27
	global_store_dwordx4 v[28:29], v[12:15], off offset:256
	s_waitcnt vmcnt(7)
	s_nop 0
	v_lshlrev_b32_e32 v12, 16, v92
	v_and_b32_e32 v13, 0xffff0000, v92
	v_lshlrev_b32_e32 v14, 16, v93
	v_and_b32_e32 v15, 0xffff0000, v93
	v_pk_mul_f32 v[14:15], v[18:19], v[14:15]
	v_pk_mul_f32 v[12:13], v[16:17], v[12:13]
	v_lshlrev_b32_e32 v16, 16, v94
	v_and_b32_e32 v17, 0xffff0000, v94
	v_lshlrev_b32_e32 v18, 16, v95
	v_and_b32_e32 v19, 0xffff0000, v95
	v_pk_mul_f32 v[18:19], v[10:11], v[18:19]
	v_pk_mul_f32 v[10:11], v[8:9], v[16:17]
	v_cvt_pk_bf16_f32 v8, v12, v13
	v_lshl_add_u64 v[12:13], s[14:15], 0, v[102:103]
	v_cvt_pk_bf16_f32 v9, v14, v15
	v_cvt_pk_bf16_f32 v10, v10, v11
	v_cvt_pk_bf16_f32 v11, v18, v19
	v_lshl_add_u64 v[12:13], v[12:13], 0, v[144:145]
	global_store_dwordx4 v[12:13], v[8:11], off
	s_waitcnt vmcnt(7)
	s_nop 0
	v_lshlrev_b32_e32 v8, 16, v64
	v_and_b32_e32 v9, 0xffff0000, v64
	v_lshlrev_b32_e32 v10, 16, v65
	v_and_b32_e32 v11, 0xffff0000, v65
	v_pk_mul_f32 v[6:7], v[6:7], v[10:11]
	v_pk_mul_f32 v[4:5], v[4:5], v[8:9]
	v_lshlrev_b32_e32 v8, 16, v66
	v_and_b32_e32 v9, 0xffff0000, v66
	v_lshlrev_b32_e32 v10, 16, v67
	v_and_b32_e32 v11, 0xffff0000, v67
	v_pk_mul_f32 v[10:11], v[2:3], v[10:11]
	v_pk_mul_f32 v[2:3], v[0:1], v[8:9]
	v_cvt_pk_bf16_f32 v0, v4, v5
	v_cvt_pk_bf16_f32 v1, v6, v7
	v_cvt_pk_bf16_f32 v2, v2, v3
	v_cvt_pk_bf16_f32 v3, v10, v11
	global_store_dwordx4 v[12:13], v[0:3], off offset:256
	s_cbranch_vccz .LBB0_728
	s_waitcnt vmcnt(0)
	s_cmpk_gt_u32 s3, 0xff
	s_cbranch_scc1 .LBB0_739
	s_barrier

; #define PG8_STAGE(bufoff, gbase, voff) do { _Pragma("unroll") for (int _i = 0; _i < 2; ++_i) \
;         __builtin_amdgcn_global_load_lds((const unsigned*)((const char*)(gbase) + (voff)[_i]), (PG8_LAS unsigned*)(lds + (bufoff) + ldsw + _i * 8192), 16, 0, 0); } while (0)
; #define PG8_LDA(dst, b, h) do { _Pragma("unroll") for (int m = 0; m < 4; ++m) _Pragma("unroll") for (int k = 0; k < 2; ++k) dst[m][k] = *(const PG8_LAS bf16x8*)(lds + PG8_SA(b, h) + aoff + m * 2048 + k * 1024); } while (0)
; #define PG8_LDB(dst, b, h) do { _Pragma("unroll") for (int n = 0; n < 2; ++n) _Pragma("unroll") for (int k = 0; k < 2; ++k) dst[n][k] = *(const PG8_LAS bf16x8*)(lds + PG8_SB(b, h) + boff + n * 2048 + k * 1024); } while (0)
; #define PG8_MMA(ai, bj, At, Bt) do { __builtin_amdgcn_s_setprio(1); _Pragma("unroll") for (int m = 0; m < 4; ++m) _Pragma("unroll") for (int n = 0; n < 2; ++n) _Pragma("unroll") for (int k = 0; k < 2; ++k) \
;         acc[ai][bj][m][n] = __builtin_amdgcn_mfma_f32_16x16x32_bf16(Bt[n][k], At[m][k], acc[ai][bj][m][n], 0, 0, 0); __builtin_amdgcn_s_setprio(0); } while (0)
; #define PG8_WAIT_V(n) asm volatile("s_waitcnt vmcnt(" #n ")" ::: "memory")
; #define PG8_BAR __builtin_amdgcn_s_barrier()
; template <class Epi, class Sched, bool ALIGN_EPI = false, bool SP2 = false>
; __device__ __forceinline__ void gemm_phase(PG8_LAS unsigned char* lds, const Gemm g, const Sched& S, const Epi& E) {
;     ...
;         for (int t = 0; t < nt; t += 2) {
;             const bool last = (t == nt - 2);
;             const char* a1 = cA + (size_t)(t + 1) * kstep;
;             const char* a2 = last ? nA : cA + (size_t)(t + 2) * kstep; const char* b2 = last ? nB : cB + (size_t)(t + 2) * kstep;
;             const char* a3 = a2 + kstep; const char* b3 = b2 + kstep;
;             if (last && has_next) S.a_ready(nxt);
;             if constexpr (SP2) {
;             PG8_LDB(B0, 0, 0); PG8_LDB(B1, 0, 1); PG8_SCHED; PG8_LDA(At, 0, 0); PG8_STAGE(PG8_SA(1, 1), a1 + hstep, voffA);
;             PG8_WAIT_V(8); PG8_WAIT_L(0); PG8_BAR; PG8_MMA(0, 0, At, B0); PG8_MMA(0, 1, At, B1); PG8_BAR; PG8_SCHED;
;             PG8_LDA(At, 0, 1); PG8_STAGE(PG8_SB(0, 0), b2, voffB); PG8_STAGE(PG8_SB(0, 1), b2 + hstep, voffB); PG8_STAGE(PG8_SA(0, 0), a2, voffA);
;             PG8_WAIT_V(8); PG8_WAIT_L(0); PG8_BAR; PG8_MMA(1, 0, At, B0); PG8_MMA(1, 1, At, B1); PG8_BAR; PG8_SCHED;
.LBB0_755:
	ds_read_b128 v[128:131], v177
	ds_read_b128 v[132:135], v177 offset:1024
	ds_read_b128 v[136:139], v177 offset:2048
	ds_read_b128 v[140:143], v177 offset:3072
	ds_read_b128 v[144:147], v178
	ds_read_b128 v[164:167], v178 offset:1024
	ds_read_b128 v[168:171], v178 offset:2048
	ds_read_b128 v[180:183], v178 offset:3072
	s_add_u32 s40, s38, 0xfffc0080
	s_addc_u32 s41, s39, -1
	s_cmp_eq_u32 s61, 12
	s_cselect_b32 s43, s29, s41
	s_cselect_b32 s42, s57, s40
	s_cselect_b32 s41, s27, s60
	s_cselect_b32 s40, s58, s59
	s_add_i32 m0, s37, 0xc000
	ds_read_b128 v[184:187], v179
	ds_read_b128 v[188:191], v179 offset:1024
	ds_read_b128 v[192:195], v179 offset:2048
	ds_read_b128 v[196:199], v179 offset:3072
	ds_read_b128 v[200:203], v179 offset:4096
	ds_read_b128 v[204:207], v179 offset:5120
	ds_read_b128 v[208:211], v179 offset:6144
	ds_read_b128 v[214:217], v179 offset:7168
	global_load_lds_dwordx4 v156, s[38:39]
	s_add_i32 m0, s37, 0xe000
	s_nop 0
	global_load_lds_dwordx4 v158, s[38:39]
	s_waitcnt vmcnt(8)
	s_waitcnt lgkmcnt(0)
	s_barrier
	s_setprio 1
	s_waitcnt lgkmcnt(0)
	v_mfma_f32_16x16x32_bf16 v[124:127], v[128:131], v[184:187], v[124:127]
	v_mfma_f32_16x16x32_bf16 v[120:123], v[136:139], v[184:187], v[120:123]
	v_mfma_f32_16x16x32_bf16 v[108:111], v[128:131], v[192:195], v[108:111]
	v_mfma_f32_16x16x32_bf16 v[104:107], v[136:139], v[192:195], v[104:107]
	v_mfma_f32_16x16x32_bf16 v[92:95], v[128:131], v[200:203], v[92:95]
	v_mfma_f32_16x16x32_bf16 v[88:91], v[136:139], v[200:203], v[88:91]
	v_mfma_f32_16x16x32_bf16 v[76:79], v[128:131], v[208:211], v[76:79]
	v_mfma_f32_16x16x32_bf16 v[72:75], v[136:139], v[208:211], v[72:75]
	v_mfma_f32_16x16x32_bf16 v[124:127], v[132:135], v[188:191], v[124:127]
	v_mfma_f32_16x16x32_bf16 v[120:123], v[140:143], v[188:191], v[120:123]
	v_mfma_f32_16x16x32_bf16 v[108:111], v[132:135], v[196:199], v[108:111]
	v_mfma_f32_16x16x32_bf16 v[104:107], v[140:143], v[196:199], v[104:107]
	v_mfma_f32_16x16x32_bf16 v[92:95], v[132:135], v[204:207], v[92:95]
	v_mfma_f32_16x16x32_bf16 v[88:91], v[140:143], v[204:207], v[88:91]
	v_mfma_f32_16x16x32_bf16 v[76:79], v[132:135], v[214:217], v[76:79]
	v_mfma_f32_16x16x32_bf16 v[72:75], v[140:143], v[214:217], v[72:75]
	s_setprio 0
	s_setprio 1
	v_mfma_f32_16x16x32_bf16 v[116:119], v[144:147], v[184:187], v[116:119]
	v_mfma_f32_16x16x32_bf16 v[112:115], v[168:171], v[184:187], v[112:115]
	v_mfma_f32_16x16x32_bf16 v[100:103], v[144:147], v[192:195], v[100:103]
	v_mfma_f32_16x16x32_bf16 v[96:99], v[168:171], v[192:195], v[96:99]
	v_mfma_f32_16x16x32_bf16 v[84:87], v[144:147], v[200:203], v[84:87]
	v_mfma_f32_16x16x32_bf16 v[80:83], v[168:171], v[200:203], v[80:83]
	v_mfma_f32_16x16x32_bf16 v[68:71], v[144:147], v[208:211], v[68:71]
	v_mfma_f32_16x16x32_bf16 v[64:67], v[168:171], v[208:211], v[64:67]
	v_mfma_f32_16x16x32_bf16 v[116:119], v[164:167], v[188:191], v[116:119]
	v_mfma_f32_16x16x32_bf16 v[112:115], v[180:183], v[188:191], v[112:115]
	v_mfma_f32_16x16x32_bf16 v[100:103], v[164:167], v[196:199], v[100:103]
	v_mfma_f32_16x16x32_bf16 v[96:99], v[180:183], v[196:199], v[96:99]
	v_mfma_f32_16x16x32_bf16 v[84:87], v[164:167], v[204:207], v[84:87]
	v_mfma_f32_16x16x32_bf16 v[80:83], v[180:183], v[204:207], v[80:83]
	v_mfma_f32_16x16x32_bf16 v[68:71], v[164:167], v[214:217], v[68:71]
	v_mfma_f32_16x16x32_bf16 v[64:67], v[180:183], v[214:217], v[64:67]
	s_setprio 0
	s_barrier
	s_add_i32 s62, s54, s45
	s_mov_b32 m0, s62
	ds_read_b128 v[184:187], v179 offset:16384
	ds_read_b128 v[188:191], v179 offset:17408
	ds_read_b128 v[192:195], v179 offset:18432
	ds_read_b128 v[196:199], v179 offset:19456
	ds_read_b128 v[200:203], v179 offset:20480
	ds_read_b128 v[204:207], v179 offset:21504
	ds_read_b128 v[208:211], v179 offset:22528
	ds_read_b128 v[214:217], v179 offset:23552
	global_load_lds_dwordx4 v150, s[40:41]
	s_add_i32 m0, s62, 0x2000
	s_add_u32 s62, s40, 0x40000
	s_addc_u32 s63, s41, 0
	s_add_i32 s64, s55, s45
	global_load_lds_dwordx4 v154, s[40:41]
	s_mov_b32 m0, s64
	s_nop 0
	global_load_lds_dwordx4 v150, s[62:63]
	s_add_i32 m0, s64, 0x2000
	s_nop 0
	global_load_lds_dwordx4 v154, s[62:63]
	s_mov_b32 m0, s37
	s_nop 0
	global_load_lds_dwordx4 v148, s[42:43]
	s_mov_b32 m0, s46
	s_nop 0
	global_load_lds_dwordx4 v152, s[42:43]
	s_waitcnt vmcnt(8)
	s_waitcnt lgkmcnt(0)
	s_barrier
	s_setprio 1
	s_waitcnt lgkmcnt(0)
	v_mfma_f32_16x16x32_bf16 v[60:63], v[128:131], v[184:187], v[60:63]
	v_mfma_f32_16x16x32_bf16 v[56:59], v[136:139], v[184:187], v[56:59]
	v_mfma_f32_16x16x32_bf16 v[44:47], v[128:131], v[192:195], v[44:47]
	v_mfma_f32_16x16x32_bf16 v[40:43], v[136:139], v[192:195], v[40:43]
	v_mfma_f32_16x16x32_bf16 v[28:31], v[128:131], v[200:203], v[28:31]
	v_mfma_f32_16x16x32_bf16 v[24:27], v[136:139], v[200:203], v[24:27]
	v_mfma_f32_16x16x32_bf16 v[12:15], v[128:131], v[208:211], v[12:15]
	v_mfma_f32_16x16x32_bf16 v[8:11], v[136:139], v[208:211], v[8:11]
	v_mfma_f32_16x16x32_bf16 v[60:63], v[132:135], v[188:191], v[60:63]
	v_mfma_f32_16x16x32_bf16 v[56:59], v[140:143], v[188:191], v[56:59]
	v_mfma_f32_16x16x32_bf16 v[44:47], v[132:135], v[196:199], v[44:47]
	v_mfma_f32_16x16x32_bf16 v[40:43], v[140:143], v[196:199], v[40:43]
	v_mfma_f32_16x16x32_bf16 v[28:31], v[132:135], v[204:207], v[28:31]
	v_mfma_f32_16x16x32_bf16 v[24:27], v[140:143], v[204:207], v[24:27]
	v_mfma_f32_16x16x32_bf16 v[12:15], v[132:135], v[214:217], v[12:15]
	v_mfma_f32_16x16x32_bf16 v[8:11], v[140:143], v[214:217], v[8:11]
	s_setprio 0
	s_setprio 1
	v_mfma_f32_16x16x32_bf16 v[52:55], v[144:147], v[184:187], v[52:55]
	v_mfma_f32_16x16x32_bf16 v[48:51], v[168:171], v[184:187], v[48:51]
	v_mfma_f32_16x16x32_bf16 v[36:39], v[144:147], v[192:195], v[36:39]
	v_mfma_f32_16x16x32_bf16 v[32:35], v[168:171], v[192:195], v[32:35]
	v_mfma_f32_16x16x32_bf16 v[20:23], v[144:147], v[200:203], v[20:23]
	v_mfma_f32_16x16x32_bf16 v[16:19], v[168:171], v[200:203], v[16:19]
	v_mfma_f32_16x16x32_bf16 v[4:7], v[144:147], v[208:211], v[4:7]
	v_mfma_f32_16x16x32_bf16 v[0:3], v[168:171], v[208:211], v[0:3]
	v_mfma_f32_16x16x32_bf16 v[52:55], v[164:167], v[188:191], v[52:55]
	v_mfma_f32_16x16x32_bf16 v[48:51], v[180:183], v[188:191], v[48:51]
	v_mfma_f32_16x16x32_bf16 v[36:39], v[164:167], v[196:199], v[36:39]
	v_mfma_f32_16x16x32_bf16 v[32:35], v[180:183], v[196:199], v[32:35]
	v_mfma_f32_16x16x32_bf16 v[20:23], v[164:167], v[204:207], v[20:23]
	v_mfma_f32_16x16x32_bf16 v[16:19], v[180:183], v[204:207], v[16:19]
	v_mfma_f32_16x16x32_bf16 v[4:7], v[164:167], v[214:217], v[4:7]
	v_mfma_f32_16x16x32_bf16 v[0:3], v[180:183], v[214:217], v[0:3]
	s_setprio 0
	s_barrier
; #define PG8_STAGE(bufoff, gbase, voff) do { _Pragma("unroll") for (int _i = 0; _i < 2; ++_i) \
;         __builtin_amdgcn_global_load_lds((const unsigned*)((const char*)(gbase) + (voff)[_i]), (PG8_LAS unsigned*)(lds + (bufoff) + ldsw + _i * 8192), 16, 0, 0); } while (0)
; #define PG8_LDA(dst, b, h) do { _Pragma("unroll") for (int m = 0; m < 4; ++m) _Pragma("unroll") for (int k = 0; k < 2; ++k) dst[m][k] = *(const PG8_LAS bf16x8*)(lds + PG8_SA(b, h) + aoff + m * 2048 + k * 1024); } while (0)
; #define PG8_LDB(dst, b, h) do { _Pragma("unroll") for (int n = 0; n < 2; ++n) _Pragma("unroll") for (int k = 0; k < 2; ++k) dst[n][k] = *(const PG8_LAS bf16x8*)(lds + PG8_SB(b, h) + boff + n * 2048 + k * 1024); } while (0)
; #define PG8_MMA(ai, bj, At, Bt) do { __builtin_amdgcn_s_setprio(1); _Pragma("unroll") for (int m = 0; m < 4; ++m) _Pragma("unroll") for (int n = 0; n < 2; ++n) _Pragma("unroll") for (int k = 0; k < 2; ++k) \
;         acc[ai][bj][m][n] = __builtin_amdgcn_mfma_f32_16x16x32_bf16(Bt[n][k], At[m][k], acc[ai][bj][m][n], 0, 0, 0); __builtin_amdgcn_s_setprio(0); } while (0)
; #define PG8_WAIT_V(n) asm volatile("s_waitcnt vmcnt(" #n ")" ::: "memory")
; #define PG8_WAIT_L(n) asm volatile("s_waitcnt lgkmcnt(" #n ")" ::: "memory")
; #define PG8_BAR __builtin_amdgcn_s_barrier()
; #define PG8_SCHED __builtin_amdgcn_sched_barrier(0)
; template <class Epi, class Sched, bool ALIGN_EPI = false, bool SP2 = false>
; __device__ __forceinline__ void gemm_phase(PG8_LAS unsigned char* lds, const Gemm g, const Sched& S, const Epi& E) {
;     ...
;             PG8_LDB(B0, 1, 0); PG8_LDB(B1, 1, 1); PG8_SCHED; PG8_LDA(At, 1, 0); PG8_STAGE(PG8_SA(0, 1), a2 + hstep, voffA);
;             PG8_WAIT_V(8); PG8_WAIT_L(0); PG8_BAR; PG8_MMA(0, 0, At, B0); PG8_MMA(0, 1, At, B1); PG8_BAR; PG8_SCHED;
;             PG8_LDA(At, 1, 1); PG8_STAGE(PG8_SB(1, 0), b3, voffB); PG8_STAGE(PG8_SB(1, 1), b3 + hstep, voffB); PG8_STAGE(PG8_SA(1, 0), a3, voffA);
;             PG8_WAIT_V(8); PG8_WAIT_L(0); PG8_BAR; PG8_MMA(1, 0, At, B0); PG8_MMA(1, 1, At, B1); PG8_BAR; PG8_SCHED;
	s_add_i32 s62, 0, 0x18000
	s_add_i32 s63, 0, 0x1c000
	v_add_u32_e32 v140, s62, v175
	v_add_u32_e32 v180, s63, v175
	ds_read_b128 v[128:131], v140
	ds_read_b128 v[132:135], v140 offset:1024
	ds_read_b128 v[136:139], v140 offset:2048
	ds_read_b128 v[140:143], v140 offset:3072
	ds_read_b128 v[144:147], v180
	ds_read_b128 v[164:167], v180 offset:1024
	ds_read_b128 v[168:171], v180 offset:2048
	ds_read_b128 v[180:183], v180 offset:3072
	s_add_u32 s84, s42, 0x80
	s_addc_u32 s85, s43, 0
	s_add_u32 s42, s42, 0x40000
	s_addc_u32 s43, s43, 0
	s_mov_b32 m0, s47
	ds_read_b128 v[184:187], v179 offset:32768
	ds_read_b128 v[188:191], v179 offset:33792
	ds_read_b128 v[192:195], v179 offset:34816
	ds_read_b128 v[196:199], v179 offset:35840
	ds_read_b128 v[200:203], v179 offset:36864
	ds_read_b128 v[204:207], v179 offset:37888
	ds_read_b128 v[208:211], v179 offset:38912
	ds_read_b128 v[214:217], v179 offset:39936
	global_load_lds_dwordx4 v148, s[42:43]
	s_mov_b32 m0, s48
	s_nop 0
	global_load_lds_dwordx4 v152, s[42:43]
	s_waitcnt vmcnt(8)
	s_waitcnt lgkmcnt(0)
	s_barrier
	s_setprio 1
	s_waitcnt lgkmcnt(0)
	v_mfma_f32_16x16x32_bf16 v[124:127], v[128:131], v[184:187], v[124:127]
	v_mfma_f32_16x16x32_bf16 v[120:123], v[136:139], v[184:187], v[120:123]
	v_mfma_f32_16x16x32_bf16 v[108:111], v[128:131], v[192:195], v[108:111]
	v_mfma_f32_16x16x32_bf16 v[104:107], v[136:139], v[192:195], v[104:107]
	v_mfma_f32_16x16x32_bf16 v[92:95], v[128:131], v[200:203], v[92:95]
	v_mfma_f32_16x16x32_bf16 v[88:91], v[136:139], v[200:203], v[88:91]
	v_mfma_f32_16x16x32_bf16 v[76:79], v[128:131], v[208:211], v[76:79]
	v_mfma_f32_16x16x32_bf16 v[72:75], v[136:139], v[208:211], v[72:75]
	v_mfma_f32_16x16x32_bf16 v[124:127], v[132:135], v[188:191], v[124:127]
	v_mfma_f32_16x16x32_bf16 v[120:123], v[140:143], v[188:191], v[120:123]
	v_mfma_f32_16x16x32_bf16 v[108:111], v[132:135], v[196:199], v[108:111]
	v_mfma_f32_16x16x32_bf16 v[104:107], v[140:143], v[196:199], v[104:107]
	v_mfma_f32_16x16x32_bf16 v[92:95], v[132:135], v[204:207], v[92:95]
	v_mfma_f32_16x16x32_bf16 v[88:91], v[140:143], v[204:207], v[88:91]
	v_mfma_f32_16x16x32_bf16 v[76:79], v[132:135], v[214:217], v[76:79]
	v_mfma_f32_16x16x32_bf16 v[72:75], v[140:143], v[214:217], v[72:75]
	s_setprio 0
	s_setprio 1
	v_mfma_f32_16x16x32_bf16 v[116:119], v[144:147], v[184:187], v[116:119]
	v_mfma_f32_16x16x32_bf16 v[112:115], v[168:171], v[184:187], v[112:115]
	v_mfma_f32_16x16x32_bf16 v[100:103], v[144:147], v[192:195], v[100:103]
	v_mfma_f32_16x16x32_bf16 v[96:99], v[168:171], v[192:195], v[96:99]
	v_mfma_f32_16x16x32_bf16 v[84:87], v[144:147], v[200:203], v[84:87]
	v_mfma_f32_16x16x32_bf16 v[80:83], v[168:171], v[200:203], v[80:83]
	v_mfma_f32_16x16x32_bf16 v[68:71], v[144:147], v[208:211], v[68:71]
	v_mfma_f32_16x16x32_bf16 v[64:67], v[168:171], v[208:211], v[64:67]
	v_mfma_f32_16x16x32_bf16 v[116:119], v[164:167], v[188:191], v[116:119]
	v_mfma_f32_16x16x32_bf16 v[112:115], v[180:183], v[188:191], v[112:115]
	v_mfma_f32_16x16x32_bf16 v[100:103], v[164:167], v[196:199], v[100:103]
	v_mfma_f32_16x16x32_bf16 v[96:99], v[180:183], v[196:199], v[96:99]
	v_mfma_f32_16x16x32_bf16 v[84:87], v[164:167], v[204:207], v[84:87]
	v_mfma_f32_16x16x32_bf16 v[80:83], v[180:183], v[204:207], v[80:83]
	v_mfma_f32_16x16x32_bf16 v[68:71], v[164:167], v[214:217], v[68:71]
	v_mfma_f32_16x16x32_bf16 v[64:67], v[180:183], v[214:217], v[64:67]
	s_setprio 0
	s_barrier
	s_add_i32 s42, s62, s45
	s_add_u32 s86, s40, 0x80
	s_addc_u32 s87, s41, 0
	s_mov_b32 m0, s42
	ds_read_b128 v[184:187], v179 offset:49152
	ds_read_b128 v[188:191], v179 offset:50176
	ds_read_b128 v[192:195], v179 offset:51200
	ds_read_b128 v[196:199], v179 offset:52224
	ds_read_b128 v[200:203], v179 offset:53248
	ds_read_b128 v[204:207], v179 offset:54272
	ds_read_b128 v[208:211], v179 offset:55296
	ds_read_b128 v[214:217], v179 offset:56320
	global_load_lds_dwordx4 v150, s[86:87]
	s_add_i32 m0, s42, 0x2000
	s_add_u32 s40, s40, 0x40080
	s_addc_u32 s41, s41, 0
	s_add_i32 s42, s63, s45
	global_load_lds_dwordx4 v154, s[86:87]
	s_mov_b32 m0, s42
	s_nop 0
	global_load_lds_dwordx4 v150, s[40:41]
	s_add_i32 m0, s42, 0x2000
	s_nop 0
	global_load_lds_dwordx4 v154, s[40:41]
	s_mov_b32 m0, s50
	s_nop 0
	global_load_lds_dwordx4 v148, s[84:85]
	s_mov_b32 m0, s51
	s_nop 0
	global_load_lds_dwordx4 v152, s[84:85]
	s_waitcnt vmcnt(8)
	s_waitcnt lgkmcnt(0)
	s_barrier
	s_setprio 1
	s_waitcnt lgkmcnt(0)
	v_mfma_f32_16x16x32_bf16 v[60:63], v[128:131], v[184:187], v[60:63]
	v_mfma_f32_16x16x32_bf16 v[56:59], v[136:139], v[184:187], v[56:59]
	v_mfma_f32_16x16x32_bf16 v[44:47], v[128:131], v[192:195], v[44:47]
	v_mfma_f32_16x16x32_bf16 v[40:43], v[136:139], v[192:195], v[40:43]
	v_mfma_f32_16x16x32_bf16 v[28:31], v[128:131], v[200:203], v[28:31]
	v_mfma_f32_16x16x32_bf16 v[24:27], v[136:139], v[200:203], v[24:27]
	v_mfma_f32_16x16x32_bf16 v[12:15], v[128:131], v[208:211], v[12:15]
	v_mfma_f32_16x16x32_bf16 v[8:11], v[136:139], v[208:211], v[8:11]
	v_mfma_f32_16x16x32_bf16 v[60:63], v[132:135], v[188:191], v[60:63]
	v_mfma_f32_16x16x32_bf16 v[56:59], v[140:143], v[188:191], v[56:59]
	v_mfma_f32_16x16x32_bf16 v[44:47], v[132:135], v[196:199], v[44:47]
	v_mfma_f32_16x16x32_bf16 v[40:43], v[140:143], v[196:199], v[40:43]
	v_mfma_f32_16x16x32_bf16 v[28:31], v[132:135], v[204:207], v[28:31]
	v_mfma_f32_16x16x32_bf16 v[24:27], v[140:143], v[204:207], v[24:27]
	v_mfma_f32_16x16x32_bf16 v[12:15], v[132:135], v[214:217], v[12:15]
	v_mfma_f32_16x16x32_bf16 v[8:11], v[140:143], v[214:217], v[8:11]
	s_setprio 0
	s_setprio 1
	v_mfma_f32_16x16x32_bf16 v[52:55], v[144:147], v[184:187], v[52:55]
	v_mfma_f32_16x16x32_bf16 v[48:51], v[168:171], v[184:187], v[48:51]
	v_mfma_f32_16x16x32_bf16 v[36:39], v[144:147], v[192:195], v[36:39]
	v_mfma_f32_16x16x32_bf16 v[32:35], v[168:171], v[192:195], v[32:35]
	v_mfma_f32_16x16x32_bf16 v[20:23], v[144:147], v[200:203], v[20:23]
	v_mfma_f32_16x16x32_bf16 v[16:19], v[168:171], v[200:203], v[16:19]
	v_mfma_f32_16x16x32_bf16 v[4:7], v[144:147], v[208:211], v[4:7]
	v_mfma_f32_16x16x32_bf16 v[0:3], v[168:171], v[208:211], v[0:3]
	v_mfma_f32_16x16x32_bf16 v[52:55], v[164:167], v[188:191], v[52:55]
	v_mfma_f32_16x16x32_bf16 v[48:51], v[180:183], v[188:191], v[48:51]
	v_mfma_f32_16x16x32_bf16 v[36:39], v[164:167], v[196:199], v[36:39]
	v_mfma_f32_16x16x32_bf16 v[32:35], v[180:183], v[196:199], v[32:35]
	v_mfma_f32_16x16x32_bf16 v[20:23], v[164:167], v[204:207], v[20:23]
	v_mfma_f32_16x16x32_bf16 v[16:19], v[180:183], v[204:207], v[16:19]
	v_mfma_f32_16x16x32_bf16 v[4:7], v[164:167], v[214:217], v[4:7]
	v_mfma_f32_16x16x32_bf16 v[0:3], v[180:183], v[214:217], v[0:3]
	s_setprio 0
	s_barrier
; __device__ __forceinline__ float bf_lo(unsigned w) { return __uint_as_float(w << 16); }
; __device__ __forceinline__ float bf_hi(unsigned w) { return __uint_as_float(w & 0xffff0000u); }
; __device__ __forceinline__ u32x4 pack8(const f32x4 a, const f32x4 b) { u32x4 w; w.x = cvt_pk_bf16(a[0], a[1]); w.y = cvt_pk_bf16(a[2], a[3]); w.z = cvt_pk_bf16(b[0], b[1]); w.w = cvt_pk_bf16(b[2], b[3]); return w; }
;     __device__ __forceinline__ void operator()(const f32x4 (&acc)[2][2][4][2], const Unit& u, int wr, int wc, int fr, int fq) const {
;     ...
;         for (int ai = 0; ai < 2; ++ai) { u32x4 gw[4][2], pw[4][2];
; #pragma unroll
;             for (int m = 0; m < 4; ++m) { const size_t off = (size_t)(row0 + ai * HALF + m * 16) * 2048 + col0;
; #pragma unroll
;                 for (int bj = 0; bj < 2; ++bj) { gw[m][bj] = *(const u32x4*)(G + off + bj * HALF); if (PASS == 1) pw[m][bj] = *(const u32x4*)(MIX + off + bj * HALF); } }
; #pragma unroll
;             for (int m = 0; m < 4; ++m) { const size_t off = (size_t)(row0 + ai * HALF + m * 16) * 2048 + col0;
; #pragma unroll
;                 for (int bj = 0; bj < 2; ++bj) { const u32x4 g4 = gw[m][bj];
;                     f32x4 v0 = (f32x4){bf_lo(g4.x), bf_hi(g4.x), bf_lo(g4.y), bf_hi(g4.y)} * acc[ai][bj][m][0], v1 = (f32x4){bf_lo(g4.z), bf_hi(g4.z), bf_lo(g4.w), bf_hi(g4.w)} * acc[ai][bj][m][1];
;                     if (PASS == 1) { const u32x4 p4 = pw[m][bj]; v0 += (f32x4){bf_lo(p4.x), bf_hi(p4.x), bf_lo(p4.y), bf_hi(p4.y)}; v1 += (f32x4){bf_lo(p4.z), bf_hi(p4.z), bf_lo(p4.w), bf_hi(p4.w)}; }
;                     *(u32x4*)(MIX + off + bj * HALF) = pack8(v0, v1); } } }
; template <class Epi, class Sched, bool ALIGN_EPI = false, bool SP2 = false>
; __device__ __forceinline__ void gemm_phase(PG8_LAS unsigned char* lds, const Gemm g, const Sched& S, const Epi& E) {
;     ...
;         for (int t = 0; t < nt; t += 2) {
;             const bool last = (t == nt - 2);
;             const char* a1 = cA + (size_t)(t + 1) * kstep;
;             const char* a2 = last ? nA : cA + (size_t)(t + 2) * kstep; const char* b2 = last ? nB : cB + (size_t)(t + 2) * kstep;
	s_add_i32 s61, s61, 2
	s_add_u32 s38, s38, 0x100
	s_addc_u32 s39, s39, 0
	s_add_u32 s59, s59, 0x100
	s_addc_u32 s60, s60, 0
	s_cmp_gt_u32 s61, 13
	s_cbranch_scc0 .LBB0_755
	v_lshl_add_u32 v168, s36, 8, v174
	v_lshl_or_b32 v166, s56, 8, v176
	v_ashrrev_i32_e32 v169, 31, v168
	v_ashrrev_i32_e32 v167, 31, v166
	v_lshlrev_b64 v[128:129], 11, v[168:169]
	v_lshl_add_u64 v[128:129], v[128:129], 0, v[166:167]
	v_lshlrev_b64 v[128:129], 1, v[128:129]
	v_lshl_add_u64 v[130:131], s[12:13], 0, v[128:129]
	global_load_dwordx4 v[180:183], v[130:131], off
	v_lshl_add_u64 v[128:129], s[14:15], 0, v[128:129]
	v_or_b32_e32 v212, 16, v168
	global_load_dwordx4 v[184:187], v[128:129], off
	global_load_dwordx4 v[188:191], v[130:131], off offset:256
	global_load_dwordx4 v[192:195], v[128:129], off offset:256
	v_ashrrev_i32_e32 v213, 31, v212
	v_lshlrev_b64 v[128:129], 11, v[212:213]
	v_lshl_add_u64 v[128:129], v[128:129], 0, v[166:167]
	v_lshlrev_b64 v[128:129], 1, v[128:129]
	v_lshl_add_u64 v[130:131], s[12:13], 0, v[128:129]
	v_lshl_add_u64 v[128:129], s[14:15], 0, v[128:129]
	global_load_dwordx4 v[196:199], v[130:131], off
	global_load_dwordx4 v[200:203], v[128:129], off
	v_or_b32_e32 v172, 32, v168
	v_or_b32_e32 v170, 48, v168
	v_ashrrev_i32_e32 v173, 31, v172
	v_ashrrev_i32_e32 v171, 31, v170
	v_lshlrev_b64 v[132:133], 12, v[168:169]
	v_lshlrev_b64 v[134:135], 11, v[172:173]
	v_lshlrev_b64 v[136:137], 11, v[170:171]
	v_lshlrev_b64 v[164:165], 1, v[166:167]
	v_lshl_add_u64 v[132:133], s[14:15], 0, v[132:133]
	v_lshl_add_u64 v[134:135], v[134:135], 0, v[166:167]
	v_lshl_add_u64 v[136:137], v[136:137], 0, v[166:167]
	v_lshl_add_u64 v[218:219], v[132:133], 0, v[164:165]
	v_lshlrev_b64 v[132:133], 1, v[134:135]
	v_lshlrev_b64 v[134:135], 1, v[136:137]
	v_lshl_add_u64 v[136:137], s[12:13], 0, v[132:133]
	v_lshl_add_u64 v[132:133], s[14:15], 0, v[132:133]
	v_lshl_add_u64 v[138:139], s[12:13], 0, v[134:135]
	v_lshl_add_u64 v[230:231], s[14:15], 0, v[134:135]
	global_load_dwordx4 v[204:207], v[130:131], off offset:256
	global_load_dwordx4 v[208:211], v[128:129], off offset:256
	global_load_dwordx4 v[214:217], v[136:137], off
	global_load_dwordx4 v[222:225], v[136:137], off offset:256
	global_load_dwordx4 v[232:235], v[132:133], off
	global_load_dwordx4 v[144:147], v[132:133], off offset:256
	global_load_dwordx4 v[140:143], v[138:139], off
	s_nop 0
	global_load_dwordx4 v[132:135], v[138:139], off offset:256
	s_nop 0
	global_load_dwordx4 v[136:139], v[230:231], off
	global_load_dwordx4 v[128:131], v[230:231], off offset:256
	s_and_b64 vcc, exec, s[10:11]
	s_mov_b32 s56, s26
	s_mov_b32 s36, s28
	s_mov_b64 s[40:41], s[34:35]
	s_mov_b64 s[38:39], s[30:31]
	s_waitcnt vmcnt(0)
	v_lshlrev_b32_e32 v230, 16, v180
	v_and_b32_e32 v231, 0xffff0000, v180
	v_lshlrev_b32_e32 v180, 16, v181
	v_and_b32_e32 v181, 0xffff0000, v181
	v_lshlrev_b32_e32 v236, 16, v182
	v_and_b32_e32 v237, 0xffff0000, v182
	v_lshlrev_b32_e32 v182, 16, v183
	v_and_b32_e32 v183, 0xffff0000, v183
	v_lshlrev_b32_e32 v238, 16, v184
	v_and_b32_e32 v239, 0xffff0000, v184
	v_lshlrev_b32_e32 v184, 16, v185
	v_and_b32_e32 v185, 0xffff0000, v185
	v_lshlrev_b32_e32 v240, 16, v186
	v_and_b32_e32 v241, 0xffff0000, v186
	v_lshlrev_b32_e32 v186, 16, v187
	v_and_b32_e32 v187, 0xffff0000, v187
	v_lshlrev_b32_e32 v242, 16, v188
	v_and_b32_e32 v243, 0xffff0000, v188
	v_lshlrev_b32_e32 v188, 16, v189
	v_and_b32_e32 v189, 0xffff0000, v189
	v_lshlrev_b32_e32 v246, 16, v192
	v_and_b32_e32 v247, 0xffff0000, v192
	v_lshlrev_b32_e32 v192, 16, v193
	v_and_b32_e32 v193, 0xffff0000, v193
	v_pk_fma_f32 v[126:127], v[126:127], v[180:181], v[184:185]
	v_pk_fma_f32 v[124:125], v[124:125], v[230:231], v[238:239]
	v_pk_fma_f32 v[122:123], v[122:123], v[182:183], v[186:187]
	v_pk_fma_f32 v[120:121], v[120:121], v[236:237], v[240:241]
	v_pk_fma_f32 v[180:181], v[118:119], v[188:189], v[192:193]
	v_pk_fma_f32 v[182:183], v[116:117], v[242:243], v[246:247]
	v_cvt_pk_bf16_f32 v116, v124, v125
	v_cvt_pk_bf16_f32 v117, v126, v127
	v_cvt_pk_bf16_f32 v118, v120, v121
	v_cvt_pk_bf16_f32 v119, v122, v123
	v_lshlrev_b32_e32 v244, 16, v190
	v_and_b32_e32 v245, 0xffff0000, v190
	v_lshlrev_b32_e32 v190, 16, v191
	v_and_b32_e32 v191, 0xffff0000, v191
	v_lshlrev_b32_e32 v248, 16, v194
	global_store_dwordx4 v[218:219], v[116:119], off
	v_and_b32_e32 v249, 0xffff0000, v194
	v_lshlrev_b32_e32 v122, 16, v200
	v_lshlrev_b32_e32 v116, 16, v195
	v_and_b32_e32 v117, 0xffff0000, v195
	v_pk_fma_f32 v[116:117], v[114:115], v[190:191], v[116:117]
	v_pk_fma_f32 v[114:115], v[112:113], v[244:245], v[248:249]
	v_cvt_pk_bf16_f32 v112, v182, v183
	v_cvt_pk_bf16_f32 v113, v180, v181
	v_cvt_pk_bf16_f32 v114, v114, v115
	v_cvt_pk_bf16_f32 v115, v116, v117
	global_store_dwordx4 v[218:219], v[112:115], off offset:256
	v_lshlrev_b32_e32 v116, 16, v197
	v_and_b32_e32 v117, 0xffff0000, v197
	v_lshlrev_b32_e32 v114, 16, v196
	v_and_b32_e32 v115, 0xffff0000, v196
	v_and_b32_e32 v123, 0xffff0000, v200
	v_lshlrev_b32_e32 v124, 16, v201
	v_and_b32_e32 v125, 0xffff0000, v201
	v_lshlrev_b64 v[112:113], 12, v[212:213]
	v_lshlrev_b32_e32 v118, 16, v198
	v_and_b32_e32 v119, 0xffff0000, v198
	v_lshlrev_b32_e32 v120, 16, v199
	v_and_b32_e32 v121, 0xffff0000, v199
	v_pk_fma_f32 v[110:111], v[110:111], v[116:117], v[124:125]
	v_pk_fma_f32 v[108:109], v[108:109], v[114:115], v[122:123]
	v_lshlrev_b32_e32 v114, 16, v202
	v_and_b32_e32 v115, 0xffff0000, v202
	v_lshlrev_b32_e32 v116, 16, v203
	v_and_b32_e32 v117, 0xffff0000, v203
	v_pk_fma_f32 v[116:117], v[106:107], v[120:121], v[116:117]
	v_pk_fma_f32 v[106:107], v[104:105], v[118:119], v[114:115]
	v_cvt_pk_bf16_f32 v104, v108, v109
; __device__ __forceinline__ float bf_lo(unsigned w) { return __uint_as_float(w << 16); }
; __device__ __forceinline__ float bf_hi(unsigned w) { return __uint_as_float(w & 0xffff0000u); }
; __device__ __forceinline__ u32x4 pack8(const f32x4 a, const f32x4 b) { u32x4 w; w.x = cvt_pk_bf16(a[0], a[1]); w.y = cvt_pk_bf16(a[2], a[3]); w.z = cvt_pk_bf16(b[0], b[1]); w.w = cvt_pk_bf16(b[2], b[3]); return w; }
;     __device__ __forceinline__ void operator()(const f32x4 (&acc)[2][2][4][2], const Unit& u, int wr, int wc, int fr, int fq) const {
;     ...
;         for (int ai = 0; ai < 2; ++ai) { u32x4 gw[4][2], pw[4][2];
; #pragma unroll
;             for (int m = 0; m < 4; ++m) { const size_t off = (size_t)(row0 + ai * HALF + m * 16) * 2048 + col0;
; #pragma unroll
;                 for (int bj = 0; bj < 2; ++bj) { gw[m][bj] = *(const u32x4*)(G + off + bj * HALF); if (PASS == 1) pw[m][bj] = *(const u32x4*)(MIX + off + bj * HALF); } }
; #pragma unroll
;             for (int m = 0; m < 4; ++m) { const size_t off = (size_t)(row0 + ai * HALF + m * 16) * 2048 + col0;
; #pragma unroll
;                 for (int bj = 0; bj < 2; ++bj) { const u32x4 g4 = gw[m][bj];
;                     f32x4 v0 = (f32x4){bf_lo(g4.x), bf_hi(g4.x), bf_lo(g4.y), bf_hi(g4.y)} * acc[ai][bj][m][0], v1 = (f32x4){bf_lo(g4.z), bf_hi(g4.z), bf_lo(g4.w), bf_hi(g4.w)} * acc[ai][bj][m][1];
;                     if (PASS == 1) { const u32x4 p4 = pw[m][bj]; v0 += (f32x4){bf_lo(p4.x), bf_hi(p4.x), bf_lo(p4.y), bf_hi(p4.y)}; v1 += (f32x4){bf_lo(p4.z), bf_hi(p4.z), bf_lo(p4.w), bf_hi(p4.w)}; }
;                     *(u32x4*)(MIX + off + bj * HALF) = pack8(v0, v1); } } }
	v_lshl_add_u64 v[108:109], s[14:15], 0, v[112:113]
	v_cvt_pk_bf16_f32 v105, v110, v111
	v_cvt_pk_bf16_f32 v106, v106, v107
	v_cvt_pk_bf16_f32 v107, v116, v117
	v_lshl_add_u64 v[108:109], v[108:109], 0, v[164:165]
	global_store_dwordx4 v[108:109], v[104:107], off
	v_lshlrev_b32_e32 v114, 16, v208
	v_and_b32_e32 v115, 0xffff0000, v208
	v_lshlrev_b32_e32 v104, 16, v204
	v_and_b32_e32 v105, 0xffff0000, v204
	v_lshlrev_b32_e32 v106, 16, v205
	v_and_b32_e32 v107, 0xffff0000, v205
	v_lshlrev_b32_e32 v116, 16, v209
	v_and_b32_e32 v117, 0xffff0000, v209
	v_lshlrev_b32_e32 v110, 16, v206
	v_and_b32_e32 v111, 0xffff0000, v206
	v_lshlrev_b32_e32 v112, 16, v207
	v_and_b32_e32 v113, 0xffff0000, v207
	v_pk_fma_f32 v[102:103], v[102:103], v[106:107], v[116:117]
	v_pk_fma_f32 v[100:101], v[100:101], v[104:105], v[114:115]
	v_lshlrev_b32_e32 v104, 16, v210
	v_and_b32_e32 v105, 0xffff0000, v210
	v_lshlrev_b32_e32 v106, 16, v211
	v_and_b32_e32 v107, 0xffff0000, v211
	v_pk_fma_f32 v[106:107], v[98:99], v[112:113], v[106:107]
	v_pk_fma_f32 v[98:99], v[96:97], v[110:111], v[104:105]
	v_cvt_pk_bf16_f32 v96, v100, v101
	v_cvt_pk_bf16_f32 v97, v102, v103
	v_cvt_pk_bf16_f32 v98, v98, v99
	v_cvt_pk_bf16_f32 v99, v106, v107
	global_store_dwordx4 v[108:109], v[96:99], off offset:256
	v_lshlrev_b32_e32 v100, 16, v215
	v_and_b32_e32 v101, 0xffff0000, v215
	v_lshlrev_b32_e32 v98, 16, v214
	v_and_b32_e32 v99, 0xffff0000, v214
	v_lshlrev_b32_e32 v106, 16, v232
	v_and_b32_e32 v107, 0xffff0000, v232
	v_lshlrev_b32_e32 v108, 16, v233
	v_and_b32_e32 v109, 0xffff0000, v233
	v_lshlrev_b64 v[96:97], 12, v[172:173]
	v_lshlrev_b32_e32 v102, 16, v216
	v_and_b32_e32 v103, 0xffff0000, v216
	v_lshlrev_b32_e32 v104, 16, v217
	v_and_b32_e32 v105, 0xffff0000, v217
	v_pk_fma_f32 v[94:95], v[94:95], v[100:101], v[108:109]
	v_pk_fma_f32 v[92:93], v[92:93], v[98:99], v[106:107]
	v_lshlrev_b32_e32 v98, 16, v234
	v_and_b32_e32 v99, 0xffff0000, v234
	v_lshlrev_b32_e32 v100, 16, v235
	v_and_b32_e32 v101, 0xffff0000, v235
	v_pk_fma_f32 v[100:101], v[90:91], v[104:105], v[100:101]
	v_pk_fma_f32 v[90:91], v[88:89], v[102:103], v[98:99]
	v_cvt_pk_bf16_f32 v88, v92, v93
	v_lshl_add_u64 v[92:93], s[14:15], 0, v[96:97]
	v_cvt_pk_bf16_f32 v89, v94, v95
	v_cvt_pk_bf16_f32 v90, v90, v91
	v_cvt_pk_bf16_f32 v91, v100, v101
	v_lshl_add_u64 v[92:93], v[92:93], 0, v[164:165]
	global_store_dwordx4 v[92:93], v[88:91], off
	v_lshlrev_b32_e32 v98, 16, v144
	v_and_b32_e32 v99, 0xffff0000, v144
	v_lshlrev_b32_e32 v88, 16, v222
	v_and_b32_e32 v89, 0xffff0000, v222
	v_lshlrev_b32_e32 v90, 16, v223
	v_and_b32_e32 v91, 0xffff0000, v223
	v_lshlrev_b32_e32 v100, 16, v145
	v_and_b32_e32 v101, 0xffff0000, v145
	v_lshlrev_b32_e32 v94, 16, v224
	v_and_b32_e32 v95, 0xffff0000, v224
	v_lshlrev_b32_e32 v96, 16, v225
	v_and_b32_e32 v97, 0xffff0000, v225
	v_pk_fma_f32 v[86:87], v[86:87], v[90:91], v[100:101]
	v_pk_fma_f32 v[84:85], v[84:85], v[88:89], v[98:99]
	v_lshlrev_b32_e32 v88, 16, v146
	v_and_b32_e32 v89, 0xffff0000, v146
	v_lshlrev_b32_e32 v90, 16, v147
	v_and_b32_e32 v91, 0xffff0000, v147
	v_pk_fma_f32 v[90:91], v[82:83], v[96:97], v[90:91]
	v_pk_fma_f32 v[82:83], v[80:81], v[94:95], v[88:89]
	v_cvt_pk_bf16_f32 v80, v84, v85
	v_cvt_pk_bf16_f32 v81, v86, v87
	v_cvt_pk_bf16_f32 v82, v82, v83
	v_cvt_pk_bf16_f32 v83, v90, v91
	global_store_dwordx4 v[92:93], v[80:83], off offset:256
	v_lshlrev_b32_e32 v84, 16, v141
	v_and_b32_e32 v85, 0xffff0000, v141
	v_lshlrev_b32_e32 v82, 16, v140
	v_and_b32_e32 v83, 0xffff0000, v140
	v_lshlrev_b32_e32 v90, 16, v136
	v_and_b32_e32 v91, 0xffff0000, v136
	v_lshlrev_b32_e32 v92, 16, v137
	v_and_b32_e32 v93, 0xffff0000, v137
	v_lshlrev_b64 v[80:81], 12, v[170:171]
	v_lshlrev_b32_e32 v86, 16, v142
	v_and_b32_e32 v87, 0xffff0000, v142
	v_lshlrev_b32_e32 v88, 16, v143
	v_and_b32_e32 v89, 0xffff0000, v143
	v_pk_fma_f32 v[78:79], v[78:79], v[84:85], v[92:93]
	v_pk_fma_f32 v[76:77], v[76:77], v[82:83], v[90:91]
	v_lshlrev_b32_e32 v82, 16, v138
	v_and_b32_e32 v83, 0xffff0000, v138
	v_lshlrev_b32_e32 v84, 16, v139
	v_and_b32_e32 v85, 0xffff0000, v139
	v_pk_fma_f32 v[84:85], v[74:75], v[88:89], v[84:85]
	v_pk_fma_f32 v[74:75], v[72:73], v[86:87], v[82:83]
	v_cvt_pk_bf16_f32 v72, v76, v77
	v_lshl_add_u64 v[76:77], s[14:15], 0, v[80:81]
	v_cvt_pk_bf16_f32 v73, v78, v79
	v_cvt_pk_bf16_f32 v74, v74, v75
	v_cvt_pk_bf16_f32 v75, v84, v85
	v_lshl_add_u64 v[76:77], v[76:77], 0, v[164:165]
	global_store_dwordx4 v[76:77], v[72:75], off
	v_lshlrev_b32_e32 v82, 16, v128
	v_and_b32_e32 v83, 0xffff0000, v128
	v_lshlrev_b32_e32 v72, 16, v132
	v_and_b32_e32 v73, 0xffff0000, v132
	v_lshlrev_b32_e32 v74, 16, v133
	v_and_b32_e32 v75, 0xffff0000, v133
	v_lshlrev_b32_e32 v84, 16, v129
	v_and_b32_e32 v85, 0xffff0000, v129
	v_lshlrev_b32_e32 v78, 16, v134
	v_and_b32_e32 v79, 0xffff0000, v134
	v_lshlrev_b32_e32 v80, 16, v135
	v_and_b32_e32 v81, 0xffff0000, v135
	v_pk_fma_f32 v[70:71], v[70:71], v[74:75], v[84:85]
	v_pk_fma_f32 v[68:69], v[68:69], v[72:73], v[82:83]
	v_lshlrev_b32_e32 v72, 16, v130
	v_and_b32_e32 v73, 0xffff0000, v130
	v_lshlrev_b32_e32 v74, 16, v131
	v_and_b32_e32 v75, 0xffff0000, v131
	v_pk_fma_f32 v[74:75], v[66:67], v[80:81], v[74:75]
	v_pk_fma_f32 v[66:67], v[64:65], v[78:79], v[72:73]
	v_add_u32_e32 v130, 0x80, v168
	v_cvt_pk_bf16_f32 v64, v68, v69
	v_cvt_pk_bf16_f32 v65, v70, v71
	v_cvt_pk_bf16_f32 v66, v66, v67
	v_cvt_pk_bf16_f32 v67, v74, v75
	v_ashrrev_i32_e32 v131, 31, v130
	global_store_dwordx4 v[76:77], v[64:67], off offset:256
	v_add_u32_e32 v132, 0x90, v168
	v_ashrrev_i32_e32 v133, 31, v132
	v_lshlrev_b64 v[64:65], 11, v[130:131]
	v_lshl_add_u64 v[64:65], v[64:65], 0, v[166:167]
; __device__ __forceinline__ float bf_lo(unsigned w) { return __uint_as_float(w << 16); }
; __device__ __forceinline__ float bf_hi(unsigned w) { return __uint_as_float(w & 0xffff0000u); }
; __device__ __forceinline__ u32x4 pack8(const f32x4 a, const f32x4 b) { u32x4 w; w.x = cvt_pk_bf16(a[0], a[1]); w.y = cvt_pk_bf16(a[2], a[3]); w.z = cvt_pk_bf16(b[0], b[1]); w.w = cvt_pk_bf16(b[2], b[3]); return w; }
;     __device__ __forceinline__ void operator()(const f32x4 (&acc)[2][2][4][2], const Unit& u, int wr, int wc, int fr, int fq) const {
;     ...
;         for (int ai = 0; ai < 2; ++ai) { u32x4 gw[4][2], pw[4][2];
; #pragma unroll
;             for (int m = 0; m < 4; ++m) { const size_t off = (size_t)(row0 + ai * HALF + m * 16) * 2048 + col0;
; #pragma unroll
;                 for (int bj = 0; bj < 2; ++bj) { gw[m][bj] = *(const u32x4*)(G + off + bj * HALF); if (PASS == 1) pw[m][bj] = *(const u32x4*)(MIX + off + bj * HALF); } }
; #pragma unroll
;             for (int m = 0; m < 4; ++m) { const size_t off = (size_t)(row0 + ai * HALF + m * 16) * 2048 + col0;
; #pragma unroll
;                 for (int bj = 0; bj < 2; ++bj) { const u32x4 g4 = gw[m][bj];
;                     f32x4 v0 = (f32x4){bf_lo(g4.x), bf_hi(g4.x), bf_lo(g4.y), bf_hi(g4.y)} * acc[ai][bj][m][0], v1 = (f32x4){bf_lo(g4.z), bf_hi(g4.z), bf_lo(g4.w), bf_hi(g4.w)} * acc[ai][bj][m][1];
;                     if (PASS == 1) { const u32x4 p4 = pw[m][bj]; v0 += (f32x4){bf_lo(p4.x), bf_hi(p4.x), bf_lo(p4.y), bf_hi(p4.y)}; v1 += (f32x4){bf_lo(p4.z), bf_hi(p4.z), bf_lo(p4.w), bf_hi(p4.w)}; }
;                     *(u32x4*)(MIX + off + bj * HALF) = pack8(v0, v1); } } }
	v_lshlrev_b64 v[64:65], 1, v[64:65]
	v_lshl_add_u64 v[66:67], s[12:13], 0, v[64:65]
	global_load_dwordx4 v[90:93], v[66:67], off
	v_lshl_add_u64 v[64:65], s[14:15], 0, v[64:65]
	global_load_dwordx4 v[94:97], v[64:65], off
	global_load_dwordx4 v[98:101], v[66:67], off offset:256
	global_load_dwordx4 v[102:105], v[64:65], off offset:256
	v_lshlrev_b64 v[64:65], 11, v[132:133]
	v_lshl_add_u64 v[64:65], v[64:65], 0, v[166:167]
	v_lshlrev_b64 v[64:65], 1, v[64:65]
	v_lshl_add_u64 v[66:67], s[12:13], 0, v[64:65]
	v_lshl_add_u64 v[64:65], s[14:15], 0, v[64:65]
	global_load_dwordx4 v[106:109], v[66:67], off
	global_load_dwordx4 v[110:113], v[66:67], off offset:256
	global_load_dwordx4 v[114:117], v[64:65], off
	global_load_dwordx4 v[118:121], v[64:65], off offset:256
	v_add_u32_e32 v134, 0xa0, v168
	v_ashrrev_i32_e32 v135, 31, v134
	v_lshlrev_b64 v[64:65], 11, v[134:135]
	v_lshl_add_u64 v[64:65], v[64:65], 0, v[166:167]
	v_lshlrev_b64 v[64:65], 1, v[64:65]
	v_lshl_add_u64 v[66:67], s[12:13], 0, v[64:65]
	v_lshl_add_u64 v[64:65], s[14:15], 0, v[64:65]
	global_load_dwordx4 v[122:125], v[66:67], off
	global_load_dwordx4 v[84:87], v[66:67], off offset:256
	global_load_dwordx4 v[126:129], v[64:65], off
	global_load_dwordx4 v[80:83], v[64:65], off offset:256
	v_add_u32_e32 v88, 0xb0, v168
	v_ashrrev_i32_e32 v89, 31, v88
	v_lshlrev_b64 v[64:65], 11, v[88:89]
	v_lshl_add_u64 v[64:65], v[64:65], 0, v[166:167]
	v_lshlrev_b64 v[64:65], 1, v[64:65]
	v_lshl_add_u64 v[66:67], s[12:13], 0, v[64:65]
	v_lshl_add_u64 v[64:65], s[14:15], 0, v[64:65]
	global_load_dwordx4 v[76:79], v[66:67], off
	global_load_dwordx4 v[68:71], v[66:67], off offset:256
	global_load_dwordx4 v[72:75], v[64:65], off
	s_nop 0
	global_load_dwordx4 v[64:67], v[64:65], off offset:256
	v_lshlrev_b64 v[130:131], 12, v[130:131]
	s_waitcnt vmcnt(15)
	v_lshlrev_b32_e32 v136, 16, v90
	v_and_b32_e32 v137, 0xffff0000, v90
	v_lshlrev_b32_e32 v90, 16, v91
	v_and_b32_e32 v91, 0xffff0000, v91
	s_waitcnt vmcnt(14)
	v_lshlrev_b32_e32 v140, 16, v94
	v_and_b32_e32 v141, 0xffff0000, v94
	v_lshlrev_b32_e32 v94, 16, v95
	v_and_b32_e32 v95, 0xffff0000, v95
	v_lshlrev_b32_e32 v138, 16, v92
	v_and_b32_e32 v139, 0xffff0000, v92
	v_lshlrev_b32_e32 v92, 16, v93
	v_and_b32_e32 v93, 0xffff0000, v93
	v_pk_fma_f32 v[62:63], v[62:63], v[90:91], v[94:95]
	v_pk_fma_f32 v[60:61], v[60:61], v[136:137], v[140:141]
	v_lshlrev_b32_e32 v90, 16, v96
	v_and_b32_e32 v91, 0xffff0000, v96
	v_lshlrev_b32_e32 v94, 16, v97
	v_and_b32_e32 v95, 0xffff0000, v97
	v_pk_fma_f32 v[92:93], v[58:59], v[92:93], v[94:95]
	v_pk_fma_f32 v[58:59], v[56:57], v[138:139], v[90:91]
	v_cvt_pk_bf16_f32 v56, v60, v61
	v_lshl_add_u64 v[60:61], s[14:15], 0, v[130:131]
	v_cvt_pk_bf16_f32 v57, v62, v63
	v_cvt_pk_bf16_f32 v58, v58, v59
	v_cvt_pk_bf16_f32 v59, v92, v93
	v_lshl_add_u64 v[60:61], v[60:61], 0, v[164:165]
	global_store_dwordx4 v[60:61], v[56:59], off
	s_waitcnt vmcnt(13)
	v_lshlrev_b32_e32 v92, 16, v102
	v_and_b32_e32 v93, 0xffff0000, v102
	v_lshlrev_b32_e32 v56, 16, v98
	v_and_b32_e32 v57, 0xffff0000, v98
	v_lshlrev_b32_e32 v58, 16, v99
	v_and_b32_e32 v59, 0xffff0000, v99
	v_lshlrev_b32_e32 v94, 16, v103
	v_and_b32_e32 v95, 0xffff0000, v103
	v_lshlrev_b32_e32 v62, 16, v100
	v_and_b32_e32 v63, 0xffff0000, v100
	v_lshlrev_b32_e32 v90, 16, v101
	v_and_b32_e32 v91, 0xffff0000, v101
	v_pk_fma_f32 v[54:55], v[54:55], v[58:59], v[94:95]
	v_pk_fma_f32 v[52:53], v[52:53], v[56:57], v[92:93]
	v_lshlrev_b32_e32 v56, 16, v104
	v_and_b32_e32 v57, 0xffff0000, v104
	v_lshlrev_b32_e32 v58, 16, v105
	v_and_b32_e32 v59, 0xffff0000, v105
	v_pk_fma_f32 v[58:59], v[50:51], v[90:91], v[58:59]
	v_pk_fma_f32 v[50:51], v[48:49], v[62:63], v[56:57]
	v_cvt_pk_bf16_f32 v48, v52, v53
	v_cvt_pk_bf16_f32 v49, v54, v55
	v_cvt_pk_bf16_f32 v50, v50, v51
	v_cvt_pk_bf16_f32 v51, v58, v59
	global_store_dwordx4 v[60:61], v[48:51], off offset:256
	s_waitcnt vmcnt(13)
	v_lshlrev_b32_e32 v52, 16, v107
	v_and_b32_e32 v53, 0xffff0000, v107
	v_lshlrev_b32_e32 v50, 16, v106
	v_and_b32_e32 v51, 0xffff0000, v106
	s_waitcnt vmcnt(11)
	v_lshlrev_b32_e32 v58, 16, v114
	v_and_b32_e32 v59, 0xffff0000, v114
	v_lshlrev_b32_e32 v60, 16, v115
	v_and_b32_e32 v61, 0xffff0000, v115
	v_lshlrev_b64 v[48:49], 12, v[132:133]
	v_lshlrev_b32_e32 v54, 16, v108
	v_and_b32_e32 v55, 0xffff0000, v108
	v_lshlrev_b32_e32 v56, 16, v109
	v_and_b32_e32 v57, 0xffff0000, v109
	v_pk_fma_f32 v[46:47], v[46:47], v[52:53], v[60:61]
	v_pk_fma_f32 v[44:45], v[44:45], v[50:51], v[58:59]
	v_lshlrev_b32_e32 v50, 16, v116
	v_and_b32_e32 v51, 0xffff0000, v116
	v_lshlrev_b32_e32 v52, 16, v117
	v_and_b32_e32 v53, 0xffff0000, v117
	v_pk_fma_f32 v[52:53], v[42:43], v[56:57], v[52:53]
	v_pk_fma_f32 v[42:43], v[40:41], v[54:55], v[50:51]
	v_cvt_pk_bf16_f32 v40, v44, v45
	v_lshl_add_u64 v[44:45], s[14:15], 0, v[48:49]
	v_cvt_pk_bf16_f32 v41, v46, v47
	v_cvt_pk_bf16_f32 v42, v42, v43
	v_cvt_pk_bf16_f32 v43, v52, v53
	v_lshl_add_u64 v[44:45], v[44:45], 0, v[164:165]
	global_store_dwordx4 v[44:45], v[40:43], off
	s_waitcnt vmcnt(11)
; __device__ __forceinline__ float bf_lo(unsigned w) { return __uint_as_float(w << 16); }
; __device__ __forceinline__ float bf_hi(unsigned w) { return __uint_as_float(w & 0xffff0000u); }
; __device__ __forceinline__ u32x4 pack8(const f32x4 a, const f32x4 b) { u32x4 w; w.x = cvt_pk_bf16(a[0], a[1]); w.y = cvt_pk_bf16(a[2], a[3]); w.z = cvt_pk_bf16(b[0], b[1]); w.w = cvt_pk_bf16(b[2], b[3]); return w; }
; #define PG8_WAIT_V(n) asm volatile("s_waitcnt vmcnt(" #n ")" ::: "memory")
; #define PG8_BAR __builtin_amdgcn_s_barrier()
;     __device__ __forceinline__ void operator()(const f32x4 (&acc)[2][2][4][2], const Unit& u, int wr, int wc, int fr, int fq) const {
;     ...
;         for (int ai = 0; ai < 2; ++ai) { u32x4 gw[4][2], pw[4][2];
; #pragma unroll
;             for (int m = 0; m < 4; ++m) { const size_t off = (size_t)(row0 + ai * HALF + m * 16) * 2048 + col0;
; #pragma unroll
;                 for (int bj = 0; bj < 2; ++bj) { gw[m][bj] = *(const u32x4*)(G + off + bj * HALF); if (PASS == 1) pw[m][bj] = *(const u32x4*)(MIX + off + bj * HALF); } }
; #pragma unroll
;             for (int m = 0; m < 4; ++m) { const size_t off = (size_t)(row0 + ai * HALF + m * 16) * 2048 + col0;
; #pragma unroll
;                 for (int bj = 0; bj < 2; ++bj) { const u32x4 g4 = gw[m][bj];
;                     f32x4 v0 = (f32x4){bf_lo(g4.x), bf_hi(g4.x), bf_lo(g4.y), bf_hi(g4.y)} * acc[ai][bj][m][0], v1 = (f32x4){bf_lo(g4.z), bf_hi(g4.z), bf_lo(g4.w), bf_hi(g4.w)} * acc[ai][bj][m][1];
;                     if (PASS == 1) { const u32x4 p4 = pw[m][bj]; v0 += (f32x4){bf_lo(p4.x), bf_hi(p4.x), bf_lo(p4.y), bf_hi(p4.y)}; v1 += (f32x4){bf_lo(p4.z), bf_hi(p4.z), bf_lo(p4.w), bf_hi(p4.w)}; }
;                     *(u32x4*)(MIX + off + bj * HALF) = pack8(v0, v1); } } }
; template <class Epi, class Sched, bool ALIGN_EPI = false, bool SP2 = false>
; __device__ __forceinline__ void gemm_phase(PG8_LAS unsigned char* lds, const Gemm g, const Sched& S, const Epi& E) {
;     ...
;     PG8_WAIT_V(0);
;     if constexpr (!ALIGN_EPI) { if (wr == 0) PG8_BAR; }
;     PG8_BAR;
	v_lshlrev_b32_e32 v50, 16, v118
	v_and_b32_e32 v51, 0xffff0000, v118
	v_lshlrev_b32_e32 v40, 16, v110
	v_and_b32_e32 v41, 0xffff0000, v110
	v_lshlrev_b32_e32 v42, 16, v111
	v_and_b32_e32 v43, 0xffff0000, v111
	v_lshlrev_b32_e32 v52, 16, v119
	v_and_b32_e32 v53, 0xffff0000, v119
	v_lshlrev_b32_e32 v46, 16, v112
	v_and_b32_e32 v47, 0xffff0000, v112
	v_lshlrev_b32_e32 v48, 16, v113
	v_and_b32_e32 v49, 0xffff0000, v113
	v_pk_fma_f32 v[38:39], v[38:39], v[42:43], v[52:53]
	v_pk_fma_f32 v[36:37], v[36:37], v[40:41], v[50:51]
	v_lshlrev_b32_e32 v40, 16, v120
	v_and_b32_e32 v41, 0xffff0000, v120
	v_lshlrev_b32_e32 v42, 16, v121
	v_and_b32_e32 v43, 0xffff0000, v121
	v_pk_fma_f32 v[42:43], v[34:35], v[48:49], v[42:43]
	v_pk_fma_f32 v[34:35], v[32:33], v[46:47], v[40:41]
	v_cvt_pk_bf16_f32 v32, v36, v37
	v_cvt_pk_bf16_f32 v33, v38, v39
	v_cvt_pk_bf16_f32 v34, v34, v35
	v_cvt_pk_bf16_f32 v35, v42, v43
	global_store_dwordx4 v[44:45], v[32:35], off offset:256
	s_waitcnt vmcnt(11)
	v_lshlrev_b32_e32 v36, 16, v123
	v_and_b32_e32 v37, 0xffff0000, v123
	v_lshlrev_b32_e32 v34, 16, v122
	v_and_b32_e32 v35, 0xffff0000, v122
	s_waitcnt vmcnt(9)
	v_lshlrev_b32_e32 v42, 16, v126
	v_and_b32_e32 v43, 0xffff0000, v126
	v_lshlrev_b32_e32 v44, 16, v127
	v_and_b32_e32 v45, 0xffff0000, v127
	v_lshlrev_b64 v[32:33], 12, v[134:135]
	v_lshlrev_b32_e32 v38, 16, v124
	v_and_b32_e32 v39, 0xffff0000, v124
	v_lshlrev_b32_e32 v40, 16, v125
	v_and_b32_e32 v41, 0xffff0000, v125
	v_pk_fma_f32 v[30:31], v[30:31], v[36:37], v[44:45]
	v_pk_fma_f32 v[28:29], v[28:29], v[34:35], v[42:43]
	v_lshlrev_b32_e32 v34, 16, v128
	v_and_b32_e32 v35, 0xffff0000, v128
	v_lshlrev_b32_e32 v36, 16, v129
	v_and_b32_e32 v37, 0xffff0000, v129
	v_pk_fma_f32 v[36:37], v[26:27], v[40:41], v[36:37]
	v_pk_fma_f32 v[26:27], v[24:25], v[38:39], v[34:35]
	v_cvt_pk_bf16_f32 v24, v28, v29
	v_lshl_add_u64 v[28:29], s[14:15], 0, v[32:33]
	v_cvt_pk_bf16_f32 v25, v30, v31
	v_cvt_pk_bf16_f32 v26, v26, v27
	v_cvt_pk_bf16_f32 v27, v36, v37
	v_lshl_add_u64 v[28:29], v[28:29], 0, v[164:165]
	global_store_dwordx4 v[28:29], v[24:27], off
	s_waitcnt vmcnt(9)
	v_lshlrev_b32_e32 v34, 16, v80
	v_and_b32_e32 v35, 0xffff0000, v80
	v_lshlrev_b32_e32 v24, 16, v84
	v_and_b32_e32 v25, 0xffff0000, v84
	v_lshlrev_b32_e32 v26, 16, v85
	v_and_b32_e32 v27, 0xffff0000, v85
	v_lshlrev_b32_e32 v36, 16, v81
	v_and_b32_e32 v37, 0xffff0000, v81
	v_lshlrev_b32_e32 v30, 16, v86
	v_and_b32_e32 v31, 0xffff0000, v86
	v_lshlrev_b32_e32 v32, 16, v87
	v_and_b32_e32 v33, 0xffff0000, v87
	v_pk_fma_f32 v[22:23], v[22:23], v[26:27], v[36:37]
	v_pk_fma_f32 v[20:21], v[20:21], v[24:25], v[34:35]
	v_lshlrev_b32_e32 v24, 16, v82
	v_and_b32_e32 v25, 0xffff0000, v82
	v_lshlrev_b32_e32 v26, 16, v83
	v_and_b32_e32 v27, 0xffff0000, v83
	v_pk_fma_f32 v[26:27], v[18:19], v[32:33], v[26:27]
	v_pk_fma_f32 v[18:19], v[16:17], v[30:31], v[24:25]
	v_cvt_pk_bf16_f32 v16, v20, v21
	v_cvt_pk_bf16_f32 v17, v22, v23
	v_cvt_pk_bf16_f32 v18, v18, v19
	v_cvt_pk_bf16_f32 v19, v26, v27
	global_store_dwordx4 v[28:29], v[16:19], off offset:256
	s_waitcnt vmcnt(9)
	v_lshlrev_b32_e32 v20, 16, v77
	v_and_b32_e32 v21, 0xffff0000, v77
	v_lshlrev_b32_e32 v18, 16, v76
	v_and_b32_e32 v19, 0xffff0000, v76
	s_waitcnt vmcnt(7)
	v_lshlrev_b32_e32 v26, 16, v72
	v_and_b32_e32 v27, 0xffff0000, v72
	v_lshlrev_b32_e32 v28, 16, v73
	v_and_b32_e32 v29, 0xffff0000, v73
	v_lshlrev_b64 v[16:17], 12, v[88:89]
	v_lshlrev_b32_e32 v22, 16, v78
	v_and_b32_e32 v23, 0xffff0000, v78
	v_lshlrev_b32_e32 v24, 16, v79
	v_and_b32_e32 v25, 0xffff0000, v79
	v_pk_fma_f32 v[14:15], v[14:15], v[20:21], v[28:29]
	v_pk_fma_f32 v[12:13], v[12:13], v[18:19], v[26:27]
	v_lshlrev_b32_e32 v18, 16, v74
	v_and_b32_e32 v19, 0xffff0000, v74
	v_lshlrev_b32_e32 v20, 16, v75
	v_and_b32_e32 v21, 0xffff0000, v75
	v_pk_fma_f32 v[20:21], v[10:11], v[24:25], v[20:21]
	v_pk_fma_f32 v[10:11], v[8:9], v[22:23], v[18:19]
	v_cvt_pk_bf16_f32 v8, v12, v13
	v_lshl_add_u64 v[12:13], s[14:15], 0, v[16:17]
	v_cvt_pk_bf16_f32 v9, v14, v15
	v_cvt_pk_bf16_f32 v10, v10, v11
	v_cvt_pk_bf16_f32 v11, v20, v21
	v_lshl_add_u64 v[12:13], v[12:13], 0, v[164:165]
	global_store_dwordx4 v[12:13], v[8:11], off
	s_waitcnt vmcnt(7)
	v_lshlrev_b32_e32 v18, 16, v64
	v_and_b32_e32 v19, 0xffff0000, v64
	v_lshlrev_b32_e32 v8, 16, v68
	v_and_b32_e32 v9, 0xffff0000, v68
	v_lshlrev_b32_e32 v10, 16, v69
	v_and_b32_e32 v11, 0xffff0000, v69
	v_lshlrev_b32_e32 v20, 16, v65
	v_and_b32_e32 v21, 0xffff0000, v65
	v_lshlrev_b32_e32 v14, 16, v70
	v_and_b32_e32 v15, 0xffff0000, v70
	v_lshlrev_b32_e32 v16, 16, v71
	v_and_b32_e32 v17, 0xffff0000, v71
	v_pk_fma_f32 v[6:7], v[6:7], v[10:11], v[20:21]
	v_pk_fma_f32 v[4:5], v[4:5], v[8:9], v[18:19]
	v_lshlrev_b32_e32 v8, 16, v66
	v_and_b32_e32 v9, 0xffff0000, v66
	v_lshlrev_b32_e32 v10, 16, v67
	v_and_b32_e32 v11, 0xffff0000, v67
	v_pk_fma_f32 v[10:11], v[2:3], v[16:17], v[10:11]
	v_pk_fma_f32 v[2:3], v[0:1], v[14:15], v[8:9]
	v_cvt_pk_bf16_f32 v0, v4, v5
	v_cvt_pk_bf16_f32 v1, v6, v7
	v_cvt_pk_bf16_f32 v2, v2, v3
	v_cvt_pk_bf16_f32 v3, v10, v11
	global_store_dwordx4 v[12:13], v[0:3], off offset:256
	s_cbranch_vccz .LBB0_748
	s_waitcnt vmcnt(0)
	s_cmpk_gt_u32 s3, 0xff
	s_cbranch_scc1 .LBB0_759
	s_barrier

; #define PG8_STAGE(bufoff, gbase, voff) do { _Pragma("unroll") for (int _i = 0; _i < 2; ++_i) \
;         __builtin_amdgcn_global_load_lds((const unsigned*)((const char*)(gbase) + (voff)[_i]), (PG8_LAS unsigned*)(lds + (bufoff) + ldsw + _i * 8192), 16, 0, 0); } while (0)
; #define PG8_LDA(dst, b, h) do { _Pragma("unroll") for (int m = 0; m < 4; ++m) _Pragma("unroll") for (int k = 0; k < 2; ++k) dst[m][k] = *(const PG8_LAS bf16x8*)(lds + PG8_SA(b, h) + aoff + m * 2048 + k * 1024); } while (0)
; #define PG8_LDB(dst, b, h) do { _Pragma("unroll") for (int n = 0; n < 2; ++n) _Pragma("unroll") for (int k = 0; k < 2; ++k) dst[n][k] = *(const PG8_LAS bf16x8*)(lds + PG8_SB(b, h) + boff + n * 2048 + k * 1024); } while (0)
; #define PG8_MMA(ai, bj, At, Bt) do { __builtin_amdgcn_s_setprio(1); _Pragma("unroll") for (int m = 0; m < 4; ++m) _Pragma("unroll") for (int n = 0; n < 2; ++n) _Pragma("unroll") for (int k = 0; k < 2; ++k) \
;         acc[ai][bj][m][n] = __builtin_amdgcn_mfma_f32_16x16x32_bf16(Bt[n][k], At[m][k], acc[ai][bj][m][n], 0, 0, 0); __builtin_amdgcn_s_setprio(0); } while (0)
; #define PG8_WAIT_V(n) asm volatile("s_waitcnt vmcnt(" #n ")" ::: "memory")
; #define PG8_BAR __builtin_amdgcn_s_barrier()
; template <class Epi, class Sched, bool ALIGN_EPI = false, bool SP2 = false>
; __device__ __forceinline__ void gemm_phase(PG8_LAS unsigned char* lds, const Gemm g, const Sched& S, const Epi& E) {
;     ...
;         for (int t = 0; t < nt; t += 2) {
;             const bool last = (t == nt - 2);
;             const char* a1 = cA + (size_t)(t + 1) * kstep;
;             const char* a2 = last ? nA : cA + (size_t)(t + 2) * kstep; const char* b2 = last ? nB : cB + (size_t)(t + 2) * kstep;
;             const char* a3 = a2 + kstep; const char* b3 = b2 + kstep;
;             if (last && has_next) S.a_ready(nxt);
;             if constexpr (SP2) {
;             PG8_LDB(B0, 0, 0); PG8_LDB(B1, 0, 1); PG8_SCHED; PG8_LDA(At, 0, 0); PG8_STAGE(PG8_SA(1, 1), a1 + hstep, voffA);
;             PG8_WAIT_V(8); PG8_WAIT_L(0); PG8_BAR; PG8_MMA(0, 0, At, B0); PG8_MMA(0, 1, At, B1); PG8_BAR; PG8_SCHED;
;             PG8_LDA(At, 0, 1); PG8_STAGE(PG8_SB(0, 0), b2, voffB); PG8_STAGE(PG8_SB(0, 1), b2 + hstep, voffB); PG8_STAGE(PG8_SA(0, 0), a2, voffA);
;             PG8_WAIT_V(8); PG8_WAIT_L(0); PG8_BAR; PG8_MMA(1, 0, At, B0); PG8_MMA(1, 1, At, B1); PG8_BAR; PG8_SCHED;
.LBB0_827:
	ds_read_b128 v[128:131], v169
	ds_read_b128 v[132:135], v169 offset:1024
	ds_read_b128 v[136:139], v169 offset:2048
	ds_read_b128 v[140:143], v169 offset:3072
	ds_read_b128 v[160:163], v170
	ds_read_b128 v[172:175], v170 offset:1024
	ds_read_b128 v[176:179], v170 offset:2048
	ds_read_b128 v[180:183], v170 offset:3072
	s_add_u32 s48, s46, 0xfff80080
	s_addc_u32 s49, s47, -1
	s_cmp_eq_u32 s71, 28
	s_cselect_b32 s51, s39, s49
	s_cselect_b32 s50, s67, s48
	s_cselect_b32 s49, s37, s70
	s_cselect_b32 s48, s68, s69
	s_add_i32 m0, s45, 0xc000
	ds_read_b128 v[184:187], v171
	ds_read_b128 v[188:191], v171 offset:1024
	ds_read_b128 v[192:195], v171 offset:2048
	ds_read_b128 v[196:199], v171 offset:3072
	ds_read_b128 v[200:203], v171 offset:4096
	ds_read_b128 v[204:207], v171 offset:5120
	ds_read_b128 v[208:211], v171 offset:6144
	ds_read_b128 v[214:217], v171 offset:7168
	global_load_lds_dwordx4 v152, s[46:47]
	s_add_i32 m0, s45, 0xe000
	s_nop 0
	global_load_lds_dwordx4 v154, s[46:47]
	s_waitcnt vmcnt(8)
	s_waitcnt lgkmcnt(0)
	s_barrier
	s_setprio 1
	s_waitcnt lgkmcnt(0)
	v_mfma_f32_16x16x32_bf16 v[124:127], v[128:131], v[184:187], v[124:127]
	v_mfma_f32_16x16x32_bf16 v[120:123], v[136:139], v[184:187], v[120:123]
	v_mfma_f32_16x16x32_bf16 v[116:119], v[128:131], v[192:195], v[116:119]
	v_mfma_f32_16x16x32_bf16 v[112:115], v[136:139], v[192:195], v[112:115]
	v_mfma_f32_16x16x32_bf16 v[108:111], v[128:131], v[200:203], v[108:111]
	v_mfma_f32_16x16x32_bf16 v[96:99], v[136:139], v[200:203], v[96:99]
	v_mfma_f32_16x16x32_bf16 v[80:83], v[128:131], v[208:211], v[80:83]
	v_mfma_f32_16x16x32_bf16 v[72:75], v[136:139], v[208:211], v[72:75]
	v_mfma_f32_16x16x32_bf16 v[124:127], v[132:135], v[188:191], v[124:127]
	v_mfma_f32_16x16x32_bf16 v[120:123], v[140:143], v[188:191], v[120:123]
	v_mfma_f32_16x16x32_bf16 v[116:119], v[132:135], v[196:199], v[116:119]
	v_mfma_f32_16x16x32_bf16 v[112:115], v[140:143], v[196:199], v[112:115]
	v_mfma_f32_16x16x32_bf16 v[108:111], v[132:135], v[204:207], v[108:111]
	v_mfma_f32_16x16x32_bf16 v[96:99], v[140:143], v[204:207], v[96:99]
	v_mfma_f32_16x16x32_bf16 v[80:83], v[132:135], v[214:217], v[80:83]
	v_mfma_f32_16x16x32_bf16 v[72:75], v[140:143], v[214:217], v[72:75]
	s_setprio 0
	s_setprio 1
	v_mfma_f32_16x16x32_bf16 v[104:107], v[160:163], v[184:187], v[104:107]
	v_mfma_f32_16x16x32_bf16 v[100:103], v[176:179], v[184:187], v[100:103]
	v_mfma_f32_16x16x32_bf16 v[92:95], v[160:163], v[192:195], v[92:95]
	v_mfma_f32_16x16x32_bf16 v[88:91], v[176:179], v[192:195], v[88:91]
	v_mfma_f32_16x16x32_bf16 v[84:87], v[160:163], v[200:203], v[84:87]
	v_mfma_f32_16x16x32_bf16 v[76:79], v[176:179], v[200:203], v[76:79]
	v_mfma_f32_16x16x32_bf16 v[68:71], v[160:163], v[208:211], v[68:71]
	v_mfma_f32_16x16x32_bf16 v[64:67], v[176:179], v[208:211], v[64:67]
	v_mfma_f32_16x16x32_bf16 v[104:107], v[172:175], v[188:191], v[104:107]
	v_mfma_f32_16x16x32_bf16 v[100:103], v[180:183], v[188:191], v[100:103]
	v_mfma_f32_16x16x32_bf16 v[92:95], v[172:175], v[196:199], v[92:95]
	v_mfma_f32_16x16x32_bf16 v[88:91], v[180:183], v[196:199], v[88:91]
	v_mfma_f32_16x16x32_bf16 v[84:87], v[172:175], v[204:207], v[84:87]
	v_mfma_f32_16x16x32_bf16 v[76:79], v[180:183], v[204:207], v[76:79]
	v_mfma_f32_16x16x32_bf16 v[68:71], v[172:175], v[214:217], v[68:71]
	v_mfma_f32_16x16x32_bf16 v[64:67], v[180:183], v[214:217], v[64:67]
	s_setprio 0
	s_barrier
	s_add_i32 s72, s64, s53
	s_mov_b32 m0, s72
	ds_read_b128 v[184:187], v171 offset:16384
	ds_read_b128 v[188:191], v171 offset:17408
	ds_read_b128 v[192:195], v171 offset:18432
	ds_read_b128 v[196:199], v171 offset:19456
	ds_read_b128 v[200:203], v171 offset:20480
	ds_read_b128 v[204:207], v171 offset:21504
	ds_read_b128 v[208:211], v171 offset:22528
	ds_read_b128 v[214:217], v171 offset:23552
	global_load_lds_dwordx4 v146, s[48:49]
	s_add_i32 m0, s72, 0x2000
	s_add_u32 s72, s48, 0x80000
	s_addc_u32 s73, s49, 0
	s_add_i32 s74, s65, s53
	global_load_lds_dwordx4 v150, s[48:49]
	s_mov_b32 m0, s74
	s_nop 0
	global_load_lds_dwordx4 v146, s[72:73]
	s_add_i32 m0, s74, 0x2000
	s_nop 0
	global_load_lds_dwordx4 v150, s[72:73]
	s_mov_b32 m0, s45
	s_nop 0
	global_load_lds_dwordx4 v144, s[50:51]
	s_mov_b32 m0, s54
	s_nop 0
	global_load_lds_dwordx4 v148, s[50:51]
	s_waitcnt vmcnt(8)
	s_waitcnt lgkmcnt(0)
	s_barrier
	s_setprio 1
	s_waitcnt lgkmcnt(0)
	v_mfma_f32_16x16x32_bf16 v[60:63], v[128:131], v[184:187], v[60:63]
	v_mfma_f32_16x16x32_bf16 v[56:59], v[136:139], v[184:187], v[56:59]
	v_mfma_f32_16x16x32_bf16 v[52:55], v[128:131], v[192:195], v[52:55]
	v_mfma_f32_16x16x32_bf16 v[48:51], v[136:139], v[192:195], v[48:51]
	v_mfma_f32_16x16x32_bf16 v[44:47], v[128:131], v[200:203], v[44:47]
	v_mfma_f32_16x16x32_bf16 v[32:35], v[136:139], v[200:203], v[32:35]
	v_mfma_f32_16x16x32_bf16 v[20:23], v[128:131], v[208:211], v[20:23]
	v_mfma_f32_16x16x32_bf16 v[8:11], v[136:139], v[208:211], v[8:11]
	v_mfma_f32_16x16x32_bf16 v[60:63], v[132:135], v[188:191], v[60:63]
	v_mfma_f32_16x16x32_bf16 v[56:59], v[140:143], v[188:191], v[56:59]
	v_mfma_f32_16x16x32_bf16 v[52:55], v[132:135], v[196:199], v[52:55]
	v_mfma_f32_16x16x32_bf16 v[48:51], v[140:143], v[196:199], v[48:51]
	v_mfma_f32_16x16x32_bf16 v[44:47], v[132:135], v[204:207], v[44:47]
	v_mfma_f32_16x16x32_bf16 v[32:35], v[140:143], v[204:207], v[32:35]
	v_mfma_f32_16x16x32_bf16 v[20:23], v[132:135], v[214:217], v[20:23]
	v_mfma_f32_16x16x32_bf16 v[8:11], v[140:143], v[214:217], v[8:11]
	s_setprio 0
	s_setprio 1
	v_mfma_f32_16x16x32_bf16 v[40:43], v[160:163], v[184:187], v[40:43]
	v_mfma_f32_16x16x32_bf16 v[36:39], v[176:179], v[184:187], v[36:39]
	v_mfma_f32_16x16x32_bf16 v[28:31], v[160:163], v[192:195], v[28:31]
	v_mfma_f32_16x16x32_bf16 v[24:27], v[176:179], v[192:195], v[24:27]
	v_mfma_f32_16x16x32_bf16 v[16:19], v[160:163], v[200:203], v[16:19]
	v_mfma_f32_16x16x32_bf16 v[12:15], v[176:179], v[200:203], v[12:15]
	v_mfma_f32_16x16x32_bf16 v[4:7], v[160:163], v[208:211], v[4:7]
	v_mfma_f32_16x16x32_bf16 v[0:3], v[176:179], v[208:211], v[0:3]
	v_mfma_f32_16x16x32_bf16 v[40:43], v[172:175], v[188:191], v[40:43]
	v_mfma_f32_16x16x32_bf16 v[36:39], v[180:183], v[188:191], v[36:39]
	v_mfma_f32_16x16x32_bf16 v[28:31], v[172:175], v[196:199], v[28:31]
	v_mfma_f32_16x16x32_bf16 v[24:27], v[180:183], v[196:199], v[24:27]
	v_mfma_f32_16x16x32_bf16 v[16:19], v[172:175], v[204:207], v[16:19]
	v_mfma_f32_16x16x32_bf16 v[12:15], v[180:183], v[204:207], v[12:15]
	v_mfma_f32_16x16x32_bf16 v[4:7], v[172:175], v[214:217], v[4:7]
	v_mfma_f32_16x16x32_bf16 v[0:3], v[180:183], v[214:217], v[0:3]
	s_setprio 0
	s_barrier
; #define PG8_STAGE(bufoff, gbase, voff) do { _Pragma("unroll") for (int _i = 0; _i < 2; ++_i) \
;         __builtin_amdgcn_global_load_lds((const unsigned*)((const char*)(gbase) + (voff)[_i]), (PG8_LAS unsigned*)(lds + (bufoff) + ldsw + _i * 8192), 16, 0, 0); } while (0)
; #define PG8_LDA(dst, b, h) do { _Pragma("unroll") for (int m = 0; m < 4; ++m) _Pragma("unroll") for (int k = 0; k < 2; ++k) dst[m][k] = *(const PG8_LAS bf16x8*)(lds + PG8_SA(b, h) + aoff + m * 2048 + k * 1024); } while (0)
; #define PG8_LDB(dst, b, h) do { _Pragma("unroll") for (int n = 0; n < 2; ++n) _Pragma("unroll") for (int k = 0; k < 2; ++k) dst[n][k] = *(const PG8_LAS bf16x8*)(lds + PG8_SB(b, h) + boff + n * 2048 + k * 1024); } while (0)
; #define PG8_MMA(ai, bj, At, Bt) do { __builtin_amdgcn_s_setprio(1); _Pragma("unroll") for (int m = 0; m < 4; ++m) _Pragma("unroll") for (int n = 0; n < 2; ++n) _Pragma("unroll") for (int k = 0; k < 2; ++k) \
;         acc[ai][bj][m][n] = __builtin_amdgcn_mfma_f32_16x16x32_bf16(Bt[n][k], At[m][k], acc[ai][bj][m][n], 0, 0, 0); __builtin_amdgcn_s_setprio(0); } while (0)
; #define PG8_WAIT_V(n) asm volatile("s_waitcnt vmcnt(" #n ")" ::: "memory")
; #define PG8_WAIT_L(n) asm volatile("s_waitcnt lgkmcnt(" #n ")" ::: "memory")
; #define PG8_BAR __builtin_amdgcn_s_barrier()
; #define PG8_SCHED __builtin_amdgcn_sched_barrier(0)
; template <class Epi, class Sched, bool ALIGN_EPI = false, bool SP2 = false>
; __device__ __forceinline__ void gemm_phase(PG8_LAS unsigned char* lds, const Gemm g, const Sched& S, const Epi& E) {
;     ...
;             PG8_LDB(B0, 1, 0); PG8_LDB(B1, 1, 1); PG8_SCHED; PG8_LDA(At, 1, 0); PG8_STAGE(PG8_SA(0, 1), a2 + hstep, voffA);
;             PG8_WAIT_V(8); PG8_WAIT_L(0); PG8_BAR; PG8_MMA(0, 0, At, B0); PG8_MMA(0, 1, At, B1); PG8_BAR; PG8_SCHED;
;             PG8_LDA(At, 1, 1); PG8_STAGE(PG8_SB(1, 0), b3, voffB); PG8_STAGE(PG8_SB(1, 1), b3 + hstep, voffB); PG8_STAGE(PG8_SA(1, 0), a3, voffA);
;             PG8_WAIT_V(8); PG8_WAIT_L(0); PG8_BAR; PG8_MMA(1, 0, At, B0); PG8_MMA(1, 1, At, B1); PG8_BAR; PG8_SCHED;
	s_add_i32 s72, 0, 0x18000
	s_add_i32 s73, 0, 0x1c000
	v_add_u32_e32 v140, s72, v167
	v_add_u32_e32 v180, s73, v167
	ds_read_b128 v[128:131], v140
	ds_read_b128 v[132:135], v140 offset:1024
	ds_read_b128 v[136:139], v140 offset:2048
	ds_read_b128 v[140:143], v140 offset:3072
	ds_read_b128 v[160:163], v180
	ds_read_b128 v[172:175], v180 offset:1024
	ds_read_b128 v[176:179], v180 offset:2048
	ds_read_b128 v[180:183], v180 offset:3072
	s_add_u32 s84, s50, 0x80
	s_addc_u32 s85, s51, 0
	s_add_u32 s50, s50, 0x80000
	s_addc_u32 s51, s51, 0
	s_mov_b32 m0, s55
	ds_read_b128 v[184:187], v171 offset:32768
	ds_read_b128 v[188:191], v171 offset:33792
	ds_read_b128 v[192:195], v171 offset:34816
	ds_read_b128 v[196:199], v171 offset:35840
	ds_read_b128 v[200:203], v171 offset:36864
	ds_read_b128 v[204:207], v171 offset:37888
	ds_read_b128 v[208:211], v171 offset:38912
	ds_read_b128 v[214:217], v171 offset:39936
	global_load_lds_dwordx4 v144, s[50:51]
	s_mov_b32 m0, s56
	s_nop 0
	global_load_lds_dwordx4 v148, s[50:51]
	s_waitcnt vmcnt(8)
	s_waitcnt lgkmcnt(0)
	s_barrier
	s_setprio 1
	s_waitcnt lgkmcnt(0)
	v_mfma_f32_16x16x32_bf16 v[124:127], v[128:131], v[184:187], v[124:127]
	v_mfma_f32_16x16x32_bf16 v[120:123], v[136:139], v[184:187], v[120:123]
	v_mfma_f32_16x16x32_bf16 v[116:119], v[128:131], v[192:195], v[116:119]
	v_mfma_f32_16x16x32_bf16 v[112:115], v[136:139], v[192:195], v[112:115]
	v_mfma_f32_16x16x32_bf16 v[108:111], v[128:131], v[200:203], v[108:111]
	v_mfma_f32_16x16x32_bf16 v[96:99], v[136:139], v[200:203], v[96:99]
	v_mfma_f32_16x16x32_bf16 v[80:83], v[128:131], v[208:211], v[80:83]
	v_mfma_f32_16x16x32_bf16 v[72:75], v[136:139], v[208:211], v[72:75]
	v_mfma_f32_16x16x32_bf16 v[124:127], v[132:135], v[188:191], v[124:127]
	v_mfma_f32_16x16x32_bf16 v[120:123], v[140:143], v[188:191], v[120:123]
	v_mfma_f32_16x16x32_bf16 v[116:119], v[132:135], v[196:199], v[116:119]
	v_mfma_f32_16x16x32_bf16 v[112:115], v[140:143], v[196:199], v[112:115]
	v_mfma_f32_16x16x32_bf16 v[108:111], v[132:135], v[204:207], v[108:111]
	v_mfma_f32_16x16x32_bf16 v[96:99], v[140:143], v[204:207], v[96:99]
	v_mfma_f32_16x16x32_bf16 v[80:83], v[132:135], v[214:217], v[80:83]
	v_mfma_f32_16x16x32_bf16 v[72:75], v[140:143], v[214:217], v[72:75]
	s_setprio 0
	s_setprio 1
	v_mfma_f32_16x16x32_bf16 v[104:107], v[160:163], v[184:187], v[104:107]
	v_mfma_f32_16x16x32_bf16 v[100:103], v[176:179], v[184:187], v[100:103]
	v_mfma_f32_16x16x32_bf16 v[92:95], v[160:163], v[192:195], v[92:95]
	v_mfma_f32_16x16x32_bf16 v[88:91], v[176:179], v[192:195], v[88:91]
	v_mfma_f32_16x16x32_bf16 v[84:87], v[160:163], v[200:203], v[84:87]
	v_mfma_f32_16x16x32_bf16 v[76:79], v[176:179], v[200:203], v[76:79]
	v_mfma_f32_16x16x32_bf16 v[68:71], v[160:163], v[208:211], v[68:71]
	v_mfma_f32_16x16x32_bf16 v[64:67], v[176:179], v[208:211], v[64:67]
	v_mfma_f32_16x16x32_bf16 v[104:107], v[172:175], v[188:191], v[104:107]
	v_mfma_f32_16x16x32_bf16 v[100:103], v[180:183], v[188:191], v[100:103]
	v_mfma_f32_16x16x32_bf16 v[92:95], v[172:175], v[196:199], v[92:95]
	v_mfma_f32_16x16x32_bf16 v[88:91], v[180:183], v[196:199], v[88:91]
	v_mfma_f32_16x16x32_bf16 v[84:87], v[172:175], v[204:207], v[84:87]
	v_mfma_f32_16x16x32_bf16 v[76:79], v[180:183], v[204:207], v[76:79]
	v_mfma_f32_16x16x32_bf16 v[68:71], v[172:175], v[214:217], v[68:71]
	v_mfma_f32_16x16x32_bf16 v[64:67], v[180:183], v[214:217], v[64:67]
	s_setprio 0
	s_barrier
	s_add_i32 s50, s72, s53
	s_add_u32 s86, s48, 0x80
	s_addc_u32 s87, s49, 0
	s_mov_b32 m0, s50
	ds_read_b128 v[184:187], v171 offset:49152
	ds_read_b128 v[188:191], v171 offset:50176
	ds_read_b128 v[192:195], v171 offset:51200
	ds_read_b128 v[196:199], v171 offset:52224
	ds_read_b128 v[200:203], v171 offset:53248
	ds_read_b128 v[204:207], v171 offset:54272
	ds_read_b128 v[208:211], v171 offset:55296
	ds_read_b128 v[214:217], v171 offset:56320
	global_load_lds_dwordx4 v146, s[86:87]
	s_add_i32 m0, s50, 0x2000
	s_add_u32 s48, s48, 0x80080
	s_addc_u32 s49, s49, 0
	s_add_i32 s50, s73, s53
	global_load_lds_dwordx4 v150, s[86:87]
	s_mov_b32 m0, s50
	s_nop 0
	global_load_lds_dwordx4 v146, s[48:49]
	s_add_i32 m0, s50, 0x2000
	s_nop 0
	global_load_lds_dwordx4 v150, s[48:49]
	s_mov_b32 m0, s60
	s_nop 0
	global_load_lds_dwordx4 v144, s[84:85]
	s_mov_b32 m0, s61
	s_nop 0
	global_load_lds_dwordx4 v148, s[84:85]
	s_waitcnt vmcnt(8)
	s_waitcnt lgkmcnt(0)
	s_barrier
	s_setprio 1
	s_waitcnt lgkmcnt(0)
	v_mfma_f32_16x16x32_bf16 v[60:63], v[128:131], v[184:187], v[60:63]
	v_mfma_f32_16x16x32_bf16 v[56:59], v[136:139], v[184:187], v[56:59]
	v_mfma_f32_16x16x32_bf16 v[52:55], v[128:131], v[192:195], v[52:55]
	v_mfma_f32_16x16x32_bf16 v[48:51], v[136:139], v[192:195], v[48:51]
	v_mfma_f32_16x16x32_bf16 v[44:47], v[128:131], v[200:203], v[44:47]
	v_mfma_f32_16x16x32_bf16 v[32:35], v[136:139], v[200:203], v[32:35]
	v_mfma_f32_16x16x32_bf16 v[20:23], v[128:131], v[208:211], v[20:23]
	v_mfma_f32_16x16x32_bf16 v[8:11], v[136:139], v[208:211], v[8:11]
	v_mfma_f32_16x16x32_bf16 v[60:63], v[132:135], v[188:191], v[60:63]
	v_mfma_f32_16x16x32_bf16 v[56:59], v[140:143], v[188:191], v[56:59]
	v_mfma_f32_16x16x32_bf16 v[52:55], v[132:135], v[196:199], v[52:55]
	v_mfma_f32_16x16x32_bf16 v[48:51], v[140:143], v[196:199], v[48:51]
	v_mfma_f32_16x16x32_bf16 v[44:47], v[132:135], v[204:207], v[44:47]
	v_mfma_f32_16x16x32_bf16 v[32:35], v[140:143], v[204:207], v[32:35]
	v_mfma_f32_16x16x32_bf16 v[20:23], v[132:135], v[214:217], v[20:23]
	v_mfma_f32_16x16x32_bf16 v[8:11], v[140:143], v[214:217], v[8:11]
	s_setprio 0
	s_setprio 1
	v_mfma_f32_16x16x32_bf16 v[40:43], v[160:163], v[184:187], v[40:43]
	v_mfma_f32_16x16x32_bf16 v[36:39], v[176:179], v[184:187], v[36:39]
	v_mfma_f32_16x16x32_bf16 v[28:31], v[160:163], v[192:195], v[28:31]
	v_mfma_f32_16x16x32_bf16 v[24:27], v[176:179], v[192:195], v[24:27]
	v_mfma_f32_16x16x32_bf16 v[16:19], v[160:163], v[200:203], v[16:19]
	v_mfma_f32_16x16x32_bf16 v[12:15], v[176:179], v[200:203], v[12:15]
	v_mfma_f32_16x16x32_bf16 v[4:7], v[160:163], v[208:211], v[4:7]
	v_mfma_f32_16x16x32_bf16 v[0:3], v[176:179], v[208:211], v[0:3]
	v_mfma_f32_16x16x32_bf16 v[40:43], v[172:175], v[188:191], v[40:43]
	v_mfma_f32_16x16x32_bf16 v[36:39], v[180:183], v[188:191], v[36:39]
	v_mfma_f32_16x16x32_bf16 v[28:31], v[172:175], v[196:199], v[28:31]
	v_mfma_f32_16x16x32_bf16 v[24:27], v[180:183], v[196:199], v[24:27]
	v_mfma_f32_16x16x32_bf16 v[16:19], v[172:175], v[204:207], v[16:19]
	v_mfma_f32_16x16x32_bf16 v[12:15], v[180:183], v[204:207], v[12:15]
	v_mfma_f32_16x16x32_bf16 v[4:7], v[172:175], v[214:217], v[4:7]
	v_mfma_f32_16x16x32_bf16 v[0:3], v[180:183], v[214:217], v[0:3]
	s_setprio 0
	s_barrier
;     __device__ __forceinline__ void operator()(const f32x4 (&acc)[2][2][4][2], const Unit& u, int wr, int wc, int fr, int fq) const {
;         const int row0 = u.pm * BM + wr * 64 + fr, col0 = u.pn * BM + wc * 32 + 8 * fq;
;         const float* gp = gate + (u.pm >> 5) * 18432 + col0;
;         f32x4 gv[2][2];
; #pragma unroll
;         for (int bj = 0; bj < 2; ++bj)
; #pragma unroll
;             for (int n = 0; n < 2; ++n) gv[bj][n] = *(const f32x4*)(gp + bj * HALF + 4 * n) * scale;
; #pragma unroll
;         for (int ai = 0; ai < 2; ++ai) { f32x4 r[4][2][2];
; #pragma unroll
;             for (int m = 0; m < 4; ++m) { const size_t off = (size_t)(row0 + ai * HALF + m * 16) * 2048 + col0;
; #pragma unroll
;                 for (int bj = 0; bj < 2; ++bj)
; #pragma unroll
;                     for (int n = 0; n < 2; ++n) r[m][bj][n] = *(const f32x4*)(res + off + bj * HALF + 4 * n); }
; #pragma unroll
;             for (int m = 0; m < 4; ++m) { const size_t off = (size_t)(row0 + ai * HALF + m * 16) * 2048 + col0;
; #pragma unroll
;                 for (int bj = 0; bj < 2; ++bj)
; #pragma unroll
;                     for (int n = 0; n < 2; ++n) *(f32x4*)(out + off + bj * HALF + 4 * n) = r[m][bj][n] + gv[bj][n] * acc[ai][bj][m][n]; } }
; template <class Epi, class Sched, bool ALIGN_EPI = false, bool SP2 = false>
; __device__ __forceinline__ void gemm_phase(PG8_LAS unsigned char* lds, const Gemm g, const Sched& S, const Epi& E) {
;     ...
;         for (int t = 0; t < nt; t += 2) {
;             const bool last = (t == nt - 2);
;             const char* a1 = cA + (size_t)(t + 1) * kstep;
;             const char* a2 = last ? nA : cA + (size_t)(t + 2) * kstep; const char* b2 = last ? nB : cB + (size_t)(t + 2) * kstep;
	s_add_i32 s71, s71, 2
	s_add_u32 s46, s46, 0x100
	s_addc_u32 s47, s47, 0
	s_add_u32 s69, s69, 0x100
	s_addc_u32 s70, s70, 0
	s_cmp_gt_u32 s71, 29
	s_cbranch_scc0 .LBB0_827
	s_lshr_b32 s37, s44, 5
	s_mul_i32 s46, s37, 0x4800
	v_lshl_or_b32 v128, s66, 8, v168
	s_ashr_i32 s47, s46, 31
	v_lshl_add_u32 v212, s44, 8, v166
	s_lshl_b64 s[46:47], s[46:47], 2
	v_ashrrev_i32_e32 v129, 31, v128
	v_or_b32_e32 v188, 16, v212
	v_or_b32_e32 v204, 32, v212
	s_add_u32 s46, s58, s46
	v_lshlrev_b64 v[160:161], 2, v[128:129]
	v_ashrrev_i32_e32 v213, 31, v212
	v_ashrrev_i32_e32 v189, 31, v188
	v_ashrrev_i32_e32 v205, 31, v204
	s_addc_u32 s47, s59, s47
	v_lshl_add_u64 v[162:163], s[12:13], 0, v[160:161]
	v_lshlrev_b64 v[164:165], 13, v[212:213]
	v_lshlrev_b64 v[218:219], 13, v[188:189]
	v_lshlrev_b64 v[230:231], 13, v[204:205]
	v_or_b32_e32 v212, 48, v212
	v_lshl_add_u64 v[136:137], s[46:47], 0, v[160:161]
	v_lshl_add_u64 v[184:185], v[162:163], 0, v[164:165]
	v_lshl_add_u64 v[200:201], v[162:163], 0, v[218:219]
	v_lshl_add_u64 v[222:223], v[162:163], 0, v[230:231]
	v_ashrrev_i32_e32 v213, 31, v212
	global_load_dwordx4 v[132:135], v[136:137], off offset:16
	global_load_dwordx4 v[140:143], v[136:137], off
	global_load_dwordx4 v[172:175], v[184:185], off offset:16
	global_load_dwordx4 v[176:179], v[184:185], off
	global_load_dwordx4 v[128:131], v[136:137], off offset:528
	s_nop 0
	global_load_dwordx4 v[136:139], v[136:137], off offset:512
	s_nop 0
	global_load_dwordx4 v[180:183], v[184:185], off offset:528
	s_nop 0
	global_load_dwordx4 v[184:187], v[184:185], off offset:512
	s_nop 0
	global_load_dwordx4 v[188:191], v[200:201], off
	global_load_dwordx4 v[192:195], v[200:201], off offset:16
	global_load_dwordx4 v[196:199], v[200:201], off offset:528
	s_nop 0
	global_load_dwordx4 v[200:203], v[200:201], off offset:512
	s_nop 0
	global_load_dwordx4 v[204:207], v[222:223], off
	global_load_dwordx4 v[208:211], v[222:223], off offset:16
	global_load_dwordx4 v[214:217], v[222:223], off offset:512
	s_nop 0
	global_load_dwordx4 v[222:225], v[222:223], off offset:528
	v_lshlrev_b64 v[212:213], 13, v[212:213]
	v_lshl_add_u64 v[244:245], v[162:163], 0, v[212:213]
	global_load_dwordx4 v[232:235], v[244:245], off
	global_load_dwordx4 v[236:239], v[244:245], off offset:16
	global_load_dwordx4 v[240:243], v[244:245], off offset:512
	s_nop 0
	global_load_dwordx4 v[244:247], v[244:245], off offset:528
	v_lshl_add_u64 v[248:249], s[14:15], 0, v[164:165]
	v_lshl_add_u64 v[248:249], v[248:249], 0, v[160:161]
	v_lshl_add_u64 v[218:219], s[14:15], 0, v[218:219]
	v_lshl_add_u64 v[230:231], s[14:15], 0, v[230:231]
	v_lshl_add_u64 v[218:219], v[218:219], 0, v[160:161]
	v_lshl_add_u64 v[230:231], v[230:231], 0, v[160:161]
	s_and_b64 vcc, exec, s[10:11]
	s_mov_b32 s66, s36
	s_mov_b32 s44, s38
	s_mov_b64 s[48:49], s[42:43]
	s_mov_b64 s[46:47], s[40:41]
	s_waitcnt vmcnt(0)
	v_pk_fma_f32 v[122:123], v[122:123], v[134:135], v[174:175]
	v_pk_fma_f32 v[126:127], v[126:127], v[142:143], v[178:179]
	v_pk_fma_f32 v[124:125], v[124:125], v[140:141], v[176:177]
	v_pk_fma_f32 v[120:121], v[120:121], v[132:133], v[172:173]
	v_pk_fma_f32 v[76:77], v[76:77], v[128:129], v[222:223]
	v_pk_fma_f32 v[106:107], v[106:107], v[138:139], v[186:187]
	v_pk_fma_f32 v[104:105], v[104:105], v[136:137], v[184:185]
	v_pk_fma_f32 v[102:103], v[102:103], v[130:131], v[182:183]
	v_pk_fma_f32 v[100:101], v[100:101], v[128:129], v[180:181]
	v_pk_fma_f32 v[118:119], v[118:119], v[142:143], v[190:191]
	v_pk_fma_f32 v[116:117], v[116:117], v[140:141], v[188:189]
	v_pk_fma_f32 v[114:115], v[114:115], v[134:135], v[194:195]
	v_pk_fma_f32 v[112:113], v[112:113], v[132:133], v[192:193]
	v_pk_fma_f32 v[94:95], v[94:95], v[138:139], v[202:203]
	v_pk_fma_f32 v[92:93], v[92:93], v[136:137], v[200:201]
	v_pk_fma_f32 v[90:91], v[90:91], v[130:131], v[198:199]
	v_pk_fma_f32 v[88:89], v[88:89], v[128:129], v[196:197]
	v_pk_fma_f32 v[110:111], v[110:111], v[142:143], v[206:207]
	v_pk_fma_f32 v[108:109], v[108:109], v[140:141], v[204:205]
	v_pk_fma_f32 v[98:99], v[98:99], v[134:135], v[210:211]
	v_pk_fma_f32 v[96:97], v[96:97], v[132:133], v[208:209]
	v_pk_fma_f32 v[86:87], v[86:87], v[138:139], v[216:217]
	v_pk_fma_f32 v[84:85], v[84:85], v[136:137], v[214:215]
	v_pk_fma_f32 v[78:79], v[78:79], v[130:131], v[224:225]
	global_store_dwordx4 v[248:249], v[124:127], off
	global_store_dwordx4 v[248:249], v[120:123], off offset:16
	global_store_dwordx4 v[248:249], v[104:107], off offset:512
	global_store_dwordx4 v[248:249], v[100:103], off offset:528
	global_store_dwordx4 v[218:219], v[116:119], off
	global_store_dwordx4 v[218:219], v[112:115], off offset:16
	global_store_dwordx4 v[218:219], v[92:95], off offset:512
	global_store_dwordx4 v[218:219], v[88:91], off offset:528
	global_store_dwordx4 v[230:231], v[108:111], off
	global_store_dwordx4 v[230:231], v[96:99], off offset:16
	global_store_dwordx4 v[230:231], v[84:87], off offset:512
	global_store_dwordx4 v[230:231], v[76:79], off offset:528
	v_pk_fma_f32 v[74:75], v[74:75], v[134:135], v[238:239]
	v_pk_fma_f32 v[72:73], v[72:73], v[132:133], v[236:237]
	v_pk_fma_f32 v[76:77], v[80:81], v[140:141], v[232:233]
	v_lshl_add_u64 v[80:81], s[14:15], 0, v[212:213]
; #define PG8_WAIT_V(n) asm volatile("s_waitcnt vmcnt(" #n ")" ::: "memory")
; #define PG8_BAR __builtin_amdgcn_s_barrier()
;     __device__ __forceinline__ void operator()(const f32x4 (&acc)[2][2][4][2], const Unit& u, int wr, int wc, int fr, int fq) const {
;         const int row0 = u.pm * BM + wr * 64 + fr, col0 = u.pn * BM + wc * 32 + 8 * fq;
;         const float* gp = gate + (u.pm >> 5) * 18432 + col0;
;         f32x4 gv[2][2];
; #pragma unroll
;         for (int bj = 0; bj < 2; ++bj)
; #pragma unroll
;             for (int n = 0; n < 2; ++n) gv[bj][n] = *(const f32x4*)(gp + bj * HALF + 4 * n) * scale;
; #pragma unroll
;         for (int ai = 0; ai < 2; ++ai) { f32x4 r[4][2][2];
; #pragma unroll
;             for (int m = 0; m < 4; ++m) { const size_t off = (size_t)(row0 + ai * HALF + m * 16) * 2048 + col0;
; #pragma unroll
;                 for (int bj = 0; bj < 2; ++bj)
; #pragma unroll
;                     for (int n = 0; n < 2; ++n) r[m][bj][n] = *(const f32x4*)(res + off + bj * HALF + 4 * n); }
; #pragma unroll
;             for (int m = 0; m < 4; ++m) { const size_t off = (size_t)(row0 + ai * HALF + m * 16) * 2048 + col0;
; #pragma unroll
;                 for (int bj = 0; bj < 2; ++bj)
; #pragma unroll
;                     for (int n = 0; n < 2; ++n) *(f32x4*)(out + off + bj * HALF + 4 * n) = r[m][bj][n] + gv[bj][n] * acc[ai][bj][m][n]; } }
; template <class Epi, class Sched, bool ALIGN_EPI = false, bool SP2 = false>
; __device__ __forceinline__ void gemm_phase(PG8_LAS unsigned char* lds, const Gemm g, const Sched& S, const Epi& E) {
;     ...
;     PG8_WAIT_V(0);
;     if constexpr (!ALIGN_EPI) { if (wr == 0) PG8_BAR; }
;     PG8_BAR;
	v_pk_fma_f32 v[78:79], v[82:83], v[142:143], v[234:235]
	v_lshl_add_u64 v[80:81], v[80:81], 0, v[160:161]
	v_pk_fma_f32 v[70:71], v[70:71], v[138:139], v[242:243]
	v_pk_fma_f32 v[68:69], v[68:69], v[136:137], v[240:241]
	v_pk_fma_f32 v[66:67], v[66:67], v[130:131], v[246:247]
	v_pk_fma_f32 v[64:65], v[64:65], v[128:129], v[244:245]
	v_lshl_add_u64 v[172:173], v[164:165], 0, s[26:27]
	v_lshl_add_u64 v[174:175], v[164:165], 0, s[28:29]
	v_lshl_add_u64 v[176:177], v[164:165], 0, s[30:31]
	global_store_dwordx4 v[80:81], v[76:79], off
	global_store_dwordx4 v[80:81], v[72:75], off offset:16
	global_store_dwordx4 v[80:81], v[68:71], off offset:512
	global_store_dwordx4 v[80:81], v[64:67], off offset:528
	v_lshl_add_u64 v[76:77], v[162:163], 0, v[172:173]
	v_lshl_add_u64 v[92:93], v[162:163], 0, v[174:175]
	v_lshl_add_u64 v[108:109], v[162:163], 0, v[176:177]
	global_load_dwordx4 v[64:67], v[76:77], off
	global_load_dwordx4 v[68:71], v[76:77], off offset:16
	global_load_dwordx4 v[72:75], v[76:77], off offset:512
	s_nop 0
	global_load_dwordx4 v[76:79], v[76:77], off offset:528
	s_nop 0
	global_load_dwordx4 v[80:83], v[92:93], off
	global_load_dwordx4 v[84:87], v[92:93], off offset:16
	global_load_dwordx4 v[88:91], v[92:93], off offset:512
	s_nop 0
	global_load_dwordx4 v[92:95], v[92:93], off offset:528
	s_nop 0
	global_load_dwordx4 v[96:99], v[108:109], off
	global_load_dwordx4 v[100:103], v[108:109], off offset:16
	global_load_dwordx4 v[104:107], v[108:109], off offset:512
	s_nop 0
	global_load_dwordx4 v[108:111], v[108:109], off offset:528
	v_lshl_add_u64 v[164:165], v[164:165], 0, s[34:35]
	v_lshl_add_u64 v[124:125], v[162:163], 0, v[164:165]
	global_load_dwordx4 v[112:115], v[124:125], off
	global_load_dwordx4 v[116:119], v[124:125], off offset:16
	global_load_dwordx4 v[120:123], v[124:125], off offset:512
	s_nop 0
	global_load_dwordx4 v[124:127], v[124:125], off offset:528
	v_lshl_add_u64 v[162:163], s[14:15], 0, v[172:173]
	v_lshl_add_u64 v[172:173], s[14:15], 0, v[174:175]
	v_lshl_add_u64 v[174:175], s[14:15], 0, v[176:177]
	v_lshl_add_u64 v[162:163], v[162:163], 0, v[160:161]
	v_lshl_add_u64 v[172:173], v[172:173], 0, v[160:161]
	v_lshl_add_u64 v[174:175], v[174:175], 0, v[160:161]
	s_waitcnt vmcnt(15)
	v_pk_fma_f32 v[62:63], v[62:63], v[142:143], v[66:67]
	v_pk_fma_f32 v[60:61], v[60:61], v[140:141], v[64:65]
	s_waitcnt vmcnt(14)
	v_pk_fma_f32 v[58:59], v[58:59], v[134:135], v[70:71]
	v_pk_fma_f32 v[56:57], v[56:57], v[132:133], v[68:69]
	s_waitcnt vmcnt(13)
	v_pk_fma_f32 v[42:43], v[42:43], v[138:139], v[74:75]
	s_waitcnt vmcnt(4)
	v_pk_fma_f32 v[12:13], v[12:13], v[128:129], v[108:109]
	v_pk_fma_f32 v[40:41], v[40:41], v[136:137], v[72:73]
	v_pk_fma_f32 v[38:39], v[38:39], v[130:131], v[78:79]
	v_pk_fma_f32 v[36:37], v[36:37], v[128:129], v[76:77]
	v_pk_fma_f32 v[54:55], v[54:55], v[142:143], v[82:83]
	v_pk_fma_f32 v[52:53], v[52:53], v[140:141], v[80:81]
	v_pk_fma_f32 v[50:51], v[50:51], v[134:135], v[86:87]
	v_pk_fma_f32 v[48:49], v[48:49], v[132:133], v[84:85]
	v_pk_fma_f32 v[30:31], v[30:31], v[138:139], v[90:91]
	v_pk_fma_f32 v[28:29], v[28:29], v[136:137], v[88:89]
	v_pk_fma_f32 v[26:27], v[26:27], v[130:131], v[94:95]
	v_pk_fma_f32 v[24:25], v[24:25], v[128:129], v[92:93]
	v_pk_fma_f32 v[46:47], v[46:47], v[142:143], v[98:99]
	v_pk_fma_f32 v[44:45], v[44:45], v[140:141], v[96:97]
	v_pk_fma_f32 v[34:35], v[34:35], v[134:135], v[102:103]
	v_pk_fma_f32 v[32:33], v[32:33], v[132:133], v[100:101]
	v_pk_fma_f32 v[18:19], v[18:19], v[138:139], v[106:107]
	v_pk_fma_f32 v[16:17], v[16:17], v[136:137], v[104:105]
	v_pk_fma_f32 v[14:15], v[14:15], v[130:131], v[110:111]
	global_store_dwordx4 v[162:163], v[60:63], off
	global_store_dwordx4 v[162:163], v[56:59], off offset:16
	global_store_dwordx4 v[162:163], v[40:43], off offset:512
	global_store_dwordx4 v[162:163], v[36:39], off offset:528
	global_store_dwordx4 v[172:173], v[52:55], off
	global_store_dwordx4 v[172:173], v[48:51], off offset:16
	global_store_dwordx4 v[172:173], v[28:31], off offset:512
	global_store_dwordx4 v[172:173], v[24:27], off offset:528
	global_store_dwordx4 v[174:175], v[44:47], off
	global_store_dwordx4 v[174:175], v[32:35], off offset:16
	global_store_dwordx4 v[174:175], v[16:19], off offset:512
	global_store_dwordx4 v[174:175], v[12:15], off offset:528
	s_waitcnt vmcnt(15)
	v_pk_fma_f32 v[22:23], v[22:23], v[142:143], v[114:115]
	v_pk_fma_f32 v[20:21], v[20:21], v[140:141], v[112:113]
	v_lshl_add_u64 v[12:13], s[14:15], 0, v[164:165]
	v_lshl_add_u64 v[12:13], v[12:13], 0, v[160:161]
	s_waitcnt vmcnt(14)
	v_pk_fma_f32 v[10:11], v[10:11], v[134:135], v[118:119]
	v_pk_fma_f32 v[8:9], v[8:9], v[132:133], v[116:117]
	s_waitcnt vmcnt(13)
	v_pk_fma_f32 v[6:7], v[6:7], v[138:139], v[122:123]
	v_pk_fma_f32 v[4:5], v[4:5], v[136:137], v[120:121]
	s_waitcnt vmcnt(12)
	v_pk_fma_f32 v[2:3], v[2:3], v[130:131], v[126:127]
	v_pk_fma_f32 v[0:1], v[0:1], v[128:129], v[124:125]
	global_store_dwordx4 v[12:13], v[20:23], off
	global_store_dwordx4 v[12:13], v[8:11], off offset:16
	global_store_dwordx4 v[12:13], v[4:7], off offset:512
	global_store_dwordx4 v[12:13], v[0:3], off offset:528
	s_cbranch_vccz .LBB0_820
	s_waitcnt vmcnt(0)
	s_cmpk_gt_u32 s3, 0xff
	s_cbranch_scc1 .LBB0_831
	s_barrier

; #define PG8_STAGE(bufoff, gbase, voff) do { _Pragma("unroll") for (int _i = 0; _i < 2; ++_i) \
;         __builtin_amdgcn_global_load_lds((const unsigned*)((const char*)(gbase) + (voff)[_i]), (PG8_LAS unsigned*)(lds + (bufoff) + ldsw + _i * 8192), 16, 0, 0); } while (0)
; #define PG8_LDA(dst, b, h) do { _Pragma("unroll") for (int m = 0; m < 4; ++m) _Pragma("unroll") for (int k = 0; k < 2; ++k) dst[m][k] = *(const PG8_LAS bf16x8*)(lds + PG8_SA(b, h) + aoff + m * 2048 + k * 1024); } while (0)
; #define PG8_LDB(dst, b, h) do { _Pragma("unroll") for (int n = 0; n < 2; ++n) _Pragma("unroll") for (int k = 0; k < 2; ++k) dst[n][k] = *(const PG8_LAS bf16x8*)(lds + PG8_SB(b, h) + boff + n * 2048 + k * 1024); } while (0)
; #define PG8_MMA(ai, bj, At, Bt) do { __builtin_amdgcn_s_setprio(1); _Pragma("unroll") for (int m = 0; m < 4; ++m) _Pragma("unroll") for (int n = 0; n < 2; ++n) _Pragma("unroll") for (int k = 0; k < 2; ++k) \
;         acc[ai][bj][m][n] = __builtin_amdgcn_mfma_f32_16x16x32_bf16(Bt[n][k], At[m][k], acc[ai][bj][m][n], 0, 0, 0); __builtin_amdgcn_s_setprio(0); } while (0)
; #define PG8_WAIT_V(n) asm volatile("s_waitcnt vmcnt(" #n ")" ::: "memory")
; #define PG8_BAR __builtin_amdgcn_s_barrier()
; template <class Epi, class Sched, bool ALIGN_EPI = false, bool SP2 = false>
; __device__ __forceinline__ void gemm_phase(PG8_LAS unsigned char* lds, const Gemm g, const Sched& S, const Epi& E) {
;     ...
;         for (int t = 0; t < nt; t += 2) {
;             const bool last = (t == nt - 2);
;             const char* a1 = cA + (size_t)(t + 1) * kstep;
;             const char* a2 = last ? nA : cA + (size_t)(t + 2) * kstep; const char* b2 = last ? nB : cB + (size_t)(t + 2) * kstep;
;             const char* a3 = a2 + kstep; const char* b3 = b2 + kstep;
;             if (last && has_next) S.a_ready(nxt);
;             if constexpr (SP2) {
;             PG8_LDB(B0, 0, 0); PG8_LDB(B1, 0, 1); PG8_SCHED; PG8_LDA(At, 0, 0); PG8_STAGE(PG8_SA(1, 1), a1 + hstep, voffA);
;             PG8_WAIT_V(8); PG8_WAIT_L(0); PG8_BAR; PG8_MMA(0, 0, At, B0); PG8_MMA(0, 1, At, B1); PG8_BAR; PG8_SCHED;
;             PG8_LDA(At, 0, 1); PG8_STAGE(PG8_SB(0, 0), b2, voffB); PG8_STAGE(PG8_SB(0, 1), b2 + hstep, voffB); PG8_STAGE(PG8_SA(0, 0), a2, voffA);
;             PG8_WAIT_V(8); PG8_WAIT_L(0); PG8_BAR; PG8_MMA(1, 0, At, B0); PG8_MMA(1, 1, At, B1); PG8_BAR; PG8_SCHED;
.LBB0_945:
	ds_read_b128 v[152:155], v149
	ds_read_b128 v[156:159], v149 offset:1024
	ds_read_b128 v[160:163], v149 offset:2048
	ds_read_b128 v[164:167], v149 offset:3072
	ds_read_b128 v[168:171], v150
	ds_read_b128 v[172:175], v150 offset:1024
	ds_read_b128 v[176:179], v150 offset:2048
	ds_read_b128 v[180:183], v150 offset:3072
	s_add_u32 s34, s30, 0xfff80080
	s_addc_u32 s35, s31, -1
	s_cmp_eq_u32 s61, 28
	s_cselect_b32 s37, s23, s35
	s_cselect_b32 s36, s57, s34
	s_cselect_b32 s35, s15, s60
	s_cselect_b32 s34, s58, s59
	s_add_i32 m0, s29, 0xc000
	ds_read_b128 v[184:187], v151
	ds_read_b128 v[188:191], v151 offset:1024
	ds_read_b128 v[192:195], v151 offset:2048
	ds_read_b128 v[196:199], v151 offset:3072
	ds_read_b128 v[200:203], v151 offset:4096
	ds_read_b128 v[204:207], v151 offset:5120
	ds_read_b128 v[208:211], v151 offset:6144
	ds_read_b128 v[212:215], v151 offset:7168
	global_load_lds_dwordx4 v136, s[30:31]
	s_add_i32 m0, s29, 0xe000
	s_nop 0
	global_load_lds_dwordx4 v138, s[30:31]
	s_waitcnt vmcnt(8)
	s_waitcnt lgkmcnt(0)
	s_barrier
	s_setprio 1
	s_waitcnt lgkmcnt(0)
	v_mfma_f32_16x16x32_bf16 v[124:127], v[152:155], v[184:187], v[124:127]
	v_mfma_f32_16x16x32_bf16 v[120:123], v[160:163], v[184:187], v[120:123]
	v_mfma_f32_16x16x32_bf16 v[108:111], v[152:155], v[192:195], v[108:111]
	v_mfma_f32_16x16x32_bf16 v[104:107], v[160:163], v[192:195], v[104:107]
	v_mfma_f32_16x16x32_bf16 v[92:95], v[152:155], v[200:203], v[92:95]
	v_mfma_f32_16x16x32_bf16 v[88:91], v[160:163], v[200:203], v[88:91]
	v_mfma_f32_16x16x32_bf16 v[76:79], v[152:155], v[208:211], v[76:79]
	v_mfma_f32_16x16x32_bf16 v[72:75], v[160:163], v[208:211], v[72:75]
	v_mfma_f32_16x16x32_bf16 v[124:127], v[156:159], v[188:191], v[124:127]
	v_mfma_f32_16x16x32_bf16 v[120:123], v[164:167], v[188:191], v[120:123]
	v_mfma_f32_16x16x32_bf16 v[108:111], v[156:159], v[196:199], v[108:111]
	v_mfma_f32_16x16x32_bf16 v[104:107], v[164:167], v[196:199], v[104:107]
	v_mfma_f32_16x16x32_bf16 v[92:95], v[156:159], v[204:207], v[92:95]
	v_mfma_f32_16x16x32_bf16 v[88:91], v[164:167], v[204:207], v[88:91]
	v_mfma_f32_16x16x32_bf16 v[76:79], v[156:159], v[212:215], v[76:79]
	v_mfma_f32_16x16x32_bf16 v[72:75], v[164:167], v[212:215], v[72:75]
	s_setprio 0
	s_setprio 1
	v_mfma_f32_16x16x32_bf16 v[116:119], v[168:171], v[184:187], v[116:119]
	v_mfma_f32_16x16x32_bf16 v[112:115], v[176:179], v[184:187], v[112:115]
	v_mfma_f32_16x16x32_bf16 v[100:103], v[168:171], v[192:195], v[100:103]
	v_mfma_f32_16x16x32_bf16 v[96:99], v[176:179], v[192:195], v[96:99]
	v_mfma_f32_16x16x32_bf16 v[84:87], v[168:171], v[200:203], v[84:87]
	v_mfma_f32_16x16x32_bf16 v[80:83], v[176:179], v[200:203], v[80:83]
	v_mfma_f32_16x16x32_bf16 v[68:71], v[168:171], v[208:211], v[68:71]
	v_mfma_f32_16x16x32_bf16 v[64:67], v[176:179], v[208:211], v[64:67]
	v_mfma_f32_16x16x32_bf16 v[116:119], v[172:175], v[188:191], v[116:119]
	v_mfma_f32_16x16x32_bf16 v[112:115], v[180:183], v[188:191], v[112:115]
	v_mfma_f32_16x16x32_bf16 v[100:103], v[172:175], v[196:199], v[100:103]
	v_mfma_f32_16x16x32_bf16 v[96:99], v[180:183], v[196:199], v[96:99]
	v_mfma_f32_16x16x32_bf16 v[84:87], v[172:175], v[204:207], v[84:87]
	v_mfma_f32_16x16x32_bf16 v[80:83], v[180:183], v[204:207], v[80:83]
	v_mfma_f32_16x16x32_bf16 v[68:71], v[172:175], v[212:215], v[68:71]
	v_mfma_f32_16x16x32_bf16 v[64:67], v[180:183], v[212:215], v[64:67]
	s_setprio 0
	s_barrier
	s_add_i32 s62, s53, s42
	s_mov_b32 m0, s62
	ds_read_b128 v[184:187], v151 offset:16384
	ds_read_b128 v[188:191], v151 offset:17408
	ds_read_b128 v[192:195], v151 offset:18432
	ds_read_b128 v[196:199], v151 offset:19456
	ds_read_b128 v[200:203], v151 offset:20480
	ds_read_b128 v[204:207], v151 offset:21504
	ds_read_b128 v[208:211], v151 offset:22528
	ds_read_b128 v[212:215], v151 offset:23552
	global_load_lds_dwordx4 v132, s[34:35]
	s_add_i32 m0, s62, 0x2000
	s_add_u32 s62, s34, 0x80000
	s_addc_u32 s63, s35, 0
	s_add_i32 s64, s54, s42
	global_load_lds_dwordx4 v128, s[34:35]
	s_mov_b32 m0, s64
	s_nop 0
	global_load_lds_dwordx4 v132, s[62:63]
	s_add_i32 m0, s64, 0x2000
	s_nop 0
	global_load_lds_dwordx4 v128, s[62:63]
	s_mov_b32 m0, s29
	s_nop 0
	global_load_lds_dwordx4 v134, s[36:37]
	s_mov_b32 m0, s45
	s_nop 0
	global_load_lds_dwordx4 v130, s[36:37]
	s_waitcnt vmcnt(8)
	s_waitcnt lgkmcnt(0)
	s_barrier
	s_setprio 1
	s_waitcnt lgkmcnt(0)
	v_mfma_f32_16x16x32_bf16 v[60:63], v[152:155], v[184:187], v[60:63]
	v_mfma_f32_16x16x32_bf16 v[56:59], v[160:163], v[184:187], v[56:59]
	v_mfma_f32_16x16x32_bf16 v[44:47], v[152:155], v[192:195], v[44:47]
	v_mfma_f32_16x16x32_bf16 v[40:43], v[160:163], v[192:195], v[40:43]
	v_mfma_f32_16x16x32_bf16 v[28:31], v[152:155], v[200:203], v[28:31]
	v_mfma_f32_16x16x32_bf16 v[24:27], v[160:163], v[200:203], v[24:27]
	v_mfma_f32_16x16x32_bf16 v[12:15], v[152:155], v[208:211], v[12:15]
	v_mfma_f32_16x16x32_bf16 v[8:11], v[160:163], v[208:211], v[8:11]
	v_mfma_f32_16x16x32_bf16 v[60:63], v[156:159], v[188:191], v[60:63]
	v_mfma_f32_16x16x32_bf16 v[56:59], v[164:167], v[188:191], v[56:59]
	v_mfma_f32_16x16x32_bf16 v[44:47], v[156:159], v[196:199], v[44:47]
	v_mfma_f32_16x16x32_bf16 v[40:43], v[164:167], v[196:199], v[40:43]
	v_mfma_f32_16x16x32_bf16 v[28:31], v[156:159], v[204:207], v[28:31]
	v_mfma_f32_16x16x32_bf16 v[24:27], v[164:167], v[204:207], v[24:27]
	v_mfma_f32_16x16x32_bf16 v[12:15], v[156:159], v[212:215], v[12:15]
	v_mfma_f32_16x16x32_bf16 v[8:11], v[164:167], v[212:215], v[8:11]
	s_setprio 0
	s_setprio 1
	v_mfma_f32_16x16x32_bf16 v[52:55], v[168:171], v[184:187], v[52:55]
	v_mfma_f32_16x16x32_bf16 v[48:51], v[176:179], v[184:187], v[48:51]
	v_mfma_f32_16x16x32_bf16 v[36:39], v[168:171], v[192:195], v[36:39]
	v_mfma_f32_16x16x32_bf16 v[32:35], v[176:179], v[192:195], v[32:35]
	v_mfma_f32_16x16x32_bf16 v[20:23], v[168:171], v[200:203], v[20:23]
	v_mfma_f32_16x16x32_bf16 v[16:19], v[176:179], v[200:203], v[16:19]
	v_mfma_f32_16x16x32_bf16 v[4:7], v[168:171], v[208:211], v[4:7]
	v_mfma_f32_16x16x32_bf16 v[0:3], v[176:179], v[208:211], v[0:3]
	v_mfma_f32_16x16x32_bf16 v[52:55], v[172:175], v[188:191], v[52:55]
	v_mfma_f32_16x16x32_bf16 v[48:51], v[180:183], v[188:191], v[48:51]
	v_mfma_f32_16x16x32_bf16 v[36:39], v[172:175], v[196:199], v[36:39]
	v_mfma_f32_16x16x32_bf16 v[32:35], v[180:183], v[196:199], v[32:35]
	v_mfma_f32_16x16x32_bf16 v[20:23], v[172:175], v[204:207], v[20:23]
	v_mfma_f32_16x16x32_bf16 v[16:19], v[180:183], v[204:207], v[16:19]
	v_mfma_f32_16x16x32_bf16 v[4:7], v[172:175], v[212:215], v[4:7]
	v_mfma_f32_16x16x32_bf16 v[0:3], v[180:183], v[212:215], v[0:3]
	s_setprio 0
	s_barrier
; #define PG8_STAGE(bufoff, gbase, voff) do { _Pragma("unroll") for (int _i = 0; _i < 2; ++_i) \
;         __builtin_amdgcn_global_load_lds((const unsigned*)((const char*)(gbase) + (voff)[_i]), (PG8_LAS unsigned*)(lds + (bufoff) + ldsw + _i * 8192), 16, 0, 0); } while (0)
; #define PG8_LDA(dst, b, h) do { _Pragma("unroll") for (int m = 0; m < 4; ++m) _Pragma("unroll") for (int k = 0; k < 2; ++k) dst[m][k] = *(const PG8_LAS bf16x8*)(lds + PG8_SA(b, h) + aoff + m * 2048 + k * 1024); } while (0)
; #define PG8_LDB(dst, b, h) do { _Pragma("unroll") for (int n = 0; n < 2; ++n) _Pragma("unroll") for (int k = 0; k < 2; ++k) dst[n][k] = *(const PG8_LAS bf16x8*)(lds + PG8_SB(b, h) + boff + n * 2048 + k * 1024); } while (0)
; #define PG8_MMA(ai, bj, At, Bt) do { __builtin_amdgcn_s_setprio(1); _Pragma("unroll") for (int m = 0; m < 4; ++m) _Pragma("unroll") for (int n = 0; n < 2; ++n) _Pragma("unroll") for (int k = 0; k < 2; ++k) \
;         acc[ai][bj][m][n] = __builtin_amdgcn_mfma_f32_16x16x32_bf16(Bt[n][k], At[m][k], acc[ai][bj][m][n], 0, 0, 0); __builtin_amdgcn_s_setprio(0); } while (0)
; #define PG8_WAIT_V(n) asm volatile("s_waitcnt vmcnt(" #n ")" ::: "memory")
; #define PG8_WAIT_L(n) asm volatile("s_waitcnt lgkmcnt(" #n ")" ::: "memory")
; #define PG8_BAR __builtin_amdgcn_s_barrier()
; #define PG8_SCHED __builtin_amdgcn_sched_barrier(0)
; template <class Epi, class Sched, bool ALIGN_EPI = false, bool SP2 = false>
; __device__ __forceinline__ void gemm_phase(PG8_LAS unsigned char* lds, const Gemm g, const Sched& S, const Epi& E) {
;     ...
;             PG8_LDB(B0, 1, 0); PG8_LDB(B1, 1, 1); PG8_SCHED; PG8_LDA(At, 1, 0); PG8_STAGE(PG8_SA(0, 1), a2 + hstep, voffA);
;             PG8_WAIT_V(8); PG8_WAIT_L(0); PG8_BAR; PG8_MMA(0, 0, At, B0); PG8_MMA(0, 1, At, B1); PG8_BAR; PG8_SCHED;
;             PG8_LDA(At, 1, 1); PG8_STAGE(PG8_SB(1, 0), b3, voffB); PG8_STAGE(PG8_SB(1, 1), b3 + hstep, voffB); PG8_STAGE(PG8_SA(1, 0), a3, voffA);
;             PG8_WAIT_V(8); PG8_WAIT_L(0); PG8_BAR; PG8_MMA(1, 0, At, B0); PG8_MMA(1, 1, At, B1); PG8_BAR; PG8_SCHED;
	s_add_i32 s62, 0, 0x18000
	s_add_i32 s63, 0, 0x1c000
	v_add_u32_e32 v164, s62, v147
	v_add_u32_e32 v180, s63, v147
	ds_read_b128 v[152:155], v164
	ds_read_b128 v[156:159], v164 offset:1024
	ds_read_b128 v[160:163], v164 offset:2048
	ds_read_b128 v[164:167], v164 offset:3072
	ds_read_b128 v[168:171], v180
	ds_read_b128 v[172:175], v180 offset:1024
	ds_read_b128 v[176:179], v180 offset:2048
	ds_read_b128 v[180:183], v180 offset:3072
	s_add_u32 s84, s36, 0x80
	s_addc_u32 s85, s37, 0
	s_add_u32 s36, s36, 0x80000
	s_addc_u32 s37, s37, 0
	s_mov_b32 m0, s46
	ds_read_b128 v[184:187], v151 offset:32768
	ds_read_b128 v[188:191], v151 offset:33792
	ds_read_b128 v[192:195], v151 offset:34816
	ds_read_b128 v[196:199], v151 offset:35840
	ds_read_b128 v[200:203], v151 offset:36864
	ds_read_b128 v[204:207], v151 offset:37888
	ds_read_b128 v[208:211], v151 offset:38912
	ds_read_b128 v[212:215], v151 offset:39936
	global_load_lds_dwordx4 v134, s[36:37]
	s_mov_b32 m0, s47
	s_nop 0
	global_load_lds_dwordx4 v130, s[36:37]
	s_waitcnt vmcnt(8)
	s_waitcnt lgkmcnt(0)
	s_barrier
	s_setprio 1
	s_waitcnt lgkmcnt(0)
	v_mfma_f32_16x16x32_bf16 v[124:127], v[152:155], v[184:187], v[124:127]
	v_mfma_f32_16x16x32_bf16 v[120:123], v[160:163], v[184:187], v[120:123]
	v_mfma_f32_16x16x32_bf16 v[108:111], v[152:155], v[192:195], v[108:111]
	v_mfma_f32_16x16x32_bf16 v[104:107], v[160:163], v[192:195], v[104:107]
	v_mfma_f32_16x16x32_bf16 v[92:95], v[152:155], v[200:203], v[92:95]
	v_mfma_f32_16x16x32_bf16 v[88:91], v[160:163], v[200:203], v[88:91]
	v_mfma_f32_16x16x32_bf16 v[76:79], v[152:155], v[208:211], v[76:79]
	v_mfma_f32_16x16x32_bf16 v[72:75], v[160:163], v[208:211], v[72:75]
	v_mfma_f32_16x16x32_bf16 v[124:127], v[156:159], v[188:191], v[124:127]
	v_mfma_f32_16x16x32_bf16 v[120:123], v[164:167], v[188:191], v[120:123]
	v_mfma_f32_16x16x32_bf16 v[108:111], v[156:159], v[196:199], v[108:111]
	v_mfma_f32_16x16x32_bf16 v[104:107], v[164:167], v[196:199], v[104:107]
	v_mfma_f32_16x16x32_bf16 v[92:95], v[156:159], v[204:207], v[92:95]
	v_mfma_f32_16x16x32_bf16 v[88:91], v[164:167], v[204:207], v[88:91]
	v_mfma_f32_16x16x32_bf16 v[76:79], v[156:159], v[212:215], v[76:79]
	v_mfma_f32_16x16x32_bf16 v[72:75], v[164:167], v[212:215], v[72:75]
	s_setprio 0
	s_setprio 1
	v_mfma_f32_16x16x32_bf16 v[116:119], v[168:171], v[184:187], v[116:119]
	v_mfma_f32_16x16x32_bf16 v[112:115], v[176:179], v[184:187], v[112:115]
	v_mfma_f32_16x16x32_bf16 v[100:103], v[168:171], v[192:195], v[100:103]
	v_mfma_f32_16x16x32_bf16 v[96:99], v[176:179], v[192:195], v[96:99]
	v_mfma_f32_16x16x32_bf16 v[84:87], v[168:171], v[200:203], v[84:87]
	v_mfma_f32_16x16x32_bf16 v[80:83], v[176:179], v[200:203], v[80:83]
	v_mfma_f32_16x16x32_bf16 v[68:71], v[168:171], v[208:211], v[68:71]
	v_mfma_f32_16x16x32_bf16 v[64:67], v[176:179], v[208:211], v[64:67]
	v_mfma_f32_16x16x32_bf16 v[116:119], v[172:175], v[188:191], v[116:119]
	v_mfma_f32_16x16x32_bf16 v[112:115], v[180:183], v[188:191], v[112:115]
	v_mfma_f32_16x16x32_bf16 v[100:103], v[172:175], v[196:199], v[100:103]
	v_mfma_f32_16x16x32_bf16 v[96:99], v[180:183], v[196:199], v[96:99]
	v_mfma_f32_16x16x32_bf16 v[84:87], v[172:175], v[204:207], v[84:87]
	v_mfma_f32_16x16x32_bf16 v[80:83], v[180:183], v[204:207], v[80:83]
	v_mfma_f32_16x16x32_bf16 v[68:71], v[172:175], v[212:215], v[68:71]
	v_mfma_f32_16x16x32_bf16 v[64:67], v[180:183], v[212:215], v[64:67]
	s_setprio 0
	s_barrier
	s_add_i32 s36, s62, s42
	s_add_u32 s86, s34, 0x80
	s_addc_u32 s87, s35, 0
	s_mov_b32 m0, s36
	ds_read_b128 v[184:187], v151 offset:49152
	ds_read_b128 v[188:191], v151 offset:50176
	ds_read_b128 v[192:195], v151 offset:51200
	ds_read_b128 v[196:199], v151 offset:52224
	ds_read_b128 v[200:203], v151 offset:53248
	ds_read_b128 v[204:207], v151 offset:54272
	ds_read_b128 v[208:211], v151 offset:55296
	ds_read_b128 v[212:215], v151 offset:56320
	global_load_lds_dwordx4 v132, s[86:87]
	s_add_i32 m0, s36, 0x2000
	s_add_u32 s34, s34, 0x80080
	s_addc_u32 s35, s35, 0
	s_add_i32 s36, s63, s42
	global_load_lds_dwordx4 v128, s[86:87]
	s_mov_b32 m0, s36
	s_nop 0
	global_load_lds_dwordx4 v132, s[34:35]
	s_add_i32 m0, s36, 0x2000
	s_nop 0
	global_load_lds_dwordx4 v128, s[34:35]
	s_mov_b32 m0, s49
	s_nop 0
	global_load_lds_dwordx4 v134, s[84:85]
	s_mov_b32 m0, s50
	s_nop 0
	global_load_lds_dwordx4 v130, s[84:85]
	s_waitcnt vmcnt(8)
	s_waitcnt lgkmcnt(0)
	s_barrier
	s_setprio 1
	s_waitcnt lgkmcnt(0)
	v_mfma_f32_16x16x32_bf16 v[60:63], v[152:155], v[184:187], v[60:63]
	v_mfma_f32_16x16x32_bf16 v[56:59], v[160:163], v[184:187], v[56:59]
	v_mfma_f32_16x16x32_bf16 v[44:47], v[152:155], v[192:195], v[44:47]
	v_mfma_f32_16x16x32_bf16 v[40:43], v[160:163], v[192:195], v[40:43]
	v_mfma_f32_16x16x32_bf16 v[28:31], v[152:155], v[200:203], v[28:31]
	v_mfma_f32_16x16x32_bf16 v[24:27], v[160:163], v[200:203], v[24:27]
	v_mfma_f32_16x16x32_bf16 v[12:15], v[152:155], v[208:211], v[12:15]
	v_mfma_f32_16x16x32_bf16 v[8:11], v[160:163], v[208:211], v[8:11]
	v_mfma_f32_16x16x32_bf16 v[60:63], v[156:159], v[188:191], v[60:63]
	v_mfma_f32_16x16x32_bf16 v[56:59], v[164:167], v[188:191], v[56:59]
	v_mfma_f32_16x16x32_bf16 v[44:47], v[156:159], v[196:199], v[44:47]
	v_mfma_f32_16x16x32_bf16 v[40:43], v[164:167], v[196:199], v[40:43]
	v_mfma_f32_16x16x32_bf16 v[28:31], v[156:159], v[204:207], v[28:31]
	v_mfma_f32_16x16x32_bf16 v[24:27], v[164:167], v[204:207], v[24:27]
	v_mfma_f32_16x16x32_bf16 v[12:15], v[156:159], v[212:215], v[12:15]
	v_mfma_f32_16x16x32_bf16 v[8:11], v[164:167], v[212:215], v[8:11]
	s_setprio 0
	s_setprio 1
	v_mfma_f32_16x16x32_bf16 v[52:55], v[168:171], v[184:187], v[52:55]
	v_mfma_f32_16x16x32_bf16 v[48:51], v[176:179], v[184:187], v[48:51]
	v_mfma_f32_16x16x32_bf16 v[36:39], v[168:171], v[192:195], v[36:39]
	v_mfma_f32_16x16x32_bf16 v[32:35], v[176:179], v[192:195], v[32:35]
	v_mfma_f32_16x16x32_bf16 v[20:23], v[168:171], v[200:203], v[20:23]
	v_mfma_f32_16x16x32_bf16 v[16:19], v[176:179], v[200:203], v[16:19]
	v_mfma_f32_16x16x32_bf16 v[4:7], v[168:171], v[208:211], v[4:7]
	v_mfma_f32_16x16x32_bf16 v[0:3], v[176:179], v[208:211], v[0:3]
	v_mfma_f32_16x16x32_bf16 v[52:55], v[172:175], v[188:191], v[52:55]
	v_mfma_f32_16x16x32_bf16 v[48:51], v[180:183], v[188:191], v[48:51]
	v_mfma_f32_16x16x32_bf16 v[36:39], v[172:175], v[196:199], v[36:39]
	v_mfma_f32_16x16x32_bf16 v[32:35], v[180:183], v[196:199], v[32:35]
	v_mfma_f32_16x16x32_bf16 v[20:23], v[172:175], v[204:207], v[20:23]
	v_mfma_f32_16x16x32_bf16 v[16:19], v[180:183], v[204:207], v[16:19]
	v_mfma_f32_16x16x32_bf16 v[4:7], v[172:175], v[212:215], v[4:7]
	v_mfma_f32_16x16x32_bf16 v[0:3], v[180:183], v[212:215], v[0:3]
	s_setprio 0
	s_barrier
; __device__ __forceinline__ float fsilu(float v) { return v * fsigmoid(v); }
; __device__ __forceinline__ u32x4 pack8(const f32x4 a, const f32x4 b) { u32x4 w; w.x = cvt_pk_bf16(a[0], a[1]); w.y = cvt_pk_bf16(a[2], a[3]); w.z = cvt_pk_bf16(b[0], b[1]); w.w = cvt_pk_bf16(b[2], b[3]); return w; }
;     __device__ __forceinline__ void operator()(const f32x4 (&acc)[2][2][4][2], const Unit& u, int wr, int wc, int fr, int fq) const {
;         const int row0 = u.pm * BM + wr * 64 + fr, col0 = u.pn * 128 + wc * 32 + 8 * fq;
; #pragma unroll
;         for (int ai = 0; ai < 2; ++ai)
; #pragma unroll
;             for (int m = 0; m < 4; ++m) {
;                 bf16_t* rowp = O + (size_t)(row0 + ai * HALF + m * 16) * ldc + col0;
;                 f32x4 h0, h1;
; #pragma unroll
;                 for (int j = 0; j < 4; ++j) { h0[j] = fsilu(acc[ai][0][m][0][j]) * acc[ai][1][m][0][j]; h1[j] = fsilu(acc[ai][0][m][1][j]) * acc[ai][1][m][1][j]; }
;                 *(u32x4*)rowp = pack8(h0, h1);
;             }
; template <class Epi, class Sched, bool ALIGN_EPI = false, bool SP2 = false>
; __device__ __forceinline__ void gemm_phase(PG8_LAS unsigned char* lds, const Gemm g, const Sched& S, const Epi& E) {
;     ...
;         for (int t = 0; t < nt; t += 2) {
;             const bool last = (t == nt - 2);
;             const char* a1 = cA + (size_t)(t + 1) * kstep;
;             const char* a2 = last ? nA : cA + (size_t)(t + 2) * kstep; const char* b2 = last ? nB : cB + (size_t)(t + 2) * kstep;
	s_add_i32 s61, s61, 2
	s_add_u32 s30, s30, 0x100
	s_addc_u32 s31, s31, 0
	s_add_u32 s59, s59, 0x100
	s_addc_u32 s60, s60, 0
	s_cmp_gt_u32 s61, 29
	s_cbranch_scc0 .LBB0_945
	v_mul_f32_e32 v153, 0xbfb8aa3b, v124
	v_mul_f32_e32 v158, 0xbfb8aa3b, v120
	v_exp_f32_e32 v153, v153
	v_exp_f32_e32 v159, v158
	v_mul_f32_e32 v158, 0xbfb8aa3b, v125
	v_exp_f32_e32 v160, v158
	v_add_f32_e32 v153, 1.0, v153
	v_rcp_f32_e32 v158, v153
	v_add_f32_e32 v153, 1.0, v159
	v_add_f32_e32 v159, 1.0, v160
	v_rcp_f32_e32 v159, v159
	v_mul_f32_e32 v160, 0xbfb8aa3b, v121
	v_exp_f32_e32 v161, v160
	v_rcp_f32_e32 v160, v153
	v_pk_mul_f32 v[124:125], v[124:125], v[158:159]
	v_mul_f32_e32 v153, 0xbfb8aa3b, v127
	v_pk_mul_f32 v[116:117], v[124:125], v[116:117]
	v_add_f32_e32 v124, 1.0, v161
	v_mul_f32_e32 v125, 0xbfb8aa3b, v122
	v_rcp_f32_e32 v161, v124
	v_mul_f32_e32 v124, 0xbfb8aa3b, v126
	v_exp_f32_e32 v125, v125
	v_exp_f32_e32 v124, v124
	v_exp_f32_e32 v153, v153
	v_mul_f32_e32 v158, 0xbfb8aa3b, v123
	v_exp_f32_e32 v159, v158
	v_add_f32_e32 v125, 1.0, v125
	v_add_f32_e32 v124, 1.0, v124
	v_rcp_f32_e32 v158, v125
	v_add_f32_e32 v125, 1.0, v153
	v_rcp_f32_e32 v124, v124
	v_rcp_f32_e32 v125, v125
	v_add_f32_e32 v153, 1.0, v159
	v_rcp_f32_e32 v159, v153
	v_pk_mul_f32 v[120:121], v[120:121], v[160:161]
	v_lshl_or_b32 v154, s56, 7, v148
	v_pk_mul_f32 v[120:121], v[120:121], v[112:113]
	v_pk_mul_f32 v[112:113], v[126:127], v[124:125]
	v_lshl_add_u32 v152, s28, 8, v146
	v_ashrrev_i32_e32 v155, 31, v154
	v_mov_b64_e32 v[144:145], s[10:11]
	v_pk_mul_f32 v[118:119], v[112:113], v[118:119]
	v_pk_mul_f32 v[112:113], v[122:123], v[158:159]
	v_mad_i64_i32 v[156:157], s[30:31], v152, s55, v[144:145]
	v_pk_mul_f32 v[122:123], v[112:113], v[114:115]
	v_lshlrev_b64 v[112:113], 1, v[154:155]
	v_lshl_add_u64 v[124:125], v[156:157], 0, v[112:113]
	v_cvt_pk_bf16_f32 v114, v116, v117
	v_cvt_pk_bf16_f32 v115, v118, v119
	v_cvt_pk_bf16_f32 v116, v120, v121
	v_cvt_pk_bf16_f32 v117, v122, v123
	global_store_dwordx4 v[124:125], v[114:117], off
	v_mul_f32_e32 v118, 0xbfb8aa3b, v109
	v_exp_f32_e32 v118, v118
	v_mul_f32_e32 v116, 0xbfb8aa3b, v108
	v_mul_f32_e32 v117, 0xbfb8aa3b, v104
	v_exp_f32_e32 v116, v116
	v_exp_f32_e32 v117, v117
	v_or_b32_e32 v114, 16, v152
	v_mad_i64_i32 v[114:115], s[30:31], v114, s55, v[144:145]
	v_add_f32_e32 v116, 1.0, v116
	v_add_f32_e32 v119, 1.0, v117
	v_add_f32_e32 v117, 1.0, v118
	v_rcp_f32_e32 v116, v116
	v_rcp_f32_e32 v117, v117
	v_mul_f32_e32 v118, 0xbfb8aa3b, v105
	v_exp_f32_e32 v120, v118
	v_rcp_f32_e32 v118, v119
	v_pk_mul_f32 v[108:109], v[108:109], v[116:117]
	v_mul_f32_e32 v116, 0xbfb8aa3b, v111
	v_pk_mul_f32 v[100:101], v[108:109], v[100:101]
	v_add_f32_e32 v108, 1.0, v120
	v_rcp_f32_e32 v119, v108
	v_mul_f32_e32 v109, 0xbfb8aa3b, v106
	v_mul_f32_e32 v108, 0xbfb8aa3b, v110
	v_exp_f32_e32 v109, v109
	v_exp_f32_e32 v108, v108
	v_exp_f32_e32 v117, v116
	v_mul_f32_e32 v116, 0xbfb8aa3b, v107
	v_pk_mul_f32 v[104:105], v[104:105], v[118:119]
	v_exp_f32_e32 v118, v116
	v_add_f32_e32 v109, 1.0, v109
	v_add_f32_e32 v108, 1.0, v108
	v_rcp_f32_e32 v116, v109
	v_add_f32_e32 v109, 1.0, v117
	v_rcp_f32_e32 v108, v108
	v_rcp_f32_e32 v109, v109
	v_add_f32_e32 v117, 1.0, v118
	v_rcp_f32_e32 v117, v117
	v_pk_mul_f32 v[104:105], v[104:105], v[96:97]
	v_pk_mul_f32 v[96:97], v[110:111], v[108:109]
	v_lshl_add_u64 v[108:109], v[114:115], 0, v[112:113]
	v_pk_mul_f32 v[102:103], v[96:97], v[102:103]
	v_pk_mul_f32 v[96:97], v[106:107], v[116:117]
	s_and_b64 vcc, exec, s[8:9]
	v_pk_mul_f32 v[106:107], v[96:97], v[98:99]
	v_cvt_pk_bf16_f32 v96, v100, v101
	v_cvt_pk_bf16_f32 v97, v102, v103
	v_cvt_pk_bf16_f32 v98, v104, v105
	v_cvt_pk_bf16_f32 v99, v106, v107
	global_store_dwordx4 v[108:109], v[96:99], off
	v_mul_f32_e32 v100, 0xbfb8aa3b, v93
	v_exp_f32_e32 v100, v100
	v_mul_f32_e32 v98, 0xbfb8aa3b, v92
	v_mul_f32_e32 v99, 0xbfb8aa3b, v88
	v_exp_f32_e32 v98, v98
	v_exp_f32_e32 v99, v99
	v_or_b32_e32 v96, 32, v152
	v_mad_i64_i32 v[96:97], s[30:31], v96, s55, v[144:145]
	v_add_f32_e32 v98, 1.0, v98
	v_add_f32_e32 v101, 1.0, v99
	v_add_f32_e32 v99, 1.0, v100
	v_rcp_f32_e32 v98, v98
	v_rcp_f32_e32 v99, v99
	v_mul_f32_e32 v100, 0xbfb8aa3b, v89
	v_exp_f32_e32 v102, v100
	v_rcp_f32_e32 v100, v101
	v_pk_mul_f32 v[92:93], v[92:93], v[98:99]
	v_mul_f32_e32 v98, 0xbfb8aa3b, v95
	v_pk_mul_f32 v[84:85], v[92:93], v[84:85]
	v_add_f32_e32 v92, 1.0, v102
	v_rcp_f32_e32 v101, v92
	v_mul_f32_e32 v93, 0xbfb8aa3b, v90
	v_mul_f32_e32 v92, 0xbfb8aa3b, v94
	v_exp_f32_e32 v93, v93
	v_exp_f32_e32 v92, v92
	v_exp_f32_e32 v99, v98
	v_mul_f32_e32 v98, 0xbfb8aa3b, v91
	v_pk_mul_f32 v[88:89], v[88:89], v[100:101]
	v_exp_f32_e32 v100, v98
	v_add_f32_e32 v93, 1.0, v93
	v_add_f32_e32 v92, 1.0, v92
	v_rcp_f32_e32 v98, v93
	v_add_f32_e32 v93, 1.0, v99
	v_rcp_f32_e32 v92, v92
	v_rcp_f32_e32 v93, v93
	v_add_f32_e32 v99, 1.0, v100
	v_rcp_f32_e32 v99, v99
	v_pk_mul_f32 v[88:89], v[88:89], v[80:81]
	v_pk_mul_f32 v[80:81], v[94:95], v[92:93]
	v_lshl_add_u64 v[92:93], v[96:97], 0, v[112:113]
	v_pk_mul_f32 v[86:87], v[80:81], v[86:87]
	v_pk_mul_f32 v[80:81], v[90:91], v[98:99]
	s_mov_b32 s56, s14
	v_pk_mul_f32 v[90:91], v[80:81], v[82:83]
	v_cvt_pk_bf16_f32 v80, v84, v85
	v_cvt_pk_bf16_f32 v81, v86, v87
	v_cvt_pk_bf16_f32 v82, v88, v89
	v_cvt_pk_bf16_f32 v83, v90, v91
	global_store_dwordx4 v[92:93], v[80:83], off
	v_mul_f32_e32 v84, 0xbfb8aa3b, v77
	v_exp_f32_e32 v84, v84
	v_mul_f32_e32 v82, 0xbfb8aa3b, v76
	v_mul_f32_e32 v83, 0xbfb8aa3b, v72
	v_exp_f32_e32 v82, v82
	v_exp_f32_e32 v83, v83
	v_or_b32_e32 v80, 48, v152
	v_mad_i64_i32 v[80:81], s[30:31], v80, s55, v[144:145]
	v_add_f32_e32 v82, 1.0, v82
	v_add_f32_e32 v85, 1.0, v83
; __device__ __forceinline__ float fsilu(float v) { return v * fsigmoid(v); }
; __device__ __forceinline__ u32x4 pack8(const f32x4 a, const f32x4 b) { u32x4 w; w.x = cvt_pk_bf16(a[0], a[1]); w.y = cvt_pk_bf16(a[2], a[3]); w.z = cvt_pk_bf16(b[0], b[1]); w.w = cvt_pk_bf16(b[2], b[3]); return w; }
;     __device__ __forceinline__ void operator()(const f32x4 (&acc)[2][2][4][2], const Unit& u, int wr, int wc, int fr, int fq) const {
;         const int row0 = u.pm * BM + wr * 64 + fr, col0 = u.pn * 128 + wc * 32 + 8 * fq;
; #pragma unroll
;         for (int ai = 0; ai < 2; ++ai)
; #pragma unroll
;             for (int m = 0; m < 4; ++m) {
;                 bf16_t* rowp = O + (size_t)(row0 + ai * HALF + m * 16) * ldc + col0;
;                 f32x4 h0, h1;
; #pragma unroll
;                 for (int j = 0; j < 4; ++j) { h0[j] = fsilu(acc[ai][0][m][0][j]) * acc[ai][1][m][0][j]; h1[j] = fsilu(acc[ai][0][m][1][j]) * acc[ai][1][m][1][j]; }
;                 *(u32x4*)rowp = pack8(h0, h1);
;             }
	v_add_f32_e32 v83, 1.0, v84
	v_rcp_f32_e32 v82, v82
	v_rcp_f32_e32 v83, v83
	v_mul_f32_e32 v84, 0xbfb8aa3b, v73
	v_exp_f32_e32 v86, v84
	v_rcp_f32_e32 v84, v85
	v_pk_mul_f32 v[76:77], v[76:77], v[82:83]
	v_mul_f32_e32 v82, 0xbfb8aa3b, v79
	v_pk_mul_f32 v[68:69], v[76:77], v[68:69]
	v_add_f32_e32 v76, 1.0, v86
	v_rcp_f32_e32 v85, v76
	v_mul_f32_e32 v77, 0xbfb8aa3b, v74
	v_mul_f32_e32 v76, 0xbfb8aa3b, v78
	v_exp_f32_e32 v77, v77
	v_exp_f32_e32 v76, v76
	v_exp_f32_e32 v83, v82
	v_mul_f32_e32 v82, 0xbfb8aa3b, v75
	v_pk_mul_f32 v[72:73], v[72:73], v[84:85]
	v_exp_f32_e32 v84, v82
	v_add_f32_e32 v77, 1.0, v77
	v_add_f32_e32 v76, 1.0, v76
	v_rcp_f32_e32 v82, v77
	v_add_f32_e32 v77, 1.0, v83
	v_rcp_f32_e32 v76, v76
	v_rcp_f32_e32 v77, v77
	v_add_f32_e32 v83, 1.0, v84
	v_rcp_f32_e32 v83, v83
	v_pk_mul_f32 v[72:73], v[72:73], v[64:65]
	v_pk_mul_f32 v[64:65], v[78:79], v[76:77]
	v_lshl_add_u64 v[76:77], v[80:81], 0, v[112:113]
	v_pk_mul_f32 v[70:71], v[64:65], v[70:71]
	v_pk_mul_f32 v[64:65], v[74:75], v[82:83]
	s_mov_b32 s28, s22
	v_pk_mul_f32 v[74:75], v[64:65], v[66:67]
	v_cvt_pk_bf16_f32 v64, v68, v69
	v_cvt_pk_bf16_f32 v65, v70, v71
	v_cvt_pk_bf16_f32 v66, v72, v73
	v_cvt_pk_bf16_f32 v67, v74, v75
	global_store_dwordx4 v[76:77], v[64:67], off
	v_mul_f32_e32 v68, 0xbfb8aa3b, v61
	v_exp_f32_e32 v68, v68
	v_mul_f32_e32 v66, 0xbfb8aa3b, v60
	v_mul_f32_e32 v67, 0xbfb8aa3b, v56
	v_exp_f32_e32 v66, v66
	v_exp_f32_e32 v67, v67
	v_add_u32_e32 v64, 0x80, v152
	v_mad_i64_i32 v[64:65], s[30:31], v64, s55, v[144:145]
	v_add_f32_e32 v66, 1.0, v66
	v_add_f32_e32 v69, 1.0, v67
	v_add_f32_e32 v67, 1.0, v68
	v_rcp_f32_e32 v66, v66
	v_rcp_f32_e32 v67, v67
	v_mul_f32_e32 v68, 0xbfb8aa3b, v57
	v_exp_f32_e32 v70, v68
	v_rcp_f32_e32 v68, v69
	v_pk_mul_f32 v[60:61], v[60:61], v[66:67]
	v_mul_f32_e32 v66, 0xbfb8aa3b, v63
	v_pk_mul_f32 v[52:53], v[60:61], v[52:53]
	v_add_f32_e32 v60, 1.0, v70
	v_rcp_f32_e32 v69, v60
	v_mul_f32_e32 v61, 0xbfb8aa3b, v58
	v_mul_f32_e32 v60, 0xbfb8aa3b, v62
	v_exp_f32_e32 v61, v61
	v_exp_f32_e32 v60, v60
	v_exp_f32_e32 v67, v66
	v_mul_f32_e32 v66, 0xbfb8aa3b, v59
	v_pk_mul_f32 v[56:57], v[56:57], v[68:69]
	v_exp_f32_e32 v68, v66
	v_add_f32_e32 v61, 1.0, v61
	v_add_f32_e32 v60, 1.0, v60
	v_rcp_f32_e32 v66, v61
	v_add_f32_e32 v61, 1.0, v67
	v_rcp_f32_e32 v60, v60
	v_rcp_f32_e32 v61, v61
	v_add_f32_e32 v67, 1.0, v68
	v_rcp_f32_e32 v67, v67
	v_pk_mul_f32 v[56:57], v[56:57], v[48:49]
	v_pk_mul_f32 v[48:49], v[62:63], v[60:61]
	v_lshl_add_u64 v[60:61], v[64:65], 0, v[112:113]
	v_pk_mul_f32 v[54:55], v[48:49], v[54:55]
	v_pk_mul_f32 v[48:49], v[58:59], v[66:67]
	s_mov_b64 s[34:35], s[26:27]
	v_pk_mul_f32 v[58:59], v[48:49], v[50:51]
	v_cvt_pk_bf16_f32 v48, v52, v53
	v_cvt_pk_bf16_f32 v49, v54, v55
	v_cvt_pk_bf16_f32 v50, v56, v57
	v_cvt_pk_bf16_f32 v51, v58, v59
	global_store_dwordx4 v[60:61], v[48:51], off
	v_mul_f32_e32 v52, 0xbfb8aa3b, v45
	v_exp_f32_e32 v52, v52
	v_mul_f32_e32 v50, 0xbfb8aa3b, v44
	v_mul_f32_e32 v51, 0xbfb8aa3b, v40
	v_exp_f32_e32 v50, v50
	v_exp_f32_e32 v51, v51
	v_add_u32_e32 v48, 0x90, v152
	v_mad_i64_i32 v[48:49], s[30:31], v48, s55, v[144:145]
	v_add_f32_e32 v50, 1.0, v50
	v_add_f32_e32 v53, 1.0, v51
	v_add_f32_e32 v51, 1.0, v52
	v_rcp_f32_e32 v50, v50
	v_rcp_f32_e32 v51, v51
	v_mul_f32_e32 v52, 0xbfb8aa3b, v41
	v_exp_f32_e32 v54, v52
	v_rcp_f32_e32 v52, v53
	v_pk_mul_f32 v[44:45], v[44:45], v[50:51]
	v_mul_f32_e32 v50, 0xbfb8aa3b, v47
	v_pk_mul_f32 v[36:37], v[44:45], v[36:37]
	v_add_f32_e32 v44, 1.0, v54
	v_rcp_f32_e32 v53, v44
	v_mul_f32_e32 v45, 0xbfb8aa3b, v42
	v_mul_f32_e32 v44, 0xbfb8aa3b, v46
	v_exp_f32_e32 v45, v45
	v_exp_f32_e32 v44, v44
	v_exp_f32_e32 v51, v50
	v_mul_f32_e32 v50, 0xbfb8aa3b, v43
	v_pk_mul_f32 v[40:41], v[40:41], v[52:53]
	v_exp_f32_e32 v52, v50
	v_add_f32_e32 v45, 1.0, v45
	v_add_f32_e32 v44, 1.0, v44
; __device__ __forceinline__ float fsilu(float v) { return v * fsigmoid(v); }
; __device__ __forceinline__ u32x4 pack8(const f32x4 a, const f32x4 b) { u32x4 w; w.x = cvt_pk_bf16(a[0], a[1]); w.y = cvt_pk_bf16(a[2], a[3]); w.z = cvt_pk_bf16(b[0], b[1]); w.w = cvt_pk_bf16(b[2], b[3]); return w; }
; #define PG8_WAIT_V(n) asm volatile("s_waitcnt vmcnt(" #n ")" ::: "memory")
; #define PG8_BAR __builtin_amdgcn_s_barrier()
;     __device__ __forceinline__ void operator()(const f32x4 (&acc)[2][2][4][2], const Unit& u, int wr, int wc, int fr, int fq) const {
;         const int row0 = u.pm * BM + wr * 64 + fr, col0 = u.pn * 128 + wc * 32 + 8 * fq;
; #pragma unroll
;         for (int ai = 0; ai < 2; ++ai)
; #pragma unroll
;             for (int m = 0; m < 4; ++m) {
;                 bf16_t* rowp = O + (size_t)(row0 + ai * HALF + m * 16) * ldc + col0;
;                 f32x4 h0, h1;
; #pragma unroll
;                 for (int j = 0; j < 4; ++j) { h0[j] = fsilu(acc[ai][0][m][0][j]) * acc[ai][1][m][0][j]; h1[j] = fsilu(acc[ai][0][m][1][j]) * acc[ai][1][m][1][j]; }
;                 *(u32x4*)rowp = pack8(h0, h1);
;             }
; template <class Epi, class Sched, bool ALIGN_EPI = false, bool SP2 = false>
; __device__ __forceinline__ void gemm_phase(PG8_LAS unsigned char* lds, const Gemm g, const Sched& S, const Epi& E) {
;     ...
;     PG8_WAIT_V(0);
;     if constexpr (!ALIGN_EPI) { if (wr == 0) PG8_BAR; }
;     PG8_BAR;
	v_rcp_f32_e32 v50, v45
	v_add_f32_e32 v45, 1.0, v51
	v_rcp_f32_e32 v44, v44
	v_rcp_f32_e32 v45, v45
	v_add_f32_e32 v51, 1.0, v52
	v_rcp_f32_e32 v51, v51
	v_pk_mul_f32 v[40:41], v[40:41], v[32:33]
	v_pk_mul_f32 v[32:33], v[46:47], v[44:45]
	v_lshl_add_u64 v[44:45], v[48:49], 0, v[112:113]
	v_pk_mul_f32 v[38:39], v[32:33], v[38:39]
	v_pk_mul_f32 v[32:33], v[42:43], v[50:51]
	s_nop 0
	v_pk_mul_f32 v[42:43], v[32:33], v[34:35]
	v_cvt_pk_bf16_f32 v32, v36, v37
	v_cvt_pk_bf16_f32 v33, v38, v39
	v_cvt_pk_bf16_f32 v34, v40, v41
	v_cvt_pk_bf16_f32 v35, v42, v43
	global_store_dwordx4 v[44:45], v[32:35], off
	v_mul_f32_e32 v36, 0xbfb8aa3b, v29
	v_exp_f32_e32 v36, v36
	v_mul_f32_e32 v34, 0xbfb8aa3b, v28
	v_mul_f32_e32 v35, 0xbfb8aa3b, v24
	v_exp_f32_e32 v34, v34
	v_exp_f32_e32 v35, v35
	v_add_u32_e32 v32, 0xa0, v152
	v_mad_i64_i32 v[32:33], s[30:31], v32, s55, v[144:145]
	v_add_f32_e32 v34, 1.0, v34
	v_add_f32_e32 v37, 1.0, v35
	v_add_f32_e32 v35, 1.0, v36
	v_rcp_f32_e32 v34, v34
	v_rcp_f32_e32 v35, v35
	v_mul_f32_e32 v36, 0xbfb8aa3b, v25
	v_exp_f32_e32 v38, v36
	v_rcp_f32_e32 v36, v37
	v_pk_mul_f32 v[28:29], v[28:29], v[34:35]
	v_mul_f32_e32 v34, 0xbfb8aa3b, v31
	v_pk_mul_f32 v[20:21], v[28:29], v[20:21]
	v_add_f32_e32 v28, 1.0, v38
	v_rcp_f32_e32 v37, v28
	v_mul_f32_e32 v29, 0xbfb8aa3b, v26
	v_mul_f32_e32 v28, 0xbfb8aa3b, v30
	v_exp_f32_e32 v29, v29
	v_exp_f32_e32 v28, v28
	v_exp_f32_e32 v35, v34
	v_mul_f32_e32 v34, 0xbfb8aa3b, v27
	v_pk_mul_f32 v[24:25], v[24:25], v[36:37]
	v_exp_f32_e32 v36, v34
	v_add_f32_e32 v29, 1.0, v29
	v_add_f32_e32 v28, 1.0, v28
	v_rcp_f32_e32 v34, v29
	v_add_f32_e32 v29, 1.0, v35
	v_rcp_f32_e32 v28, v28
	v_rcp_f32_e32 v29, v29
	v_add_f32_e32 v35, 1.0, v36
	v_rcp_f32_e32 v35, v35
	v_pk_mul_f32 v[24:25], v[24:25], v[16:17]
	v_pk_mul_f32 v[16:17], v[30:31], v[28:29]
	v_lshl_add_u64 v[28:29], v[32:33], 0, v[112:113]
	v_pk_mul_f32 v[22:23], v[16:17], v[22:23]
	v_pk_mul_f32 v[16:17], v[26:27], v[34:35]
	s_nop 0
	v_pk_mul_f32 v[26:27], v[16:17], v[18:19]
	v_cvt_pk_bf16_f32 v16, v20, v21
	v_cvt_pk_bf16_f32 v17, v22, v23
	v_cvt_pk_bf16_f32 v18, v24, v25
	v_cvt_pk_bf16_f32 v19, v26, v27
	global_store_dwordx4 v[28:29], v[16:19], off
	v_mul_f32_e32 v20, 0xbfb8aa3b, v13
	v_exp_f32_e32 v20, v20
	v_mul_f32_e32 v18, 0xbfb8aa3b, v12
	v_mul_f32_e32 v19, 0xbfb8aa3b, v8
	v_exp_f32_e32 v18, v18
	v_exp_f32_e32 v19, v19
	v_add_u32_e32 v16, 0xb0, v152
	v_mad_i64_i32 v[16:17], s[30:31], v16, s55, v[144:145]
	v_add_f32_e32 v18, 1.0, v18
	v_add_f32_e32 v21, 1.0, v19
	v_add_f32_e32 v19, 1.0, v20
	v_rcp_f32_e32 v18, v18
	v_rcp_f32_e32 v19, v19
	v_mul_f32_e32 v20, 0xbfb8aa3b, v9
	v_exp_f32_e32 v22, v20
	v_rcp_f32_e32 v20, v21
	v_pk_mul_f32 v[12:13], v[12:13], v[18:19]
	v_mul_f32_e32 v18, 0xbfb8aa3b, v15
	v_pk_mul_f32 v[4:5], v[12:13], v[4:5]
	v_add_f32_e32 v12, 1.0, v22
	v_rcp_f32_e32 v21, v12
	v_mul_f32_e32 v13, 0xbfb8aa3b, v10
	v_mul_f32_e32 v12, 0xbfb8aa3b, v14
	v_exp_f32_e32 v13, v13
	v_exp_f32_e32 v12, v12
	v_exp_f32_e32 v19, v18
	v_mul_f32_e32 v18, 0xbfb8aa3b, v11
	v_pk_mul_f32 v[8:9], v[8:9], v[20:21]
	v_exp_f32_e32 v20, v18
	v_add_f32_e32 v13, 1.0, v13
	v_add_f32_e32 v12, 1.0, v12
	v_rcp_f32_e32 v18, v13
	v_add_f32_e32 v13, 1.0, v19
	v_rcp_f32_e32 v12, v12
	v_rcp_f32_e32 v13, v13
	v_add_f32_e32 v19, 1.0, v20
	v_rcp_f32_e32 v19, v19
	v_pk_mul_f32 v[8:9], v[8:9], v[0:1]
	v_pk_mul_f32 v[0:1], v[14:15], v[12:13]
	v_lshl_add_u64 v[12:13], v[16:17], 0, v[112:113]
	v_pk_mul_f32 v[6:7], v[0:1], v[6:7]
	v_pk_mul_f32 v[0:1], v[10:11], v[18:19]
	s_mov_b64 s[30:31], s[24:25]
	v_pk_mul_f32 v[10:11], v[0:1], v[2:3]
	v_cvt_pk_bf16_f32 v0, v4, v5
	v_cvt_pk_bf16_f32 v1, v6, v7
	v_cvt_pk_bf16_f32 v2, v8, v9
	v_cvt_pk_bf16_f32 v3, v10, v11
	global_store_dwordx4 v[12:13], v[0:3], off
	s_cbranch_vccz .LBB0_942
	s_waitcnt vmcnt(0)
	s_cmpk_gt_u32 s3, 0xff
	s_cbranch_scc1 .LBB0_949
	s_barrier

; #define PG8_STAGE(bufoff, gbase, voff) do { _Pragma("unroll") for (int _i = 0; _i < 2; ++_i) \
;         __builtin_amdgcn_global_load_lds((const unsigned*)((const char*)(gbase) + (voff)[_i]), (PG8_LAS unsigned*)(lds + (bufoff) + ldsw + _i * 8192), 16, 0, 0); } while (0)
; #define PG8_LDA(dst, b, h) do { _Pragma("unroll") for (int m = 0; m < 4; ++m) _Pragma("unroll") for (int k = 0; k < 2; ++k) dst[m][k] = *(const PG8_LAS bf16x8*)(lds + PG8_SA(b, h) + aoff + m * 2048 + k * 1024); } while (0)
; #define PG8_LDB(dst, b, h) do { _Pragma("unroll") for (int n = 0; n < 2; ++n) _Pragma("unroll") for (int k = 0; k < 2; ++k) dst[n][k] = *(const PG8_LAS bf16x8*)(lds + PG8_SB(b, h) + boff + n * 2048 + k * 1024); } while (0)
; #define PG8_MMA(ai, bj, At, Bt) do { __builtin_amdgcn_s_setprio(1); _Pragma("unroll") for (int m = 0; m < 4; ++m) _Pragma("unroll") for (int n = 0; n < 2; ++n) _Pragma("unroll") for (int k = 0; k < 2; ++k) \
;         acc[ai][bj][m][n] = __builtin_amdgcn_mfma_f32_16x16x32_bf16(Bt[n][k], At[m][k], acc[ai][bj][m][n], 0, 0, 0); __builtin_amdgcn_s_setprio(0); } while (0)
; #define PG8_WAIT_V(n) asm volatile("s_waitcnt vmcnt(" #n ")" ::: "memory")
; #define PG8_BAR __builtin_amdgcn_s_barrier()
; template <class Epi, class Sched, bool ALIGN_EPI = false, bool SP2 = false>
; __device__ __forceinline__ void gemm_phase(PG8_LAS unsigned char* lds, const Gemm g, const Sched& S, const Epi& E) {
;     ...
;         for (int t = 0; t < nt; t += 2) {
;             const bool last = (t == nt - 2);
;             const char* a1 = cA + (size_t)(t + 1) * kstep;
;             const char* a2 = last ? nA : cA + (size_t)(t + 2) * kstep; const char* b2 = last ? nB : cB + (size_t)(t + 2) * kstep;
;             const char* a3 = a2 + kstep; const char* b3 = b2 + kstep;
;             if (last && has_next) S.a_ready(nxt);
;             if constexpr (SP2) {
;             PG8_LDB(B0, 0, 0); PG8_LDB(B1, 0, 1); PG8_SCHED; PG8_LDA(At, 0, 0); PG8_STAGE(PG8_SA(1, 1), a1 + hstep, voffA);
;             PG8_WAIT_V(8); PG8_WAIT_L(0); PG8_BAR; PG8_MMA(0, 0, At, B0); PG8_MMA(0, 1, At, B1); PG8_BAR; PG8_SCHED;
;             PG8_LDA(At, 0, 1); PG8_STAGE(PG8_SB(0, 0), b2, voffB); PG8_STAGE(PG8_SB(0, 1), b2 + hstep, voffB); PG8_STAGE(PG8_SA(0, 0), a2, voffA);
;             PG8_WAIT_V(8); PG8_WAIT_L(0); PG8_BAR; PG8_MMA(1, 0, At, B0); PG8_MMA(1, 1, At, B1); PG8_BAR; PG8_SCHED;
.LBB0_1021:
	ds_read_b128 v[144:147], v169
	ds_read_b128 v[148:151], v169 offset:1024
	ds_read_b128 v[152:155], v169 offset:2048
	ds_read_b128 v[156:159], v169 offset:3072
	ds_read_b128 v[160:163], v170
	ds_read_b128 v[172:175], v170 offset:1024
	ds_read_b128 v[176:179], v170 offset:2048
	ds_read_b128 v[180:183], v170 offset:3072
	s_add_u32 s26, s24, 0x100
	s_addc_u32 s27, s25, 0
	s_cmpk_eq_i32 s56, 0x54
	s_cselect_b32 s31, s5, s27
	s_cselect_b32 s30, s4, s26
	s_cselect_b32 s29, s7, s55
	s_cselect_b32 s28, s6, s54
	s_add_i32 m0, s38, 0xc000
	ds_read_b128 v[184:187], v171
	ds_read_b128 v[188:191], v171 offset:1024
	ds_read_b128 v[192:195], v171 offset:2048
	ds_read_b128 v[196:199], v171 offset:3072
	ds_read_b128 v[200:203], v171 offset:4096
	ds_read_b128 v[204:207], v171 offset:5120
	ds_read_b128 v[208:211], v171 offset:6144
	ds_read_b128 v[212:215], v171 offset:7168
	global_load_lds_dwordx4 v136, s[24:25]
	s_add_i32 m0, s38, 0xe000
	s_nop 0
	global_load_lds_dwordx4 v138, s[24:25]
	s_waitcnt vmcnt(8)
	s_waitcnt lgkmcnt(0)
	s_barrier
	s_setprio 1
	s_waitcnt lgkmcnt(0)
	v_mfma_f32_16x16x32_bf16 v[124:127], v[144:147], v[184:187], v[124:127]
	v_mfma_f32_16x16x32_bf16 v[120:123], v[152:155], v[184:187], v[120:123]
	v_mfma_f32_16x16x32_bf16 v[116:119], v[144:147], v[192:195], v[116:119]
	v_mfma_f32_16x16x32_bf16 v[112:115], v[152:155], v[192:195], v[112:115]
	v_mfma_f32_16x16x32_bf16 v[108:111], v[144:147], v[200:203], v[108:111]
	v_mfma_f32_16x16x32_bf16 v[96:99], v[152:155], v[200:203], v[96:99]
	v_mfma_f32_16x16x32_bf16 v[84:87], v[144:147], v[208:211], v[84:87]
	v_mfma_f32_16x16x32_bf16 v[76:79], v[152:155], v[208:211], v[76:79]
	v_mfma_f32_16x16x32_bf16 v[124:127], v[148:151], v[188:191], v[124:127]
	v_mfma_f32_16x16x32_bf16 v[120:123], v[156:159], v[188:191], v[120:123]
	v_mfma_f32_16x16x32_bf16 v[116:119], v[148:151], v[196:199], v[116:119]
	v_mfma_f32_16x16x32_bf16 v[112:115], v[156:159], v[196:199], v[112:115]
	v_mfma_f32_16x16x32_bf16 v[108:111], v[148:151], v[204:207], v[108:111]
	v_mfma_f32_16x16x32_bf16 v[96:99], v[156:159], v[204:207], v[96:99]
	v_mfma_f32_16x16x32_bf16 v[84:87], v[148:151], v[212:215], v[84:87]
	v_mfma_f32_16x16x32_bf16 v[76:79], v[156:159], v[212:215], v[76:79]
	s_setprio 0
	s_setprio 1
	v_mfma_f32_16x16x32_bf16 v[104:107], v[160:163], v[184:187], v[104:107]
	v_mfma_f32_16x16x32_bf16 v[100:103], v[176:179], v[184:187], v[100:103]
	v_mfma_f32_16x16x32_bf16 v[92:95], v[160:163], v[192:195], v[92:95]
	v_mfma_f32_16x16x32_bf16 v[88:91], v[176:179], v[192:195], v[88:91]
	v_mfma_f32_16x16x32_bf16 v[80:83], v[160:163], v[200:203], v[80:83]
	v_mfma_f32_16x16x32_bf16 v[72:75], v[176:179], v[200:203], v[72:75]
	v_mfma_f32_16x16x32_bf16 v[68:71], v[160:163], v[208:211], v[68:71]
	v_mfma_f32_16x16x32_bf16 v[64:67], v[176:179], v[208:211], v[64:67]
	v_mfma_f32_16x16x32_bf16 v[104:107], v[172:175], v[188:191], v[104:107]
	v_mfma_f32_16x16x32_bf16 v[100:103], v[180:183], v[188:191], v[100:103]
	v_mfma_f32_16x16x32_bf16 v[92:95], v[172:175], v[196:199], v[92:95]
	v_mfma_f32_16x16x32_bf16 v[88:91], v[180:183], v[196:199], v[88:91]
	v_mfma_f32_16x16x32_bf16 v[80:83], v[172:175], v[204:207], v[80:83]
	v_mfma_f32_16x16x32_bf16 v[72:75], v[180:183], v[204:207], v[72:75]
	v_mfma_f32_16x16x32_bf16 v[68:71], v[172:175], v[212:215], v[68:71]
	v_mfma_f32_16x16x32_bf16 v[64:67], v[180:183], v[212:215], v[64:67]
	s_setprio 0
	s_barrier
	s_add_i32 s24, s48, s37
	s_mov_b32 m0, s24
	ds_read_b128 v[184:187], v171 offset:16384
	ds_read_b128 v[188:191], v171 offset:17408
	ds_read_b128 v[192:195], v171 offset:18432
	ds_read_b128 v[196:199], v171 offset:19456
	ds_read_b128 v[200:203], v171 offset:20480
	ds_read_b128 v[204:207], v171 offset:21504
	ds_read_b128 v[208:211], v171 offset:22528
	ds_read_b128 v[212:215], v171 offset:23552
	global_load_lds_dwordx4 v130, s[28:29]
	s_add_i32 m0, s24, 0x2000
	s_add_u32 s24, s28, 0x160000
	s_addc_u32 s25, s29, 0
	s_add_i32 s57, s49, s37
	global_load_lds_dwordx4 v134, s[28:29]
	s_mov_b32 m0, s57
	s_nop 0
	global_load_lds_dwordx4 v130, s[24:25]
	s_add_i32 m0, s57, 0x2000
	s_nop 0
	global_load_lds_dwordx4 v134, s[24:25]
	s_mov_b32 m0, s38
	s_nop 0
	global_load_lds_dwordx4 v128, s[30:31]
	s_mov_b32 m0, s39
	s_nop 0
	global_load_lds_dwordx4 v132, s[30:31]
	s_waitcnt vmcnt(8)
	s_waitcnt lgkmcnt(0)
	s_barrier
	s_setprio 1
	s_waitcnt lgkmcnt(0)
	v_mfma_f32_16x16x32_bf16 v[60:63], v[144:147], v[184:187], v[60:63]
	v_mfma_f32_16x16x32_bf16 v[56:59], v[152:155], v[184:187], v[56:59]
	v_mfma_f32_16x16x32_bf16 v[52:55], v[144:147], v[192:195], v[52:55]
	v_mfma_f32_16x16x32_bf16 v[48:51], v[152:155], v[192:195], v[48:51]
	v_mfma_f32_16x16x32_bf16 v[44:47], v[144:147], v[200:203], v[44:47]
	v_mfma_f32_16x16x32_bf16 v[32:35], v[152:155], v[200:203], v[32:35]
	v_mfma_f32_16x16x32_bf16 v[20:23], v[144:147], v[208:211], v[20:23]
	v_mfma_f32_16x16x32_bf16 v[12:15], v[152:155], v[208:211], v[12:15]
	v_mfma_f32_16x16x32_bf16 v[60:63], v[148:151], v[188:191], v[60:63]
	v_mfma_f32_16x16x32_bf16 v[56:59], v[156:159], v[188:191], v[56:59]
	v_mfma_f32_16x16x32_bf16 v[52:55], v[148:151], v[196:199], v[52:55]
	v_mfma_f32_16x16x32_bf16 v[48:51], v[156:159], v[196:199], v[48:51]
	v_mfma_f32_16x16x32_bf16 v[44:47], v[148:151], v[204:207], v[44:47]
	v_mfma_f32_16x16x32_bf16 v[32:35], v[156:159], v[204:207], v[32:35]
	v_mfma_f32_16x16x32_bf16 v[20:23], v[148:151], v[212:215], v[20:23]
	v_mfma_f32_16x16x32_bf16 v[12:15], v[156:159], v[212:215], v[12:15]
	s_setprio 0
	s_setprio 1
	v_mfma_f32_16x16x32_bf16 v[40:43], v[160:163], v[184:187], v[40:43]
	v_mfma_f32_16x16x32_bf16 v[36:39], v[176:179], v[184:187], v[36:39]
	v_mfma_f32_16x16x32_bf16 v[28:31], v[160:163], v[192:195], v[28:31]
	v_mfma_f32_16x16x32_bf16 v[24:27], v[176:179], v[192:195], v[24:27]
	v_mfma_f32_16x16x32_bf16 v[16:19], v[160:163], v[200:203], v[16:19]
	v_mfma_f32_16x16x32_bf16 v[8:11], v[176:179], v[200:203], v[8:11]
	v_mfma_f32_16x16x32_bf16 v[4:7], v[160:163], v[208:211], v[4:7]
	v_mfma_f32_16x16x32_bf16 v[0:3], v[176:179], v[208:211], v[0:3]
	v_mfma_f32_16x16x32_bf16 v[40:43], v[172:175], v[188:191], v[40:43]
	v_mfma_f32_16x16x32_bf16 v[36:39], v[180:183], v[188:191], v[36:39]
	v_mfma_f32_16x16x32_bf16 v[28:31], v[172:175], v[196:199], v[28:31]
	v_mfma_f32_16x16x32_bf16 v[24:27], v[180:183], v[196:199], v[24:27]
	v_mfma_f32_16x16x32_bf16 v[16:19], v[172:175], v[204:207], v[16:19]
	v_mfma_f32_16x16x32_bf16 v[8:11], v[180:183], v[204:207], v[8:11]
	v_mfma_f32_16x16x32_bf16 v[4:7], v[172:175], v[212:215], v[4:7]
	v_mfma_f32_16x16x32_bf16 v[0:3], v[180:183], v[212:215], v[0:3]
	s_setprio 0
	s_barrier
; #define PG8_STAGE(bufoff, gbase, voff) do { _Pragma("unroll") for (int _i = 0; _i < 2; ++_i) \
;         __builtin_amdgcn_global_load_lds((const unsigned*)((const char*)(gbase) + (voff)[_i]), (PG8_LAS unsigned*)(lds + (bufoff) + ldsw + _i * 8192), 16, 0, 0); } while (0)
; #define PG8_LDA(dst, b, h) do { _Pragma("unroll") for (int m = 0; m < 4; ++m) _Pragma("unroll") for (int k = 0; k < 2; ++k) dst[m][k] = *(const PG8_LAS bf16x8*)(lds + PG8_SA(b, h) + aoff + m * 2048 + k * 1024); } while (0)
; #define PG8_LDB(dst, b, h) do { _Pragma("unroll") for (int n = 0; n < 2; ++n) _Pragma("unroll") for (int k = 0; k < 2; ++k) dst[n][k] = *(const PG8_LAS bf16x8*)(lds + PG8_SB(b, h) + boff + n * 2048 + k * 1024); } while (0)
; #define PG8_MMA(ai, bj, At, Bt) do { __builtin_amdgcn_s_setprio(1); _Pragma("unroll") for (int m = 0; m < 4; ++m) _Pragma("unroll") for (int n = 0; n < 2; ++n) _Pragma("unroll") for (int k = 0; k < 2; ++k) \
;         acc[ai][bj][m][n] = __builtin_amdgcn_mfma_f32_16x16x32_bf16(Bt[n][k], At[m][k], acc[ai][bj][m][n], 0, 0, 0); __builtin_amdgcn_s_setprio(0); } while (0)
; #define PG8_WAIT_V(n) asm volatile("s_waitcnt vmcnt(" #n ")" ::: "memory")
; #define PG8_WAIT_L(n) asm volatile("s_waitcnt lgkmcnt(" #n ")" ::: "memory")
; #define PG8_BAR __builtin_amdgcn_s_barrier()
; #define PG8_SCHED __builtin_amdgcn_sched_barrier(0)
; template <class Epi, class Sched, bool ALIGN_EPI = false, bool SP2 = false>
; __device__ __forceinline__ void gemm_phase(PG8_LAS unsigned char* lds, const Gemm g, const Sched& S, const Epi& E) {
;     ...
;             PG8_LDB(B0, 1, 0); PG8_LDB(B1, 1, 1); PG8_SCHED; PG8_LDA(At, 1, 0); PG8_STAGE(PG8_SA(0, 1), a2 + hstep, voffA);
;             PG8_WAIT_V(8); PG8_WAIT_L(0); PG8_BAR; PG8_MMA(0, 0, At, B0); PG8_MMA(0, 1, At, B1); PG8_BAR; PG8_SCHED;
;             PG8_LDA(At, 1, 1); PG8_STAGE(PG8_SB(1, 0), b3, voffB); PG8_STAGE(PG8_SB(1, 1), b3 + hstep, voffB); PG8_STAGE(PG8_SA(1, 0), a3, voffA);
;             PG8_WAIT_V(8); PG8_WAIT_L(0); PG8_BAR; PG8_MMA(1, 0, At, B0); PG8_MMA(1, 1, At, B1); PG8_BAR; PG8_SCHED;
	s_add_i32 s57, 0, 0x18000
	s_add_i32 s58, 0, 0x1c000
	v_add_u32_e32 v156, s57, v167
	v_add_u32_e32 v180, s58, v167
	ds_read_b128 v[144:147], v156
	ds_read_b128 v[148:151], v156 offset:1024
	ds_read_b128 v[152:155], v156 offset:2048
	ds_read_b128 v[156:159], v156 offset:3072
	ds_read_b128 v[160:163], v180
	ds_read_b128 v[172:175], v180 offset:1024
	ds_read_b128 v[176:179], v180 offset:2048
	ds_read_b128 v[180:183], v180 offset:3072
	s_add_u32 s24, s30, 0x160000
	s_addc_u32 s25, s31, 0
	s_mov_b32 m0, s40
	ds_read_b128 v[184:187], v171 offset:32768
	ds_read_b128 v[188:191], v171 offset:33792
	ds_read_b128 v[192:195], v171 offset:34816
	ds_read_b128 v[196:199], v171 offset:35840
	ds_read_b128 v[200:203], v171 offset:36864
	ds_read_b128 v[204:207], v171 offset:37888
	ds_read_b128 v[208:211], v171 offset:38912
	ds_read_b128 v[212:215], v171 offset:39936
	global_load_lds_dwordx4 v128, s[24:25]
	s_mov_b32 m0, s41
	s_nop 0
	global_load_lds_dwordx4 v132, s[24:25]
	s_waitcnt vmcnt(8)
	s_waitcnt lgkmcnt(0)
	s_barrier
	s_setprio 1
	s_waitcnt lgkmcnt(0)
	v_mfma_f32_16x16x32_bf16 v[124:127], v[144:147], v[184:187], v[124:127]
	v_mfma_f32_16x16x32_bf16 v[120:123], v[152:155], v[184:187], v[120:123]
	v_mfma_f32_16x16x32_bf16 v[116:119], v[144:147], v[192:195], v[116:119]
	v_mfma_f32_16x16x32_bf16 v[112:115], v[152:155], v[192:195], v[112:115]
	v_mfma_f32_16x16x32_bf16 v[108:111], v[144:147], v[200:203], v[108:111]
	v_mfma_f32_16x16x32_bf16 v[96:99], v[152:155], v[200:203], v[96:99]
	v_mfma_f32_16x16x32_bf16 v[84:87], v[144:147], v[208:211], v[84:87]
	v_mfma_f32_16x16x32_bf16 v[76:79], v[152:155], v[208:211], v[76:79]
	v_mfma_f32_16x16x32_bf16 v[124:127], v[148:151], v[188:191], v[124:127]
	v_mfma_f32_16x16x32_bf16 v[120:123], v[156:159], v[188:191], v[120:123]
	v_mfma_f32_16x16x32_bf16 v[116:119], v[148:151], v[196:199], v[116:119]
	v_mfma_f32_16x16x32_bf16 v[112:115], v[156:159], v[196:199], v[112:115]
	v_mfma_f32_16x16x32_bf16 v[108:111], v[148:151], v[204:207], v[108:111]
	v_mfma_f32_16x16x32_bf16 v[96:99], v[156:159], v[204:207], v[96:99]
	v_mfma_f32_16x16x32_bf16 v[84:87], v[148:151], v[212:215], v[84:87]
	v_mfma_f32_16x16x32_bf16 v[76:79], v[156:159], v[212:215], v[76:79]
	s_setprio 0
	s_setprio 1
	v_mfma_f32_16x16x32_bf16 v[104:107], v[160:163], v[184:187], v[104:107]
	v_mfma_f32_16x16x32_bf16 v[100:103], v[176:179], v[184:187], v[100:103]
	v_mfma_f32_16x16x32_bf16 v[92:95], v[160:163], v[192:195], v[92:95]
	v_mfma_f32_16x16x32_bf16 v[88:91], v[176:179], v[192:195], v[88:91]
	v_mfma_f32_16x16x32_bf16 v[80:83], v[160:163], v[200:203], v[80:83]
	v_mfma_f32_16x16x32_bf16 v[72:75], v[176:179], v[200:203], v[72:75]
	v_mfma_f32_16x16x32_bf16 v[68:71], v[160:163], v[208:211], v[68:71]
	v_mfma_f32_16x16x32_bf16 v[64:67], v[176:179], v[208:211], v[64:67]
	v_mfma_f32_16x16x32_bf16 v[104:107], v[172:175], v[188:191], v[104:107]
	v_mfma_f32_16x16x32_bf16 v[100:103], v[180:183], v[188:191], v[100:103]
	v_mfma_f32_16x16x32_bf16 v[92:95], v[172:175], v[196:199], v[92:95]
	v_mfma_f32_16x16x32_bf16 v[88:91], v[180:183], v[196:199], v[88:91]
	v_mfma_f32_16x16x32_bf16 v[80:83], v[172:175], v[204:207], v[80:83]
	v_mfma_f32_16x16x32_bf16 v[72:75], v[180:183], v[204:207], v[72:75]
	v_mfma_f32_16x16x32_bf16 v[68:71], v[172:175], v[212:215], v[68:71]
	v_mfma_f32_16x16x32_bf16 v[64:67], v[180:183], v[212:215], v[64:67]
	s_setprio 0
	s_barrier
	s_add_i32 s24, s57, s37
	s_add_u32 s86, s28, 0x80
	s_addc_u32 s87, s29, 0
	s_mov_b32 m0, s24
	ds_read_b128 v[184:187], v171 offset:49152
	ds_read_b128 v[188:191], v171 offset:50176
	ds_read_b128 v[192:195], v171 offset:51200
	ds_read_b128 v[196:199], v171 offset:52224
	ds_read_b128 v[200:203], v171 offset:53248
	ds_read_b128 v[204:207], v171 offset:54272
	ds_read_b128 v[208:211], v171 offset:55296
	ds_read_b128 v[212:215], v171 offset:56320
	global_load_lds_dwordx4 v130, s[86:87]
	s_add_i32 m0, s24, 0x2000
	s_add_u32 s24, s28, 0x160080
	s_addc_u32 s25, s29, 0
	s_add_i32 s28, s58, s37
	global_load_lds_dwordx4 v134, s[86:87]
	s_mov_b32 m0, s28
	s_nop 0
	global_load_lds_dwordx4 v130, s[24:25]
	s_add_i32 m0, s28, 0x2000
	s_nop 0
	global_load_lds_dwordx4 v134, s[24:25]
	s_add_u32 s84, s30, 0x80
	s_addc_u32 s85, s31, 0
	s_mov_b32 m0, s45
	s_nop 0
	global_load_lds_dwordx4 v128, s[84:85]
	s_mov_b32 m0, s46
	s_nop 0
	global_load_lds_dwordx4 v132, s[84:85]
	s_waitcnt vmcnt(8)
	s_waitcnt lgkmcnt(0)
	s_barrier
	s_setprio 1
	s_waitcnt lgkmcnt(0)
	v_mfma_f32_16x16x32_bf16 v[60:63], v[144:147], v[184:187], v[60:63]
	v_mfma_f32_16x16x32_bf16 v[56:59], v[152:155], v[184:187], v[56:59]
	v_mfma_f32_16x16x32_bf16 v[52:55], v[144:147], v[192:195], v[52:55]
	v_mfma_f32_16x16x32_bf16 v[48:51], v[152:155], v[192:195], v[48:51]
	v_mfma_f32_16x16x32_bf16 v[44:47], v[144:147], v[200:203], v[44:47]
	v_mfma_f32_16x16x32_bf16 v[32:35], v[152:155], v[200:203], v[32:35]
	v_mfma_f32_16x16x32_bf16 v[20:23], v[144:147], v[208:211], v[20:23]
	v_mfma_f32_16x16x32_bf16 v[12:15], v[152:155], v[208:211], v[12:15]
	v_mfma_f32_16x16x32_bf16 v[60:63], v[148:151], v[188:191], v[60:63]
	v_mfma_f32_16x16x32_bf16 v[56:59], v[156:159], v[188:191], v[56:59]
	v_mfma_f32_16x16x32_bf16 v[52:55], v[148:151], v[196:199], v[52:55]
	v_mfma_f32_16x16x32_bf16 v[48:51], v[156:159], v[196:199], v[48:51]
	v_mfma_f32_16x16x32_bf16 v[44:47], v[148:151], v[204:207], v[44:47]
	v_mfma_f32_16x16x32_bf16 v[32:35], v[156:159], v[204:207], v[32:35]
	v_mfma_f32_16x16x32_bf16 v[20:23], v[148:151], v[212:215], v[20:23]
	v_mfma_f32_16x16x32_bf16 v[12:15], v[156:159], v[212:215], v[12:15]
	s_setprio 0
	s_setprio 1
	v_mfma_f32_16x16x32_bf16 v[40:43], v[160:163], v[184:187], v[40:43]
	v_mfma_f32_16x16x32_bf16 v[36:39], v[176:179], v[184:187], v[36:39]
	v_mfma_f32_16x16x32_bf16 v[28:31], v[160:163], v[192:195], v[28:31]
	v_mfma_f32_16x16x32_bf16 v[24:27], v[176:179], v[192:195], v[24:27]
	v_mfma_f32_16x16x32_bf16 v[16:19], v[160:163], v[200:203], v[16:19]
	v_mfma_f32_16x16x32_bf16 v[8:11], v[176:179], v[200:203], v[8:11]
	v_mfma_f32_16x16x32_bf16 v[4:7], v[160:163], v[208:211], v[4:7]
	v_mfma_f32_16x16x32_bf16 v[0:3], v[176:179], v[208:211], v[0:3]
	v_mfma_f32_16x16x32_bf16 v[40:43], v[172:175], v[188:191], v[40:43]
	v_mfma_f32_16x16x32_bf16 v[36:39], v[180:183], v[188:191], v[36:39]
	v_mfma_f32_16x16x32_bf16 v[28:31], v[172:175], v[196:199], v[28:31]
	v_mfma_f32_16x16x32_bf16 v[24:27], v[180:183], v[196:199], v[24:27]
	v_mfma_f32_16x16x32_bf16 v[16:19], v[172:175], v[204:207], v[16:19]
	v_mfma_f32_16x16x32_bf16 v[8:11], v[180:183], v[204:207], v[8:11]
	v_mfma_f32_16x16x32_bf16 v[4:7], v[172:175], v[212:215], v[4:7]
	v_mfma_f32_16x16x32_bf16 v[0:3], v[180:183], v[212:215], v[0:3]
	s_setprio 0
	s_barrier
;     __device__ __forceinline__ void operator()(const f32x4 (&acc)[2][2][4][2], const Unit& u, int wr, int wc, int fr, int fq) const {
;         const int row0 = u.pm * BM + wr * 64 + fr, col0 = u.pn * BM + wc * 32 + 8 * fq;
;         const float* gp = gate + (u.pm >> 5) * 18432 + col0;
;         f32x4 gv[2][2];
; #pragma unroll
;         for (int bj = 0; bj < 2; ++bj)
; #pragma unroll
;             for (int n = 0; n < 2; ++n) gv[bj][n] = *(const f32x4*)(gp + bj * HALF + 4 * n) * scale;
; #pragma unroll
;         for (int ai = 0; ai < 2; ++ai) { f32x4 r[4][2][2];
; #pragma unroll
;             for (int m = 0; m < 4; ++m) { const size_t off = (size_t)(row0 + ai * HALF + m * 16) * 2048 + col0;
; #pragma unroll
;                 for (int bj = 0; bj < 2; ++bj)
; #pragma unroll
;                     for (int n = 0; n < 2; ++n) r[m][bj][n] = *(const f32x4*)(res + off + bj * HALF + 4 * n); }
; #pragma unroll
;             for (int m = 0; m < 4; ++m) { const size_t off = (size_t)(row0 + ai * HALF + m * 16) * 2048 + col0;
; #pragma unroll
;                 for (int bj = 0; bj < 2; ++bj)
; #pragma unroll
;                     for (int n = 0; n < 2; ++n) *(f32x4*)(out + off + bj * HALF + 4 * n) = r[m][bj][n] + gv[bj][n] * acc[ai][bj][m][n]; } }
	s_add_i32 s56, s56, 2
	s_add_u32 s54, s54, 0x100
	s_addc_u32 s55, s55, 0
	s_cmpk_gt_u32 s56, 0x55
	s_mov_b64 s[24:25], s[26:27]
	s_cbranch_scc0 .LBB0_1021
	s_lshr_b32 s24, s52, 5
	s_mulk_i32 s24, 0x4800
	s_ashr_i32 s25, s24, 31
	v_lshl_or_b32 v144, s53, 8, v168
	s_lshl_b64 s[24:25], s[24:25], 2
	s_add_u32 s24, s43, s24
	v_ashrrev_i32_e32 v145, 31, v144
	s_addc_u32 s25, s44, s25
	v_lshlrev_b64 v[144:145], 2, v[144:145]
	v_lshl_add_u64 v[154:155], s[24:25], 0, v[144:145]
	global_load_dwordx4 v[146:149], v[154:155], off offset:16
	global_load_dwordx4 v[150:153], v[154:155], off
	global_load_dwordx4 v[172:175], v[154:155], off offset:528
	global_load_dwordx4 v[176:179], v[154:155], off offset:512
	v_lshl_add_u32 v154, s52, 8, v166
	v_ashrrev_i32_e32 v155, 31, v154
	v_lshl_add_u64 v[162:163], s[8:9], 0, v[144:145]
	v_lshlrev_b64 v[164:165], 13, v[154:155]
	v_lshl_add_u64 v[156:157], v[162:163], 0, v[164:165]
	global_load_dwordx4 v[180:183], v[156:157], off
	global_load_dwordx4 v[184:187], v[156:157], off offset:16
	global_load_dwordx4 v[188:191], v[156:157], off offset:528
	global_load_dwordx4 v[192:195], v[156:157], off offset:512
	v_or_b32_e32 v156, 16, v154
	v_ashrrev_i32_e32 v157, 31, v156
	v_lshlrev_b64 v[156:157], 13, v[156:157]
	v_lshl_add_u64 v[158:159], v[162:163], 0, v[156:157]
	global_load_dwordx4 v[196:199], v[158:159], off
	global_load_dwordx4 v[200:203], v[158:159], off offset:16
	global_load_dwordx4 v[204:207], v[158:159], off offset:528
	global_load_dwordx4 v[208:211], v[158:159], off offset:512
	v_or_b32_e32 v158, 32, v154
	v_ashrrev_i32_e32 v159, 31, v158
	v_lshlrev_b64 v[158:159], 13, v[158:159]
	v_or_b32_e32 v154, 48, v154
	v_lshl_add_u64 v[160:161], v[162:163], 0, v[158:159]
	v_ashrrev_i32_e32 v155, 31, v154
	global_load_dwordx4 v[212:215], v[160:161], off
	global_load_dwordx4 v[216:219], v[160:161], off offset:16
	global_load_dwordx4 v[220:223], v[160:161], off offset:512
	global_load_dwordx4 v[224:227], v[160:161], off offset:528
	v_lshlrev_b64 v[244:245], 13, v[154:155]
	v_lshl_add_u64 v[154:155], v[162:163], 0, v[244:245]
	global_load_dwordx4 v[228:231], v[154:155], off
	global_load_dwordx4 v[232:235], v[154:155], off offset:16
	global_load_dwordx4 v[236:239], v[154:155], off offset:512
	global_load_dwordx4 v[240:243], v[154:155], off offset:528
	v_lshl_add_u64 v[154:155], s[10:11], 0, v[164:165]
	v_lshl_add_u64 v[246:247], v[154:155], 0, v[144:145]
	v_lshl_add_u64 v[154:155], s[10:11], 0, v[156:157]
	v_lshl_add_u64 v[156:157], s[10:11], 0, v[158:159]
	v_lshl_add_u64 v[248:249], v[154:155], 0, v[144:145]
	v_lshl_add_u64 v[250:251], v[156:157], 0, v[144:145]
	s_and_b64 vcc, exec, s[0:1]
	s_mov_b32 s53, s50
	s_mov_b32 s52, s51
	s_mov_b64 s[26:27], s[6:7]
	s_mov_b64 s[24:25], s[4:5]
	s_waitcnt vmcnt(0)
	v_pk_mul_f32 v[154:155], v[148:149], 0.5 op_sel_hi:[1,0]
	v_pk_mul_f32 v[158:159], v[152:153], 0.5 op_sel_hi:[1,0]
	v_pk_mul_f32 v[160:161], v[150:151], 0.5 op_sel_hi:[1,0]
	v_pk_mul_f32 v[150:151], v[178:179], 0.5 op_sel_hi:[1,0]
	v_pk_mul_f32 v[152:153], v[176:177], 0.5 op_sel_hi:[1,0]
	v_pk_mul_f32 v[156:157], v[146:147], 0.5 op_sel_hi:[1,0]
	v_pk_mul_f32 v[146:147], v[174:175], 0.5 op_sel_hi:[1,0]
	v_pk_mul_f32 v[148:149], v[172:173], 0.5 op_sel_hi:[1,0]
	v_pk_fma_f32 v[126:127], v[126:127], v[158:159], v[182:183]
	v_pk_fma_f32 v[124:125], v[124:125], v[160:161], v[180:181]
	v_pk_fma_f32 v[122:123], v[122:123], v[154:155], v[186:187]
	v_pk_fma_f32 v[120:121], v[120:121], v[156:157], v[184:185]
	v_pk_fma_f32 v[106:107], v[106:107], v[150:151], v[194:195]
	v_pk_fma_f32 v[104:105], v[104:105], v[152:153], v[192:193]
	v_pk_fma_f32 v[102:103], v[102:103], v[146:147], v[190:191]
	v_pk_fma_f32 v[100:101], v[100:101], v[148:149], v[188:189]
	v_pk_fma_f32 v[118:119], v[118:119], v[158:159], v[198:199]
	v_pk_fma_f32 v[116:117], v[116:117], v[160:161], v[196:197]
	v_pk_fma_f32 v[114:115], v[114:115], v[154:155], v[202:203]
	v_pk_fma_f32 v[112:113], v[112:113], v[156:157], v[200:201]
	v_pk_fma_f32 v[82:83], v[82:83], v[150:151], v[222:223]
	v_pk_fma_f32 v[80:81], v[80:81], v[152:153], v[220:221]
	v_pk_fma_f32 v[94:95], v[94:95], v[150:151], v[210:211]
	v_pk_fma_f32 v[92:93], v[92:93], v[152:153], v[208:209]
	v_pk_fma_f32 v[90:91], v[90:91], v[146:147], v[206:207]
	v_pk_fma_f32 v[88:89], v[88:89], v[148:149], v[204:205]
	v_pk_fma_f32 v[110:111], v[110:111], v[158:159], v[214:215]
	v_pk_fma_f32 v[108:109], v[108:109], v[160:161], v[212:213]
	v_pk_fma_f32 v[98:99], v[98:99], v[154:155], v[218:219]
	v_pk_fma_f32 v[96:97], v[96:97], v[156:157], v[216:217]
	global_store_dwordx4 v[246:247], v[124:127], off
	global_store_dwordx4 v[246:247], v[120:123], off offset:16
	global_store_dwordx4 v[246:247], v[104:107], off offset:512
	global_store_dwordx4 v[246:247], v[100:103], off offset:528
	global_store_dwordx4 v[248:249], v[116:119], off
	global_store_dwordx4 v[248:249], v[112:115], off offset:16
	global_store_dwordx4 v[248:249], v[92:95], off offset:512
	global_store_dwordx4 v[248:249], v[88:91], off offset:528
	global_store_dwordx4 v[250:251], v[108:111], off
	global_store_dwordx4 v[250:251], v[96:99], off offset:16
	global_store_dwordx4 v[250:251], v[80:83], off offset:512
	v_pk_fma_f32 v[74:75], v[74:75], v[146:147], v[226:227]
	v_pk_fma_f32 v[72:73], v[72:73], v[148:149], v[224:225]
	v_lshl_add_u64 v[80:81], s[10:11], 0, v[244:245]
	global_store_dwordx4 v[250:251], v[72:75], off offset:528
; #define PG8_WAIT_V(n) asm volatile("s_waitcnt vmcnt(" #n ")" ::: "memory")
; #define PG8_BAR __builtin_amdgcn_s_barrier()
;     __device__ __forceinline__ void operator()(const f32x4 (&acc)[2][2][4][2], const Unit& u, int wr, int wc, int fr, int fq) const {
;         const int row0 = u.pm * BM + wr * 64 + fr, col0 = u.pn * BM + wc * 32 + 8 * fq;
;         const float* gp = gate + (u.pm >> 5) * 18432 + col0;
;         f32x4 gv[2][2];
; #pragma unroll
;         for (int bj = 0; bj < 2; ++bj)
; #pragma unroll
;             for (int n = 0; n < 2; ++n) gv[bj][n] = *(const f32x4*)(gp + bj * HALF + 4 * n) * scale;
; #pragma unroll
;         for (int ai = 0; ai < 2; ++ai) { f32x4 r[4][2][2];
; #pragma unroll
;             for (int m = 0; m < 4; ++m) { const size_t off = (size_t)(row0 + ai * HALF + m * 16) * 2048 + col0;
; #pragma unroll
;                 for (int bj = 0; bj < 2; ++bj)
; #pragma unroll
;                     for (int n = 0; n < 2; ++n) r[m][bj][n] = *(const f32x4*)(res + off + bj * HALF + 4 * n); }
; #pragma unroll
;             for (int m = 0; m < 4; ++m) { const size_t off = (size_t)(row0 + ai * HALF + m * 16) * 2048 + col0;
; #pragma unroll
;                 for (int bj = 0; bj < 2; ++bj)
; #pragma unroll
;                     for (int n = 0; n < 2; ++n) *(f32x4*)(out + off + bj * HALF + 4 * n) = r[m][bj][n] + gv[bj][n] * acc[ai][bj][m][n]; } }
; template <class Epi, class Sched, bool ALIGN_EPI = false, bool SP2 = false>
; __device__ __forceinline__ void gemm_phase(PG8_LAS unsigned char* lds, const Gemm g, const Sched& S, const Epi& E) {
;     ...
;     PG8_WAIT_V(0);
;     if constexpr (!ALIGN_EPI) { if (wr == 0) PG8_BAR; }
;     PG8_BAR;
	v_lshl_add_u64 v[80:81], v[80:81], 0, v[144:145]
	v_pk_fma_f32 v[70:71], v[70:71], v[150:151], v[238:239]
	v_pk_fma_f32 v[74:75], v[86:87], v[158:159], v[230:231]
	v_pk_fma_f32 v[72:73], v[84:85], v[160:161], v[228:229]
	global_store_dwordx4 v[80:81], v[72:75], off
	v_pk_fma_f32 v[68:69], v[68:69], v[152:153], v[236:237]
	v_pk_fma_f32 v[66:67], v[66:67], v[146:147], v[242:243]
	v_pk_fma_f32 v[74:75], v[78:79], v[154:155], v[234:235]
	v_pk_fma_f32 v[72:73], v[76:77], v[156:157], v[232:233]
	v_pk_fma_f32 v[64:65], v[64:65], v[148:149], v[240:241]
	v_lshl_add_u64 v[172:173], v[164:165], 0, s[18:19]
	v_lshl_add_u64 v[174:175], v[164:165], 0, s[20:21]
	v_lshl_add_u64 v[176:177], v[164:165], 0, s[22:23]
	global_store_dwordx4 v[80:81], v[72:75], off offset:16
	global_store_dwordx4 v[80:81], v[68:71], off offset:512
	global_store_dwordx4 v[80:81], v[64:67], off offset:528
	v_lshl_add_u64 v[80:81], v[162:163], 0, v[172:173]
	v_lshl_add_u64 v[92:93], v[162:163], 0, v[174:175]
	v_lshl_add_u64 v[108:109], v[162:163], 0, v[176:177]
	global_load_dwordx4 v[64:67], v[80:81], off
	global_load_dwordx4 v[68:71], v[80:81], off offset:16
	global_load_dwordx4 v[72:75], v[80:81], off offset:512
	global_load_dwordx4 v[76:79], v[80:81], off offset:528
	s_nop 0
	global_load_dwordx4 v[80:83], v[92:93], off
	global_load_dwordx4 v[84:87], v[92:93], off offset:16
	global_load_dwordx4 v[88:91], v[92:93], off offset:512
	s_nop 0
	global_load_dwordx4 v[92:95], v[92:93], off offset:528
	s_nop 0
	global_load_dwordx4 v[96:99], v[108:109], off
	global_load_dwordx4 v[100:103], v[108:109], off offset:16
	global_load_dwordx4 v[104:107], v[108:109], off offset:512
	s_nop 0
	global_load_dwordx4 v[108:111], v[108:109], off offset:528
	v_lshl_add_u64 v[164:165], v[164:165], 0, s[12:13]
	v_lshl_add_u64 v[124:125], v[162:163], 0, v[164:165]
	global_load_dwordx4 v[112:115], v[124:125], off
	global_load_dwordx4 v[116:119], v[124:125], off offset:16
	global_load_dwordx4 v[120:123], v[124:125], off offset:512
	s_nop 0
	global_load_dwordx4 v[124:127], v[124:125], off offset:528
	v_lshl_add_u64 v[162:163], s[10:11], 0, v[172:173]
	v_lshl_add_u64 v[172:173], s[10:11], 0, v[174:175]
	v_lshl_add_u64 v[174:175], s[10:11], 0, v[176:177]
	v_lshl_add_u64 v[162:163], v[162:163], 0, v[144:145]
	v_lshl_add_u64 v[174:175], v[174:175], 0, v[144:145]
	v_lshl_add_u64 v[172:173], v[172:173], 0, v[144:145]
	s_waitcnt vmcnt(15)
	v_pk_fma_f32 v[62:63], v[62:63], v[158:159], v[66:67]
	v_pk_fma_f32 v[60:61], v[60:61], v[160:161], v[64:65]
	s_waitcnt vmcnt(14)
	v_pk_fma_f32 v[58:59], v[58:59], v[154:155], v[70:71]
	v_pk_fma_f32 v[56:57], v[56:57], v[156:157], v[68:69]
	s_waitcnt vmcnt(5)
	v_pk_fma_f32 v[18:19], v[18:19], v[150:151], v[106:107]
	v_pk_fma_f32 v[16:17], v[16:17], v[152:153], v[104:105]
	v_pk_fma_f32 v[42:43], v[42:43], v[150:151], v[74:75]
	v_pk_fma_f32 v[40:41], v[40:41], v[152:153], v[72:73]
	v_pk_fma_f32 v[38:39], v[38:39], v[146:147], v[78:79]
	v_pk_fma_f32 v[36:37], v[36:37], v[148:149], v[76:77]
	v_pk_fma_f32 v[54:55], v[54:55], v[158:159], v[82:83]
	v_pk_fma_f32 v[52:53], v[52:53], v[160:161], v[80:81]
	v_pk_fma_f32 v[50:51], v[50:51], v[154:155], v[86:87]
	v_pk_fma_f32 v[48:49], v[48:49], v[156:157], v[84:85]
	v_pk_fma_f32 v[30:31], v[30:31], v[150:151], v[90:91]
	v_pk_fma_f32 v[28:29], v[28:29], v[152:153], v[88:89]
	v_pk_fma_f32 v[26:27], v[26:27], v[146:147], v[94:95]
	v_pk_fma_f32 v[24:25], v[24:25], v[148:149], v[92:93]
	v_pk_fma_f32 v[46:47], v[46:47], v[158:159], v[98:99]
	v_pk_fma_f32 v[44:45], v[44:45], v[160:161], v[96:97]
	v_pk_fma_f32 v[34:35], v[34:35], v[154:155], v[102:103]
	v_pk_fma_f32 v[32:33], v[32:33], v[156:157], v[100:101]
	global_store_dwordx4 v[162:163], v[60:63], off
	global_store_dwordx4 v[162:163], v[56:59], off offset:16
	global_store_dwordx4 v[162:163], v[40:43], off offset:512
	global_store_dwordx4 v[162:163], v[36:39], off offset:528
	global_store_dwordx4 v[172:173], v[52:55], off
	global_store_dwordx4 v[172:173], v[48:51], off offset:16
	global_store_dwordx4 v[172:173], v[28:31], off offset:512
	global_store_dwordx4 v[172:173], v[24:27], off offset:528
	global_store_dwordx4 v[174:175], v[44:47], off
	global_store_dwordx4 v[174:175], v[32:35], off offset:16
	global_store_dwordx4 v[174:175], v[16:19], off offset:512
	s_waitcnt vmcnt(15)
	v_pk_fma_f32 v[10:11], v[10:11], v[146:147], v[110:111]
	v_pk_fma_f32 v[8:9], v[8:9], v[148:149], v[108:109]
	v_lshl_add_u64 v[16:17], s[10:11], 0, v[164:165]
	global_store_dwordx4 v[174:175], v[8:11], off offset:528
	v_lshl_add_u64 v[16:17], v[16:17], 0, v[144:145]
	s_waitcnt vmcnt(13)
	v_pk_fma_f32 v[6:7], v[6:7], v[150:151], v[122:123]
	v_pk_fma_f32 v[10:11], v[22:23], v[158:159], v[114:115]
	v_pk_fma_f32 v[8:9], v[20:21], v[160:161], v[112:113]
	global_store_dwordx4 v[16:17], v[8:11], off
	v_pk_fma_f32 v[4:5], v[4:5], v[152:153], v[120:121]
	s_waitcnt vmcnt(13)
	v_pk_fma_f32 v[2:3], v[2:3], v[146:147], v[126:127]
	v_pk_fma_f32 v[10:11], v[14:15], v[154:155], v[118:119]
	v_pk_fma_f32 v[8:9], v[12:13], v[156:157], v[116:117]
	v_pk_fma_f32 v[0:1], v[0:1], v[148:149], v[124:125]
	global_store_dwordx4 v[16:17], v[8:11], off offset:16
	global_store_dwordx4 v[16:17], v[4:7], off offset:512
	global_store_dwordx4 v[16:17], v[0:3], off offset:528
	s_cbranch_vccz .LBB0_1010
	s_waitcnt vmcnt(0)
	s_cmpk_gt_u32 s3, 0xff
	s_cbranch_scc1 .LBB0_1025
	s_barrier
